# hand-written post and prep phases: 5 tokens per wave, token loads up front, LoRA tables streamed through a register ring
# speedup vs baseline: 1.2188x; 1.0217x over previous
.LBB0_523:
	s_andn2_b64 vcc, exec, s[2:3]
	s_cbranch_vccnz .LBB0_597
	v_readlane_b32 s10, v164, 0
	v_readlane_b32 s11, v162, 14
	v_lshrrev_b32_e32 v234, 6, v128
	v_and_b32_e32 v235, 63, v128
	v_readlane_b32 s16, v164, 43
	v_readlane_b32 s17, v164, 44
	v_readlane_b32 s18, v164, 47
	v_readlane_b32 s19, v164, 48
	v_readfirstlane_b32 s12, v234
	v_lshlrev_b32_e32 v232, 4, v235
	v_lshlrev_b32_e32 v233, 2, v235
	v_readlane_b32 s20, v164, 41
	v_readlane_b32 s21, v164, 42
	v_readlane_b32 s22, v164, 45
	v_readlane_b32 s23, v164, 46
	v_readlane_b32 s6, v164, 51
	v_readlane_b32 s7, v164, 52
	s_lshl_b32 s13, s10, 2
	s_add_u32 s13, s13, s12
	s_mul_i32 s13, s13, 5
	s_mul_i32 s14, s11, 20
	s_lshl_b32 s4, s34, 16
	s_add_u32 s16, s16, s4
	s_addc_u32 s17, s17, 0
	s_add_u32 s18, s18, s4
	s_addc_u32 s19, s19, 0
	s_lshl_b32 s4, s34, 11
	s_add_u32 s20, s20, s4
	s_addc_u32 s21, s21, 0
	s_add_u32 s22, s22, s4
	s_addc_u32 s23, s23, 0
	s_lshl_b32 s4, s34, 10
	s_add_u32 s6, s6, s4
	s_addc_u32 s7, s7, 0
	global_load_dwordx4 v[30:33], v232, s[6:7]
	global_load_dwordx4 v[34:37], v232, s[20:21]
	global_load_dwordx4 v[38:41], v232, s[20:21] offset:1024
	global_load_dwordx4 v[42:45], v232, s[22:23]
	global_load_dwordx4 v[46:49], v232, s[22:23] offset:1024
.Lgprep_batch:
	s_mov_b32 s6, s13
	s_min_u32 s6, s6, 0x27ff
	s_mul_i32 s7, s6, 0x2f00
	s_add_u32 s7, s7, 0x2400
	s_add_u32 s8, s74, s7
	s_addc_u32 s9, s75, 0
	global_load_dword v20, v233, s[8:9] offset:2048
	global_load_dword v25, v233, s[8:9] offset:2304
	s_add_u32 s6, s13, 1
	s_min_u32 s6, s6, 0x27ff
	s_mul_i32 s7, s6, 0x2f00
	s_add_u32 s7, s7, 0x2400
	s_add_u32 s8, s74, s7
	s_addc_u32 s9, s75, 0
	global_load_dword v21, v233, s[8:9] offset:2048
	global_load_dword v26, v233, s[8:9] offset:2304
	s_add_u32 s6, s13, 2
	s_min_u32 s6, s6, 0x27ff
	s_mul_i32 s7, s6, 0x2f00
	s_add_u32 s7, s7, 0x2400
	s_add_u32 s8, s74, s7
	s_addc_u32 s9, s75, 0
	global_load_dword v22, v233, s[8:9] offset:2048
	global_load_dword v27, v233, s[8:9] offset:2304
	s_add_u32 s6, s13, 3
	s_min_u32 s6, s6, 0x27ff
	s_mul_i32 s7, s6, 0x2f00
	s_add_u32 s7, s7, 0x2400
	s_add_u32 s8, s74, s7
	s_addc_u32 s9, s75, 0
	global_load_dword v23, v233, s[8:9] offset:2048
	global_load_dword v28, v233, s[8:9] offset:2304
	s_add_u32 s6, s13, 4
	s_min_u32 s6, s6, 0x27ff
	s_mul_i32 s7, s6, 0x2f00
	s_add_u32 s7, s7, 0x2400
	s_add_u32 s8, s74, s7
	s_addc_u32 s9, s75, 0
	global_load_dword v24, v233, s[8:9] offset:2048
	global_load_dword v29, v233, s[8:9] offset:2304
	s_mov_b32 s6, s13
	s_min_u32 s6, s6, 0x27ff
	s_mul_i32 s7, s6, 0x2f00
	s_add_u32 s7, s7, 0x2400
	s_add_u32 s8, s74, s7
	s_addc_u32 s9, s75, 0
	global_load_dwordx4 v[0:3], v232, s[8:9]
	s_add_u32 s6, s13, 1
	s_min_u32 s6, s6, 0x27ff
	s_mul_i32 s7, s6, 0x2f00
	s_add_u32 s7, s7, 0x2400
	s_add_u32 s8, s74, s7
	s_addc_u32 s9, s75, 0
	global_load_dwordx4 v[4:7], v232, s[8:9]
	s_add_u32 s6, s13, 2
	s_min_u32 s6, s6, 0x27ff
	s_mul_i32 s7, s6, 0x2f00
	s_add_u32 s7, s7, 0x2400
	s_add_u32 s8, s74, s7
	s_addc_u32 s9, s75, 0
	global_load_dwordx4 v[8:11], v232, s[8:9]
	s_add_u32 s6, s13, 3
	s_min_u32 s6, s6, 0x27ff
	s_mul_i32 s7, s6, 0x2f00
	s_add_u32 s7, s7, 0x2400
	s_add_u32 s8, s74, s7
	s_addc_u32 s9, s75, 0
	global_load_dwordx4 v[12:15], v232, s[8:9]
	s_add_u32 s6, s13, 4
	s_min_u32 s6, s6, 0x27ff
	s_mul_i32 s7, s6, 0x2f00
	s_add_u32 s7, s7, 0x2400
	s_add_u32 s8, s74, s7
	s_addc_u32 s9, s75, 0
	global_load_dwordx4 v[16:19], v232, s[8:9]
	s_add_u32 s2, s16, 0x0
	s_addc_u32 s3, s17, 0
	s_add_u32 s40, s18, 0x0
	s_addc_u32 s41, s19, 0
	global_load_dwordx4 v[168:171], v232, s[2:3]
	global_load_dwordx4 v[172:175], v232, s[40:41]
	global_load_dwordx4 v[176:179], v232, s[2:3] offset:1024
	global_load_dwordx4 v[180:183], v232, s[40:41] offset:1024
	global_load_dwordx4 v[184:187], v232, s[2:3] offset:2048
	global_load_dwordx4 v[188:191], v232, s[40:41] offset:2048
	global_load_dwordx4 v[192:195], v232, s[2:3] offset:3072
	global_load_dwordx4 v[196:199], v232, s[40:41] offset:3072
	s_add_u32 s2, s2, 0x1000
	s_addc_u32 s3, s3, 0
	s_add_u32 s40, s40, 0x1000
	s_addc_u32 s41, s41, 0
	global_load_dwordx4 v[200:203], v232, s[2:3]
	global_load_dwordx4 v[204:207], v232, s[40:41]
	global_load_dwordx4 v[208:211], v232, s[2:3] offset:1024
	global_load_dwordx4 v[212:215], v232, s[40:41] offset:1024
	s_waitcnt vmcnt(17)
	v_add_f32_e64 v92, |v20|, |v20|
	v_mul_f32_e32 v93, 0x3fb8aa3b, v92
	v_rndne_f32_e32 v94, v93
	s_mov_b32 s4, 0x3fb8aa3b
	v_sub_f32_e32 v95, v93, v94
	v_fma_f32 v93, v92, s4, -v93
	v_fmac_f32_e32 v93, 0x32a5705f, v92
	v_add_f32_e32 v93, v95, v93
	v_cvt_i32_f32_e32 v94, v94
	v_exp_f32_e32 v93, v93
	s_mov_b32 s4, 0xc2ce8ed0
	v_cmp_ngt_f32_e32 vcc, s4, v92
	s_mov_b32 s4, 0x42b17218
	v_ldexp_f32 v93, v93, v94
	s_nop 0
	v_cndmask_b32_e32 v93, 0, v93, vcc
	v_cmp_nlt_f32_e32 vcc, s4, v92
	s_nop 1
	v_cndmask_b32_e32 v92, v134, v93, vcc
	v_add_f32_e32 v92, 1.0, v92
	v_rcp_f32_e32 v92, v92
	s_nop 0
	v_fma_f32 v96, v92, -2.0, 1.0
	v_mul_f32_e32 v98, v20, v20
	v_fmamk_f32 v97, v98, 0xbbbac73d, v131
	v_fmaak_f32 v97, v98, v97, 0xbd5c1c4e
	v_fmaak_f32 v97, v98, v97, 0x3e088382
	v_fmaak_f32 v97, v98, v97, 0xbeaaaa99
	v_mul_f32_e64 v97, |v20|, v97
	v_fma_f32 v97, v98, v97, |v20|
	s_mov_b32 s4, 0x3f200000
	v_cmp_nlt_f32_e64 vcc, |v20|, s4
	s_nop 1
	v_cndmask_b32_e32 v97, v97, v96, vcc
	s_brev_b32 s4, -2
	v_bfi_b32 v20, s4, v97, v20
	v_add_f32_e64 v92, |v21|, |v21|
	v_mul_f32_e32 v93, 0x3fb8aa3b, v92
	v_rndne_f32_e32 v94, v93
	s_mov_b32 s4, 0x3fb8aa3b
	v_sub_f32_e32 v95, v93, v94
	v_fma_f32 v93, v92, s4, -v93
	v_fmac_f32_e32 v93, 0x32a5705f, v92
	v_add_f32_e32 v93, v95, v93
	v_cvt_i32_f32_e32 v94, v94
	v_exp_f32_e32 v93, v93
	s_mov_b32 s4, 0xc2ce8ed0
	v_cmp_ngt_f32_e32 vcc, s4, v92
	s_mov_b32 s4, 0x42b17218
	v_ldexp_f32 v93, v93, v94
	s_nop 0
	v_cndmask_b32_e32 v93, 0, v93, vcc
	v_cmp_nlt_f32_e32 vcc, s4, v92
	s_nop 1
	v_cndmask_b32_e32 v92, v134, v93, vcc
	v_add_f32_e32 v92, 1.0, v92
	v_rcp_f32_e32 v92, v92
	s_nop 0
	v_fma_f32 v96, v92, -2.0, 1.0
	v_mul_f32_e32 v98, v21, v21
	v_fmamk_f32 v97, v98, 0xbbbac73d, v131
	v_fmaak_f32 v97, v98, v97, 0xbd5c1c4e
	v_fmaak_f32 v97, v98, v97, 0x3e088382
	v_fmaak_f32 v97, v98, v97, 0xbeaaaa99
	v_mul_f32_e64 v97, |v21|, v97
	v_fma_f32 v97, v98, v97, |v21|
	s_mov_b32 s4, 0x3f200000
	v_cmp_nlt_f32_e64 vcc, |v21|, s4
	s_nop 1
	v_cndmask_b32_e32 v97, v97, v96, vcc
	s_brev_b32 s4, -2
	v_bfi_b32 v21, s4, v97, v21
	v_add_f32_e64 v92, |v22|, |v22|
	v_mul_f32_e32 v93, 0x3fb8aa3b, v92
	v_rndne_f32_e32 v94, v93
	s_mov_b32 s4, 0x3fb8aa3b
	v_sub_f32_e32 v95, v93, v94
	v_fma_f32 v93, v92, s4, -v93
	v_fmac_f32_e32 v93, 0x32a5705f, v92
	v_add_f32_e32 v93, v95, v93
	v_cvt_i32_f32_e32 v94, v94
	v_exp_f32_e32 v93, v93
	s_mov_b32 s4, 0xc2ce8ed0
	v_cmp_ngt_f32_e32 vcc, s4, v92
	s_mov_b32 s4, 0x42b17218
	v_ldexp_f32 v93, v93, v94
	s_nop 0
	v_cndmask_b32_e32 v93, 0, v93, vcc
	v_cmp_nlt_f32_e32 vcc, s4, v92
	s_nop 1
	v_cndmask_b32_e32 v92, v134, v93, vcc
	v_add_f32_e32 v92, 1.0, v92
	v_rcp_f32_e32 v92, v92
	s_nop 0
	v_fma_f32 v96, v92, -2.0, 1.0
	v_mul_f32_e32 v98, v22, v22
	v_fmamk_f32 v97, v98, 0xbbbac73d, v131
	v_fmaak_f32 v97, v98, v97, 0xbd5c1c4e
	v_fmaak_f32 v97, v98, v97, 0x3e088382
	v_fmaak_f32 v97, v98, v97, 0xbeaaaa99
	v_mul_f32_e64 v97, |v22|, v97
	v_fma_f32 v97, v98, v97, |v22|
	s_mov_b32 s4, 0x3f200000
	v_cmp_nlt_f32_e64 vcc, |v22|, s4
	s_nop 1
	v_cndmask_b32_e32 v97, v97, v96, vcc
	s_brev_b32 s4, -2
	v_bfi_b32 v22, s4, v97, v22
	v_add_f32_e64 v92, |v23|, |v23|
	v_mul_f32_e32 v93, 0x3fb8aa3b, v92
	v_rndne_f32_e32 v94, v93
	s_mov_b32 s4, 0x3fb8aa3b
	v_sub_f32_e32 v95, v93, v94
	v_fma_f32 v93, v92, s4, -v93
	v_fmac_f32_e32 v93, 0x32a5705f, v92
	v_add_f32_e32 v93, v95, v93
	v_cvt_i32_f32_e32 v94, v94
	v_exp_f32_e32 v93, v93
	s_mov_b32 s4, 0xc2ce8ed0
	v_cmp_ngt_f32_e32 vcc, s4, v92
	s_mov_b32 s4, 0x42b17218
	v_ldexp_f32 v93, v93, v94
	s_nop 0
	v_cndmask_b32_e32 v93, 0, v93, vcc
	v_cmp_nlt_f32_e32 vcc, s4, v92
	s_nop 1
	v_cndmask_b32_e32 v92, v134, v93, vcc
	v_add_f32_e32 v92, 1.0, v92
	v_rcp_f32_e32 v92, v92
	s_nop 0
	v_fma_f32 v96, v92, -2.0, 1.0
	v_mul_f32_e32 v98, v23, v23
	v_fmamk_f32 v97, v98, 0xbbbac73d, v131
	v_fmaak_f32 v97, v98, v97, 0xbd5c1c4e
	v_fmaak_f32 v97, v98, v97, 0x3e088382
	v_fmaak_f32 v97, v98, v97, 0xbeaaaa99
	v_mul_f32_e64 v97, |v23|, v97
	v_fma_f32 v97, v98, v97, |v23|
	s_mov_b32 s4, 0x3f200000
	v_cmp_nlt_f32_e64 vcc, |v23|, s4
	s_nop 1
	v_cndmask_b32_e32 v97, v97, v96, vcc
	s_brev_b32 s4, -2
	v_bfi_b32 v23, s4, v97, v23
	v_add_f32_e64 v92, |v24|, |v24|
	v_mul_f32_e32 v93, 0x3fb8aa3b, v92
	v_rndne_f32_e32 v94, v93
	s_mov_b32 s4, 0x3fb8aa3b
	v_sub_f32_e32 v95, v93, v94
	v_fma_f32 v93, v92, s4, -v93
	v_fmac_f32_e32 v93, 0x32a5705f, v92
	v_add_f32_e32 v93, v95, v93
	v_cvt_i32_f32_e32 v94, v94
	v_exp_f32_e32 v93, v93
	s_mov_b32 s4, 0xc2ce8ed0
	v_cmp_ngt_f32_e32 vcc, s4, v92
	s_mov_b32 s4, 0x42b17218
	v_ldexp_f32 v93, v93, v94
	s_nop 0
	v_cndmask_b32_e32 v93, 0, v93, vcc
	v_cmp_nlt_f32_e32 vcc, s4, v92
	s_nop 1
	v_cndmask_b32_e32 v92, v134, v93, vcc
	v_add_f32_e32 v92, 1.0, v92
	v_rcp_f32_e32 v92, v92
	s_nop 0
	v_fma_f32 v96, v92, -2.0, 1.0
	v_mul_f32_e32 v98, v24, v24
	v_fmamk_f32 v97, v98, 0xbbbac73d, v131
	v_fmaak_f32 v97, v98, v97, 0xbd5c1c4e
	v_fmaak_f32 v97, v98, v97, 0x3e088382
	v_fmaak_f32 v97, v98, v97, 0xbeaaaa99
	v_mul_f32_e64 v97, |v24|, v97
	v_fma_f32 v97, v98, v97, |v24|
	s_mov_b32 s4, 0x3f200000
	v_cmp_nlt_f32_e64 vcc, |v24|, s4
	s_nop 1
	v_cndmask_b32_e32 v97, v97, v96, vcc
	s_brev_b32 s4, -2
	v_bfi_b32 v24, s4, v97, v24
	s_waitcnt vmcnt(12)
	v_mul_f32_e32 v0, v30, v0
	v_mul_f32_e32 v1, v31, v1
	v_mul_f32_e32 v2, v32, v2
	v_mul_f32_e32 v3, v33, v3
	v_mul_f32_e32 v92, v0, v0
	v_mul_f32_e32 v93, v2, v2
	v_fmac_f32_e32 v92, v1, v1
	v_fmac_f32_e32 v93, v3, v3
	v_add_f32_e32 v92, v92, v93
	s_nop 1
	v_add_f32_dpp v92, v92, v92 quad_perm:[1,0,3,2] row_mask:0xf bank_mask:0xf bound_ctrl:1
	s_nop 1
	v_add_f32_dpp v92, v92, v92 quad_perm:[2,3,0,1] row_mask:0xf bank_mask:0xf bound_ctrl:1
	s_nop 1
	v_add_f32_dpp v92, v92, v92 row_half_mirror row_mask:0xf bank_mask:0xf bound_ctrl:1
	s_nop 1
	v_add_f32_dpp v92, v92, v92 row_mirror row_mask:0xf bank_mask:0xf bound_ctrl:1
	v_add_f32_e32 v92, 0x358637bd, v92
	v_rsq_f32_e32 v92, v92
	s_nop 0
	v_mul_f32_e32 v0, v0, v92
	v_mul_f32_e32 v1, v1, v92
	v_mul_f32_e32 v2, v2, v92
	v_mul_f32_e32 v3, v3, v92
	v_mul_f32_e32 v4, v30, v4
	v_mul_f32_e32 v5, v31, v5
	v_mul_f32_e32 v6, v32, v6
	v_mul_f32_e32 v7, v33, v7
	v_mul_f32_e32 v92, v4, v4
	v_mul_f32_e32 v93, v6, v6
	v_fmac_f32_e32 v92, v5, v5
	v_fmac_f32_e32 v93, v7, v7
	v_add_f32_e32 v92, v92, v93
	s_nop 1
	v_add_f32_dpp v92, v92, v92 quad_perm:[1,0,3,2] row_mask:0xf bank_mask:0xf bound_ctrl:1
	s_nop 1
	v_add_f32_dpp v92, v92, v92 quad_perm:[2,3,0,1] row_mask:0xf bank_mask:0xf bound_ctrl:1
	s_nop 1
	v_add_f32_dpp v92, v92, v92 row_half_mirror row_mask:0xf bank_mask:0xf bound_ctrl:1
	s_nop 1
	v_add_f32_dpp v92, v92, v92 row_mirror row_mask:0xf bank_mask:0xf bound_ctrl:1
	v_add_f32_e32 v92, 0x358637bd, v92
	v_rsq_f32_e32 v92, v92
	s_nop 0
	v_mul_f32_e32 v4, v4, v92
	v_mul_f32_e32 v5, v5, v92
	v_mul_f32_e32 v6, v6, v92
	v_mul_f32_e32 v7, v7, v92
	v_mul_f32_e32 v8, v30, v8
	v_mul_f32_e32 v9, v31, v9
	v_mul_f32_e32 v10, v32, v10
	v_mul_f32_e32 v11, v33, v11
	v_mul_f32_e32 v92, v8, v8
	v_mul_f32_e32 v93, v10, v10
	v_fmac_f32_e32 v92, v9, v9
	v_fmac_f32_e32 v93, v11, v11
	v_add_f32_e32 v92, v92, v93
	s_nop 1
	v_add_f32_dpp v92, v92, v92 quad_perm:[1,0,3,2] row_mask:0xf bank_mask:0xf bound_ctrl:1
	s_nop 1
	v_add_f32_dpp v92, v92, v92 quad_perm:[2,3,0,1] row_mask:0xf bank_mask:0xf bound_ctrl:1
	s_nop 1
	v_add_f32_dpp v92, v92, v92 row_half_mirror row_mask:0xf bank_mask:0xf bound_ctrl:1
	s_nop 1
	v_add_f32_dpp v92, v92, v92 row_mirror row_mask:0xf bank_mask:0xf bound_ctrl:1
	v_add_f32_e32 v92, 0x358637bd, v92
	v_rsq_f32_e32 v92, v92
	s_nop 0
	v_mul_f32_e32 v8, v8, v92
	v_mul_f32_e32 v9, v9, v92
	v_mul_f32_e32 v10, v10, v92
	v_mul_f32_e32 v11, v11, v92
	v_mul_f32_e32 v12, v30, v12
	v_mul_f32_e32 v13, v31, v13
	v_mul_f32_e32 v14, v32, v14
	v_mul_f32_e32 v15, v33, v15
	v_mul_f32_e32 v92, v12, v12
	v_mul_f32_e32 v93, v14, v14
	v_fmac_f32_e32 v92, v13, v13
	v_fmac_f32_e32 v93, v15, v15
	v_add_f32_e32 v92, v92, v93
	s_nop 1
	v_add_f32_dpp v92, v92, v92 quad_perm:[1,0,3,2] row_mask:0xf bank_mask:0xf bound_ctrl:1
	s_nop 1
	v_add_f32_dpp v92, v92, v92 quad_perm:[2,3,0,1] row_mask:0xf bank_mask:0xf bound_ctrl:1
	s_nop 1
	v_add_f32_dpp v92, v92, v92 row_half_mirror row_mask:0xf bank_mask:0xf bound_ctrl:1
	s_nop 1
	v_add_f32_dpp v92, v92, v92 row_mirror row_mask:0xf bank_mask:0xf bound_ctrl:1
	v_add_f32_e32 v92, 0x358637bd, v92
	v_rsq_f32_e32 v92, v92
	s_nop 0
	v_mul_f32_e32 v12, v12, v92
	v_mul_f32_e32 v13, v13, v92
	v_mul_f32_e32 v14, v14, v92
	v_mul_f32_e32 v15, v15, v92
	v_mul_f32_e32 v16, v30, v16
	v_mul_f32_e32 v17, v31, v17
	v_mul_f32_e32 v18, v32, v18
	v_mul_f32_e32 v19, v33, v19
	v_mul_f32_e32 v92, v16, v16
	v_mul_f32_e32 v93, v18, v18
	v_fmac_f32_e32 v92, v17, v17
	v_fmac_f32_e32 v93, v19, v19
	v_add_f32_e32 v92, v92, v93
	s_nop 1
	v_add_f32_dpp v92, v92, v92 quad_perm:[1,0,3,2] row_mask:0xf bank_mask:0xf bound_ctrl:1
	s_nop 1
	v_add_f32_dpp v92, v92, v92 quad_perm:[2,3,0,1] row_mask:0xf bank_mask:0xf bound_ctrl:1
	s_nop 1
	v_add_f32_dpp v92, v92, v92 row_half_mirror row_mask:0xf bank_mask:0xf bound_ctrl:1
	s_nop 1
	v_add_f32_dpp v92, v92, v92 row_mirror row_mask:0xf bank_mask:0xf bound_ctrl:1
	v_add_f32_e32 v92, 0x358637bd, v92
	v_rsq_f32_e32 v92, v92
	s_nop 0
	v_mul_f32_e32 v16, v16, v92
	v_mul_f32_e32 v17, v17, v92
	v_mul_f32_e32 v18, v18, v92
	v_mul_f32_e32 v19, v19, v92
	v_mov_b32_e32 v52, v34
	v_mov_b32_e32 v56, v42
	v_mov_b32_e32 v53, v35
	v_mov_b32_e32 v57, v43
	v_mov_b32_e32 v54, v36
	v_mov_b32_e32 v58, v44
	v_mov_b32_e32 v55, v37
	v_mov_b32_e32 v59, v45
	v_mov_b32_e32 v60, v34
	v_mov_b32_e32 v64, v42
	v_mov_b32_e32 v61, v35
	v_mov_b32_e32 v65, v43
	v_mov_b32_e32 v62, v36
	v_mov_b32_e32 v66, v44
	v_mov_b32_e32 v63, v37
	v_mov_b32_e32 v67, v45
	v_mov_b32_e32 v68, v34
	v_mov_b32_e32 v72, v42
	v_mov_b32_e32 v69, v35
	v_mov_b32_e32 v73, v43
	v_mov_b32_e32 v70, v36
	v_mov_b32_e32 v74, v44
	v_mov_b32_e32 v71, v37
	v_mov_b32_e32 v75, v45
	v_mov_b32_e32 v76, v34
	v_mov_b32_e32 v80, v42
	v_mov_b32_e32 v77, v35
	v_mov_b32_e32 v81, v43
	v_mov_b32_e32 v78, v36
	v_mov_b32_e32 v82, v44
	v_mov_b32_e32 v79, v37
	v_mov_b32_e32 v83, v45
	v_mov_b32_e32 v84, v34
	v_mov_b32_e32 v88, v42
	v_mov_b32_e32 v85, v35
	v_mov_b32_e32 v89, v43
	v_mov_b32_e32 v86, v36
	v_mov_b32_e32 v90, v44
	v_mov_b32_e32 v87, v37
	v_mov_b32_e32 v91, v45
	global_load_dwordx4 v[216:219], v232, s[2:3] offset:2048
	global_load_dwordx4 v[220:223], v232, s[40:41] offset:2048
	s_waitcnt vmcnt(12)
	v_readlane_b32 s48, v20, 0
	v_readlane_b32 s58, v25, 0
	v_readlane_b32 s50, v21, 0
	v_readlane_b32 s60, v26, 0
	v_readlane_b32 s52, v22, 0
	v_readlane_b32 s62, v27, 0
	v_readlane_b32 s54, v23, 0
	v_readlane_b32 s64, v28, 0
	v_readlane_b32 s56, v24, 0
	v_readlane_b32 s66, v29, 0
	v_pk_fma_f32 v[52:53], v[168:169], s[48:49], v[52:53] op_sel_hi:[1,0,1]
	v_pk_fma_f32 v[54:55], v[170:171], s[48:49], v[54:55] op_sel_hi:[1,0,1]
	v_pk_fma_f32 v[56:57], v[172:173], s[58:59], v[56:57] op_sel_hi:[1,0,1]
	v_pk_fma_f32 v[58:59], v[174:175], s[58:59], v[58:59] op_sel_hi:[1,0,1]
	v_pk_fma_f32 v[60:61], v[168:169], s[50:51], v[60:61] op_sel_hi:[1,0,1]
	v_pk_fma_f32 v[62:63], v[170:171], s[50:51], v[62:63] op_sel_hi:[1,0,1]
	v_pk_fma_f32 v[64:65], v[172:173], s[60:61], v[64:65] op_sel_hi:[1,0,1]
	v_pk_fma_f32 v[66:67], v[174:175], s[60:61], v[66:67] op_sel_hi:[1,0,1]
	v_pk_fma_f32 v[68:69], v[168:169], s[52:53], v[68:69] op_sel_hi:[1,0,1]
	v_pk_fma_f32 v[70:71], v[170:171], s[52:53], v[70:71] op_sel_hi:[1,0,1]
	v_pk_fma_f32 v[72:73], v[172:173], s[62:63], v[72:73] op_sel_hi:[1,0,1]
	v_pk_fma_f32 v[74:75], v[174:175], s[62:63], v[74:75] op_sel_hi:[1,0,1]
	v_pk_fma_f32 v[76:77], v[168:169], s[54:55], v[76:77] op_sel_hi:[1,0,1]
	v_pk_fma_f32 v[78:79], v[170:171], s[54:55], v[78:79] op_sel_hi:[1,0,1]
	v_pk_fma_f32 v[80:81], v[172:173], s[64:65], v[80:81] op_sel_hi:[1,0,1]
	v_pk_fma_f32 v[82:83], v[174:175], s[64:65], v[82:83] op_sel_hi:[1,0,1]
	v_pk_fma_f32 v[84:85], v[168:169], s[56:57], v[84:85] op_sel_hi:[1,0,1]
	v_pk_fma_f32 v[86:87], v[170:171], s[56:57], v[86:87] op_sel_hi:[1,0,1]
	v_pk_fma_f32 v[88:89], v[172:173], s[66:67], v[88:89] op_sel_hi:[1,0,1]
	v_pk_fma_f32 v[90:91], v[174:175], s[66:67], v[90:91] op_sel_hi:[1,0,1]
	global_load_dwordx4 v[224:227], v232, s[2:3] offset:3072
	global_load_dwordx4 v[228:231], v232, s[40:41] offset:3072
	s_add_u32 s2, s2, 0x1000
	s_addc_u32 s3, s3, 0
	s_add_u32 s40, s40, 0x1000
	s_addc_u32 s41, s41, 0
	s_waitcnt vmcnt(12)
	v_readlane_b32 s48, v20, 1
	v_readlane_b32 s58, v25, 1
	v_readlane_b32 s50, v21, 1
	v_readlane_b32 s60, v26, 1
	v_readlane_b32 s52, v22, 1
	v_readlane_b32 s62, v27, 1
	v_readlane_b32 s54, v23, 1
	v_readlane_b32 s64, v28, 1
	v_readlane_b32 s56, v24, 1
	v_readlane_b32 s66, v29, 1
	v_pk_fma_f32 v[52:53], v[176:177], s[48:49], v[52:53] op_sel_hi:[1,0,1]
	v_pk_fma_f32 v[54:55], v[178:179], s[48:49], v[54:55] op_sel_hi:[1,0,1]
	v_pk_fma_f32 v[56:57], v[180:181], s[58:59], v[56:57] op_sel_hi:[1,0,1]
	v_pk_fma_f32 v[58:59], v[182:183], s[58:59], v[58:59] op_sel_hi:[1,0,1]
	v_pk_fma_f32 v[60:61], v[176:177], s[50:51], v[60:61] op_sel_hi:[1,0,1]
	v_pk_fma_f32 v[62:63], v[178:179], s[50:51], v[62:63] op_sel_hi:[1,0,1]
	v_pk_fma_f32 v[64:65], v[180:181], s[60:61], v[64:65] op_sel_hi:[1,0,1]
	v_pk_fma_f32 v[66:67], v[182:183], s[60:61], v[66:67] op_sel_hi:[1,0,1]
	v_pk_fma_f32 v[68:69], v[176:177], s[52:53], v[68:69] op_sel_hi:[1,0,1]
	v_pk_fma_f32 v[70:71], v[178:179], s[52:53], v[70:71] op_sel_hi:[1,0,1]
	v_pk_fma_f32 v[72:73], v[180:181], s[62:63], v[72:73] op_sel_hi:[1,0,1]
	v_pk_fma_f32 v[74:75], v[182:183], s[62:63], v[74:75] op_sel_hi:[1,0,1]
	v_pk_fma_f32 v[76:77], v[176:177], s[54:55], v[76:77] op_sel_hi:[1,0,1]
	v_pk_fma_f32 v[78:79], v[178:179], s[54:55], v[78:79] op_sel_hi:[1,0,1]
	v_pk_fma_f32 v[80:81], v[180:181], s[64:65], v[80:81] op_sel_hi:[1,0,1]
	v_pk_fma_f32 v[82:83], v[182:183], s[64:65], v[82:83] op_sel_hi:[1,0,1]
	v_pk_fma_f32 v[84:85], v[176:177], s[56:57], v[84:85] op_sel_hi:[1,0,1]
	v_pk_fma_f32 v[86:87], v[178:179], s[56:57], v[86:87] op_sel_hi:[1,0,1]
	v_pk_fma_f32 v[88:89], v[180:181], s[66:67], v[88:89] op_sel_hi:[1,0,1]
	v_pk_fma_f32 v[90:91], v[182:183], s[66:67], v[90:91] op_sel_hi:[1,0,1]
	global_load_dwordx4 v[168:171], v232, s[2:3]
	global_load_dwordx4 v[172:175], v232, s[40:41]
	s_waitcnt vmcnt(12)
	v_readlane_b32 s48, v20, 2
	v_readlane_b32 s58, v25, 2
	v_readlane_b32 s50, v21, 2
	v_readlane_b32 s60, v26, 2
	v_readlane_b32 s52, v22, 2
	v_readlane_b32 s62, v27, 2
	v_readlane_b32 s54, v23, 2
	v_readlane_b32 s64, v28, 2
	v_readlane_b32 s56, v24, 2
	v_readlane_b32 s66, v29, 2
	v_pk_fma_f32 v[52:53], v[184:185], s[48:49], v[52:53] op_sel_hi:[1,0,1]
	v_pk_fma_f32 v[54:55], v[186:187], s[48:49], v[54:55] op_sel_hi:[1,0,1]
	v_pk_fma_f32 v[56:57], v[188:189], s[58:59], v[56:57] op_sel_hi:[1,0,1]
	v_pk_fma_f32 v[58:59], v[190:191], s[58:59], v[58:59] op_sel_hi:[1,0,1]
	v_pk_fma_f32 v[60:61], v[184:185], s[50:51], v[60:61] op_sel_hi:[1,0,1]
	v_pk_fma_f32 v[62:63], v[186:187], s[50:51], v[62:63] op_sel_hi:[1,0,1]
	v_pk_fma_f32 v[64:65], v[188:189], s[60:61], v[64:65] op_sel_hi:[1,0,1]
	v_pk_fma_f32 v[66:67], v[190:191], s[60:61], v[66:67] op_sel_hi:[1,0,1]
	v_pk_fma_f32 v[68:69], v[184:185], s[52:53], v[68:69] op_sel_hi:[1,0,1]
	v_pk_fma_f32 v[70:71], v[186:187], s[52:53], v[70:71] op_sel_hi:[1,0,1]
	v_pk_fma_f32 v[72:73], v[188:189], s[62:63], v[72:73] op_sel_hi:[1,0,1]
	v_pk_fma_f32 v[74:75], v[190:191], s[62:63], v[74:75] op_sel_hi:[1,0,1]
	v_pk_fma_f32 v[76:77], v[184:185], s[54:55], v[76:77] op_sel_hi:[1,0,1]
	v_pk_fma_f32 v[78:79], v[186:187], s[54:55], v[78:79] op_sel_hi:[1,0,1]
	v_pk_fma_f32 v[80:81], v[188:189], s[64:65], v[80:81] op_sel_hi:[1,0,1]
	v_pk_fma_f32 v[82:83], v[190:191], s[64:65], v[82:83] op_sel_hi:[1,0,1]
	v_pk_fma_f32 v[84:85], v[184:185], s[56:57], v[84:85] op_sel_hi:[1,0,1]
	v_pk_fma_f32 v[86:87], v[186:187], s[56:57], v[86:87] op_sel_hi:[1,0,1]
	v_pk_fma_f32 v[88:89], v[188:189], s[66:67], v[88:89] op_sel_hi:[1,0,1]
	v_pk_fma_f32 v[90:91], v[190:191], s[66:67], v[90:91] op_sel_hi:[1,0,1]
	global_load_dwordx4 v[176:179], v232, s[2:3] offset:1024
	global_load_dwordx4 v[180:183], v232, s[40:41] offset:1024
	s_waitcnt vmcnt(12)
	v_readlane_b32 s48, v20, 3
	v_readlane_b32 s58, v25, 3
	v_readlane_b32 s50, v21, 3
	v_readlane_b32 s60, v26, 3
	v_readlane_b32 s52, v22, 3
	v_readlane_b32 s62, v27, 3
	v_readlane_b32 s54, v23, 3
	v_readlane_b32 s64, v28, 3
	v_readlane_b32 s56, v24, 3
	v_readlane_b32 s66, v29, 3
	v_pk_fma_f32 v[52:53], v[192:193], s[48:49], v[52:53] op_sel_hi:[1,0,1]
	v_pk_fma_f32 v[54:55], v[194:195], s[48:49], v[54:55] op_sel_hi:[1,0,1]
	v_pk_fma_f32 v[56:57], v[196:197], s[58:59], v[56:57] op_sel_hi:[1,0,1]
	v_pk_fma_f32 v[58:59], v[198:199], s[58:59], v[58:59] op_sel_hi:[1,0,1]
	v_pk_fma_f32 v[60:61], v[192:193], s[50:51], v[60:61] op_sel_hi:[1,0,1]
	v_pk_fma_f32 v[62:63], v[194:195], s[50:51], v[62:63] op_sel_hi:[1,0,1]
	v_pk_fma_f32 v[64:65], v[196:197], s[60:61], v[64:65] op_sel_hi:[1,0,1]
	v_pk_fma_f32 v[66:67], v[198:199], s[60:61], v[66:67] op_sel_hi:[1,0,1]
	v_pk_fma_f32 v[68:69], v[192:193], s[52:53], v[68:69] op_sel_hi:[1,0,1]
	v_pk_fma_f32 v[70:71], v[194:195], s[52:53], v[70:71] op_sel_hi:[1,0,1]
	v_pk_fma_f32 v[72:73], v[196:197], s[62:63], v[72:73] op_sel_hi:[1,0,1]
	v_pk_fma_f32 v[74:75], v[198:199], s[62:63], v[74:75] op_sel_hi:[1,0,1]
	v_pk_fma_f32 v[76:77], v[192:193], s[54:55], v[76:77] op_sel_hi:[1,0,1]
	v_pk_fma_f32 v[78:79], v[194:195], s[54:55], v[78:79] op_sel_hi:[1,0,1]
	v_pk_fma_f32 v[80:81], v[196:197], s[64:65], v[80:81] op_sel_hi:[1,0,1]
	v_pk_fma_f32 v[82:83], v[198:199], s[64:65], v[82:83] op_sel_hi:[1,0,1]
	v_pk_fma_f32 v[84:85], v[192:193], s[56:57], v[84:85] op_sel_hi:[1,0,1]
	v_pk_fma_f32 v[86:87], v[194:195], s[56:57], v[86:87] op_sel_hi:[1,0,1]
	v_pk_fma_f32 v[88:89], v[196:197], s[66:67], v[88:89] op_sel_hi:[1,0,1]
	v_pk_fma_f32 v[90:91], v[198:199], s[66:67], v[90:91] op_sel_hi:[1,0,1]
	global_load_dwordx4 v[184:187], v232, s[2:3] offset:2048
	global_load_dwordx4 v[188:191], v232, s[40:41] offset:2048
	s_waitcnt vmcnt(12)
	v_readlane_b32 s48, v20, 4
	v_readlane_b32 s58, v25, 4
	v_readlane_b32 s50, v21, 4
	v_readlane_b32 s60, v26, 4
	v_readlane_b32 s52, v22, 4
	v_readlane_b32 s62, v27, 4
	v_readlane_b32 s54, v23, 4
	v_readlane_b32 s64, v28, 4
	v_readlane_b32 s56, v24, 4
	v_readlane_b32 s66, v29, 4
	v_pk_fma_f32 v[52:53], v[200:201], s[48:49], v[52:53] op_sel_hi:[1,0,1]
	v_pk_fma_f32 v[54:55], v[202:203], s[48:49], v[54:55] op_sel_hi:[1,0,1]
	v_pk_fma_f32 v[56:57], v[204:205], s[58:59], v[56:57] op_sel_hi:[1,0,1]
	v_pk_fma_f32 v[58:59], v[206:207], s[58:59], v[58:59] op_sel_hi:[1,0,1]
	v_pk_fma_f32 v[60:61], v[200:201], s[50:51], v[60:61] op_sel_hi:[1,0,1]
	v_pk_fma_f32 v[62:63], v[202:203], s[50:51], v[62:63] op_sel_hi:[1,0,1]
	v_pk_fma_f32 v[64:65], v[204:205], s[60:61], v[64:65] op_sel_hi:[1,0,1]
	v_pk_fma_f32 v[66:67], v[206:207], s[60:61], v[66:67] op_sel_hi:[1,0,1]
	v_pk_fma_f32 v[68:69], v[200:201], s[52:53], v[68:69] op_sel_hi:[1,0,1]
	v_pk_fma_f32 v[70:71], v[202:203], s[52:53], v[70:71] op_sel_hi:[1,0,1]
	v_pk_fma_f32 v[72:73], v[204:205], s[62:63], v[72:73] op_sel_hi:[1,0,1]
	v_pk_fma_f32 v[74:75], v[206:207], s[62:63], v[74:75] op_sel_hi:[1,0,1]
	v_pk_fma_f32 v[76:77], v[200:201], s[54:55], v[76:77] op_sel_hi:[1,0,1]
	v_pk_fma_f32 v[78:79], v[202:203], s[54:55], v[78:79] op_sel_hi:[1,0,1]
	v_pk_fma_f32 v[80:81], v[204:205], s[64:65], v[80:81] op_sel_hi:[1,0,1]
	v_pk_fma_f32 v[82:83], v[206:207], s[64:65], v[82:83] op_sel_hi:[1,0,1]
	v_pk_fma_f32 v[84:85], v[200:201], s[56:57], v[84:85] op_sel_hi:[1,0,1]
	v_pk_fma_f32 v[86:87], v[202:203], s[56:57], v[86:87] op_sel_hi:[1,0,1]
	v_pk_fma_f32 v[88:89], v[204:205], s[66:67], v[88:89] op_sel_hi:[1,0,1]
	v_pk_fma_f32 v[90:91], v[206:207], s[66:67], v[90:91] op_sel_hi:[1,0,1]
	global_load_dwordx4 v[192:195], v232, s[2:3] offset:3072
	global_load_dwordx4 v[196:199], v232, s[40:41] offset:3072
	s_add_u32 s2, s2, 0x1000
	s_addc_u32 s3, s3, 0
	s_add_u32 s40, s40, 0x1000
	s_addc_u32 s41, s41, 0
	s_waitcnt vmcnt(12)
	v_readlane_b32 s48, v20, 5
	v_readlane_b32 s58, v25, 5
	v_readlane_b32 s50, v21, 5
	v_readlane_b32 s60, v26, 5
	v_readlane_b32 s52, v22, 5
	v_readlane_b32 s62, v27, 5
	v_readlane_b32 s54, v23, 5
	v_readlane_b32 s64, v28, 5
	v_readlane_b32 s56, v24, 5
	v_readlane_b32 s66, v29, 5
	v_pk_fma_f32 v[52:53], v[208:209], s[48:49], v[52:53] op_sel_hi:[1,0,1]
	v_pk_fma_f32 v[54:55], v[210:211], s[48:49], v[54:55] op_sel_hi:[1,0,1]
	v_pk_fma_f32 v[56:57], v[212:213], s[58:59], v[56:57] op_sel_hi:[1,0,1]
	v_pk_fma_f32 v[58:59], v[214:215], s[58:59], v[58:59] op_sel_hi:[1,0,1]
	v_pk_fma_f32 v[60:61], v[208:209], s[50:51], v[60:61] op_sel_hi:[1,0,1]
	v_pk_fma_f32 v[62:63], v[210:211], s[50:51], v[62:63] op_sel_hi:[1,0,1]
	v_pk_fma_f32 v[64:65], v[212:213], s[60:61], v[64:65] op_sel_hi:[1,0,1]
	v_pk_fma_f32 v[66:67], v[214:215], s[60:61], v[66:67] op_sel_hi:[1,0,1]
	v_pk_fma_f32 v[68:69], v[208:209], s[52:53], v[68:69] op_sel_hi:[1,0,1]
	v_pk_fma_f32 v[70:71], v[210:211], s[52:53], v[70:71] op_sel_hi:[1,0,1]
	v_pk_fma_f32 v[72:73], v[212:213], s[62:63], v[72:73] op_sel_hi:[1,0,1]
	v_pk_fma_f32 v[74:75], v[214:215], s[62:63], v[74:75] op_sel_hi:[1,0,1]
	v_pk_fma_f32 v[76:77], v[208:209], s[54:55], v[76:77] op_sel_hi:[1,0,1]
	v_pk_fma_f32 v[78:79], v[210:211], s[54:55], v[78:79] op_sel_hi:[1,0,1]
	v_pk_fma_f32 v[80:81], v[212:213], s[64:65], v[80:81] op_sel_hi:[1,0,1]
	v_pk_fma_f32 v[82:83], v[214:215], s[64:65], v[82:83] op_sel_hi:[1,0,1]
	v_pk_fma_f32 v[84:85], v[208:209], s[56:57], v[84:85] op_sel_hi:[1,0,1]
	v_pk_fma_f32 v[86:87], v[210:211], s[56:57], v[86:87] op_sel_hi:[1,0,1]
	v_pk_fma_f32 v[88:89], v[212:213], s[66:67], v[88:89] op_sel_hi:[1,0,1]
	v_pk_fma_f32 v[90:91], v[214:215], s[66:67], v[90:91] op_sel_hi:[1,0,1]
	global_load_dwordx4 v[200:203], v232, s[2:3]
	global_load_dwordx4 v[204:207], v232, s[40:41]
	s_waitcnt vmcnt(12)
	v_readlane_b32 s48, v20, 6
	v_readlane_b32 s58, v25, 6
	v_readlane_b32 s50, v21, 6
	v_readlane_b32 s60, v26, 6
	v_readlane_b32 s52, v22, 6
	v_readlane_b32 s62, v27, 6
	v_readlane_b32 s54, v23, 6
	v_readlane_b32 s64, v28, 6
	v_readlane_b32 s56, v24, 6
	v_readlane_b32 s66, v29, 6
	v_pk_fma_f32 v[52:53], v[216:217], s[48:49], v[52:53] op_sel_hi:[1,0,1]
	v_pk_fma_f32 v[54:55], v[218:219], s[48:49], v[54:55] op_sel_hi:[1,0,1]
	v_pk_fma_f32 v[56:57], v[220:221], s[58:59], v[56:57] op_sel_hi:[1,0,1]
	v_pk_fma_f32 v[58:59], v[222:223], s[58:59], v[58:59] op_sel_hi:[1,0,1]
	v_pk_fma_f32 v[60:61], v[216:217], s[50:51], v[60:61] op_sel_hi:[1,0,1]
	v_pk_fma_f32 v[62:63], v[218:219], s[50:51], v[62:63] op_sel_hi:[1,0,1]
	v_pk_fma_f32 v[64:65], v[220:221], s[60:61], v[64:65] op_sel_hi:[1,0,1]
	v_pk_fma_f32 v[66:67], v[222:223], s[60:61], v[66:67] op_sel_hi:[1,0,1]
	v_pk_fma_f32 v[68:69], v[216:217], s[52:53], v[68:69] op_sel_hi:[1,0,1]
	v_pk_fma_f32 v[70:71], v[218:219], s[52:53], v[70:71] op_sel_hi:[1,0,1]
	v_pk_fma_f32 v[72:73], v[220:221], s[62:63], v[72:73] op_sel_hi:[1,0,1]
	v_pk_fma_f32 v[74:75], v[222:223], s[62:63], v[74:75] op_sel_hi:[1,0,1]
	v_pk_fma_f32 v[76:77], v[216:217], s[54:55], v[76:77] op_sel_hi:[1,0,1]
	v_pk_fma_f32 v[78:79], v[218:219], s[54:55], v[78:79] op_sel_hi:[1,0,1]
	v_pk_fma_f32 v[80:81], v[220:221], s[64:65], v[80:81] op_sel_hi:[1,0,1]
	v_pk_fma_f32 v[82:83], v[222:223], s[64:65], v[82:83] op_sel_hi:[1,0,1]
	v_pk_fma_f32 v[84:85], v[216:217], s[56:57], v[84:85] op_sel_hi:[1,0,1]
	v_pk_fma_f32 v[86:87], v[218:219], s[56:57], v[86:87] op_sel_hi:[1,0,1]
	v_pk_fma_f32 v[88:89], v[220:221], s[66:67], v[88:89] op_sel_hi:[1,0,1]
	v_pk_fma_f32 v[90:91], v[222:223], s[66:67], v[90:91] op_sel_hi:[1,0,1]
	global_load_dwordx4 v[208:211], v232, s[2:3] offset:1024
	global_load_dwordx4 v[212:215], v232, s[40:41] offset:1024
	s_waitcnt vmcnt(12)
	v_readlane_b32 s48, v20, 7
	v_readlane_b32 s58, v25, 7
	v_readlane_b32 s50, v21, 7
	v_readlane_b32 s60, v26, 7
	v_readlane_b32 s52, v22, 7
	v_readlane_b32 s62, v27, 7
	v_readlane_b32 s54, v23, 7
	v_readlane_b32 s64, v28, 7
	v_readlane_b32 s56, v24, 7
	v_readlane_b32 s66, v29, 7
	v_pk_fma_f32 v[52:53], v[224:225], s[48:49], v[52:53] op_sel_hi:[1,0,1]
	v_pk_fma_f32 v[54:55], v[226:227], s[48:49], v[54:55] op_sel_hi:[1,0,1]
	v_pk_fma_f32 v[56:57], v[228:229], s[58:59], v[56:57] op_sel_hi:[1,0,1]
	v_pk_fma_f32 v[58:59], v[230:231], s[58:59], v[58:59] op_sel_hi:[1,0,1]
	v_pk_fma_f32 v[60:61], v[224:225], s[50:51], v[60:61] op_sel_hi:[1,0,1]
	v_pk_fma_f32 v[62:63], v[226:227], s[50:51], v[62:63] op_sel_hi:[1,0,1]
	v_pk_fma_f32 v[64:65], v[228:229], s[60:61], v[64:65] op_sel_hi:[1,0,1]
	v_pk_fma_f32 v[66:67], v[230:231], s[60:61], v[66:67] op_sel_hi:[1,0,1]
	v_pk_fma_f32 v[68:69], v[224:225], s[52:53], v[68:69] op_sel_hi:[1,0,1]
	v_pk_fma_f32 v[70:71], v[226:227], s[52:53], v[70:71] op_sel_hi:[1,0,1]
	v_pk_fma_f32 v[72:73], v[228:229], s[62:63], v[72:73] op_sel_hi:[1,0,1]
	v_pk_fma_f32 v[74:75], v[230:231], s[62:63], v[74:75] op_sel_hi:[1,0,1]
	v_pk_fma_f32 v[76:77], v[224:225], s[54:55], v[76:77] op_sel_hi:[1,0,1]
	v_pk_fma_f32 v[78:79], v[226:227], s[54:55], v[78:79] op_sel_hi:[1,0,1]
	v_pk_fma_f32 v[80:81], v[228:229], s[64:65], v[80:81] op_sel_hi:[1,0,1]
	v_pk_fma_f32 v[82:83], v[230:231], s[64:65], v[82:83] op_sel_hi:[1,0,1]
	v_pk_fma_f32 v[84:85], v[224:225], s[56:57], v[84:85] op_sel_hi:[1,0,1]
	v_pk_fma_f32 v[86:87], v[226:227], s[56:57], v[86:87] op_sel_hi:[1,0,1]
	v_pk_fma_f32 v[88:89], v[228:229], s[66:67], v[88:89] op_sel_hi:[1,0,1]
	v_pk_fma_f32 v[90:91], v[230:231], s[66:67], v[90:91] op_sel_hi:[1,0,1]
	global_load_dwordx4 v[216:219], v232, s[2:3] offset:2048
	global_load_dwordx4 v[220:223], v232, s[40:41] offset:2048
	s_waitcnt vmcnt(12)
	v_readlane_b32 s48, v20, 8
	v_readlane_b32 s58, v25, 8
	v_readlane_b32 s50, v21, 8
	v_readlane_b32 s60, v26, 8
	v_readlane_b32 s52, v22, 8
	v_readlane_b32 s62, v27, 8
	v_readlane_b32 s54, v23, 8
	v_readlane_b32 s64, v28, 8
	v_readlane_b32 s56, v24, 8
	v_readlane_b32 s66, v29, 8
	v_pk_fma_f32 v[52:53], v[168:169], s[48:49], v[52:53] op_sel_hi:[1,0,1]
	v_pk_fma_f32 v[54:55], v[170:171], s[48:49], v[54:55] op_sel_hi:[1,0,1]
	v_pk_fma_f32 v[56:57], v[172:173], s[58:59], v[56:57] op_sel_hi:[1,0,1]
	v_pk_fma_f32 v[58:59], v[174:175], s[58:59], v[58:59] op_sel_hi:[1,0,1]
	v_pk_fma_f32 v[60:61], v[168:169], s[50:51], v[60:61] op_sel_hi:[1,0,1]
	v_pk_fma_f32 v[62:63], v[170:171], s[50:51], v[62:63] op_sel_hi:[1,0,1]
	v_pk_fma_f32 v[64:65], v[172:173], s[60:61], v[64:65] op_sel_hi:[1,0,1]
	v_pk_fma_f32 v[66:67], v[174:175], s[60:61], v[66:67] op_sel_hi:[1,0,1]
	v_pk_fma_f32 v[68:69], v[168:169], s[52:53], v[68:69] op_sel_hi:[1,0,1]
	v_pk_fma_f32 v[70:71], v[170:171], s[52:53], v[70:71] op_sel_hi:[1,0,1]
	v_pk_fma_f32 v[72:73], v[172:173], s[62:63], v[72:73] op_sel_hi:[1,0,1]
	v_pk_fma_f32 v[74:75], v[174:175], s[62:63], v[74:75] op_sel_hi:[1,0,1]
	v_pk_fma_f32 v[76:77], v[168:169], s[54:55], v[76:77] op_sel_hi:[1,0,1]
	v_pk_fma_f32 v[78:79], v[170:171], s[54:55], v[78:79] op_sel_hi:[1,0,1]
	v_pk_fma_f32 v[80:81], v[172:173], s[64:65], v[80:81] op_sel_hi:[1,0,1]
	v_pk_fma_f32 v[82:83], v[174:175], s[64:65], v[82:83] op_sel_hi:[1,0,1]
	v_pk_fma_f32 v[84:85], v[168:169], s[56:57], v[84:85] op_sel_hi:[1,0,1]
	v_pk_fma_f32 v[86:87], v[170:171], s[56:57], v[86:87] op_sel_hi:[1,0,1]
	v_pk_fma_f32 v[88:89], v[172:173], s[66:67], v[88:89] op_sel_hi:[1,0,1]
	v_pk_fma_f32 v[90:91], v[174:175], s[66:67], v[90:91] op_sel_hi:[1,0,1]
	global_load_dwordx4 v[224:227], v232, s[2:3] offset:3072
	global_load_dwordx4 v[228:231], v232, s[40:41] offset:3072
	s_add_u32 s2, s2, 0x1000
	s_addc_u32 s3, s3, 0
	s_add_u32 s40, s40, 0x1000
	s_addc_u32 s41, s41, 0
	s_waitcnt vmcnt(12)
	v_readlane_b32 s48, v20, 9
	v_readlane_b32 s58, v25, 9
	v_readlane_b32 s50, v21, 9
	v_readlane_b32 s60, v26, 9
	v_readlane_b32 s52, v22, 9
	v_readlane_b32 s62, v27, 9
	v_readlane_b32 s54, v23, 9
	v_readlane_b32 s64, v28, 9
	v_readlane_b32 s56, v24, 9
	v_readlane_b32 s66, v29, 9
	v_pk_fma_f32 v[52:53], v[176:177], s[48:49], v[52:53] op_sel_hi:[1,0,1]
	v_pk_fma_f32 v[54:55], v[178:179], s[48:49], v[54:55] op_sel_hi:[1,0,1]
	v_pk_fma_f32 v[56:57], v[180:181], s[58:59], v[56:57] op_sel_hi:[1,0,1]
	v_pk_fma_f32 v[58:59], v[182:183], s[58:59], v[58:59] op_sel_hi:[1,0,1]
	v_pk_fma_f32 v[60:61], v[176:177], s[50:51], v[60:61] op_sel_hi:[1,0,1]
	v_pk_fma_f32 v[62:63], v[178:179], s[50:51], v[62:63] op_sel_hi:[1,0,1]
	v_pk_fma_f32 v[64:65], v[180:181], s[60:61], v[64:65] op_sel_hi:[1,0,1]
	v_pk_fma_f32 v[66:67], v[182:183], s[60:61], v[66:67] op_sel_hi:[1,0,1]
	v_pk_fma_f32 v[68:69], v[176:177], s[52:53], v[68:69] op_sel_hi:[1,0,1]
	v_pk_fma_f32 v[70:71], v[178:179], s[52:53], v[70:71] op_sel_hi:[1,0,1]
	v_pk_fma_f32 v[72:73], v[180:181], s[62:63], v[72:73] op_sel_hi:[1,0,1]
	v_pk_fma_f32 v[74:75], v[182:183], s[62:63], v[74:75] op_sel_hi:[1,0,1]
	v_pk_fma_f32 v[76:77], v[176:177], s[54:55], v[76:77] op_sel_hi:[1,0,1]
	v_pk_fma_f32 v[78:79], v[178:179], s[54:55], v[78:79] op_sel_hi:[1,0,1]
	v_pk_fma_f32 v[80:81], v[180:181], s[64:65], v[80:81] op_sel_hi:[1,0,1]
	v_pk_fma_f32 v[82:83], v[182:183], s[64:65], v[82:83] op_sel_hi:[1,0,1]
	v_pk_fma_f32 v[84:85], v[176:177], s[56:57], v[84:85] op_sel_hi:[1,0,1]
	v_pk_fma_f32 v[86:87], v[178:179], s[56:57], v[86:87] op_sel_hi:[1,0,1]
	v_pk_fma_f32 v[88:89], v[180:181], s[66:67], v[88:89] op_sel_hi:[1,0,1]
	v_pk_fma_f32 v[90:91], v[182:183], s[66:67], v[90:91] op_sel_hi:[1,0,1]
	global_load_dwordx4 v[168:171], v232, s[2:3]
	global_load_dwordx4 v[172:175], v232, s[40:41]
	s_waitcnt vmcnt(12)
	v_readlane_b32 s48, v20, 10
	v_readlane_b32 s58, v25, 10
	v_readlane_b32 s50, v21, 10
	v_readlane_b32 s60, v26, 10
	v_readlane_b32 s52, v22, 10
	v_readlane_b32 s62, v27, 10
	v_readlane_b32 s54, v23, 10
	v_readlane_b32 s64, v28, 10
	v_readlane_b32 s56, v24, 10
	v_readlane_b32 s66, v29, 10
	v_pk_fma_f32 v[52:53], v[184:185], s[48:49], v[52:53] op_sel_hi:[1,0,1]
	v_pk_fma_f32 v[54:55], v[186:187], s[48:49], v[54:55] op_sel_hi:[1,0,1]
	v_pk_fma_f32 v[56:57], v[188:189], s[58:59], v[56:57] op_sel_hi:[1,0,1]
	v_pk_fma_f32 v[58:59], v[190:191], s[58:59], v[58:59] op_sel_hi:[1,0,1]
	v_pk_fma_f32 v[60:61], v[184:185], s[50:51], v[60:61] op_sel_hi:[1,0,1]
	v_pk_fma_f32 v[62:63], v[186:187], s[50:51], v[62:63] op_sel_hi:[1,0,1]
	v_pk_fma_f32 v[64:65], v[188:189], s[60:61], v[64:65] op_sel_hi:[1,0,1]
	v_pk_fma_f32 v[66:67], v[190:191], s[60:61], v[66:67] op_sel_hi:[1,0,1]
	v_pk_fma_f32 v[68:69], v[184:185], s[52:53], v[68:69] op_sel_hi:[1,0,1]
	v_pk_fma_f32 v[70:71], v[186:187], s[52:53], v[70:71] op_sel_hi:[1,0,1]
	v_pk_fma_f32 v[72:73], v[188:189], s[62:63], v[72:73] op_sel_hi:[1,0,1]
	v_pk_fma_f32 v[74:75], v[190:191], s[62:63], v[74:75] op_sel_hi:[1,0,1]
	v_pk_fma_f32 v[76:77], v[184:185], s[54:55], v[76:77] op_sel_hi:[1,0,1]
	v_pk_fma_f32 v[78:79], v[186:187], s[54:55], v[78:79] op_sel_hi:[1,0,1]
	v_pk_fma_f32 v[80:81], v[188:189], s[64:65], v[80:81] op_sel_hi:[1,0,1]
	v_pk_fma_f32 v[82:83], v[190:191], s[64:65], v[82:83] op_sel_hi:[1,0,1]
	v_pk_fma_f32 v[84:85], v[184:185], s[56:57], v[84:85] op_sel_hi:[1,0,1]
	v_pk_fma_f32 v[86:87], v[186:187], s[56:57], v[86:87] op_sel_hi:[1,0,1]
	v_pk_fma_f32 v[88:89], v[188:189], s[66:67], v[88:89] op_sel_hi:[1,0,1]
	v_pk_fma_f32 v[90:91], v[190:191], s[66:67], v[90:91] op_sel_hi:[1,0,1]
	global_load_dwordx4 v[176:179], v232, s[2:3] offset:1024
	global_load_dwordx4 v[180:183], v232, s[40:41] offset:1024
	s_waitcnt vmcnt(12)
	v_readlane_b32 s48, v20, 11
	v_readlane_b32 s58, v25, 11
	v_readlane_b32 s50, v21, 11
	v_readlane_b32 s60, v26, 11
	v_readlane_b32 s52, v22, 11
	v_readlane_b32 s62, v27, 11
	v_readlane_b32 s54, v23, 11
	v_readlane_b32 s64, v28, 11
	v_readlane_b32 s56, v24, 11
	v_readlane_b32 s66, v29, 11
	v_pk_fma_f32 v[52:53], v[192:193], s[48:49], v[52:53] op_sel_hi:[1,0,1]
	v_pk_fma_f32 v[54:55], v[194:195], s[48:49], v[54:55] op_sel_hi:[1,0,1]
	v_pk_fma_f32 v[56:57], v[196:197], s[58:59], v[56:57] op_sel_hi:[1,0,1]
	v_pk_fma_f32 v[58:59], v[198:199], s[58:59], v[58:59] op_sel_hi:[1,0,1]
	v_pk_fma_f32 v[60:61], v[192:193], s[50:51], v[60:61] op_sel_hi:[1,0,1]
	v_pk_fma_f32 v[62:63], v[194:195], s[50:51], v[62:63] op_sel_hi:[1,0,1]
	v_pk_fma_f32 v[64:65], v[196:197], s[60:61], v[64:65] op_sel_hi:[1,0,1]
	v_pk_fma_f32 v[66:67], v[198:199], s[60:61], v[66:67] op_sel_hi:[1,0,1]
	v_pk_fma_f32 v[68:69], v[192:193], s[52:53], v[68:69] op_sel_hi:[1,0,1]
	v_pk_fma_f32 v[70:71], v[194:195], s[52:53], v[70:71] op_sel_hi:[1,0,1]
	v_pk_fma_f32 v[72:73], v[196:197], s[62:63], v[72:73] op_sel_hi:[1,0,1]
	v_pk_fma_f32 v[74:75], v[198:199], s[62:63], v[74:75] op_sel_hi:[1,0,1]
	v_pk_fma_f32 v[76:77], v[192:193], s[54:55], v[76:77] op_sel_hi:[1,0,1]
	v_pk_fma_f32 v[78:79], v[194:195], s[54:55], v[78:79] op_sel_hi:[1,0,1]
	v_pk_fma_f32 v[80:81], v[196:197], s[64:65], v[80:81] op_sel_hi:[1,0,1]
	v_pk_fma_f32 v[82:83], v[198:199], s[64:65], v[82:83] op_sel_hi:[1,0,1]
	v_pk_fma_f32 v[84:85], v[192:193], s[56:57], v[84:85] op_sel_hi:[1,0,1]
	v_pk_fma_f32 v[86:87], v[194:195], s[56:57], v[86:87] op_sel_hi:[1,0,1]
	v_pk_fma_f32 v[88:89], v[196:197], s[66:67], v[88:89] op_sel_hi:[1,0,1]
	v_pk_fma_f32 v[90:91], v[198:199], s[66:67], v[90:91] op_sel_hi:[1,0,1]
	global_load_dwordx4 v[184:187], v232, s[2:3] offset:2048
	global_load_dwordx4 v[188:191], v232, s[40:41] offset:2048
	s_waitcnt vmcnt(12)
	v_readlane_b32 s48, v20, 12
	v_readlane_b32 s58, v25, 12
	v_readlane_b32 s50, v21, 12
	v_readlane_b32 s60, v26, 12
	v_readlane_b32 s52, v22, 12
	v_readlane_b32 s62, v27, 12
	v_readlane_b32 s54, v23, 12
	v_readlane_b32 s64, v28, 12
	v_readlane_b32 s56, v24, 12
	v_readlane_b32 s66, v29, 12
	v_pk_fma_f32 v[52:53], v[200:201], s[48:49], v[52:53] op_sel_hi:[1,0,1]
	v_pk_fma_f32 v[54:55], v[202:203], s[48:49], v[54:55] op_sel_hi:[1,0,1]
	v_pk_fma_f32 v[56:57], v[204:205], s[58:59], v[56:57] op_sel_hi:[1,0,1]
	v_pk_fma_f32 v[58:59], v[206:207], s[58:59], v[58:59] op_sel_hi:[1,0,1]
	v_pk_fma_f32 v[60:61], v[200:201], s[50:51], v[60:61] op_sel_hi:[1,0,1]
	v_pk_fma_f32 v[62:63], v[202:203], s[50:51], v[62:63] op_sel_hi:[1,0,1]
	v_pk_fma_f32 v[64:65], v[204:205], s[60:61], v[64:65] op_sel_hi:[1,0,1]
	v_pk_fma_f32 v[66:67], v[206:207], s[60:61], v[66:67] op_sel_hi:[1,0,1]
	v_pk_fma_f32 v[68:69], v[200:201], s[52:53], v[68:69] op_sel_hi:[1,0,1]
	v_pk_fma_f32 v[70:71], v[202:203], s[52:53], v[70:71] op_sel_hi:[1,0,1]
	v_pk_fma_f32 v[72:73], v[204:205], s[62:63], v[72:73] op_sel_hi:[1,0,1]
	v_pk_fma_f32 v[74:75], v[206:207], s[62:63], v[74:75] op_sel_hi:[1,0,1]
	v_pk_fma_f32 v[76:77], v[200:201], s[54:55], v[76:77] op_sel_hi:[1,0,1]
	v_pk_fma_f32 v[78:79], v[202:203], s[54:55], v[78:79] op_sel_hi:[1,0,1]
	v_pk_fma_f32 v[80:81], v[204:205], s[64:65], v[80:81] op_sel_hi:[1,0,1]
	v_pk_fma_f32 v[82:83], v[206:207], s[64:65], v[82:83] op_sel_hi:[1,0,1]
	v_pk_fma_f32 v[84:85], v[200:201], s[56:57], v[84:85] op_sel_hi:[1,0,1]
	v_pk_fma_f32 v[86:87], v[202:203], s[56:57], v[86:87] op_sel_hi:[1,0,1]
	v_pk_fma_f32 v[88:89], v[204:205], s[66:67], v[88:89] op_sel_hi:[1,0,1]
	v_pk_fma_f32 v[90:91], v[206:207], s[66:67], v[90:91] op_sel_hi:[1,0,1]
	global_load_dwordx4 v[192:195], v232, s[2:3] offset:3072
	global_load_dwordx4 v[196:199], v232, s[40:41] offset:3072
	s_add_u32 s2, s2, 0x1000
	s_addc_u32 s3, s3, 0
	s_add_u32 s40, s40, 0x1000
	s_addc_u32 s41, s41, 0
	s_waitcnt vmcnt(12)
	v_readlane_b32 s48, v20, 13
	v_readlane_b32 s58, v25, 13
	v_readlane_b32 s50, v21, 13
	v_readlane_b32 s60, v26, 13
	v_readlane_b32 s52, v22, 13
	v_readlane_b32 s62, v27, 13
	v_readlane_b32 s54, v23, 13
	v_readlane_b32 s64, v28, 13
	v_readlane_b32 s56, v24, 13
	v_readlane_b32 s66, v29, 13
	v_pk_fma_f32 v[52:53], v[208:209], s[48:49], v[52:53] op_sel_hi:[1,0,1]
	v_pk_fma_f32 v[54:55], v[210:211], s[48:49], v[54:55] op_sel_hi:[1,0,1]
	v_pk_fma_f32 v[56:57], v[212:213], s[58:59], v[56:57] op_sel_hi:[1,0,1]
	v_pk_fma_f32 v[58:59], v[214:215], s[58:59], v[58:59] op_sel_hi:[1,0,1]
	v_pk_fma_f32 v[60:61], v[208:209], s[50:51], v[60:61] op_sel_hi:[1,0,1]
	v_pk_fma_f32 v[62:63], v[210:211], s[50:51], v[62:63] op_sel_hi:[1,0,1]
	v_pk_fma_f32 v[64:65], v[212:213], s[60:61], v[64:65] op_sel_hi:[1,0,1]
	v_pk_fma_f32 v[66:67], v[214:215], s[60:61], v[66:67] op_sel_hi:[1,0,1]
	v_pk_fma_f32 v[68:69], v[208:209], s[52:53], v[68:69] op_sel_hi:[1,0,1]
	v_pk_fma_f32 v[70:71], v[210:211], s[52:53], v[70:71] op_sel_hi:[1,0,1]
	v_pk_fma_f32 v[72:73], v[212:213], s[62:63], v[72:73] op_sel_hi:[1,0,1]
	v_pk_fma_f32 v[74:75], v[214:215], s[62:63], v[74:75] op_sel_hi:[1,0,1]
	v_pk_fma_f32 v[76:77], v[208:209], s[54:55], v[76:77] op_sel_hi:[1,0,1]
	v_pk_fma_f32 v[78:79], v[210:211], s[54:55], v[78:79] op_sel_hi:[1,0,1]
	v_pk_fma_f32 v[80:81], v[212:213], s[64:65], v[80:81] op_sel_hi:[1,0,1]
	v_pk_fma_f32 v[82:83], v[214:215], s[64:65], v[82:83] op_sel_hi:[1,0,1]
	v_pk_fma_f32 v[84:85], v[208:209], s[56:57], v[84:85] op_sel_hi:[1,0,1]
	v_pk_fma_f32 v[86:87], v[210:211], s[56:57], v[86:87] op_sel_hi:[1,0,1]
	v_pk_fma_f32 v[88:89], v[212:213], s[66:67], v[88:89] op_sel_hi:[1,0,1]
	v_pk_fma_f32 v[90:91], v[214:215], s[66:67], v[90:91] op_sel_hi:[1,0,1]
	global_load_dwordx4 v[200:203], v232, s[2:3]
	global_load_dwordx4 v[204:207], v232, s[40:41]
	s_waitcnt vmcnt(12)
	v_readlane_b32 s48, v20, 14
	v_readlane_b32 s58, v25, 14
	v_readlane_b32 s50, v21, 14
	v_readlane_b32 s60, v26, 14
	v_readlane_b32 s52, v22, 14
	v_readlane_b32 s62, v27, 14
	v_readlane_b32 s54, v23, 14
	v_readlane_b32 s64, v28, 14
	v_readlane_b32 s56, v24, 14
	v_readlane_b32 s66, v29, 14
	v_pk_fma_f32 v[52:53], v[216:217], s[48:49], v[52:53] op_sel_hi:[1,0,1]
	v_pk_fma_f32 v[54:55], v[218:219], s[48:49], v[54:55] op_sel_hi:[1,0,1]
	v_pk_fma_f32 v[56:57], v[220:221], s[58:59], v[56:57] op_sel_hi:[1,0,1]
	v_pk_fma_f32 v[58:59], v[222:223], s[58:59], v[58:59] op_sel_hi:[1,0,1]
	v_pk_fma_f32 v[60:61], v[216:217], s[50:51], v[60:61] op_sel_hi:[1,0,1]
	v_pk_fma_f32 v[62:63], v[218:219], s[50:51], v[62:63] op_sel_hi:[1,0,1]
	v_pk_fma_f32 v[64:65], v[220:221], s[60:61], v[64:65] op_sel_hi:[1,0,1]
	v_pk_fma_f32 v[66:67], v[222:223], s[60:61], v[66:67] op_sel_hi:[1,0,1]
	v_pk_fma_f32 v[68:69], v[216:217], s[52:53], v[68:69] op_sel_hi:[1,0,1]
	v_pk_fma_f32 v[70:71], v[218:219], s[52:53], v[70:71] op_sel_hi:[1,0,1]
	v_pk_fma_f32 v[72:73], v[220:221], s[62:63], v[72:73] op_sel_hi:[1,0,1]
	v_pk_fma_f32 v[74:75], v[222:223], s[62:63], v[74:75] op_sel_hi:[1,0,1]
	v_pk_fma_f32 v[76:77], v[216:217], s[54:55], v[76:77] op_sel_hi:[1,0,1]
	v_pk_fma_f32 v[78:79], v[218:219], s[54:55], v[78:79] op_sel_hi:[1,0,1]
	v_pk_fma_f32 v[80:81], v[220:221], s[64:65], v[80:81] op_sel_hi:[1,0,1]
	v_pk_fma_f32 v[82:83], v[222:223], s[64:65], v[82:83] op_sel_hi:[1,0,1]
	v_pk_fma_f32 v[84:85], v[216:217], s[56:57], v[84:85] op_sel_hi:[1,0,1]
	v_pk_fma_f32 v[86:87], v[218:219], s[56:57], v[86:87] op_sel_hi:[1,0,1]
	v_pk_fma_f32 v[88:89], v[220:221], s[66:67], v[88:89] op_sel_hi:[1,0,1]
	v_pk_fma_f32 v[90:91], v[222:223], s[66:67], v[90:91] op_sel_hi:[1,0,1]
	global_load_dwordx4 v[208:211], v232, s[2:3] offset:1024
	global_load_dwordx4 v[212:215], v232, s[40:41] offset:1024
	s_waitcnt vmcnt(12)
	v_readlane_b32 s48, v20, 15
	v_readlane_b32 s58, v25, 15
	v_readlane_b32 s50, v21, 15
	v_readlane_b32 s60, v26, 15
	v_readlane_b32 s52, v22, 15
	v_readlane_b32 s62, v27, 15
	v_readlane_b32 s54, v23, 15
	v_readlane_b32 s64, v28, 15
	v_readlane_b32 s56, v24, 15
	v_readlane_b32 s66, v29, 15
	v_pk_fma_f32 v[52:53], v[224:225], s[48:49], v[52:53] op_sel_hi:[1,0,1]
	v_pk_fma_f32 v[54:55], v[226:227], s[48:49], v[54:55] op_sel_hi:[1,0,1]
	v_pk_fma_f32 v[56:57], v[228:229], s[58:59], v[56:57] op_sel_hi:[1,0,1]
	v_pk_fma_f32 v[58:59], v[230:231], s[58:59], v[58:59] op_sel_hi:[1,0,1]
	v_pk_fma_f32 v[60:61], v[224:225], s[50:51], v[60:61] op_sel_hi:[1,0,1]
	v_pk_fma_f32 v[62:63], v[226:227], s[50:51], v[62:63] op_sel_hi:[1,0,1]
	v_pk_fma_f32 v[64:65], v[228:229], s[60:61], v[64:65] op_sel_hi:[1,0,1]
	v_pk_fma_f32 v[66:67], v[230:231], s[60:61], v[66:67] op_sel_hi:[1,0,1]
	v_pk_fma_f32 v[68:69], v[224:225], s[52:53], v[68:69] op_sel_hi:[1,0,1]
	v_pk_fma_f32 v[70:71], v[226:227], s[52:53], v[70:71] op_sel_hi:[1,0,1]
	v_pk_fma_f32 v[72:73], v[228:229], s[62:63], v[72:73] op_sel_hi:[1,0,1]
	v_pk_fma_f32 v[74:75], v[230:231], s[62:63], v[74:75] op_sel_hi:[1,0,1]
	v_pk_fma_f32 v[76:77], v[224:225], s[54:55], v[76:77] op_sel_hi:[1,0,1]
	v_pk_fma_f32 v[78:79], v[226:227], s[54:55], v[78:79] op_sel_hi:[1,0,1]
	v_pk_fma_f32 v[80:81], v[228:229], s[64:65], v[80:81] op_sel_hi:[1,0,1]
	v_pk_fma_f32 v[82:83], v[230:231], s[64:65], v[82:83] op_sel_hi:[1,0,1]
	v_pk_fma_f32 v[84:85], v[224:225], s[56:57], v[84:85] op_sel_hi:[1,0,1]
	v_pk_fma_f32 v[86:87], v[226:227], s[56:57], v[86:87] op_sel_hi:[1,0,1]
	v_pk_fma_f32 v[88:89], v[228:229], s[66:67], v[88:89] op_sel_hi:[1,0,1]
	v_pk_fma_f32 v[90:91], v[230:231], s[66:67], v[90:91] op_sel_hi:[1,0,1]
	global_load_dwordx4 v[216:219], v232, s[2:3] offset:2048
	global_load_dwordx4 v[220:223], v232, s[40:41] offset:2048
	s_waitcnt vmcnt(12)
	v_readlane_b32 s48, v20, 16
	v_readlane_b32 s58, v25, 16
	v_readlane_b32 s50, v21, 16
	v_readlane_b32 s60, v26, 16
	v_readlane_b32 s52, v22, 16
	v_readlane_b32 s62, v27, 16
	v_readlane_b32 s54, v23, 16
	v_readlane_b32 s64, v28, 16
	v_readlane_b32 s56, v24, 16
	v_readlane_b32 s66, v29, 16
	v_pk_fma_f32 v[52:53], v[168:169], s[48:49], v[52:53] op_sel_hi:[1,0,1]
	v_pk_fma_f32 v[54:55], v[170:171], s[48:49], v[54:55] op_sel_hi:[1,0,1]
	v_pk_fma_f32 v[56:57], v[172:173], s[58:59], v[56:57] op_sel_hi:[1,0,1]
	v_pk_fma_f32 v[58:59], v[174:175], s[58:59], v[58:59] op_sel_hi:[1,0,1]
	v_pk_fma_f32 v[60:61], v[168:169], s[50:51], v[60:61] op_sel_hi:[1,0,1]
	v_pk_fma_f32 v[62:63], v[170:171], s[50:51], v[62:63] op_sel_hi:[1,0,1]
	v_pk_fma_f32 v[64:65], v[172:173], s[60:61], v[64:65] op_sel_hi:[1,0,1]
	v_pk_fma_f32 v[66:67], v[174:175], s[60:61], v[66:67] op_sel_hi:[1,0,1]
	v_pk_fma_f32 v[68:69], v[168:169], s[52:53], v[68:69] op_sel_hi:[1,0,1]
	v_pk_fma_f32 v[70:71], v[170:171], s[52:53], v[70:71] op_sel_hi:[1,0,1]
	v_pk_fma_f32 v[72:73], v[172:173], s[62:63], v[72:73] op_sel_hi:[1,0,1]
	v_pk_fma_f32 v[74:75], v[174:175], s[62:63], v[74:75] op_sel_hi:[1,0,1]
	v_pk_fma_f32 v[76:77], v[168:169], s[54:55], v[76:77] op_sel_hi:[1,0,1]
	v_pk_fma_f32 v[78:79], v[170:171], s[54:55], v[78:79] op_sel_hi:[1,0,1]
	v_pk_fma_f32 v[80:81], v[172:173], s[64:65], v[80:81] op_sel_hi:[1,0,1]
	v_pk_fma_f32 v[82:83], v[174:175], s[64:65], v[82:83] op_sel_hi:[1,0,1]
	v_pk_fma_f32 v[84:85], v[168:169], s[56:57], v[84:85] op_sel_hi:[1,0,1]
	v_pk_fma_f32 v[86:87], v[170:171], s[56:57], v[86:87] op_sel_hi:[1,0,1]
	v_pk_fma_f32 v[88:89], v[172:173], s[66:67], v[88:89] op_sel_hi:[1,0,1]
	v_pk_fma_f32 v[90:91], v[174:175], s[66:67], v[90:91] op_sel_hi:[1,0,1]
	global_load_dwordx4 v[224:227], v232, s[2:3] offset:3072
	global_load_dwordx4 v[228:231], v232, s[40:41] offset:3072
	s_add_u32 s2, s2, 0x1000
	s_addc_u32 s3, s3, 0
	s_add_u32 s40, s40, 0x1000
	s_addc_u32 s41, s41, 0
	s_waitcnt vmcnt(12)
	v_readlane_b32 s48, v20, 17
	v_readlane_b32 s58, v25, 17
	v_readlane_b32 s50, v21, 17
	v_readlane_b32 s60, v26, 17
	v_readlane_b32 s52, v22, 17
	v_readlane_b32 s62, v27, 17
	v_readlane_b32 s54, v23, 17
	v_readlane_b32 s64, v28, 17
	v_readlane_b32 s56, v24, 17
	v_readlane_b32 s66, v29, 17
	v_pk_fma_f32 v[52:53], v[176:177], s[48:49], v[52:53] op_sel_hi:[1,0,1]
	v_pk_fma_f32 v[54:55], v[178:179], s[48:49], v[54:55] op_sel_hi:[1,0,1]
	v_pk_fma_f32 v[56:57], v[180:181], s[58:59], v[56:57] op_sel_hi:[1,0,1]
	v_pk_fma_f32 v[58:59], v[182:183], s[58:59], v[58:59] op_sel_hi:[1,0,1]
	v_pk_fma_f32 v[60:61], v[176:177], s[50:51], v[60:61] op_sel_hi:[1,0,1]
	v_pk_fma_f32 v[62:63], v[178:179], s[50:51], v[62:63] op_sel_hi:[1,0,1]
	v_pk_fma_f32 v[64:65], v[180:181], s[60:61], v[64:65] op_sel_hi:[1,0,1]
	v_pk_fma_f32 v[66:67], v[182:183], s[60:61], v[66:67] op_sel_hi:[1,0,1]
	v_pk_fma_f32 v[68:69], v[176:177], s[52:53], v[68:69] op_sel_hi:[1,0,1]
	v_pk_fma_f32 v[70:71], v[178:179], s[52:53], v[70:71] op_sel_hi:[1,0,1]
	v_pk_fma_f32 v[72:73], v[180:181], s[62:63], v[72:73] op_sel_hi:[1,0,1]
	v_pk_fma_f32 v[74:75], v[182:183], s[62:63], v[74:75] op_sel_hi:[1,0,1]
	v_pk_fma_f32 v[76:77], v[176:177], s[54:55], v[76:77] op_sel_hi:[1,0,1]
	v_pk_fma_f32 v[78:79], v[178:179], s[54:55], v[78:79] op_sel_hi:[1,0,1]
	v_pk_fma_f32 v[80:81], v[180:181], s[64:65], v[80:81] op_sel_hi:[1,0,1]
	v_pk_fma_f32 v[82:83], v[182:183], s[64:65], v[82:83] op_sel_hi:[1,0,1]
	v_pk_fma_f32 v[84:85], v[176:177], s[56:57], v[84:85] op_sel_hi:[1,0,1]
	v_pk_fma_f32 v[86:87], v[178:179], s[56:57], v[86:87] op_sel_hi:[1,0,1]
	v_pk_fma_f32 v[88:89], v[180:181], s[66:67], v[88:89] op_sel_hi:[1,0,1]
	v_pk_fma_f32 v[90:91], v[182:183], s[66:67], v[90:91] op_sel_hi:[1,0,1]
	global_load_dwordx4 v[168:171], v232, s[2:3]
	global_load_dwordx4 v[172:175], v232, s[40:41]
	s_waitcnt vmcnt(12)
	v_readlane_b32 s48, v20, 18
	v_readlane_b32 s58, v25, 18
	v_readlane_b32 s50, v21, 18
	v_readlane_b32 s60, v26, 18
	v_readlane_b32 s52, v22, 18
	v_readlane_b32 s62, v27, 18
	v_readlane_b32 s54, v23, 18
	v_readlane_b32 s64, v28, 18
	v_readlane_b32 s56, v24, 18
	v_readlane_b32 s66, v29, 18
	v_pk_fma_f32 v[52:53], v[184:185], s[48:49], v[52:53] op_sel_hi:[1,0,1]
	v_pk_fma_f32 v[54:55], v[186:187], s[48:49], v[54:55] op_sel_hi:[1,0,1]
	v_pk_fma_f32 v[56:57], v[188:189], s[58:59], v[56:57] op_sel_hi:[1,0,1]
	v_pk_fma_f32 v[58:59], v[190:191], s[58:59], v[58:59] op_sel_hi:[1,0,1]
	v_pk_fma_f32 v[60:61], v[184:185], s[50:51], v[60:61] op_sel_hi:[1,0,1]
	v_pk_fma_f32 v[62:63], v[186:187], s[50:51], v[62:63] op_sel_hi:[1,0,1]
	v_pk_fma_f32 v[64:65], v[188:189], s[60:61], v[64:65] op_sel_hi:[1,0,1]
	v_pk_fma_f32 v[66:67], v[190:191], s[60:61], v[66:67] op_sel_hi:[1,0,1]
	v_pk_fma_f32 v[68:69], v[184:185], s[52:53], v[68:69] op_sel_hi:[1,0,1]
	v_pk_fma_f32 v[70:71], v[186:187], s[52:53], v[70:71] op_sel_hi:[1,0,1]
	v_pk_fma_f32 v[72:73], v[188:189], s[62:63], v[72:73] op_sel_hi:[1,0,1]
	v_pk_fma_f32 v[74:75], v[190:191], s[62:63], v[74:75] op_sel_hi:[1,0,1]
	v_pk_fma_f32 v[76:77], v[184:185], s[54:55], v[76:77] op_sel_hi:[1,0,1]
	v_pk_fma_f32 v[78:79], v[186:187], s[54:55], v[78:79] op_sel_hi:[1,0,1]
	v_pk_fma_f32 v[80:81], v[188:189], s[64:65], v[80:81] op_sel_hi:[1,0,1]
	v_pk_fma_f32 v[82:83], v[190:191], s[64:65], v[82:83] op_sel_hi:[1,0,1]
	v_pk_fma_f32 v[84:85], v[184:185], s[56:57], v[84:85] op_sel_hi:[1,0,1]
	v_pk_fma_f32 v[86:87], v[186:187], s[56:57], v[86:87] op_sel_hi:[1,0,1]
	v_pk_fma_f32 v[88:89], v[188:189], s[66:67], v[88:89] op_sel_hi:[1,0,1]
	v_pk_fma_f32 v[90:91], v[190:191], s[66:67], v[90:91] op_sel_hi:[1,0,1]
	global_load_dwordx4 v[176:179], v232, s[2:3] offset:1024
	global_load_dwordx4 v[180:183], v232, s[40:41] offset:1024
	s_waitcnt vmcnt(12)
	v_readlane_b32 s48, v20, 19
	v_readlane_b32 s58, v25, 19
	v_readlane_b32 s50, v21, 19
	v_readlane_b32 s60, v26, 19
	v_readlane_b32 s52, v22, 19
	v_readlane_b32 s62, v27, 19
	v_readlane_b32 s54, v23, 19
	v_readlane_b32 s64, v28, 19
	v_readlane_b32 s56, v24, 19
	v_readlane_b32 s66, v29, 19
	v_pk_fma_f32 v[52:53], v[192:193], s[48:49], v[52:53] op_sel_hi:[1,0,1]
	v_pk_fma_f32 v[54:55], v[194:195], s[48:49], v[54:55] op_sel_hi:[1,0,1]
	v_pk_fma_f32 v[56:57], v[196:197], s[58:59], v[56:57] op_sel_hi:[1,0,1]
	v_pk_fma_f32 v[58:59], v[198:199], s[58:59], v[58:59] op_sel_hi:[1,0,1]
	v_pk_fma_f32 v[60:61], v[192:193], s[50:51], v[60:61] op_sel_hi:[1,0,1]
	v_pk_fma_f32 v[62:63], v[194:195], s[50:51], v[62:63] op_sel_hi:[1,0,1]
	v_pk_fma_f32 v[64:65], v[196:197], s[60:61], v[64:65] op_sel_hi:[1,0,1]
	v_pk_fma_f32 v[66:67], v[198:199], s[60:61], v[66:67] op_sel_hi:[1,0,1]
	v_pk_fma_f32 v[68:69], v[192:193], s[52:53], v[68:69] op_sel_hi:[1,0,1]
	v_pk_fma_f32 v[70:71], v[194:195], s[52:53], v[70:71] op_sel_hi:[1,0,1]
	v_pk_fma_f32 v[72:73], v[196:197], s[62:63], v[72:73] op_sel_hi:[1,0,1]
	v_pk_fma_f32 v[74:75], v[198:199], s[62:63], v[74:75] op_sel_hi:[1,0,1]
	v_pk_fma_f32 v[76:77], v[192:193], s[54:55], v[76:77] op_sel_hi:[1,0,1]
	v_pk_fma_f32 v[78:79], v[194:195], s[54:55], v[78:79] op_sel_hi:[1,0,1]
	v_pk_fma_f32 v[80:81], v[196:197], s[64:65], v[80:81] op_sel_hi:[1,0,1]
	v_pk_fma_f32 v[82:83], v[198:199], s[64:65], v[82:83] op_sel_hi:[1,0,1]
	v_pk_fma_f32 v[84:85], v[192:193], s[56:57], v[84:85] op_sel_hi:[1,0,1]
	v_pk_fma_f32 v[86:87], v[194:195], s[56:57], v[86:87] op_sel_hi:[1,0,1]
	v_pk_fma_f32 v[88:89], v[196:197], s[66:67], v[88:89] op_sel_hi:[1,0,1]
	v_pk_fma_f32 v[90:91], v[198:199], s[66:67], v[90:91] op_sel_hi:[1,0,1]
	global_load_dwordx4 v[184:187], v232, s[2:3] offset:2048
	global_load_dwordx4 v[188:191], v232, s[40:41] offset:2048
	s_waitcnt vmcnt(12)
	v_readlane_b32 s48, v20, 20
	v_readlane_b32 s58, v25, 20
	v_readlane_b32 s50, v21, 20
	v_readlane_b32 s60, v26, 20
	v_readlane_b32 s52, v22, 20
	v_readlane_b32 s62, v27, 20
	v_readlane_b32 s54, v23, 20
	v_readlane_b32 s64, v28, 20
	v_readlane_b32 s56, v24, 20
	v_readlane_b32 s66, v29, 20
	v_pk_fma_f32 v[52:53], v[200:201], s[48:49], v[52:53] op_sel_hi:[1,0,1]
	v_pk_fma_f32 v[54:55], v[202:203], s[48:49], v[54:55] op_sel_hi:[1,0,1]
	v_pk_fma_f32 v[56:57], v[204:205], s[58:59], v[56:57] op_sel_hi:[1,0,1]
	v_pk_fma_f32 v[58:59], v[206:207], s[58:59], v[58:59] op_sel_hi:[1,0,1]
	v_pk_fma_f32 v[60:61], v[200:201], s[50:51], v[60:61] op_sel_hi:[1,0,1]
	v_pk_fma_f32 v[62:63], v[202:203], s[50:51], v[62:63] op_sel_hi:[1,0,1]
	v_pk_fma_f32 v[64:65], v[204:205], s[60:61], v[64:65] op_sel_hi:[1,0,1]
	v_pk_fma_f32 v[66:67], v[206:207], s[60:61], v[66:67] op_sel_hi:[1,0,1]
	v_pk_fma_f32 v[68:69], v[200:201], s[52:53], v[68:69] op_sel_hi:[1,0,1]
	v_pk_fma_f32 v[70:71], v[202:203], s[52:53], v[70:71] op_sel_hi:[1,0,1]
	v_pk_fma_f32 v[72:73], v[204:205], s[62:63], v[72:73] op_sel_hi:[1,0,1]
	v_pk_fma_f32 v[74:75], v[206:207], s[62:63], v[74:75] op_sel_hi:[1,0,1]
	v_pk_fma_f32 v[76:77], v[200:201], s[54:55], v[76:77] op_sel_hi:[1,0,1]
	v_pk_fma_f32 v[78:79], v[202:203], s[54:55], v[78:79] op_sel_hi:[1,0,1]
	v_pk_fma_f32 v[80:81], v[204:205], s[64:65], v[80:81] op_sel_hi:[1,0,1]
	v_pk_fma_f32 v[82:83], v[206:207], s[64:65], v[82:83] op_sel_hi:[1,0,1]
	v_pk_fma_f32 v[84:85], v[200:201], s[56:57], v[84:85] op_sel_hi:[1,0,1]
	v_pk_fma_f32 v[86:87], v[202:203], s[56:57], v[86:87] op_sel_hi:[1,0,1]
	v_pk_fma_f32 v[88:89], v[204:205], s[66:67], v[88:89] op_sel_hi:[1,0,1]
	v_pk_fma_f32 v[90:91], v[206:207], s[66:67], v[90:91] op_sel_hi:[1,0,1]
	global_load_dwordx4 v[192:195], v232, s[2:3] offset:3072
	global_load_dwordx4 v[196:199], v232, s[40:41] offset:3072
	s_add_u32 s2, s2, 0x1000
	s_addc_u32 s3, s3, 0
	s_add_u32 s40, s40, 0x1000
	s_addc_u32 s41, s41, 0
	s_waitcnt vmcnt(12)
	v_readlane_b32 s48, v20, 21
	v_readlane_b32 s58, v25, 21
	v_readlane_b32 s50, v21, 21
	v_readlane_b32 s60, v26, 21
	v_readlane_b32 s52, v22, 21
	v_readlane_b32 s62, v27, 21
	v_readlane_b32 s54, v23, 21
	v_readlane_b32 s64, v28, 21
	v_readlane_b32 s56, v24, 21
	v_readlane_b32 s66, v29, 21
	v_pk_fma_f32 v[52:53], v[208:209], s[48:49], v[52:53] op_sel_hi:[1,0,1]
	v_pk_fma_f32 v[54:55], v[210:211], s[48:49], v[54:55] op_sel_hi:[1,0,1]
	v_pk_fma_f32 v[56:57], v[212:213], s[58:59], v[56:57] op_sel_hi:[1,0,1]
	v_pk_fma_f32 v[58:59], v[214:215], s[58:59], v[58:59] op_sel_hi:[1,0,1]
	v_pk_fma_f32 v[60:61], v[208:209], s[50:51], v[60:61] op_sel_hi:[1,0,1]
	v_pk_fma_f32 v[62:63], v[210:211], s[50:51], v[62:63] op_sel_hi:[1,0,1]
	v_pk_fma_f32 v[64:65], v[212:213], s[60:61], v[64:65] op_sel_hi:[1,0,1]
	v_pk_fma_f32 v[66:67], v[214:215], s[60:61], v[66:67] op_sel_hi:[1,0,1]
	v_pk_fma_f32 v[68:69], v[208:209], s[52:53], v[68:69] op_sel_hi:[1,0,1]
	v_pk_fma_f32 v[70:71], v[210:211], s[52:53], v[70:71] op_sel_hi:[1,0,1]
	v_pk_fma_f32 v[72:73], v[212:213], s[62:63], v[72:73] op_sel_hi:[1,0,1]
	v_pk_fma_f32 v[74:75], v[214:215], s[62:63], v[74:75] op_sel_hi:[1,0,1]
	v_pk_fma_f32 v[76:77], v[208:209], s[54:55], v[76:77] op_sel_hi:[1,0,1]
	v_pk_fma_f32 v[78:79], v[210:211], s[54:55], v[78:79] op_sel_hi:[1,0,1]
	v_pk_fma_f32 v[80:81], v[212:213], s[64:65], v[80:81] op_sel_hi:[1,0,1]
	v_pk_fma_f32 v[82:83], v[214:215], s[64:65], v[82:83] op_sel_hi:[1,0,1]
	v_pk_fma_f32 v[84:85], v[208:209], s[56:57], v[84:85] op_sel_hi:[1,0,1]
	v_pk_fma_f32 v[86:87], v[210:211], s[56:57], v[86:87] op_sel_hi:[1,0,1]
	v_pk_fma_f32 v[88:89], v[212:213], s[66:67], v[88:89] op_sel_hi:[1,0,1]
	v_pk_fma_f32 v[90:91], v[214:215], s[66:67], v[90:91] op_sel_hi:[1,0,1]
	global_load_dwordx4 v[200:203], v232, s[2:3]
	global_load_dwordx4 v[204:207], v232, s[40:41]
	s_waitcnt vmcnt(12)
	v_readlane_b32 s48, v20, 22
	v_readlane_b32 s58, v25, 22
	v_readlane_b32 s50, v21, 22
	v_readlane_b32 s60, v26, 22
	v_readlane_b32 s52, v22, 22
	v_readlane_b32 s62, v27, 22
	v_readlane_b32 s54, v23, 22
	v_readlane_b32 s64, v28, 22
	v_readlane_b32 s56, v24, 22
	v_readlane_b32 s66, v29, 22
	v_pk_fma_f32 v[52:53], v[216:217], s[48:49], v[52:53] op_sel_hi:[1,0,1]
	v_pk_fma_f32 v[54:55], v[218:219], s[48:49], v[54:55] op_sel_hi:[1,0,1]
	v_pk_fma_f32 v[56:57], v[220:221], s[58:59], v[56:57] op_sel_hi:[1,0,1]
	v_pk_fma_f32 v[58:59], v[222:223], s[58:59], v[58:59] op_sel_hi:[1,0,1]
	v_pk_fma_f32 v[60:61], v[216:217], s[50:51], v[60:61] op_sel_hi:[1,0,1]
	v_pk_fma_f32 v[62:63], v[218:219], s[50:51], v[62:63] op_sel_hi:[1,0,1]
	v_pk_fma_f32 v[64:65], v[220:221], s[60:61], v[64:65] op_sel_hi:[1,0,1]
	v_pk_fma_f32 v[66:67], v[222:223], s[60:61], v[66:67] op_sel_hi:[1,0,1]
	v_pk_fma_f32 v[68:69], v[216:217], s[52:53], v[68:69] op_sel_hi:[1,0,1]
	v_pk_fma_f32 v[70:71], v[218:219], s[52:53], v[70:71] op_sel_hi:[1,0,1]
	v_pk_fma_f32 v[72:73], v[220:221], s[62:63], v[72:73] op_sel_hi:[1,0,1]
	v_pk_fma_f32 v[74:75], v[222:223], s[62:63], v[74:75] op_sel_hi:[1,0,1]
	v_pk_fma_f32 v[76:77], v[216:217], s[54:55], v[76:77] op_sel_hi:[1,0,1]
	v_pk_fma_f32 v[78:79], v[218:219], s[54:55], v[78:79] op_sel_hi:[1,0,1]
	v_pk_fma_f32 v[80:81], v[220:221], s[64:65], v[80:81] op_sel_hi:[1,0,1]
	v_pk_fma_f32 v[82:83], v[222:223], s[64:65], v[82:83] op_sel_hi:[1,0,1]
	v_pk_fma_f32 v[84:85], v[216:217], s[56:57], v[84:85] op_sel_hi:[1,0,1]
	v_pk_fma_f32 v[86:87], v[218:219], s[56:57], v[86:87] op_sel_hi:[1,0,1]
	v_pk_fma_f32 v[88:89], v[220:221], s[66:67], v[88:89] op_sel_hi:[1,0,1]
	v_pk_fma_f32 v[90:91], v[222:223], s[66:67], v[90:91] op_sel_hi:[1,0,1]
	global_load_dwordx4 v[208:211], v232, s[2:3] offset:1024
	global_load_dwordx4 v[212:215], v232, s[40:41] offset:1024
	s_waitcnt vmcnt(12)
	v_readlane_b32 s48, v20, 23
	v_readlane_b32 s58, v25, 23
	v_readlane_b32 s50, v21, 23
	v_readlane_b32 s60, v26, 23
	v_readlane_b32 s52, v22, 23
	v_readlane_b32 s62, v27, 23
	v_readlane_b32 s54, v23, 23
	v_readlane_b32 s64, v28, 23
	v_readlane_b32 s56, v24, 23
	v_readlane_b32 s66, v29, 23
	v_pk_fma_f32 v[52:53], v[224:225], s[48:49], v[52:53] op_sel_hi:[1,0,1]
	v_pk_fma_f32 v[54:55], v[226:227], s[48:49], v[54:55] op_sel_hi:[1,0,1]
	v_pk_fma_f32 v[56:57], v[228:229], s[58:59], v[56:57] op_sel_hi:[1,0,1]
	v_pk_fma_f32 v[58:59], v[230:231], s[58:59], v[58:59] op_sel_hi:[1,0,1]
	v_pk_fma_f32 v[60:61], v[224:225], s[50:51], v[60:61] op_sel_hi:[1,0,1]
	v_pk_fma_f32 v[62:63], v[226:227], s[50:51], v[62:63] op_sel_hi:[1,0,1]
	v_pk_fma_f32 v[64:65], v[228:229], s[60:61], v[64:65] op_sel_hi:[1,0,1]
	v_pk_fma_f32 v[66:67], v[230:231], s[60:61], v[66:67] op_sel_hi:[1,0,1]
	v_pk_fma_f32 v[68:69], v[224:225], s[52:53], v[68:69] op_sel_hi:[1,0,1]
	v_pk_fma_f32 v[70:71], v[226:227], s[52:53], v[70:71] op_sel_hi:[1,0,1]
	v_pk_fma_f32 v[72:73], v[228:229], s[62:63], v[72:73] op_sel_hi:[1,0,1]
	v_pk_fma_f32 v[74:75], v[230:231], s[62:63], v[74:75] op_sel_hi:[1,0,1]
	v_pk_fma_f32 v[76:77], v[224:225], s[54:55], v[76:77] op_sel_hi:[1,0,1]
	v_pk_fma_f32 v[78:79], v[226:227], s[54:55], v[78:79] op_sel_hi:[1,0,1]
	v_pk_fma_f32 v[80:81], v[228:229], s[64:65], v[80:81] op_sel_hi:[1,0,1]
	v_pk_fma_f32 v[82:83], v[230:231], s[64:65], v[82:83] op_sel_hi:[1,0,1]
	v_pk_fma_f32 v[84:85], v[224:225], s[56:57], v[84:85] op_sel_hi:[1,0,1]
	v_pk_fma_f32 v[86:87], v[226:227], s[56:57], v[86:87] op_sel_hi:[1,0,1]
	v_pk_fma_f32 v[88:89], v[228:229], s[66:67], v[88:89] op_sel_hi:[1,0,1]
	v_pk_fma_f32 v[90:91], v[230:231], s[66:67], v[90:91] op_sel_hi:[1,0,1]
	global_load_dwordx4 v[216:219], v232, s[2:3] offset:2048
	global_load_dwordx4 v[220:223], v232, s[40:41] offset:2048
	s_waitcnt vmcnt(12)
	v_readlane_b32 s48, v20, 24
	v_readlane_b32 s58, v25, 24
	v_readlane_b32 s50, v21, 24
	v_readlane_b32 s60, v26, 24
	v_readlane_b32 s52, v22, 24
	v_readlane_b32 s62, v27, 24
	v_readlane_b32 s54, v23, 24
	v_readlane_b32 s64, v28, 24
	v_readlane_b32 s56, v24, 24
	v_readlane_b32 s66, v29, 24
	v_pk_fma_f32 v[52:53], v[168:169], s[48:49], v[52:53] op_sel_hi:[1,0,1]
	v_pk_fma_f32 v[54:55], v[170:171], s[48:49], v[54:55] op_sel_hi:[1,0,1]
	v_pk_fma_f32 v[56:57], v[172:173], s[58:59], v[56:57] op_sel_hi:[1,0,1]
	v_pk_fma_f32 v[58:59], v[174:175], s[58:59], v[58:59] op_sel_hi:[1,0,1]
	v_pk_fma_f32 v[60:61], v[168:169], s[50:51], v[60:61] op_sel_hi:[1,0,1]
	v_pk_fma_f32 v[62:63], v[170:171], s[50:51], v[62:63] op_sel_hi:[1,0,1]
	v_pk_fma_f32 v[64:65], v[172:173], s[60:61], v[64:65] op_sel_hi:[1,0,1]
	v_pk_fma_f32 v[66:67], v[174:175], s[60:61], v[66:67] op_sel_hi:[1,0,1]
	v_pk_fma_f32 v[68:69], v[168:169], s[52:53], v[68:69] op_sel_hi:[1,0,1]
	v_pk_fma_f32 v[70:71], v[170:171], s[52:53], v[70:71] op_sel_hi:[1,0,1]
	v_pk_fma_f32 v[72:73], v[172:173], s[62:63], v[72:73] op_sel_hi:[1,0,1]
	v_pk_fma_f32 v[74:75], v[174:175], s[62:63], v[74:75] op_sel_hi:[1,0,1]
	v_pk_fma_f32 v[76:77], v[168:169], s[54:55], v[76:77] op_sel_hi:[1,0,1]
	v_pk_fma_f32 v[78:79], v[170:171], s[54:55], v[78:79] op_sel_hi:[1,0,1]
	v_pk_fma_f32 v[80:81], v[172:173], s[64:65], v[80:81] op_sel_hi:[1,0,1]
	v_pk_fma_f32 v[82:83], v[174:175], s[64:65], v[82:83] op_sel_hi:[1,0,1]
	v_pk_fma_f32 v[84:85], v[168:169], s[56:57], v[84:85] op_sel_hi:[1,0,1]
	v_pk_fma_f32 v[86:87], v[170:171], s[56:57], v[86:87] op_sel_hi:[1,0,1]
	v_pk_fma_f32 v[88:89], v[172:173], s[66:67], v[88:89] op_sel_hi:[1,0,1]
	v_pk_fma_f32 v[90:91], v[174:175], s[66:67], v[90:91] op_sel_hi:[1,0,1]
	global_load_dwordx4 v[224:227], v232, s[2:3] offset:3072
	global_load_dwordx4 v[228:231], v232, s[40:41] offset:3072
	s_add_u32 s2, s2, 0x1000
	s_addc_u32 s3, s3, 0
	s_add_u32 s40, s40, 0x1000
	s_addc_u32 s41, s41, 0
	s_waitcnt vmcnt(12)
	v_readlane_b32 s48, v20, 25
	v_readlane_b32 s58, v25, 25
	v_readlane_b32 s50, v21, 25
	v_readlane_b32 s60, v26, 25
	v_readlane_b32 s52, v22, 25
	v_readlane_b32 s62, v27, 25
	v_readlane_b32 s54, v23, 25
	v_readlane_b32 s64, v28, 25
	v_readlane_b32 s56, v24, 25
	v_readlane_b32 s66, v29, 25
	v_pk_fma_f32 v[52:53], v[176:177], s[48:49], v[52:53] op_sel_hi:[1,0,1]
	v_pk_fma_f32 v[54:55], v[178:179], s[48:49], v[54:55] op_sel_hi:[1,0,1]
	v_pk_fma_f32 v[56:57], v[180:181], s[58:59], v[56:57] op_sel_hi:[1,0,1]
	v_pk_fma_f32 v[58:59], v[182:183], s[58:59], v[58:59] op_sel_hi:[1,0,1]
	v_pk_fma_f32 v[60:61], v[176:177], s[50:51], v[60:61] op_sel_hi:[1,0,1]
	v_pk_fma_f32 v[62:63], v[178:179], s[50:51], v[62:63] op_sel_hi:[1,0,1]
	v_pk_fma_f32 v[64:65], v[180:181], s[60:61], v[64:65] op_sel_hi:[1,0,1]
	v_pk_fma_f32 v[66:67], v[182:183], s[60:61], v[66:67] op_sel_hi:[1,0,1]
	v_pk_fma_f32 v[68:69], v[176:177], s[52:53], v[68:69] op_sel_hi:[1,0,1]
	v_pk_fma_f32 v[70:71], v[178:179], s[52:53], v[70:71] op_sel_hi:[1,0,1]
	v_pk_fma_f32 v[72:73], v[180:181], s[62:63], v[72:73] op_sel_hi:[1,0,1]
	v_pk_fma_f32 v[74:75], v[182:183], s[62:63], v[74:75] op_sel_hi:[1,0,1]
	v_pk_fma_f32 v[76:77], v[176:177], s[54:55], v[76:77] op_sel_hi:[1,0,1]
	v_pk_fma_f32 v[78:79], v[178:179], s[54:55], v[78:79] op_sel_hi:[1,0,1]
	v_pk_fma_f32 v[80:81], v[180:181], s[64:65], v[80:81] op_sel_hi:[1,0,1]
	v_pk_fma_f32 v[82:83], v[182:183], s[64:65], v[82:83] op_sel_hi:[1,0,1]
	v_pk_fma_f32 v[84:85], v[176:177], s[56:57], v[84:85] op_sel_hi:[1,0,1]
	v_pk_fma_f32 v[86:87], v[178:179], s[56:57], v[86:87] op_sel_hi:[1,0,1]
	v_pk_fma_f32 v[88:89], v[180:181], s[66:67], v[88:89] op_sel_hi:[1,0,1]
	v_pk_fma_f32 v[90:91], v[182:183], s[66:67], v[90:91] op_sel_hi:[1,0,1]
	s_waitcnt vmcnt(10)
	v_readlane_b32 s48, v20, 26
	v_readlane_b32 s58, v25, 26
	v_readlane_b32 s50, v21, 26
	v_readlane_b32 s60, v26, 26
	v_readlane_b32 s52, v22, 26
	v_readlane_b32 s62, v27, 26
	v_readlane_b32 s54, v23, 26
	v_readlane_b32 s64, v28, 26
	v_readlane_b32 s56, v24, 26
	v_readlane_b32 s66, v29, 26
	v_pk_fma_f32 v[52:53], v[184:185], s[48:49], v[52:53] op_sel_hi:[1,0,1]
	v_pk_fma_f32 v[54:55], v[186:187], s[48:49], v[54:55] op_sel_hi:[1,0,1]
	v_pk_fma_f32 v[56:57], v[188:189], s[58:59], v[56:57] op_sel_hi:[1,0,1]
	v_pk_fma_f32 v[58:59], v[190:191], s[58:59], v[58:59] op_sel_hi:[1,0,1]
	v_pk_fma_f32 v[60:61], v[184:185], s[50:51], v[60:61] op_sel_hi:[1,0,1]
	v_pk_fma_f32 v[62:63], v[186:187], s[50:51], v[62:63] op_sel_hi:[1,0,1]
	v_pk_fma_f32 v[64:65], v[188:189], s[60:61], v[64:65] op_sel_hi:[1,0,1]
	v_pk_fma_f32 v[66:67], v[190:191], s[60:61], v[66:67] op_sel_hi:[1,0,1]
	v_pk_fma_f32 v[68:69], v[184:185], s[52:53], v[68:69] op_sel_hi:[1,0,1]
	v_pk_fma_f32 v[70:71], v[186:187], s[52:53], v[70:71] op_sel_hi:[1,0,1]
	v_pk_fma_f32 v[72:73], v[188:189], s[62:63], v[72:73] op_sel_hi:[1,0,1]
	v_pk_fma_f32 v[74:75], v[190:191], s[62:63], v[74:75] op_sel_hi:[1,0,1]
	v_pk_fma_f32 v[76:77], v[184:185], s[54:55], v[76:77] op_sel_hi:[1,0,1]
	v_pk_fma_f32 v[78:79], v[186:187], s[54:55], v[78:79] op_sel_hi:[1,0,1]
	v_pk_fma_f32 v[80:81], v[188:189], s[64:65], v[80:81] op_sel_hi:[1,0,1]
	v_pk_fma_f32 v[82:83], v[190:191], s[64:65], v[82:83] op_sel_hi:[1,0,1]
	v_pk_fma_f32 v[84:85], v[184:185], s[56:57], v[84:85] op_sel_hi:[1,0,1]
	v_pk_fma_f32 v[86:87], v[186:187], s[56:57], v[86:87] op_sel_hi:[1,0,1]
	v_pk_fma_f32 v[88:89], v[188:189], s[66:67], v[88:89] op_sel_hi:[1,0,1]
	v_pk_fma_f32 v[90:91], v[190:191], s[66:67], v[90:91] op_sel_hi:[1,0,1]
	s_waitcnt vmcnt(8)
	v_readlane_b32 s48, v20, 27
	v_readlane_b32 s58, v25, 27
	v_readlane_b32 s50, v21, 27
	v_readlane_b32 s60, v26, 27
	v_readlane_b32 s52, v22, 27
	v_readlane_b32 s62, v27, 27
	v_readlane_b32 s54, v23, 27
	v_readlane_b32 s64, v28, 27
	v_readlane_b32 s56, v24, 27
	v_readlane_b32 s66, v29, 27
	v_pk_fma_f32 v[52:53], v[192:193], s[48:49], v[52:53] op_sel_hi:[1,0,1]
	v_pk_fma_f32 v[54:55], v[194:195], s[48:49], v[54:55] op_sel_hi:[1,0,1]
	v_pk_fma_f32 v[56:57], v[196:197], s[58:59], v[56:57] op_sel_hi:[1,0,1]
	v_pk_fma_f32 v[58:59], v[198:199], s[58:59], v[58:59] op_sel_hi:[1,0,1]
	v_pk_fma_f32 v[60:61], v[192:193], s[50:51], v[60:61] op_sel_hi:[1,0,1]
	v_pk_fma_f32 v[62:63], v[194:195], s[50:51], v[62:63] op_sel_hi:[1,0,1]
	v_pk_fma_f32 v[64:65], v[196:197], s[60:61], v[64:65] op_sel_hi:[1,0,1]
	v_pk_fma_f32 v[66:67], v[198:199], s[60:61], v[66:67] op_sel_hi:[1,0,1]
	v_pk_fma_f32 v[68:69], v[192:193], s[52:53], v[68:69] op_sel_hi:[1,0,1]
	v_pk_fma_f32 v[70:71], v[194:195], s[52:53], v[70:71] op_sel_hi:[1,0,1]
	v_pk_fma_f32 v[72:73], v[196:197], s[62:63], v[72:73] op_sel_hi:[1,0,1]
	v_pk_fma_f32 v[74:75], v[198:199], s[62:63], v[74:75] op_sel_hi:[1,0,1]
	v_pk_fma_f32 v[76:77], v[192:193], s[54:55], v[76:77] op_sel_hi:[1,0,1]
	v_pk_fma_f32 v[78:79], v[194:195], s[54:55], v[78:79] op_sel_hi:[1,0,1]
	v_pk_fma_f32 v[80:81], v[196:197], s[64:65], v[80:81] op_sel_hi:[1,0,1]
	v_pk_fma_f32 v[82:83], v[198:199], s[64:65], v[82:83] op_sel_hi:[1,0,1]
	v_pk_fma_f32 v[84:85], v[192:193], s[56:57], v[84:85] op_sel_hi:[1,0,1]
	v_pk_fma_f32 v[86:87], v[194:195], s[56:57], v[86:87] op_sel_hi:[1,0,1]
	v_pk_fma_f32 v[88:89], v[196:197], s[66:67], v[88:89] op_sel_hi:[1,0,1]
	v_pk_fma_f32 v[90:91], v[198:199], s[66:67], v[90:91] op_sel_hi:[1,0,1]
	s_waitcnt vmcnt(6)
	v_readlane_b32 s48, v20, 28
	v_readlane_b32 s58, v25, 28
	v_readlane_b32 s50, v21, 28
	v_readlane_b32 s60, v26, 28
	v_readlane_b32 s52, v22, 28
	v_readlane_b32 s62, v27, 28
	v_readlane_b32 s54, v23, 28
	v_readlane_b32 s64, v28, 28
	v_readlane_b32 s56, v24, 28
	v_readlane_b32 s66, v29, 28
	v_pk_fma_f32 v[52:53], v[200:201], s[48:49], v[52:53] op_sel_hi:[1,0,1]
	v_pk_fma_f32 v[54:55], v[202:203], s[48:49], v[54:55] op_sel_hi:[1,0,1]
	v_pk_fma_f32 v[56:57], v[204:205], s[58:59], v[56:57] op_sel_hi:[1,0,1]
	v_pk_fma_f32 v[58:59], v[206:207], s[58:59], v[58:59] op_sel_hi:[1,0,1]
	v_pk_fma_f32 v[60:61], v[200:201], s[50:51], v[60:61] op_sel_hi:[1,0,1]
	v_pk_fma_f32 v[62:63], v[202:203], s[50:51], v[62:63] op_sel_hi:[1,0,1]
	v_pk_fma_f32 v[64:65], v[204:205], s[60:61], v[64:65] op_sel_hi:[1,0,1]
	v_pk_fma_f32 v[66:67], v[206:207], s[60:61], v[66:67] op_sel_hi:[1,0,1]
	v_pk_fma_f32 v[68:69], v[200:201], s[52:53], v[68:69] op_sel_hi:[1,0,1]
	v_pk_fma_f32 v[70:71], v[202:203], s[52:53], v[70:71] op_sel_hi:[1,0,1]
	v_pk_fma_f32 v[72:73], v[204:205], s[62:63], v[72:73] op_sel_hi:[1,0,1]
	v_pk_fma_f32 v[74:75], v[206:207], s[62:63], v[74:75] op_sel_hi:[1,0,1]
	v_pk_fma_f32 v[76:77], v[200:201], s[54:55], v[76:77] op_sel_hi:[1,0,1]
	v_pk_fma_f32 v[78:79], v[202:203], s[54:55], v[78:79] op_sel_hi:[1,0,1]
	v_pk_fma_f32 v[80:81], v[204:205], s[64:65], v[80:81] op_sel_hi:[1,0,1]
	v_pk_fma_f32 v[82:83], v[206:207], s[64:65], v[82:83] op_sel_hi:[1,0,1]
	v_pk_fma_f32 v[84:85], v[200:201], s[56:57], v[84:85] op_sel_hi:[1,0,1]
	v_pk_fma_f32 v[86:87], v[202:203], s[56:57], v[86:87] op_sel_hi:[1,0,1]
	v_pk_fma_f32 v[88:89], v[204:205], s[66:67], v[88:89] op_sel_hi:[1,0,1]
	v_pk_fma_f32 v[90:91], v[206:207], s[66:67], v[90:91] op_sel_hi:[1,0,1]
	s_waitcnt vmcnt(4)
	v_readlane_b32 s48, v20, 29
	v_readlane_b32 s58, v25, 29
	v_readlane_b32 s50, v21, 29
	v_readlane_b32 s60, v26, 29
	v_readlane_b32 s52, v22, 29
	v_readlane_b32 s62, v27, 29
	v_readlane_b32 s54, v23, 29
	v_readlane_b32 s64, v28, 29
	v_readlane_b32 s56, v24, 29
	v_readlane_b32 s66, v29, 29
	v_pk_fma_f32 v[52:53], v[208:209], s[48:49], v[52:53] op_sel_hi:[1,0,1]
	v_pk_fma_f32 v[54:55], v[210:211], s[48:49], v[54:55] op_sel_hi:[1,0,1]
	v_pk_fma_f32 v[56:57], v[212:213], s[58:59], v[56:57] op_sel_hi:[1,0,1]
	v_pk_fma_f32 v[58:59], v[214:215], s[58:59], v[58:59] op_sel_hi:[1,0,1]
	v_pk_fma_f32 v[60:61], v[208:209], s[50:51], v[60:61] op_sel_hi:[1,0,1]
	v_pk_fma_f32 v[62:63], v[210:211], s[50:51], v[62:63] op_sel_hi:[1,0,1]
	v_pk_fma_f32 v[64:65], v[212:213], s[60:61], v[64:65] op_sel_hi:[1,0,1]
	v_pk_fma_f32 v[66:67], v[214:215], s[60:61], v[66:67] op_sel_hi:[1,0,1]
	v_pk_fma_f32 v[68:69], v[208:209], s[52:53], v[68:69] op_sel_hi:[1,0,1]
	v_pk_fma_f32 v[70:71], v[210:211], s[52:53], v[70:71] op_sel_hi:[1,0,1]
	v_pk_fma_f32 v[72:73], v[212:213], s[62:63], v[72:73] op_sel_hi:[1,0,1]
	v_pk_fma_f32 v[74:75], v[214:215], s[62:63], v[74:75] op_sel_hi:[1,0,1]
	v_pk_fma_f32 v[76:77], v[208:209], s[54:55], v[76:77] op_sel_hi:[1,0,1]
	v_pk_fma_f32 v[78:79], v[210:211], s[54:55], v[78:79] op_sel_hi:[1,0,1]
	v_pk_fma_f32 v[80:81], v[212:213], s[64:65], v[80:81] op_sel_hi:[1,0,1]
	v_pk_fma_f32 v[82:83], v[214:215], s[64:65], v[82:83] op_sel_hi:[1,0,1]
	v_pk_fma_f32 v[84:85], v[208:209], s[56:57], v[84:85] op_sel_hi:[1,0,1]
	v_pk_fma_f32 v[86:87], v[210:211], s[56:57], v[86:87] op_sel_hi:[1,0,1]
	v_pk_fma_f32 v[88:89], v[212:213], s[66:67], v[88:89] op_sel_hi:[1,0,1]
	v_pk_fma_f32 v[90:91], v[214:215], s[66:67], v[90:91] op_sel_hi:[1,0,1]
	s_waitcnt vmcnt(2)
	v_readlane_b32 s48, v20, 30
	v_readlane_b32 s58, v25, 30
	v_readlane_b32 s50, v21, 30
	v_readlane_b32 s60, v26, 30
	v_readlane_b32 s52, v22, 30
	v_readlane_b32 s62, v27, 30
	v_readlane_b32 s54, v23, 30
	v_readlane_b32 s64, v28, 30
	v_readlane_b32 s56, v24, 30
	v_readlane_b32 s66, v29, 30
	v_pk_fma_f32 v[52:53], v[216:217], s[48:49], v[52:53] op_sel_hi:[1,0,1]
	v_pk_fma_f32 v[54:55], v[218:219], s[48:49], v[54:55] op_sel_hi:[1,0,1]
	v_pk_fma_f32 v[56:57], v[220:221], s[58:59], v[56:57] op_sel_hi:[1,0,1]
	v_pk_fma_f32 v[58:59], v[222:223], s[58:59], v[58:59] op_sel_hi:[1,0,1]
	v_pk_fma_f32 v[60:61], v[216:217], s[50:51], v[60:61] op_sel_hi:[1,0,1]
	v_pk_fma_f32 v[62:63], v[218:219], s[50:51], v[62:63] op_sel_hi:[1,0,1]
	v_pk_fma_f32 v[64:65], v[220:221], s[60:61], v[64:65] op_sel_hi:[1,0,1]
	v_pk_fma_f32 v[66:67], v[222:223], s[60:61], v[66:67] op_sel_hi:[1,0,1]
	v_pk_fma_f32 v[68:69], v[216:217], s[52:53], v[68:69] op_sel_hi:[1,0,1]
	v_pk_fma_f32 v[70:71], v[218:219], s[52:53], v[70:71] op_sel_hi:[1,0,1]
	v_pk_fma_f32 v[72:73], v[220:221], s[62:63], v[72:73] op_sel_hi:[1,0,1]
	v_pk_fma_f32 v[74:75], v[222:223], s[62:63], v[74:75] op_sel_hi:[1,0,1]
	v_pk_fma_f32 v[76:77], v[216:217], s[54:55], v[76:77] op_sel_hi:[1,0,1]
	v_pk_fma_f32 v[78:79], v[218:219], s[54:55], v[78:79] op_sel_hi:[1,0,1]
	v_pk_fma_f32 v[80:81], v[220:221], s[64:65], v[80:81] op_sel_hi:[1,0,1]
	v_pk_fma_f32 v[82:83], v[222:223], s[64:65], v[82:83] op_sel_hi:[1,0,1]
	v_pk_fma_f32 v[84:85], v[216:217], s[56:57], v[84:85] op_sel_hi:[1,0,1]
	v_pk_fma_f32 v[86:87], v[218:219], s[56:57], v[86:87] op_sel_hi:[1,0,1]
	v_pk_fma_f32 v[88:89], v[220:221], s[66:67], v[88:89] op_sel_hi:[1,0,1]
	v_pk_fma_f32 v[90:91], v[222:223], s[66:67], v[90:91] op_sel_hi:[1,0,1]
	s_waitcnt vmcnt(0)
	v_readlane_b32 s48, v20, 31
	v_readlane_b32 s58, v25, 31
	v_readlane_b32 s50, v21, 31
	v_readlane_b32 s60, v26, 31
	v_readlane_b32 s52, v22, 31
	v_readlane_b32 s62, v27, 31
	v_readlane_b32 s54, v23, 31
	v_readlane_b32 s64, v28, 31
	v_readlane_b32 s56, v24, 31
	v_readlane_b32 s66, v29, 31
	v_pk_fma_f32 v[52:53], v[224:225], s[48:49], v[52:53] op_sel_hi:[1,0,1]
	v_pk_fma_f32 v[54:55], v[226:227], s[48:49], v[54:55] op_sel_hi:[1,0,1]
	v_pk_fma_f32 v[56:57], v[228:229], s[58:59], v[56:57] op_sel_hi:[1,0,1]
	v_pk_fma_f32 v[58:59], v[230:231], s[58:59], v[58:59] op_sel_hi:[1,0,1]
	v_pk_fma_f32 v[60:61], v[224:225], s[50:51], v[60:61] op_sel_hi:[1,0,1]
	v_pk_fma_f32 v[62:63], v[226:227], s[50:51], v[62:63] op_sel_hi:[1,0,1]
	v_pk_fma_f32 v[64:65], v[228:229], s[60:61], v[64:65] op_sel_hi:[1,0,1]
	v_pk_fma_f32 v[66:67], v[230:231], s[60:61], v[66:67] op_sel_hi:[1,0,1]
	v_pk_fma_f32 v[68:69], v[224:225], s[52:53], v[68:69] op_sel_hi:[1,0,1]
	v_pk_fma_f32 v[70:71], v[226:227], s[52:53], v[70:71] op_sel_hi:[1,0,1]
	v_pk_fma_f32 v[72:73], v[228:229], s[62:63], v[72:73] op_sel_hi:[1,0,1]
	v_pk_fma_f32 v[74:75], v[230:231], s[62:63], v[74:75] op_sel_hi:[1,0,1]
	v_pk_fma_f32 v[76:77], v[224:225], s[54:55], v[76:77] op_sel_hi:[1,0,1]
	v_pk_fma_f32 v[78:79], v[226:227], s[54:55], v[78:79] op_sel_hi:[1,0,1]
	v_pk_fma_f32 v[80:81], v[228:229], s[64:65], v[80:81] op_sel_hi:[1,0,1]
	v_pk_fma_f32 v[82:83], v[230:231], s[64:65], v[82:83] op_sel_hi:[1,0,1]
	v_pk_fma_f32 v[84:85], v[224:225], s[56:57], v[84:85] op_sel_hi:[1,0,1]
	v_pk_fma_f32 v[86:87], v[226:227], s[56:57], v[86:87] op_sel_hi:[1,0,1]
	v_pk_fma_f32 v[88:89], v[228:229], s[66:67], v[88:89] op_sel_hi:[1,0,1]
	v_pk_fma_f32 v[90:91], v[230:231], s[66:67], v[90:91] op_sel_hi:[1,0,1]
	s_add_u32 s2, s16, 0x8000
	s_addc_u32 s3, s17, 0
	s_add_u32 s40, s18, 0x8000
	s_addc_u32 s41, s19, 0
	global_load_dwordx4 v[168:171], v232, s[2:3]
	global_load_dwordx4 v[172:175], v232, s[40:41]
	global_load_dwordx4 v[176:179], v232, s[2:3] offset:1024
	global_load_dwordx4 v[180:183], v232, s[40:41] offset:1024
	global_load_dwordx4 v[184:187], v232, s[2:3] offset:2048
	global_load_dwordx4 v[188:191], v232, s[40:41] offset:2048
	global_load_dwordx4 v[192:195], v232, s[2:3] offset:3072
	global_load_dwordx4 v[196:199], v232, s[40:41] offset:3072
	s_add_u32 s2, s2, 0x1000
	s_addc_u32 s3, s3, 0
	s_add_u32 s40, s40, 0x1000
	s_addc_u32 s41, s41, 0
	global_load_dwordx4 v[200:203], v232, s[2:3]
	global_load_dwordx4 v[204:207], v232, s[40:41]
	global_load_dwordx4 v[208:211], v232, s[2:3] offset:1024
	global_load_dwordx4 v[212:215], v232, s[40:41] offset:1024
	s_mov_b32 s6, s13
	s_cmp_ge_u32 s6, 0x2800
	s_cbranch_scc1 .Lgprep_sk0
	v_mul_f32_e32 v92, 0xbfb8aa3b, v52
	v_exp_f32_e32 v92, v92
	s_nop 0
	v_add_f32_e32 v92, 1.0, v92
	v_div_scale_f32 v93, s[24:25], v92, v92, 1.0
	v_rcp_f32_e32 v94, v93
	s_nop 0
	v_fma_f32 v95, -v93, v94, 1.0
	v_fmac_f32_e32 v94, v95, v94
	v_div_scale_f32 v95, vcc, 1.0, v92, 1.0
	v_mul_f32_e32 v96, v95, v94
	v_fma_f32 v97, -v93, v96, v95
	v_fmac_f32_e32 v96, v97, v94
	v_fma_f32 v93, -v93, v96, v95
	v_div_fmas_f32 v93, v93, v94, v96
	v_div_fixup_f32 v52, v93, v92, 1.0
	v_mul_f32_e32 v52, 0xbf1b4598, v52
	v_mul_f32_e32 v52, 0x3fb8aa3b, v52
	v_exp_f32_e32 v52, v52
	v_mul_f32_e32 v92, 0xbfb8aa3b, v56
	v_exp_f32_e32 v92, v92
	s_nop 0
	v_add_f32_e32 v92, 1.0, v92
	v_div_scale_f32 v93, s[24:25], v92, v92, 1.0
	v_rcp_f32_e32 v94, v93
	s_nop 0
	v_fma_f32 v95, -v93, v94, 1.0
	v_fmac_f32_e32 v94, v95, v94
	v_div_scale_f32 v95, vcc, 1.0, v92, 1.0
	v_mul_f32_e32 v96, v95, v94
	v_fma_f32 v97, -v93, v96, v95
	v_fmac_f32_e32 v96, v97, v94
	v_fma_f32 v93, -v93, v96, v95
	v_div_fmas_f32 v93, v93, v94, v96
	v_div_fixup_f32 v56, v93, v92, 1.0
	v_mul_f32_e32 v92, 0xbfb8aa3b, v53
	v_exp_f32_e32 v92, v92
	s_nop 0
	v_add_f32_e32 v92, 1.0, v92
	v_div_scale_f32 v93, s[24:25], v92, v92, 1.0
	v_rcp_f32_e32 v94, v93
	s_nop 0
	v_fma_f32 v95, -v93, v94, 1.0
	v_fmac_f32_e32 v94, v95, v94
	v_div_scale_f32 v95, vcc, 1.0, v92, 1.0
	v_mul_f32_e32 v96, v95, v94
	v_fma_f32 v97, -v93, v96, v95
	v_fmac_f32_e32 v96, v97, v94
	v_fma_f32 v93, -v93, v96, v95
	v_div_fmas_f32 v93, v93, v94, v96
	v_div_fixup_f32 v53, v93, v92, 1.0
	v_mul_f32_e32 v53, 0xbf1b4598, v53
	v_mul_f32_e32 v53, 0x3fb8aa3b, v53
	v_exp_f32_e32 v53, v53
	v_mul_f32_e32 v92, 0xbfb8aa3b, v57
	v_exp_f32_e32 v92, v92
	s_nop 0
	v_add_f32_e32 v92, 1.0, v92
	v_div_scale_f32 v93, s[24:25], v92, v92, 1.0
	v_rcp_f32_e32 v94, v93
	s_nop 0
	v_fma_f32 v95, -v93, v94, 1.0
	v_fmac_f32_e32 v94, v95, v94
	v_div_scale_f32 v95, vcc, 1.0, v92, 1.0
	v_mul_f32_e32 v96, v95, v94
	v_fma_f32 v97, -v93, v96, v95
	v_fmac_f32_e32 v96, v97, v94
	v_fma_f32 v93, -v93, v96, v95
	v_div_fmas_f32 v93, v93, v94, v96
	v_div_fixup_f32 v57, v93, v92, 1.0
	v_mul_f32_e32 v92, 0xbfb8aa3b, v54
	v_exp_f32_e32 v92, v92
	s_nop 0
	v_add_f32_e32 v92, 1.0, v92
	v_div_scale_f32 v93, s[24:25], v92, v92, 1.0
	v_rcp_f32_e32 v94, v93
	s_nop 0
	v_fma_f32 v95, -v93, v94, 1.0
	v_fmac_f32_e32 v94, v95, v94
	v_div_scale_f32 v95, vcc, 1.0, v92, 1.0
	v_mul_f32_e32 v96, v95, v94
	v_fma_f32 v97, -v93, v96, v95
	v_fmac_f32_e32 v96, v97, v94
	v_fma_f32 v93, -v93, v96, v95
	v_div_fmas_f32 v93, v93, v94, v96
	v_div_fixup_f32 v54, v93, v92, 1.0
	v_mul_f32_e32 v54, 0xbf1b4598, v54
	v_mul_f32_e32 v54, 0x3fb8aa3b, v54
	v_exp_f32_e32 v54, v54
	v_mul_f32_e32 v92, 0xbfb8aa3b, v58
	v_exp_f32_e32 v92, v92
	s_nop 0
	v_add_f32_e32 v92, 1.0, v92
	v_div_scale_f32 v93, s[24:25], v92, v92, 1.0
	v_rcp_f32_e32 v94, v93
	s_nop 0
	v_fma_f32 v95, -v93, v94, 1.0
	v_fmac_f32_e32 v94, v95, v94
	v_div_scale_f32 v95, vcc, 1.0, v92, 1.0
	v_mul_f32_e32 v96, v95, v94
	v_fma_f32 v97, -v93, v96, v95
	v_fmac_f32_e32 v96, v97, v94
	v_fma_f32 v93, -v93, v96, v95
	v_div_fmas_f32 v93, v93, v94, v96
	v_div_fixup_f32 v58, v93, v92, 1.0
	v_mul_f32_e32 v92, 0xbfb8aa3b, v55
	v_exp_f32_e32 v92, v92
	s_nop 0
	v_add_f32_e32 v92, 1.0, v92
	v_div_scale_f32 v93, s[24:25], v92, v92, 1.0
	v_rcp_f32_e32 v94, v93
	s_nop 0
	v_fma_f32 v95, -v93, v94, 1.0
	v_fmac_f32_e32 v94, v95, v94
	v_div_scale_f32 v95, vcc, 1.0, v92, 1.0
	v_mul_f32_e32 v96, v95, v94
	v_fma_f32 v97, -v93, v96, v95
	v_fmac_f32_e32 v96, v97, v94
	v_fma_f32 v93, -v93, v96, v95
	v_div_fmas_f32 v93, v93, v94, v96
	v_div_fixup_f32 v55, v93, v92, 1.0
	v_mul_f32_e32 v55, 0xbf1b4598, v55
	v_mul_f32_e32 v55, 0x3fb8aa3b, v55
	v_exp_f32_e32 v55, v55
	v_mul_f32_e32 v92, 0xbfb8aa3b, v59
	v_exp_f32_e32 v92, v92
	s_nop 0
	v_add_f32_e32 v92, 1.0, v92
	v_div_scale_f32 v93, s[24:25], v92, v92, 1.0
	v_rcp_f32_e32 v94, v93
	s_nop 0
	v_fma_f32 v95, -v93, v94, 1.0
	v_fmac_f32_e32 v94, v95, v94
	v_div_scale_f32 v95, vcc, 1.0, v92, 1.0
	v_mul_f32_e32 v96, v95, v94
	v_fma_f32 v97, -v93, v96, v95
	v_fmac_f32_e32 v96, v97, v94
	v_fma_f32 v93, -v93, v96, v95
	v_div_fmas_f32 v93, v93, v94, v96
	v_div_fixup_f32 v59, v93, v92, 1.0
	s_mul_i32 s7, s6, 0x1400
	s_add_u32 s8, s82, s7
	s_addc_u32 s9, s83, 0
	global_store_dwordx4 v232, v[52:55], s[8:9] offset:1024
	global_store_dwordx4 v232, v[56:59], s[8:9] offset:2048
	global_store_dwordx4 v232, v[0:3], s[8:9]
	s_add_u32 s6, s13, 1
	s_cmp_ge_u32 s6, 0x2800
	s_cbranch_scc1 .Lgprep_sk0
	v_mul_f32_e32 v92, 0xbfb8aa3b, v60
	v_exp_f32_e32 v92, v92
	s_nop 0
	v_add_f32_e32 v92, 1.0, v92
	v_div_scale_f32 v93, s[24:25], v92, v92, 1.0
	v_rcp_f32_e32 v94, v93
	s_nop 0
	v_fma_f32 v95, -v93, v94, 1.0
	v_fmac_f32_e32 v94, v95, v94
	v_div_scale_f32 v95, vcc, 1.0, v92, 1.0
	v_mul_f32_e32 v96, v95, v94
	v_fma_f32 v97, -v93, v96, v95
	v_fmac_f32_e32 v96, v97, v94
	v_fma_f32 v93, -v93, v96, v95
	v_div_fmas_f32 v93, v93, v94, v96
	v_div_fixup_f32 v60, v93, v92, 1.0
	v_mul_f32_e32 v60, 0xbf1b4598, v60
	v_mul_f32_e32 v60, 0x3fb8aa3b, v60
	v_exp_f32_e32 v60, v60
	v_mul_f32_e32 v92, 0xbfb8aa3b, v64
	v_exp_f32_e32 v92, v92
	s_nop 0
	v_add_f32_e32 v92, 1.0, v92
	v_div_scale_f32 v93, s[24:25], v92, v92, 1.0
	v_rcp_f32_e32 v94, v93
	s_nop 0
	v_fma_f32 v95, -v93, v94, 1.0
	v_fmac_f32_e32 v94, v95, v94
	v_div_scale_f32 v95, vcc, 1.0, v92, 1.0
	v_mul_f32_e32 v96, v95, v94
	v_fma_f32 v97, -v93, v96, v95
	v_fmac_f32_e32 v96, v97, v94
	v_fma_f32 v93, -v93, v96, v95
	v_div_fmas_f32 v93, v93, v94, v96
	v_div_fixup_f32 v64, v93, v92, 1.0
	v_mul_f32_e32 v92, 0xbfb8aa3b, v61
	v_exp_f32_e32 v92, v92
	s_nop 0
	v_add_f32_e32 v92, 1.0, v92
	v_div_scale_f32 v93, s[24:25], v92, v92, 1.0
	v_rcp_f32_e32 v94, v93
	s_nop 0
	v_fma_f32 v95, -v93, v94, 1.0
	v_fmac_f32_e32 v94, v95, v94
	v_div_scale_f32 v95, vcc, 1.0, v92, 1.0
	v_mul_f32_e32 v96, v95, v94
	v_fma_f32 v97, -v93, v96, v95
	v_fmac_f32_e32 v96, v97, v94
	v_fma_f32 v93, -v93, v96, v95
	v_div_fmas_f32 v93, v93, v94, v96
	v_div_fixup_f32 v61, v93, v92, 1.0
	v_mul_f32_e32 v61, 0xbf1b4598, v61
	v_mul_f32_e32 v61, 0x3fb8aa3b, v61
	v_exp_f32_e32 v61, v61
	v_mul_f32_e32 v92, 0xbfb8aa3b, v65
	v_exp_f32_e32 v92, v92
	s_nop 0
	v_add_f32_e32 v92, 1.0, v92
	v_div_scale_f32 v93, s[24:25], v92, v92, 1.0
	v_rcp_f32_e32 v94, v93
	s_nop 0
	v_fma_f32 v95, -v93, v94, 1.0
	v_fmac_f32_e32 v94, v95, v94
	v_div_scale_f32 v95, vcc, 1.0, v92, 1.0
	v_mul_f32_e32 v96, v95, v94
	v_fma_f32 v97, -v93, v96, v95
	v_fmac_f32_e32 v96, v97, v94
	v_fma_f32 v93, -v93, v96, v95
	v_div_fmas_f32 v93, v93, v94, v96
	v_div_fixup_f32 v65, v93, v92, 1.0
	v_mul_f32_e32 v92, 0xbfb8aa3b, v62
	v_exp_f32_e32 v92, v92
	s_nop 0
	v_add_f32_e32 v92, 1.0, v92
	v_div_scale_f32 v93, s[24:25], v92, v92, 1.0
	v_rcp_f32_e32 v94, v93
	s_nop 0
	v_fma_f32 v95, -v93, v94, 1.0
	v_fmac_f32_e32 v94, v95, v94
	v_div_scale_f32 v95, vcc, 1.0, v92, 1.0
	v_mul_f32_e32 v96, v95, v94
	v_fma_f32 v97, -v93, v96, v95
	v_fmac_f32_e32 v96, v97, v94
	v_fma_f32 v93, -v93, v96, v95
	v_div_fmas_f32 v93, v93, v94, v96
	v_div_fixup_f32 v62, v93, v92, 1.0
	v_mul_f32_e32 v62, 0xbf1b4598, v62
	v_mul_f32_e32 v62, 0x3fb8aa3b, v62
	v_exp_f32_e32 v62, v62
	v_mul_f32_e32 v92, 0xbfb8aa3b, v66
	v_exp_f32_e32 v92, v92
	s_nop 0
	v_add_f32_e32 v92, 1.0, v92
	v_div_scale_f32 v93, s[24:25], v92, v92, 1.0
	v_rcp_f32_e32 v94, v93
	s_nop 0
	v_fma_f32 v95, -v93, v94, 1.0
	v_fmac_f32_e32 v94, v95, v94
	v_div_scale_f32 v95, vcc, 1.0, v92, 1.0
	v_mul_f32_e32 v96, v95, v94
	v_fma_f32 v97, -v93, v96, v95
	v_fmac_f32_e32 v96, v97, v94
	v_fma_f32 v93, -v93, v96, v95
	v_div_fmas_f32 v93, v93, v94, v96
	v_div_fixup_f32 v66, v93, v92, 1.0
	v_mul_f32_e32 v92, 0xbfb8aa3b, v63
	v_exp_f32_e32 v92, v92
	s_nop 0
	v_add_f32_e32 v92, 1.0, v92
	v_div_scale_f32 v93, s[24:25], v92, v92, 1.0
	v_rcp_f32_e32 v94, v93
	s_nop 0
	v_fma_f32 v95, -v93, v94, 1.0
	v_fmac_f32_e32 v94, v95, v94
	v_div_scale_f32 v95, vcc, 1.0, v92, 1.0
	v_mul_f32_e32 v96, v95, v94
	v_fma_f32 v97, -v93, v96, v95
	v_fmac_f32_e32 v96, v97, v94
	v_fma_f32 v93, -v93, v96, v95
	v_div_fmas_f32 v93, v93, v94, v96
	v_div_fixup_f32 v63, v93, v92, 1.0
	v_mul_f32_e32 v63, 0xbf1b4598, v63
	v_mul_f32_e32 v63, 0x3fb8aa3b, v63
	v_exp_f32_e32 v63, v63
	v_mul_f32_e32 v92, 0xbfb8aa3b, v67
	v_exp_f32_e32 v92, v92
	s_nop 0
	v_add_f32_e32 v92, 1.0, v92
	v_div_scale_f32 v93, s[24:25], v92, v92, 1.0
	v_rcp_f32_e32 v94, v93
	s_nop 0
	v_fma_f32 v95, -v93, v94, 1.0
	v_fmac_f32_e32 v94, v95, v94
	v_div_scale_f32 v95, vcc, 1.0, v92, 1.0
	v_mul_f32_e32 v96, v95, v94
	v_fma_f32 v97, -v93, v96, v95
	v_fmac_f32_e32 v96, v97, v94
	v_fma_f32 v93, -v93, v96, v95
	v_div_fmas_f32 v93, v93, v94, v96
	v_div_fixup_f32 v67, v93, v92, 1.0
	s_mul_i32 s7, s6, 0x1400
	s_add_u32 s8, s82, s7
	s_addc_u32 s9, s83, 0
	global_store_dwordx4 v232, v[60:63], s[8:9] offset:1024
	global_store_dwordx4 v232, v[64:67], s[8:9] offset:2048
	global_store_dwordx4 v232, v[4:7], s[8:9]
	s_add_u32 s6, s13, 2
	s_cmp_ge_u32 s6, 0x2800
	s_cbranch_scc1 .Lgprep_sk0
	v_mul_f32_e32 v92, 0xbfb8aa3b, v68
	v_exp_f32_e32 v92, v92
	s_nop 0
	v_add_f32_e32 v92, 1.0, v92
	v_div_scale_f32 v93, s[24:25], v92, v92, 1.0
	v_rcp_f32_e32 v94, v93
	s_nop 0
	v_fma_f32 v95, -v93, v94, 1.0
	v_fmac_f32_e32 v94, v95, v94
	v_div_scale_f32 v95, vcc, 1.0, v92, 1.0
	v_mul_f32_e32 v96, v95, v94
	v_fma_f32 v97, -v93, v96, v95
	v_fmac_f32_e32 v96, v97, v94
	v_fma_f32 v93, -v93, v96, v95
	v_div_fmas_f32 v93, v93, v94, v96
	v_div_fixup_f32 v68, v93, v92, 1.0
	v_mul_f32_e32 v68, 0xbf1b4598, v68
	v_mul_f32_e32 v68, 0x3fb8aa3b, v68
	v_exp_f32_e32 v68, v68
	v_mul_f32_e32 v92, 0xbfb8aa3b, v72
	v_exp_f32_e32 v92, v92
	s_nop 0
	v_add_f32_e32 v92, 1.0, v92
	v_div_scale_f32 v93, s[24:25], v92, v92, 1.0
	v_rcp_f32_e32 v94, v93
	s_nop 0
	v_fma_f32 v95, -v93, v94, 1.0
	v_fmac_f32_e32 v94, v95, v94
	v_div_scale_f32 v95, vcc, 1.0, v92, 1.0
	v_mul_f32_e32 v96, v95, v94
	v_fma_f32 v97, -v93, v96, v95
	v_fmac_f32_e32 v96, v97, v94
	v_fma_f32 v93, -v93, v96, v95
	v_div_fmas_f32 v93, v93, v94, v96
	v_div_fixup_f32 v72, v93, v92, 1.0
	v_mul_f32_e32 v92, 0xbfb8aa3b, v69
	v_exp_f32_e32 v92, v92
	s_nop 0
	v_add_f32_e32 v92, 1.0, v92
	v_div_scale_f32 v93, s[24:25], v92, v92, 1.0
	v_rcp_f32_e32 v94, v93
	s_nop 0
	v_fma_f32 v95, -v93, v94, 1.0
	v_fmac_f32_e32 v94, v95, v94
	v_div_scale_f32 v95, vcc, 1.0, v92, 1.0
	v_mul_f32_e32 v96, v95, v94
	v_fma_f32 v97, -v93, v96, v95
	v_fmac_f32_e32 v96, v97, v94
	v_fma_f32 v93, -v93, v96, v95
	v_div_fmas_f32 v93, v93, v94, v96
	v_div_fixup_f32 v69, v93, v92, 1.0
	v_mul_f32_e32 v69, 0xbf1b4598, v69
	v_mul_f32_e32 v69, 0x3fb8aa3b, v69
	v_exp_f32_e32 v69, v69
	v_mul_f32_e32 v92, 0xbfb8aa3b, v73
	v_exp_f32_e32 v92, v92
	s_nop 0
	v_add_f32_e32 v92, 1.0, v92
	v_div_scale_f32 v93, s[24:25], v92, v92, 1.0
	v_rcp_f32_e32 v94, v93
	s_nop 0
	v_fma_f32 v95, -v93, v94, 1.0
	v_fmac_f32_e32 v94, v95, v94
	v_div_scale_f32 v95, vcc, 1.0, v92, 1.0
	v_mul_f32_e32 v96, v95, v94
	v_fma_f32 v97, -v93, v96, v95
	v_fmac_f32_e32 v96, v97, v94
	v_fma_f32 v93, -v93, v96, v95
	v_div_fmas_f32 v93, v93, v94, v96
	v_div_fixup_f32 v73, v93, v92, 1.0
	v_mul_f32_e32 v92, 0xbfb8aa3b, v70
	v_exp_f32_e32 v92, v92
	s_nop 0
	v_add_f32_e32 v92, 1.0, v92
	v_div_scale_f32 v93, s[24:25], v92, v92, 1.0
	v_rcp_f32_e32 v94, v93
	s_nop 0
	v_fma_f32 v95, -v93, v94, 1.0
	v_fmac_f32_e32 v94, v95, v94
	v_div_scale_f32 v95, vcc, 1.0, v92, 1.0
	v_mul_f32_e32 v96, v95, v94
	v_fma_f32 v97, -v93, v96, v95
	v_fmac_f32_e32 v96, v97, v94
	v_fma_f32 v93, -v93, v96, v95
	v_div_fmas_f32 v93, v93, v94, v96
	v_div_fixup_f32 v70, v93, v92, 1.0
	v_mul_f32_e32 v70, 0xbf1b4598, v70
	v_mul_f32_e32 v70, 0x3fb8aa3b, v70
	v_exp_f32_e32 v70, v70
	v_mul_f32_e32 v92, 0xbfb8aa3b, v74
	v_exp_f32_e32 v92, v92
	s_nop 0
	v_add_f32_e32 v92, 1.0, v92
	v_div_scale_f32 v93, s[24:25], v92, v92, 1.0
	v_rcp_f32_e32 v94, v93
	s_nop 0
	v_fma_f32 v95, -v93, v94, 1.0
	v_fmac_f32_e32 v94, v95, v94
	v_div_scale_f32 v95, vcc, 1.0, v92, 1.0
	v_mul_f32_e32 v96, v95, v94
	v_fma_f32 v97, -v93, v96, v95
	v_fmac_f32_e32 v96, v97, v94
	v_fma_f32 v93, -v93, v96, v95
	v_div_fmas_f32 v93, v93, v94, v96
	v_div_fixup_f32 v74, v93, v92, 1.0
	v_mul_f32_e32 v92, 0xbfb8aa3b, v71
	v_exp_f32_e32 v92, v92
	s_nop 0
	v_add_f32_e32 v92, 1.0, v92
	v_div_scale_f32 v93, s[24:25], v92, v92, 1.0
	v_rcp_f32_e32 v94, v93
	s_nop 0
	v_fma_f32 v95, -v93, v94, 1.0
	v_fmac_f32_e32 v94, v95, v94
	v_div_scale_f32 v95, vcc, 1.0, v92, 1.0
	v_mul_f32_e32 v96, v95, v94
	v_fma_f32 v97, -v93, v96, v95
	v_fmac_f32_e32 v96, v97, v94
	v_fma_f32 v93, -v93, v96, v95
	v_div_fmas_f32 v93, v93, v94, v96
	v_div_fixup_f32 v71, v93, v92, 1.0
	v_mul_f32_e32 v71, 0xbf1b4598, v71
	v_mul_f32_e32 v71, 0x3fb8aa3b, v71
	v_exp_f32_e32 v71, v71
	v_mul_f32_e32 v92, 0xbfb8aa3b, v75
	v_exp_f32_e32 v92, v92
	s_nop 0
	v_add_f32_e32 v92, 1.0, v92
	v_div_scale_f32 v93, s[24:25], v92, v92, 1.0
	v_rcp_f32_e32 v94, v93
	s_nop 0
	v_fma_f32 v95, -v93, v94, 1.0
	v_fmac_f32_e32 v94, v95, v94
	v_div_scale_f32 v95, vcc, 1.0, v92, 1.0
	v_mul_f32_e32 v96, v95, v94
	v_fma_f32 v97, -v93, v96, v95
	v_fmac_f32_e32 v96, v97, v94
	v_fma_f32 v93, -v93, v96, v95
	v_div_fmas_f32 v93, v93, v94, v96
	v_div_fixup_f32 v75, v93, v92, 1.0
	s_mul_i32 s7, s6, 0x1400
	s_add_u32 s8, s82, s7
	s_addc_u32 s9, s83, 0
	global_store_dwordx4 v232, v[68:71], s[8:9] offset:1024
	global_store_dwordx4 v232, v[72:75], s[8:9] offset:2048
	global_store_dwordx4 v232, v[8:11], s[8:9]
	s_add_u32 s6, s13, 3
	s_cmp_ge_u32 s6, 0x2800
	s_cbranch_scc1 .Lgprep_sk0
	v_mul_f32_e32 v92, 0xbfb8aa3b, v76
	v_exp_f32_e32 v92, v92
	s_nop 0
	v_add_f32_e32 v92, 1.0, v92
	v_div_scale_f32 v93, s[24:25], v92, v92, 1.0
	v_rcp_f32_e32 v94, v93
	s_nop 0
	v_fma_f32 v95, -v93, v94, 1.0
	v_fmac_f32_e32 v94, v95, v94
	v_div_scale_f32 v95, vcc, 1.0, v92, 1.0
	v_mul_f32_e32 v96, v95, v94
	v_fma_f32 v97, -v93, v96, v95
	v_fmac_f32_e32 v96, v97, v94
	v_fma_f32 v93, -v93, v96, v95
	v_div_fmas_f32 v93, v93, v94, v96
	v_div_fixup_f32 v76, v93, v92, 1.0
	v_mul_f32_e32 v76, 0xbf1b4598, v76
	v_mul_f32_e32 v76, 0x3fb8aa3b, v76
	v_exp_f32_e32 v76, v76
	v_mul_f32_e32 v92, 0xbfb8aa3b, v80
	v_exp_f32_e32 v92, v92
	s_nop 0
	v_add_f32_e32 v92, 1.0, v92
	v_div_scale_f32 v93, s[24:25], v92, v92, 1.0
	v_rcp_f32_e32 v94, v93
	s_nop 0
	v_fma_f32 v95, -v93, v94, 1.0
	v_fmac_f32_e32 v94, v95, v94
	v_div_scale_f32 v95, vcc, 1.0, v92, 1.0
	v_mul_f32_e32 v96, v95, v94
	v_fma_f32 v97, -v93, v96, v95
	v_fmac_f32_e32 v96, v97, v94
	v_fma_f32 v93, -v93, v96, v95
	v_div_fmas_f32 v93, v93, v94, v96
	v_div_fixup_f32 v80, v93, v92, 1.0
	v_mul_f32_e32 v92, 0xbfb8aa3b, v77
	v_exp_f32_e32 v92, v92
	s_nop 0
	v_add_f32_e32 v92, 1.0, v92
	v_div_scale_f32 v93, s[24:25], v92, v92, 1.0
	v_rcp_f32_e32 v94, v93
	s_nop 0
	v_fma_f32 v95, -v93, v94, 1.0
	v_fmac_f32_e32 v94, v95, v94
	v_div_scale_f32 v95, vcc, 1.0, v92, 1.0
	v_mul_f32_e32 v96, v95, v94
	v_fma_f32 v97, -v93, v96, v95
	v_fmac_f32_e32 v96, v97, v94
	v_fma_f32 v93, -v93, v96, v95
	v_div_fmas_f32 v93, v93, v94, v96
	v_div_fixup_f32 v77, v93, v92, 1.0
	v_mul_f32_e32 v77, 0xbf1b4598, v77
	v_mul_f32_e32 v77, 0x3fb8aa3b, v77
	v_exp_f32_e32 v77, v77
	v_mul_f32_e32 v92, 0xbfb8aa3b, v81
	v_exp_f32_e32 v92, v92
	s_nop 0
	v_add_f32_e32 v92, 1.0, v92
	v_div_scale_f32 v93, s[24:25], v92, v92, 1.0
	v_rcp_f32_e32 v94, v93
	s_nop 0
	v_fma_f32 v95, -v93, v94, 1.0
	v_fmac_f32_e32 v94, v95, v94
	v_div_scale_f32 v95, vcc, 1.0, v92, 1.0
	v_mul_f32_e32 v96, v95, v94
	v_fma_f32 v97, -v93, v96, v95
	v_fmac_f32_e32 v96, v97, v94
	v_fma_f32 v93, -v93, v96, v95
	v_div_fmas_f32 v93, v93, v94, v96
	v_div_fixup_f32 v81, v93, v92, 1.0
	v_mul_f32_e32 v92, 0xbfb8aa3b, v78
	v_exp_f32_e32 v92, v92
	s_nop 0
	v_add_f32_e32 v92, 1.0, v92
	v_div_scale_f32 v93, s[24:25], v92, v92, 1.0
	v_rcp_f32_e32 v94, v93
	s_nop 0
	v_fma_f32 v95, -v93, v94, 1.0
	v_fmac_f32_e32 v94, v95, v94
	v_div_scale_f32 v95, vcc, 1.0, v92, 1.0
	v_mul_f32_e32 v96, v95, v94
	v_fma_f32 v97, -v93, v96, v95
	v_fmac_f32_e32 v96, v97, v94
	v_fma_f32 v93, -v93, v96, v95
	v_div_fmas_f32 v93, v93, v94, v96
	v_div_fixup_f32 v78, v93, v92, 1.0
	v_mul_f32_e32 v78, 0xbf1b4598, v78
	v_mul_f32_e32 v78, 0x3fb8aa3b, v78
	v_exp_f32_e32 v78, v78
	v_mul_f32_e32 v92, 0xbfb8aa3b, v82
	v_exp_f32_e32 v92, v92
	s_nop 0
	v_add_f32_e32 v92, 1.0, v92
	v_div_scale_f32 v93, s[24:25], v92, v92, 1.0
	v_rcp_f32_e32 v94, v93
	s_nop 0
	v_fma_f32 v95, -v93, v94, 1.0
	v_fmac_f32_e32 v94, v95, v94
	v_div_scale_f32 v95, vcc, 1.0, v92, 1.0
	v_mul_f32_e32 v96, v95, v94
	v_fma_f32 v97, -v93, v96, v95
	v_fmac_f32_e32 v96, v97, v94
	v_fma_f32 v93, -v93, v96, v95
	v_div_fmas_f32 v93, v93, v94, v96
	v_div_fixup_f32 v82, v93, v92, 1.0
	v_mul_f32_e32 v92, 0xbfb8aa3b, v79
	v_exp_f32_e32 v92, v92
	s_nop 0
	v_add_f32_e32 v92, 1.0, v92
	v_div_scale_f32 v93, s[24:25], v92, v92, 1.0
	v_rcp_f32_e32 v94, v93
	s_nop 0
	v_fma_f32 v95, -v93, v94, 1.0
	v_fmac_f32_e32 v94, v95, v94
	v_div_scale_f32 v95, vcc, 1.0, v92, 1.0
	v_mul_f32_e32 v96, v95, v94
	v_fma_f32 v97, -v93, v96, v95
	v_fmac_f32_e32 v96, v97, v94
	v_fma_f32 v93, -v93, v96, v95
	v_div_fmas_f32 v93, v93, v94, v96
	v_div_fixup_f32 v79, v93, v92, 1.0
	v_mul_f32_e32 v79, 0xbf1b4598, v79
	v_mul_f32_e32 v79, 0x3fb8aa3b, v79
	v_exp_f32_e32 v79, v79
	v_mul_f32_e32 v92, 0xbfb8aa3b, v83
	v_exp_f32_e32 v92, v92
	s_nop 0
	v_add_f32_e32 v92, 1.0, v92
	v_div_scale_f32 v93, s[24:25], v92, v92, 1.0
	v_rcp_f32_e32 v94, v93
	s_nop 0
	v_fma_f32 v95, -v93, v94, 1.0
	v_fmac_f32_e32 v94, v95, v94
	v_div_scale_f32 v95, vcc, 1.0, v92, 1.0
	v_mul_f32_e32 v96, v95, v94
	v_fma_f32 v97, -v93, v96, v95
	v_fmac_f32_e32 v96, v97, v94
	v_fma_f32 v93, -v93, v96, v95
	v_div_fmas_f32 v93, v93, v94, v96
	v_div_fixup_f32 v83, v93, v92, 1.0
	s_mul_i32 s7, s6, 0x1400
	s_add_u32 s8, s82, s7
	s_addc_u32 s9, s83, 0
	global_store_dwordx4 v232, v[76:79], s[8:9] offset:1024
	global_store_dwordx4 v232, v[80:83], s[8:9] offset:2048
	global_store_dwordx4 v232, v[12:15], s[8:9]
	s_add_u32 s6, s13, 4
	s_cmp_ge_u32 s6, 0x2800
	s_cbranch_scc1 .Lgprep_sk0
	v_mul_f32_e32 v92, 0xbfb8aa3b, v84
	v_exp_f32_e32 v92, v92
	s_nop 0
	v_add_f32_e32 v92, 1.0, v92
	v_div_scale_f32 v93, s[24:25], v92, v92, 1.0
	v_rcp_f32_e32 v94, v93
	s_nop 0
	v_fma_f32 v95, -v93, v94, 1.0
	v_fmac_f32_e32 v94, v95, v94
	v_div_scale_f32 v95, vcc, 1.0, v92, 1.0
	v_mul_f32_e32 v96, v95, v94
	v_fma_f32 v97, -v93, v96, v95
	v_fmac_f32_e32 v96, v97, v94
	v_fma_f32 v93, -v93, v96, v95
	v_div_fmas_f32 v93, v93, v94, v96
	v_div_fixup_f32 v84, v93, v92, 1.0
	v_mul_f32_e32 v84, 0xbf1b4598, v84
	v_mul_f32_e32 v84, 0x3fb8aa3b, v84
	v_exp_f32_e32 v84, v84
	v_mul_f32_e32 v92, 0xbfb8aa3b, v88
	v_exp_f32_e32 v92, v92
	s_nop 0
	v_add_f32_e32 v92, 1.0, v92
	v_div_scale_f32 v93, s[24:25], v92, v92, 1.0
	v_rcp_f32_e32 v94, v93
	s_nop 0
	v_fma_f32 v95, -v93, v94, 1.0
	v_fmac_f32_e32 v94, v95, v94
	v_div_scale_f32 v95, vcc, 1.0, v92, 1.0
	v_mul_f32_e32 v96, v95, v94
	v_fma_f32 v97, -v93, v96, v95
	v_fmac_f32_e32 v96, v97, v94
	v_fma_f32 v93, -v93, v96, v95
	v_div_fmas_f32 v93, v93, v94, v96
	v_div_fixup_f32 v88, v93, v92, 1.0
	v_mul_f32_e32 v92, 0xbfb8aa3b, v85
	v_exp_f32_e32 v92, v92
	s_nop 0
	v_add_f32_e32 v92, 1.0, v92
	v_div_scale_f32 v93, s[24:25], v92, v92, 1.0
	v_rcp_f32_e32 v94, v93
	s_nop 0
	v_fma_f32 v95, -v93, v94, 1.0
	v_fmac_f32_e32 v94, v95, v94
	v_div_scale_f32 v95, vcc, 1.0, v92, 1.0
	v_mul_f32_e32 v96, v95, v94
	v_fma_f32 v97, -v93, v96, v95
	v_fmac_f32_e32 v96, v97, v94
	v_fma_f32 v93, -v93, v96, v95
	v_div_fmas_f32 v93, v93, v94, v96
	v_div_fixup_f32 v85, v93, v92, 1.0
	v_mul_f32_e32 v85, 0xbf1b4598, v85
	v_mul_f32_e32 v85, 0x3fb8aa3b, v85
	v_exp_f32_e32 v85, v85
	v_mul_f32_e32 v92, 0xbfb8aa3b, v89
	v_exp_f32_e32 v92, v92
	s_nop 0
	v_add_f32_e32 v92, 1.0, v92
	v_div_scale_f32 v93, s[24:25], v92, v92, 1.0
	v_rcp_f32_e32 v94, v93
	s_nop 0
	v_fma_f32 v95, -v93, v94, 1.0
	v_fmac_f32_e32 v94, v95, v94
	v_div_scale_f32 v95, vcc, 1.0, v92, 1.0
	v_mul_f32_e32 v96, v95, v94
	v_fma_f32 v97, -v93, v96, v95
	v_fmac_f32_e32 v96, v97, v94
	v_fma_f32 v93, -v93, v96, v95
	v_div_fmas_f32 v93, v93, v94, v96
	v_div_fixup_f32 v89, v93, v92, 1.0
	v_mul_f32_e32 v92, 0xbfb8aa3b, v86
	v_exp_f32_e32 v92, v92
	s_nop 0
	v_add_f32_e32 v92, 1.0, v92
	v_div_scale_f32 v93, s[24:25], v92, v92, 1.0
	v_rcp_f32_e32 v94, v93
	s_nop 0
	v_fma_f32 v95, -v93, v94, 1.0
	v_fmac_f32_e32 v94, v95, v94
	v_div_scale_f32 v95, vcc, 1.0, v92, 1.0
	v_mul_f32_e32 v96, v95, v94
	v_fma_f32 v97, -v93, v96, v95
	v_fmac_f32_e32 v96, v97, v94
	v_fma_f32 v93, -v93, v96, v95
	v_div_fmas_f32 v93, v93, v94, v96
	v_div_fixup_f32 v86, v93, v92, 1.0
	v_mul_f32_e32 v86, 0xbf1b4598, v86
	v_mul_f32_e32 v86, 0x3fb8aa3b, v86
	v_exp_f32_e32 v86, v86
	v_mul_f32_e32 v92, 0xbfb8aa3b, v90
	v_exp_f32_e32 v92, v92
	s_nop 0
	v_add_f32_e32 v92, 1.0, v92
	v_div_scale_f32 v93, s[24:25], v92, v92, 1.0
	v_rcp_f32_e32 v94, v93
	s_nop 0
	v_fma_f32 v95, -v93, v94, 1.0
	v_fmac_f32_e32 v94, v95, v94
	v_div_scale_f32 v95, vcc, 1.0, v92, 1.0
	v_mul_f32_e32 v96, v95, v94
	v_fma_f32 v97, -v93, v96, v95
	v_fmac_f32_e32 v96, v97, v94
	v_fma_f32 v93, -v93, v96, v95
	v_div_fmas_f32 v93, v93, v94, v96
	v_div_fixup_f32 v90, v93, v92, 1.0
	v_mul_f32_e32 v92, 0xbfb8aa3b, v87
	v_exp_f32_e32 v92, v92
	s_nop 0
	v_add_f32_e32 v92, 1.0, v92
	v_div_scale_f32 v93, s[24:25], v92, v92, 1.0
	v_rcp_f32_e32 v94, v93
	s_nop 0
	v_fma_f32 v95, -v93, v94, 1.0
	v_fmac_f32_e32 v94, v95, v94
	v_div_scale_f32 v95, vcc, 1.0, v92, 1.0
	v_mul_f32_e32 v96, v95, v94
	v_fma_f32 v97, -v93, v96, v95
	v_fmac_f32_e32 v96, v97, v94
	v_fma_f32 v93, -v93, v96, v95
	v_div_fmas_f32 v93, v93, v94, v96
	v_div_fixup_f32 v87, v93, v92, 1.0
	v_mul_f32_e32 v87, 0xbf1b4598, v87
	v_mul_f32_e32 v87, 0x3fb8aa3b, v87
	v_exp_f32_e32 v87, v87
	v_mul_f32_e32 v92, 0xbfb8aa3b, v91
	v_exp_f32_e32 v92, v92
	s_nop 0
	v_add_f32_e32 v92, 1.0, v92
	v_div_scale_f32 v93, s[24:25], v92, v92, 1.0
	v_rcp_f32_e32 v94, v93
	s_nop 0
	v_fma_f32 v95, -v93, v94, 1.0
	v_fmac_f32_e32 v94, v95, v94
	v_div_scale_f32 v95, vcc, 1.0, v92, 1.0
	v_mul_f32_e32 v96, v95, v94
	v_fma_f32 v97, -v93, v96, v95
	v_fmac_f32_e32 v96, v97, v94
	v_fma_f32 v93, -v93, v96, v95
	v_div_fmas_f32 v93, v93, v94, v96
	v_div_fixup_f32 v91, v93, v92, 1.0
	s_mul_i32 s7, s6, 0x1400
	s_add_u32 s8, s82, s7
	s_addc_u32 s9, s83, 0
	global_store_dwordx4 v232, v[84:87], s[8:9] offset:1024
	global_store_dwordx4 v232, v[88:91], s[8:9] offset:2048
	global_store_dwordx4 v232, v[16:19], s[8:9]
	s_branch .Lgprep_e0

.Lgprep_e0:
	v_mov_b32_e32 v52, v38
	v_mov_b32_e32 v56, v46
	v_mov_b32_e32 v53, v39
	v_mov_b32_e32 v57, v47
	v_mov_b32_e32 v54, v40
	v_mov_b32_e32 v58, v48
	v_mov_b32_e32 v55, v41
	v_mov_b32_e32 v59, v49
	v_mov_b32_e32 v60, v38
	v_mov_b32_e32 v64, v46
	v_mov_b32_e32 v61, v39
	v_mov_b32_e32 v65, v47
	v_mov_b32_e32 v62, v40
	v_mov_b32_e32 v66, v48
	v_mov_b32_e32 v63, v41
	v_mov_b32_e32 v67, v49
	v_mov_b32_e32 v68, v38
	v_mov_b32_e32 v72, v46
	v_mov_b32_e32 v69, v39
	v_mov_b32_e32 v73, v47
	v_mov_b32_e32 v70, v40
	v_mov_b32_e32 v74, v48
	v_mov_b32_e32 v71, v41
	v_mov_b32_e32 v75, v49
	v_mov_b32_e32 v76, v38
	v_mov_b32_e32 v80, v46
	v_mov_b32_e32 v77, v39
	v_mov_b32_e32 v81, v47
	v_mov_b32_e32 v78, v40
	v_mov_b32_e32 v82, v48
	v_mov_b32_e32 v79, v41
	v_mov_b32_e32 v83, v49
	v_mov_b32_e32 v84, v38
	v_mov_b32_e32 v88, v46
	v_mov_b32_e32 v85, v39
	v_mov_b32_e32 v89, v47
	v_mov_b32_e32 v86, v40
	v_mov_b32_e32 v90, v48
	v_mov_b32_e32 v87, v41
	v_mov_b32_e32 v91, v49
	global_load_dwordx4 v[216:219], v232, s[2:3] offset:2048
	global_load_dwordx4 v[220:223], v232, s[40:41] offset:2048
	s_waitcnt vmcnt(27)
	v_readlane_b32 s48, v20, 32
	v_readlane_b32 s58, v25, 32
	v_readlane_b32 s50, v21, 32
	v_readlane_b32 s60, v26, 32
	v_readlane_b32 s52, v22, 32
	v_readlane_b32 s62, v27, 32
	v_readlane_b32 s54, v23, 32
	v_readlane_b32 s64, v28, 32
	v_readlane_b32 s56, v24, 32
	v_readlane_b32 s66, v29, 32
	v_pk_fma_f32 v[52:53], v[168:169], s[48:49], v[52:53] op_sel_hi:[1,0,1]
	v_pk_fma_f32 v[54:55], v[170:171], s[48:49], v[54:55] op_sel_hi:[1,0,1]
	v_pk_fma_f32 v[56:57], v[172:173], s[58:59], v[56:57] op_sel_hi:[1,0,1]
	v_pk_fma_f32 v[58:59], v[174:175], s[58:59], v[58:59] op_sel_hi:[1,0,1]
	v_pk_fma_f32 v[60:61], v[168:169], s[50:51], v[60:61] op_sel_hi:[1,0,1]
	v_pk_fma_f32 v[62:63], v[170:171], s[50:51], v[62:63] op_sel_hi:[1,0,1]
	v_pk_fma_f32 v[64:65], v[172:173], s[60:61], v[64:65] op_sel_hi:[1,0,1]
	v_pk_fma_f32 v[66:67], v[174:175], s[60:61], v[66:67] op_sel_hi:[1,0,1]
	v_pk_fma_f32 v[68:69], v[168:169], s[52:53], v[68:69] op_sel_hi:[1,0,1]
	v_pk_fma_f32 v[70:71], v[170:171], s[52:53], v[70:71] op_sel_hi:[1,0,1]
	v_pk_fma_f32 v[72:73], v[172:173], s[62:63], v[72:73] op_sel_hi:[1,0,1]
	v_pk_fma_f32 v[74:75], v[174:175], s[62:63], v[74:75] op_sel_hi:[1,0,1]
	v_pk_fma_f32 v[76:77], v[168:169], s[54:55], v[76:77] op_sel_hi:[1,0,1]
	v_pk_fma_f32 v[78:79], v[170:171], s[54:55], v[78:79] op_sel_hi:[1,0,1]
	v_pk_fma_f32 v[80:81], v[172:173], s[64:65], v[80:81] op_sel_hi:[1,0,1]
	v_pk_fma_f32 v[82:83], v[174:175], s[64:65], v[82:83] op_sel_hi:[1,0,1]
	v_pk_fma_f32 v[84:85], v[168:169], s[56:57], v[84:85] op_sel_hi:[1,0,1]
	v_pk_fma_f32 v[86:87], v[170:171], s[56:57], v[86:87] op_sel_hi:[1,0,1]
	v_pk_fma_f32 v[88:89], v[172:173], s[66:67], v[88:89] op_sel_hi:[1,0,1]
	v_pk_fma_f32 v[90:91], v[174:175], s[66:67], v[90:91] op_sel_hi:[1,0,1]
	global_load_dwordx4 v[224:227], v232, s[2:3] offset:3072
	global_load_dwordx4 v[228:231], v232, s[40:41] offset:3072
	s_add_u32 s2, s2, 0x1000
	s_addc_u32 s3, s3, 0
	s_add_u32 s40, s40, 0x1000
	s_addc_u32 s41, s41, 0
	s_waitcnt vmcnt(27)
	v_readlane_b32 s48, v20, 33
	v_readlane_b32 s58, v25, 33
	v_readlane_b32 s50, v21, 33
	v_readlane_b32 s60, v26, 33
	v_readlane_b32 s52, v22, 33
	v_readlane_b32 s62, v27, 33
	v_readlane_b32 s54, v23, 33
	v_readlane_b32 s64, v28, 33
	v_readlane_b32 s56, v24, 33
	v_readlane_b32 s66, v29, 33
	v_pk_fma_f32 v[52:53], v[176:177], s[48:49], v[52:53] op_sel_hi:[1,0,1]
	v_pk_fma_f32 v[54:55], v[178:179], s[48:49], v[54:55] op_sel_hi:[1,0,1]
	v_pk_fma_f32 v[56:57], v[180:181], s[58:59], v[56:57] op_sel_hi:[1,0,1]
	v_pk_fma_f32 v[58:59], v[182:183], s[58:59], v[58:59] op_sel_hi:[1,0,1]
	v_pk_fma_f32 v[60:61], v[176:177], s[50:51], v[60:61] op_sel_hi:[1,0,1]
	v_pk_fma_f32 v[62:63], v[178:179], s[50:51], v[62:63] op_sel_hi:[1,0,1]
	v_pk_fma_f32 v[64:65], v[180:181], s[60:61], v[64:65] op_sel_hi:[1,0,1]
	v_pk_fma_f32 v[66:67], v[182:183], s[60:61], v[66:67] op_sel_hi:[1,0,1]
	v_pk_fma_f32 v[68:69], v[176:177], s[52:53], v[68:69] op_sel_hi:[1,0,1]
	v_pk_fma_f32 v[70:71], v[178:179], s[52:53], v[70:71] op_sel_hi:[1,0,1]
	v_pk_fma_f32 v[72:73], v[180:181], s[62:63], v[72:73] op_sel_hi:[1,0,1]
	v_pk_fma_f32 v[74:75], v[182:183], s[62:63], v[74:75] op_sel_hi:[1,0,1]
	v_pk_fma_f32 v[76:77], v[176:177], s[54:55], v[76:77] op_sel_hi:[1,0,1]
	v_pk_fma_f32 v[78:79], v[178:179], s[54:55], v[78:79] op_sel_hi:[1,0,1]
	v_pk_fma_f32 v[80:81], v[180:181], s[64:65], v[80:81] op_sel_hi:[1,0,1]
	v_pk_fma_f32 v[82:83], v[182:183], s[64:65], v[82:83] op_sel_hi:[1,0,1]
	v_pk_fma_f32 v[84:85], v[176:177], s[56:57], v[84:85] op_sel_hi:[1,0,1]
	v_pk_fma_f32 v[86:87], v[178:179], s[56:57], v[86:87] op_sel_hi:[1,0,1]
	v_pk_fma_f32 v[88:89], v[180:181], s[66:67], v[88:89] op_sel_hi:[1,0,1]
	v_pk_fma_f32 v[90:91], v[182:183], s[66:67], v[90:91] op_sel_hi:[1,0,1]
	global_load_dwordx4 v[168:171], v232, s[2:3]
	global_load_dwordx4 v[172:175], v232, s[40:41]
	s_waitcnt vmcnt(27)
	v_readlane_b32 s48, v20, 34
	v_readlane_b32 s58, v25, 34
	v_readlane_b32 s50, v21, 34
	v_readlane_b32 s60, v26, 34
	v_readlane_b32 s52, v22, 34
	v_readlane_b32 s62, v27, 34
	v_readlane_b32 s54, v23, 34
	v_readlane_b32 s64, v28, 34
	v_readlane_b32 s56, v24, 34
	v_readlane_b32 s66, v29, 34
	v_pk_fma_f32 v[52:53], v[184:185], s[48:49], v[52:53] op_sel_hi:[1,0,1]
	v_pk_fma_f32 v[54:55], v[186:187], s[48:49], v[54:55] op_sel_hi:[1,0,1]
	v_pk_fma_f32 v[56:57], v[188:189], s[58:59], v[56:57] op_sel_hi:[1,0,1]
	v_pk_fma_f32 v[58:59], v[190:191], s[58:59], v[58:59] op_sel_hi:[1,0,1]
	v_pk_fma_f32 v[60:61], v[184:185], s[50:51], v[60:61] op_sel_hi:[1,0,1]
	v_pk_fma_f32 v[62:63], v[186:187], s[50:51], v[62:63] op_sel_hi:[1,0,1]
	v_pk_fma_f32 v[64:65], v[188:189], s[60:61], v[64:65] op_sel_hi:[1,0,1]
	v_pk_fma_f32 v[66:67], v[190:191], s[60:61], v[66:67] op_sel_hi:[1,0,1]
	v_pk_fma_f32 v[68:69], v[184:185], s[52:53], v[68:69] op_sel_hi:[1,0,1]
	v_pk_fma_f32 v[70:71], v[186:187], s[52:53], v[70:71] op_sel_hi:[1,0,1]
	v_pk_fma_f32 v[72:73], v[188:189], s[62:63], v[72:73] op_sel_hi:[1,0,1]
	v_pk_fma_f32 v[74:75], v[190:191], s[62:63], v[74:75] op_sel_hi:[1,0,1]
	v_pk_fma_f32 v[76:77], v[184:185], s[54:55], v[76:77] op_sel_hi:[1,0,1]
	v_pk_fma_f32 v[78:79], v[186:187], s[54:55], v[78:79] op_sel_hi:[1,0,1]
	v_pk_fma_f32 v[80:81], v[188:189], s[64:65], v[80:81] op_sel_hi:[1,0,1]
	v_pk_fma_f32 v[82:83], v[190:191], s[64:65], v[82:83] op_sel_hi:[1,0,1]
	v_pk_fma_f32 v[84:85], v[184:185], s[56:57], v[84:85] op_sel_hi:[1,0,1]
	v_pk_fma_f32 v[86:87], v[186:187], s[56:57], v[86:87] op_sel_hi:[1,0,1]
	v_pk_fma_f32 v[88:89], v[188:189], s[66:67], v[88:89] op_sel_hi:[1,0,1]
	v_pk_fma_f32 v[90:91], v[190:191], s[66:67], v[90:91] op_sel_hi:[1,0,1]
	global_load_dwordx4 v[176:179], v232, s[2:3] offset:1024
	global_load_dwordx4 v[180:183], v232, s[40:41] offset:1024
	s_waitcnt vmcnt(27)
	v_readlane_b32 s48, v20, 35
	v_readlane_b32 s58, v25, 35
	v_readlane_b32 s50, v21, 35
	v_readlane_b32 s60, v26, 35
	v_readlane_b32 s52, v22, 35
	v_readlane_b32 s62, v27, 35
	v_readlane_b32 s54, v23, 35
	v_readlane_b32 s64, v28, 35
	v_readlane_b32 s56, v24, 35
	v_readlane_b32 s66, v29, 35
	v_pk_fma_f32 v[52:53], v[192:193], s[48:49], v[52:53] op_sel_hi:[1,0,1]
	v_pk_fma_f32 v[54:55], v[194:195], s[48:49], v[54:55] op_sel_hi:[1,0,1]
	v_pk_fma_f32 v[56:57], v[196:197], s[58:59], v[56:57] op_sel_hi:[1,0,1]
	v_pk_fma_f32 v[58:59], v[198:199], s[58:59], v[58:59] op_sel_hi:[1,0,1]
	v_pk_fma_f32 v[60:61], v[192:193], s[50:51], v[60:61] op_sel_hi:[1,0,1]
	v_pk_fma_f32 v[62:63], v[194:195], s[50:51], v[62:63] op_sel_hi:[1,0,1]
	v_pk_fma_f32 v[64:65], v[196:197], s[60:61], v[64:65] op_sel_hi:[1,0,1]
	v_pk_fma_f32 v[66:67], v[198:199], s[60:61], v[66:67] op_sel_hi:[1,0,1]
	v_pk_fma_f32 v[68:69], v[192:193], s[52:53], v[68:69] op_sel_hi:[1,0,1]
	v_pk_fma_f32 v[70:71], v[194:195], s[52:53], v[70:71] op_sel_hi:[1,0,1]
	v_pk_fma_f32 v[72:73], v[196:197], s[62:63], v[72:73] op_sel_hi:[1,0,1]
	v_pk_fma_f32 v[74:75], v[198:199], s[62:63], v[74:75] op_sel_hi:[1,0,1]
	v_pk_fma_f32 v[76:77], v[192:193], s[54:55], v[76:77] op_sel_hi:[1,0,1]
	v_pk_fma_f32 v[78:79], v[194:195], s[54:55], v[78:79] op_sel_hi:[1,0,1]
	v_pk_fma_f32 v[80:81], v[196:197], s[64:65], v[80:81] op_sel_hi:[1,0,1]
	v_pk_fma_f32 v[82:83], v[198:199], s[64:65], v[82:83] op_sel_hi:[1,0,1]
	v_pk_fma_f32 v[84:85], v[192:193], s[56:57], v[84:85] op_sel_hi:[1,0,1]
	v_pk_fma_f32 v[86:87], v[194:195], s[56:57], v[86:87] op_sel_hi:[1,0,1]
	v_pk_fma_f32 v[88:89], v[196:197], s[66:67], v[88:89] op_sel_hi:[1,0,1]
	v_pk_fma_f32 v[90:91], v[198:199], s[66:67], v[90:91] op_sel_hi:[1,0,1]
	global_load_dwordx4 v[184:187], v232, s[2:3] offset:2048
	global_load_dwordx4 v[188:191], v232, s[40:41] offset:2048
	s_waitcnt vmcnt(27)
	v_readlane_b32 s48, v20, 36
	v_readlane_b32 s58, v25, 36
	v_readlane_b32 s50, v21, 36
	v_readlane_b32 s60, v26, 36
	v_readlane_b32 s52, v22, 36
	v_readlane_b32 s62, v27, 36
	v_readlane_b32 s54, v23, 36
	v_readlane_b32 s64, v28, 36
	v_readlane_b32 s56, v24, 36
	v_readlane_b32 s66, v29, 36
	v_pk_fma_f32 v[52:53], v[200:201], s[48:49], v[52:53] op_sel_hi:[1,0,1]
	v_pk_fma_f32 v[54:55], v[202:203], s[48:49], v[54:55] op_sel_hi:[1,0,1]
	v_pk_fma_f32 v[56:57], v[204:205], s[58:59], v[56:57] op_sel_hi:[1,0,1]
	v_pk_fma_f32 v[58:59], v[206:207], s[58:59], v[58:59] op_sel_hi:[1,0,1]
	v_pk_fma_f32 v[60:61], v[200:201], s[50:51], v[60:61] op_sel_hi:[1,0,1]
	v_pk_fma_f32 v[62:63], v[202:203], s[50:51], v[62:63] op_sel_hi:[1,0,1]
	v_pk_fma_f32 v[64:65], v[204:205], s[60:61], v[64:65] op_sel_hi:[1,0,1]
	v_pk_fma_f32 v[66:67], v[206:207], s[60:61], v[66:67] op_sel_hi:[1,0,1]
	v_pk_fma_f32 v[68:69], v[200:201], s[52:53], v[68:69] op_sel_hi:[1,0,1]
	v_pk_fma_f32 v[70:71], v[202:203], s[52:53], v[70:71] op_sel_hi:[1,0,1]
	v_pk_fma_f32 v[72:73], v[204:205], s[62:63], v[72:73] op_sel_hi:[1,0,1]
	v_pk_fma_f32 v[74:75], v[206:207], s[62:63], v[74:75] op_sel_hi:[1,0,1]
	v_pk_fma_f32 v[76:77], v[200:201], s[54:55], v[76:77] op_sel_hi:[1,0,1]
	v_pk_fma_f32 v[78:79], v[202:203], s[54:55], v[78:79] op_sel_hi:[1,0,1]
	v_pk_fma_f32 v[80:81], v[204:205], s[64:65], v[80:81] op_sel_hi:[1,0,1]
	v_pk_fma_f32 v[82:83], v[206:207], s[64:65], v[82:83] op_sel_hi:[1,0,1]
	v_pk_fma_f32 v[84:85], v[200:201], s[56:57], v[84:85] op_sel_hi:[1,0,1]
	v_pk_fma_f32 v[86:87], v[202:203], s[56:57], v[86:87] op_sel_hi:[1,0,1]
	v_pk_fma_f32 v[88:89], v[204:205], s[66:67], v[88:89] op_sel_hi:[1,0,1]
	v_pk_fma_f32 v[90:91], v[206:207], s[66:67], v[90:91] op_sel_hi:[1,0,1]
	global_load_dwordx4 v[192:195], v232, s[2:3] offset:3072
	global_load_dwordx4 v[196:199], v232, s[40:41] offset:3072
	s_add_u32 s2, s2, 0x1000
	s_addc_u32 s3, s3, 0
	s_add_u32 s40, s40, 0x1000
	s_addc_u32 s41, s41, 0
	s_waitcnt vmcnt(27)
	v_readlane_b32 s48, v20, 37
	v_readlane_b32 s58, v25, 37
	v_readlane_b32 s50, v21, 37
	v_readlane_b32 s60, v26, 37
	v_readlane_b32 s52, v22, 37
	v_readlane_b32 s62, v27, 37
	v_readlane_b32 s54, v23, 37
	v_readlane_b32 s64, v28, 37
	v_readlane_b32 s56, v24, 37
	v_readlane_b32 s66, v29, 37
	v_pk_fma_f32 v[52:53], v[208:209], s[48:49], v[52:53] op_sel_hi:[1,0,1]
	v_pk_fma_f32 v[54:55], v[210:211], s[48:49], v[54:55] op_sel_hi:[1,0,1]
	v_pk_fma_f32 v[56:57], v[212:213], s[58:59], v[56:57] op_sel_hi:[1,0,1]
	v_pk_fma_f32 v[58:59], v[214:215], s[58:59], v[58:59] op_sel_hi:[1,0,1]
	v_pk_fma_f32 v[60:61], v[208:209], s[50:51], v[60:61] op_sel_hi:[1,0,1]
	v_pk_fma_f32 v[62:63], v[210:211], s[50:51], v[62:63] op_sel_hi:[1,0,1]
	v_pk_fma_f32 v[64:65], v[212:213], s[60:61], v[64:65] op_sel_hi:[1,0,1]
	v_pk_fma_f32 v[66:67], v[214:215], s[60:61], v[66:67] op_sel_hi:[1,0,1]
	v_pk_fma_f32 v[68:69], v[208:209], s[52:53], v[68:69] op_sel_hi:[1,0,1]
	v_pk_fma_f32 v[70:71], v[210:211], s[52:53], v[70:71] op_sel_hi:[1,0,1]
	v_pk_fma_f32 v[72:73], v[212:213], s[62:63], v[72:73] op_sel_hi:[1,0,1]
	v_pk_fma_f32 v[74:75], v[214:215], s[62:63], v[74:75] op_sel_hi:[1,0,1]
	v_pk_fma_f32 v[76:77], v[208:209], s[54:55], v[76:77] op_sel_hi:[1,0,1]
	v_pk_fma_f32 v[78:79], v[210:211], s[54:55], v[78:79] op_sel_hi:[1,0,1]
	v_pk_fma_f32 v[80:81], v[212:213], s[64:65], v[80:81] op_sel_hi:[1,0,1]
	v_pk_fma_f32 v[82:83], v[214:215], s[64:65], v[82:83] op_sel_hi:[1,0,1]
	v_pk_fma_f32 v[84:85], v[208:209], s[56:57], v[84:85] op_sel_hi:[1,0,1]
	v_pk_fma_f32 v[86:87], v[210:211], s[56:57], v[86:87] op_sel_hi:[1,0,1]
	v_pk_fma_f32 v[88:89], v[212:213], s[66:67], v[88:89] op_sel_hi:[1,0,1]
	v_pk_fma_f32 v[90:91], v[214:215], s[66:67], v[90:91] op_sel_hi:[1,0,1]
	global_load_dwordx4 v[200:203], v232, s[2:3]
	global_load_dwordx4 v[204:207], v232, s[40:41]
	s_waitcnt vmcnt(12)
	v_readlane_b32 s48, v20, 38
	v_readlane_b32 s58, v25, 38
	v_readlane_b32 s50, v21, 38
	v_readlane_b32 s60, v26, 38
	v_readlane_b32 s52, v22, 38
	v_readlane_b32 s62, v27, 38
	v_readlane_b32 s54, v23, 38
	v_readlane_b32 s64, v28, 38
	v_readlane_b32 s56, v24, 38
	v_readlane_b32 s66, v29, 38
	v_pk_fma_f32 v[52:53], v[216:217], s[48:49], v[52:53] op_sel_hi:[1,0,1]
	v_pk_fma_f32 v[54:55], v[218:219], s[48:49], v[54:55] op_sel_hi:[1,0,1]
	v_pk_fma_f32 v[56:57], v[220:221], s[58:59], v[56:57] op_sel_hi:[1,0,1]
	v_pk_fma_f32 v[58:59], v[222:223], s[58:59], v[58:59] op_sel_hi:[1,0,1]
	v_pk_fma_f32 v[60:61], v[216:217], s[50:51], v[60:61] op_sel_hi:[1,0,1]
	v_pk_fma_f32 v[62:63], v[218:219], s[50:51], v[62:63] op_sel_hi:[1,0,1]
	v_pk_fma_f32 v[64:65], v[220:221], s[60:61], v[64:65] op_sel_hi:[1,0,1]
	v_pk_fma_f32 v[66:67], v[222:223], s[60:61], v[66:67] op_sel_hi:[1,0,1]
	v_pk_fma_f32 v[68:69], v[216:217], s[52:53], v[68:69] op_sel_hi:[1,0,1]
	v_pk_fma_f32 v[70:71], v[218:219], s[52:53], v[70:71] op_sel_hi:[1,0,1]
	v_pk_fma_f32 v[72:73], v[220:221], s[62:63], v[72:73] op_sel_hi:[1,0,1]
	v_pk_fma_f32 v[74:75], v[222:223], s[62:63], v[74:75] op_sel_hi:[1,0,1]
	v_pk_fma_f32 v[76:77], v[216:217], s[54:55], v[76:77] op_sel_hi:[1,0,1]
	v_pk_fma_f32 v[78:79], v[218:219], s[54:55], v[78:79] op_sel_hi:[1,0,1]
	v_pk_fma_f32 v[80:81], v[220:221], s[64:65], v[80:81] op_sel_hi:[1,0,1]
	v_pk_fma_f32 v[82:83], v[222:223], s[64:65], v[82:83] op_sel_hi:[1,0,1]
	v_pk_fma_f32 v[84:85], v[216:217], s[56:57], v[84:85] op_sel_hi:[1,0,1]
	v_pk_fma_f32 v[86:87], v[218:219], s[56:57], v[86:87] op_sel_hi:[1,0,1]
	v_pk_fma_f32 v[88:89], v[220:221], s[66:67], v[88:89] op_sel_hi:[1,0,1]
	v_pk_fma_f32 v[90:91], v[222:223], s[66:67], v[90:91] op_sel_hi:[1,0,1]
	global_load_dwordx4 v[208:211], v232, s[2:3] offset:1024
	global_load_dwordx4 v[212:215], v232, s[40:41] offset:1024
	s_waitcnt vmcnt(12)
	v_readlane_b32 s48, v20, 39
	v_readlane_b32 s58, v25, 39
	v_readlane_b32 s50, v21, 39
	v_readlane_b32 s60, v26, 39
	v_readlane_b32 s52, v22, 39
	v_readlane_b32 s62, v27, 39
	v_readlane_b32 s54, v23, 39
	v_readlane_b32 s64, v28, 39
	v_readlane_b32 s56, v24, 39
	v_readlane_b32 s66, v29, 39
	v_pk_fma_f32 v[52:53], v[224:225], s[48:49], v[52:53] op_sel_hi:[1,0,1]
	v_pk_fma_f32 v[54:55], v[226:227], s[48:49], v[54:55] op_sel_hi:[1,0,1]
	v_pk_fma_f32 v[56:57], v[228:229], s[58:59], v[56:57] op_sel_hi:[1,0,1]
	v_pk_fma_f32 v[58:59], v[230:231], s[58:59], v[58:59] op_sel_hi:[1,0,1]
	v_pk_fma_f32 v[60:61], v[224:225], s[50:51], v[60:61] op_sel_hi:[1,0,1]
	v_pk_fma_f32 v[62:63], v[226:227], s[50:51], v[62:63] op_sel_hi:[1,0,1]
	v_pk_fma_f32 v[64:65], v[228:229], s[60:61], v[64:65] op_sel_hi:[1,0,1]
	v_pk_fma_f32 v[66:67], v[230:231], s[60:61], v[66:67] op_sel_hi:[1,0,1]
	v_pk_fma_f32 v[68:69], v[224:225], s[52:53], v[68:69] op_sel_hi:[1,0,1]
	v_pk_fma_f32 v[70:71], v[226:227], s[52:53], v[70:71] op_sel_hi:[1,0,1]
	v_pk_fma_f32 v[72:73], v[228:229], s[62:63], v[72:73] op_sel_hi:[1,0,1]
	v_pk_fma_f32 v[74:75], v[230:231], s[62:63], v[74:75] op_sel_hi:[1,0,1]
	v_pk_fma_f32 v[76:77], v[224:225], s[54:55], v[76:77] op_sel_hi:[1,0,1]
	v_pk_fma_f32 v[78:79], v[226:227], s[54:55], v[78:79] op_sel_hi:[1,0,1]
	v_pk_fma_f32 v[80:81], v[228:229], s[64:65], v[80:81] op_sel_hi:[1,0,1]
	v_pk_fma_f32 v[82:83], v[230:231], s[64:65], v[82:83] op_sel_hi:[1,0,1]
	v_pk_fma_f32 v[84:85], v[224:225], s[56:57], v[84:85] op_sel_hi:[1,0,1]
	v_pk_fma_f32 v[86:87], v[226:227], s[56:57], v[86:87] op_sel_hi:[1,0,1]
	v_pk_fma_f32 v[88:89], v[228:229], s[66:67], v[88:89] op_sel_hi:[1,0,1]
	v_pk_fma_f32 v[90:91], v[230:231], s[66:67], v[90:91] op_sel_hi:[1,0,1]
	global_load_dwordx4 v[216:219], v232, s[2:3] offset:2048
	global_load_dwordx4 v[220:223], v232, s[40:41] offset:2048
	s_waitcnt vmcnt(12)
	v_readlane_b32 s48, v20, 40
	v_readlane_b32 s58, v25, 40
	v_readlane_b32 s50, v21, 40
	v_readlane_b32 s60, v26, 40
	v_readlane_b32 s52, v22, 40
	v_readlane_b32 s62, v27, 40
	v_readlane_b32 s54, v23, 40
	v_readlane_b32 s64, v28, 40
	v_readlane_b32 s56, v24, 40
	v_readlane_b32 s66, v29, 40
	v_pk_fma_f32 v[52:53], v[168:169], s[48:49], v[52:53] op_sel_hi:[1,0,1]
	v_pk_fma_f32 v[54:55], v[170:171], s[48:49], v[54:55] op_sel_hi:[1,0,1]
	v_pk_fma_f32 v[56:57], v[172:173], s[58:59], v[56:57] op_sel_hi:[1,0,1]
	v_pk_fma_f32 v[58:59], v[174:175], s[58:59], v[58:59] op_sel_hi:[1,0,1]
	v_pk_fma_f32 v[60:61], v[168:169], s[50:51], v[60:61] op_sel_hi:[1,0,1]
	v_pk_fma_f32 v[62:63], v[170:171], s[50:51], v[62:63] op_sel_hi:[1,0,1]
	v_pk_fma_f32 v[64:65], v[172:173], s[60:61], v[64:65] op_sel_hi:[1,0,1]
	v_pk_fma_f32 v[66:67], v[174:175], s[60:61], v[66:67] op_sel_hi:[1,0,1]
	v_pk_fma_f32 v[68:69], v[168:169], s[52:53], v[68:69] op_sel_hi:[1,0,1]
	v_pk_fma_f32 v[70:71], v[170:171], s[52:53], v[70:71] op_sel_hi:[1,0,1]
	v_pk_fma_f32 v[72:73], v[172:173], s[62:63], v[72:73] op_sel_hi:[1,0,1]
	v_pk_fma_f32 v[74:75], v[174:175], s[62:63], v[74:75] op_sel_hi:[1,0,1]
	v_pk_fma_f32 v[76:77], v[168:169], s[54:55], v[76:77] op_sel_hi:[1,0,1]
	v_pk_fma_f32 v[78:79], v[170:171], s[54:55], v[78:79] op_sel_hi:[1,0,1]
	v_pk_fma_f32 v[80:81], v[172:173], s[64:65], v[80:81] op_sel_hi:[1,0,1]
	v_pk_fma_f32 v[82:83], v[174:175], s[64:65], v[82:83] op_sel_hi:[1,0,1]
	v_pk_fma_f32 v[84:85], v[168:169], s[56:57], v[84:85] op_sel_hi:[1,0,1]
	v_pk_fma_f32 v[86:87], v[170:171], s[56:57], v[86:87] op_sel_hi:[1,0,1]
	v_pk_fma_f32 v[88:89], v[172:173], s[66:67], v[88:89] op_sel_hi:[1,0,1]
	v_pk_fma_f32 v[90:91], v[174:175], s[66:67], v[90:91] op_sel_hi:[1,0,1]
	global_load_dwordx4 v[224:227], v232, s[2:3] offset:3072
	global_load_dwordx4 v[228:231], v232, s[40:41] offset:3072
	s_add_u32 s2, s2, 0x1000
	s_addc_u32 s3, s3, 0
	s_add_u32 s40, s40, 0x1000
	s_addc_u32 s41, s41, 0
	s_waitcnt vmcnt(12)
	v_readlane_b32 s48, v20, 41
	v_readlane_b32 s58, v25, 41
	v_readlane_b32 s50, v21, 41
	v_readlane_b32 s60, v26, 41
	v_readlane_b32 s52, v22, 41
	v_readlane_b32 s62, v27, 41
	v_readlane_b32 s54, v23, 41
	v_readlane_b32 s64, v28, 41
	v_readlane_b32 s56, v24, 41
	v_readlane_b32 s66, v29, 41
	v_pk_fma_f32 v[52:53], v[176:177], s[48:49], v[52:53] op_sel_hi:[1,0,1]
	v_pk_fma_f32 v[54:55], v[178:179], s[48:49], v[54:55] op_sel_hi:[1,0,1]
	v_pk_fma_f32 v[56:57], v[180:181], s[58:59], v[56:57] op_sel_hi:[1,0,1]
	v_pk_fma_f32 v[58:59], v[182:183], s[58:59], v[58:59] op_sel_hi:[1,0,1]
	v_pk_fma_f32 v[60:61], v[176:177], s[50:51], v[60:61] op_sel_hi:[1,0,1]
	v_pk_fma_f32 v[62:63], v[178:179], s[50:51], v[62:63] op_sel_hi:[1,0,1]
	v_pk_fma_f32 v[64:65], v[180:181], s[60:61], v[64:65] op_sel_hi:[1,0,1]
	v_pk_fma_f32 v[66:67], v[182:183], s[60:61], v[66:67] op_sel_hi:[1,0,1]
	v_pk_fma_f32 v[68:69], v[176:177], s[52:53], v[68:69] op_sel_hi:[1,0,1]
	v_pk_fma_f32 v[70:71], v[178:179], s[52:53], v[70:71] op_sel_hi:[1,0,1]
	v_pk_fma_f32 v[72:73], v[180:181], s[62:63], v[72:73] op_sel_hi:[1,0,1]
	v_pk_fma_f32 v[74:75], v[182:183], s[62:63], v[74:75] op_sel_hi:[1,0,1]
	v_pk_fma_f32 v[76:77], v[176:177], s[54:55], v[76:77] op_sel_hi:[1,0,1]
	v_pk_fma_f32 v[78:79], v[178:179], s[54:55], v[78:79] op_sel_hi:[1,0,1]
	v_pk_fma_f32 v[80:81], v[180:181], s[64:65], v[80:81] op_sel_hi:[1,0,1]
	v_pk_fma_f32 v[82:83], v[182:183], s[64:65], v[82:83] op_sel_hi:[1,0,1]
	v_pk_fma_f32 v[84:85], v[176:177], s[56:57], v[84:85] op_sel_hi:[1,0,1]
	v_pk_fma_f32 v[86:87], v[178:179], s[56:57], v[86:87] op_sel_hi:[1,0,1]
	v_pk_fma_f32 v[88:89], v[180:181], s[66:67], v[88:89] op_sel_hi:[1,0,1]
	v_pk_fma_f32 v[90:91], v[182:183], s[66:67], v[90:91] op_sel_hi:[1,0,1]
	global_load_dwordx4 v[168:171], v232, s[2:3]
	global_load_dwordx4 v[172:175], v232, s[40:41]
	s_waitcnt vmcnt(12)
	v_readlane_b32 s48, v20, 42
	v_readlane_b32 s58, v25, 42
	v_readlane_b32 s50, v21, 42
	v_readlane_b32 s60, v26, 42
	v_readlane_b32 s52, v22, 42
	v_readlane_b32 s62, v27, 42
	v_readlane_b32 s54, v23, 42
	v_readlane_b32 s64, v28, 42
	v_readlane_b32 s56, v24, 42
	v_readlane_b32 s66, v29, 42
	v_pk_fma_f32 v[52:53], v[184:185], s[48:49], v[52:53] op_sel_hi:[1,0,1]
	v_pk_fma_f32 v[54:55], v[186:187], s[48:49], v[54:55] op_sel_hi:[1,0,1]
	v_pk_fma_f32 v[56:57], v[188:189], s[58:59], v[56:57] op_sel_hi:[1,0,1]
	v_pk_fma_f32 v[58:59], v[190:191], s[58:59], v[58:59] op_sel_hi:[1,0,1]
	v_pk_fma_f32 v[60:61], v[184:185], s[50:51], v[60:61] op_sel_hi:[1,0,1]
	v_pk_fma_f32 v[62:63], v[186:187], s[50:51], v[62:63] op_sel_hi:[1,0,1]
	v_pk_fma_f32 v[64:65], v[188:189], s[60:61], v[64:65] op_sel_hi:[1,0,1]
	v_pk_fma_f32 v[66:67], v[190:191], s[60:61], v[66:67] op_sel_hi:[1,0,1]
	v_pk_fma_f32 v[68:69], v[184:185], s[52:53], v[68:69] op_sel_hi:[1,0,1]
	v_pk_fma_f32 v[70:71], v[186:187], s[52:53], v[70:71] op_sel_hi:[1,0,1]
	v_pk_fma_f32 v[72:73], v[188:189], s[62:63], v[72:73] op_sel_hi:[1,0,1]
	v_pk_fma_f32 v[74:75], v[190:191], s[62:63], v[74:75] op_sel_hi:[1,0,1]
	v_pk_fma_f32 v[76:77], v[184:185], s[54:55], v[76:77] op_sel_hi:[1,0,1]
	v_pk_fma_f32 v[78:79], v[186:187], s[54:55], v[78:79] op_sel_hi:[1,0,1]
	v_pk_fma_f32 v[80:81], v[188:189], s[64:65], v[80:81] op_sel_hi:[1,0,1]
	v_pk_fma_f32 v[82:83], v[190:191], s[64:65], v[82:83] op_sel_hi:[1,0,1]
	v_pk_fma_f32 v[84:85], v[184:185], s[56:57], v[84:85] op_sel_hi:[1,0,1]
	v_pk_fma_f32 v[86:87], v[186:187], s[56:57], v[86:87] op_sel_hi:[1,0,1]
	v_pk_fma_f32 v[88:89], v[188:189], s[66:67], v[88:89] op_sel_hi:[1,0,1]
	v_pk_fma_f32 v[90:91], v[190:191], s[66:67], v[90:91] op_sel_hi:[1,0,1]
	global_load_dwordx4 v[176:179], v232, s[2:3] offset:1024
	global_load_dwordx4 v[180:183], v232, s[40:41] offset:1024
	s_waitcnt vmcnt(12)
	v_readlane_b32 s48, v20, 43
	v_readlane_b32 s58, v25, 43
	v_readlane_b32 s50, v21, 43
	v_readlane_b32 s60, v26, 43
	v_readlane_b32 s52, v22, 43
	v_readlane_b32 s62, v27, 43
	v_readlane_b32 s54, v23, 43
	v_readlane_b32 s64, v28, 43
	v_readlane_b32 s56, v24, 43
	v_readlane_b32 s66, v29, 43
	v_pk_fma_f32 v[52:53], v[192:193], s[48:49], v[52:53] op_sel_hi:[1,0,1]
	v_pk_fma_f32 v[54:55], v[194:195], s[48:49], v[54:55] op_sel_hi:[1,0,1]
	v_pk_fma_f32 v[56:57], v[196:197], s[58:59], v[56:57] op_sel_hi:[1,0,1]
	v_pk_fma_f32 v[58:59], v[198:199], s[58:59], v[58:59] op_sel_hi:[1,0,1]
	v_pk_fma_f32 v[60:61], v[192:193], s[50:51], v[60:61] op_sel_hi:[1,0,1]
	v_pk_fma_f32 v[62:63], v[194:195], s[50:51], v[62:63] op_sel_hi:[1,0,1]
	v_pk_fma_f32 v[64:65], v[196:197], s[60:61], v[64:65] op_sel_hi:[1,0,1]
	v_pk_fma_f32 v[66:67], v[198:199], s[60:61], v[66:67] op_sel_hi:[1,0,1]
	v_pk_fma_f32 v[68:69], v[192:193], s[52:53], v[68:69] op_sel_hi:[1,0,1]
	v_pk_fma_f32 v[70:71], v[194:195], s[52:53], v[70:71] op_sel_hi:[1,0,1]
	v_pk_fma_f32 v[72:73], v[196:197], s[62:63], v[72:73] op_sel_hi:[1,0,1]
	v_pk_fma_f32 v[74:75], v[198:199], s[62:63], v[74:75] op_sel_hi:[1,0,1]
	v_pk_fma_f32 v[76:77], v[192:193], s[54:55], v[76:77] op_sel_hi:[1,0,1]
	v_pk_fma_f32 v[78:79], v[194:195], s[54:55], v[78:79] op_sel_hi:[1,0,1]
	v_pk_fma_f32 v[80:81], v[196:197], s[64:65], v[80:81] op_sel_hi:[1,0,1]
	v_pk_fma_f32 v[82:83], v[198:199], s[64:65], v[82:83] op_sel_hi:[1,0,1]
	v_pk_fma_f32 v[84:85], v[192:193], s[56:57], v[84:85] op_sel_hi:[1,0,1]
	v_pk_fma_f32 v[86:87], v[194:195], s[56:57], v[86:87] op_sel_hi:[1,0,1]
	v_pk_fma_f32 v[88:89], v[196:197], s[66:67], v[88:89] op_sel_hi:[1,0,1]
	v_pk_fma_f32 v[90:91], v[198:199], s[66:67], v[90:91] op_sel_hi:[1,0,1]
	global_load_dwordx4 v[184:187], v232, s[2:3] offset:2048
	global_load_dwordx4 v[188:191], v232, s[40:41] offset:2048
	s_waitcnt vmcnt(12)
	v_readlane_b32 s48, v20, 44
	v_readlane_b32 s58, v25, 44
	v_readlane_b32 s50, v21, 44
	v_readlane_b32 s60, v26, 44
	v_readlane_b32 s52, v22, 44
	v_readlane_b32 s62, v27, 44
	v_readlane_b32 s54, v23, 44
	v_readlane_b32 s64, v28, 44
	v_readlane_b32 s56, v24, 44
	v_readlane_b32 s66, v29, 44
	v_pk_fma_f32 v[52:53], v[200:201], s[48:49], v[52:53] op_sel_hi:[1,0,1]
	v_pk_fma_f32 v[54:55], v[202:203], s[48:49], v[54:55] op_sel_hi:[1,0,1]
	v_pk_fma_f32 v[56:57], v[204:205], s[58:59], v[56:57] op_sel_hi:[1,0,1]
	v_pk_fma_f32 v[58:59], v[206:207], s[58:59], v[58:59] op_sel_hi:[1,0,1]
	v_pk_fma_f32 v[60:61], v[200:201], s[50:51], v[60:61] op_sel_hi:[1,0,1]
	v_pk_fma_f32 v[62:63], v[202:203], s[50:51], v[62:63] op_sel_hi:[1,0,1]
	v_pk_fma_f32 v[64:65], v[204:205], s[60:61], v[64:65] op_sel_hi:[1,0,1]
	v_pk_fma_f32 v[66:67], v[206:207], s[60:61], v[66:67] op_sel_hi:[1,0,1]
	v_pk_fma_f32 v[68:69], v[200:201], s[52:53], v[68:69] op_sel_hi:[1,0,1]
	v_pk_fma_f32 v[70:71], v[202:203], s[52:53], v[70:71] op_sel_hi:[1,0,1]
	v_pk_fma_f32 v[72:73], v[204:205], s[62:63], v[72:73] op_sel_hi:[1,0,1]
	v_pk_fma_f32 v[74:75], v[206:207], s[62:63], v[74:75] op_sel_hi:[1,0,1]
	v_pk_fma_f32 v[76:77], v[200:201], s[54:55], v[76:77] op_sel_hi:[1,0,1]
	v_pk_fma_f32 v[78:79], v[202:203], s[54:55], v[78:79] op_sel_hi:[1,0,1]
	v_pk_fma_f32 v[80:81], v[204:205], s[64:65], v[80:81] op_sel_hi:[1,0,1]
	v_pk_fma_f32 v[82:83], v[206:207], s[64:65], v[82:83] op_sel_hi:[1,0,1]
	v_pk_fma_f32 v[84:85], v[200:201], s[56:57], v[84:85] op_sel_hi:[1,0,1]
	v_pk_fma_f32 v[86:87], v[202:203], s[56:57], v[86:87] op_sel_hi:[1,0,1]
	v_pk_fma_f32 v[88:89], v[204:205], s[66:67], v[88:89] op_sel_hi:[1,0,1]
	v_pk_fma_f32 v[90:91], v[206:207], s[66:67], v[90:91] op_sel_hi:[1,0,1]
	global_load_dwordx4 v[192:195], v232, s[2:3] offset:3072
	global_load_dwordx4 v[196:199], v232, s[40:41] offset:3072
	s_add_u32 s2, s2, 0x1000
	s_addc_u32 s3, s3, 0
	s_add_u32 s40, s40, 0x1000
	s_addc_u32 s41, s41, 0
	s_waitcnt vmcnt(12)
	v_readlane_b32 s48, v20, 45
	v_readlane_b32 s58, v25, 45
	v_readlane_b32 s50, v21, 45
	v_readlane_b32 s60, v26, 45
	v_readlane_b32 s52, v22, 45
	v_readlane_b32 s62, v27, 45
	v_readlane_b32 s54, v23, 45
	v_readlane_b32 s64, v28, 45
	v_readlane_b32 s56, v24, 45
	v_readlane_b32 s66, v29, 45
	v_pk_fma_f32 v[52:53], v[208:209], s[48:49], v[52:53] op_sel_hi:[1,0,1]
	v_pk_fma_f32 v[54:55], v[210:211], s[48:49], v[54:55] op_sel_hi:[1,0,1]
	v_pk_fma_f32 v[56:57], v[212:213], s[58:59], v[56:57] op_sel_hi:[1,0,1]
	v_pk_fma_f32 v[58:59], v[214:215], s[58:59], v[58:59] op_sel_hi:[1,0,1]
	v_pk_fma_f32 v[60:61], v[208:209], s[50:51], v[60:61] op_sel_hi:[1,0,1]
	v_pk_fma_f32 v[62:63], v[210:211], s[50:51], v[62:63] op_sel_hi:[1,0,1]
	v_pk_fma_f32 v[64:65], v[212:213], s[60:61], v[64:65] op_sel_hi:[1,0,1]
	v_pk_fma_f32 v[66:67], v[214:215], s[60:61], v[66:67] op_sel_hi:[1,0,1]
	v_pk_fma_f32 v[68:69], v[208:209], s[52:53], v[68:69] op_sel_hi:[1,0,1]
	v_pk_fma_f32 v[70:71], v[210:211], s[52:53], v[70:71] op_sel_hi:[1,0,1]
	v_pk_fma_f32 v[72:73], v[212:213], s[62:63], v[72:73] op_sel_hi:[1,0,1]
	v_pk_fma_f32 v[74:75], v[214:215], s[62:63], v[74:75] op_sel_hi:[1,0,1]
	v_pk_fma_f32 v[76:77], v[208:209], s[54:55], v[76:77] op_sel_hi:[1,0,1]
	v_pk_fma_f32 v[78:79], v[210:211], s[54:55], v[78:79] op_sel_hi:[1,0,1]
	v_pk_fma_f32 v[80:81], v[212:213], s[64:65], v[80:81] op_sel_hi:[1,0,1]
	v_pk_fma_f32 v[82:83], v[214:215], s[64:65], v[82:83] op_sel_hi:[1,0,1]
	v_pk_fma_f32 v[84:85], v[208:209], s[56:57], v[84:85] op_sel_hi:[1,0,1]
	v_pk_fma_f32 v[86:87], v[210:211], s[56:57], v[86:87] op_sel_hi:[1,0,1]
	v_pk_fma_f32 v[88:89], v[212:213], s[66:67], v[88:89] op_sel_hi:[1,0,1]
	v_pk_fma_f32 v[90:91], v[214:215], s[66:67], v[90:91] op_sel_hi:[1,0,1]
	global_load_dwordx4 v[200:203], v232, s[2:3]
	global_load_dwordx4 v[204:207], v232, s[40:41]
	s_waitcnt vmcnt(12)
	v_readlane_b32 s48, v20, 46
	v_readlane_b32 s58, v25, 46
	v_readlane_b32 s50, v21, 46
	v_readlane_b32 s60, v26, 46
	v_readlane_b32 s52, v22, 46
	v_readlane_b32 s62, v27, 46
	v_readlane_b32 s54, v23, 46
	v_readlane_b32 s64, v28, 46
	v_readlane_b32 s56, v24, 46
	v_readlane_b32 s66, v29, 46
	v_pk_fma_f32 v[52:53], v[216:217], s[48:49], v[52:53] op_sel_hi:[1,0,1]
	v_pk_fma_f32 v[54:55], v[218:219], s[48:49], v[54:55] op_sel_hi:[1,0,1]
	v_pk_fma_f32 v[56:57], v[220:221], s[58:59], v[56:57] op_sel_hi:[1,0,1]
	v_pk_fma_f32 v[58:59], v[222:223], s[58:59], v[58:59] op_sel_hi:[1,0,1]
	v_pk_fma_f32 v[60:61], v[216:217], s[50:51], v[60:61] op_sel_hi:[1,0,1]
	v_pk_fma_f32 v[62:63], v[218:219], s[50:51], v[62:63] op_sel_hi:[1,0,1]
	v_pk_fma_f32 v[64:65], v[220:221], s[60:61], v[64:65] op_sel_hi:[1,0,1]
	v_pk_fma_f32 v[66:67], v[222:223], s[60:61], v[66:67] op_sel_hi:[1,0,1]
	v_pk_fma_f32 v[68:69], v[216:217], s[52:53], v[68:69] op_sel_hi:[1,0,1]
	v_pk_fma_f32 v[70:71], v[218:219], s[52:53], v[70:71] op_sel_hi:[1,0,1]
	v_pk_fma_f32 v[72:73], v[220:221], s[62:63], v[72:73] op_sel_hi:[1,0,1]
	v_pk_fma_f32 v[74:75], v[222:223], s[62:63], v[74:75] op_sel_hi:[1,0,1]
	v_pk_fma_f32 v[76:77], v[216:217], s[54:55], v[76:77] op_sel_hi:[1,0,1]
	v_pk_fma_f32 v[78:79], v[218:219], s[54:55], v[78:79] op_sel_hi:[1,0,1]
	v_pk_fma_f32 v[80:81], v[220:221], s[64:65], v[80:81] op_sel_hi:[1,0,1]
	v_pk_fma_f32 v[82:83], v[222:223], s[64:65], v[82:83] op_sel_hi:[1,0,1]
	v_pk_fma_f32 v[84:85], v[216:217], s[56:57], v[84:85] op_sel_hi:[1,0,1]
	v_pk_fma_f32 v[86:87], v[218:219], s[56:57], v[86:87] op_sel_hi:[1,0,1]
	v_pk_fma_f32 v[88:89], v[220:221], s[66:67], v[88:89] op_sel_hi:[1,0,1]
	v_pk_fma_f32 v[90:91], v[222:223], s[66:67], v[90:91] op_sel_hi:[1,0,1]
	global_load_dwordx4 v[208:211], v232, s[2:3] offset:1024
	global_load_dwordx4 v[212:215], v232, s[40:41] offset:1024
	s_waitcnt vmcnt(12)
	v_readlane_b32 s48, v20, 47
	v_readlane_b32 s58, v25, 47
	v_readlane_b32 s50, v21, 47
	v_readlane_b32 s60, v26, 47
	v_readlane_b32 s52, v22, 47
	v_readlane_b32 s62, v27, 47
	v_readlane_b32 s54, v23, 47
	v_readlane_b32 s64, v28, 47
	v_readlane_b32 s56, v24, 47
	v_readlane_b32 s66, v29, 47
	v_pk_fma_f32 v[52:53], v[224:225], s[48:49], v[52:53] op_sel_hi:[1,0,1]
	v_pk_fma_f32 v[54:55], v[226:227], s[48:49], v[54:55] op_sel_hi:[1,0,1]
	v_pk_fma_f32 v[56:57], v[228:229], s[58:59], v[56:57] op_sel_hi:[1,0,1]
	v_pk_fma_f32 v[58:59], v[230:231], s[58:59], v[58:59] op_sel_hi:[1,0,1]
	v_pk_fma_f32 v[60:61], v[224:225], s[50:51], v[60:61] op_sel_hi:[1,0,1]
	v_pk_fma_f32 v[62:63], v[226:227], s[50:51], v[62:63] op_sel_hi:[1,0,1]
	v_pk_fma_f32 v[64:65], v[228:229], s[60:61], v[64:65] op_sel_hi:[1,0,1]
	v_pk_fma_f32 v[66:67], v[230:231], s[60:61], v[66:67] op_sel_hi:[1,0,1]
	v_pk_fma_f32 v[68:69], v[224:225], s[52:53], v[68:69] op_sel_hi:[1,0,1]
	v_pk_fma_f32 v[70:71], v[226:227], s[52:53], v[70:71] op_sel_hi:[1,0,1]
	v_pk_fma_f32 v[72:73], v[228:229], s[62:63], v[72:73] op_sel_hi:[1,0,1]
	v_pk_fma_f32 v[74:75], v[230:231], s[62:63], v[74:75] op_sel_hi:[1,0,1]
	v_pk_fma_f32 v[76:77], v[224:225], s[54:55], v[76:77] op_sel_hi:[1,0,1]
	v_pk_fma_f32 v[78:79], v[226:227], s[54:55], v[78:79] op_sel_hi:[1,0,1]
	v_pk_fma_f32 v[80:81], v[228:229], s[64:65], v[80:81] op_sel_hi:[1,0,1]
	v_pk_fma_f32 v[82:83], v[230:231], s[64:65], v[82:83] op_sel_hi:[1,0,1]
	v_pk_fma_f32 v[84:85], v[224:225], s[56:57], v[84:85] op_sel_hi:[1,0,1]
	v_pk_fma_f32 v[86:87], v[226:227], s[56:57], v[86:87] op_sel_hi:[1,0,1]
	v_pk_fma_f32 v[88:89], v[228:229], s[66:67], v[88:89] op_sel_hi:[1,0,1]
	v_pk_fma_f32 v[90:91], v[230:231], s[66:67], v[90:91] op_sel_hi:[1,0,1]
	global_load_dwordx4 v[216:219], v232, s[2:3] offset:2048
	global_load_dwordx4 v[220:223], v232, s[40:41] offset:2048
	s_waitcnt vmcnt(12)
	v_readlane_b32 s48, v20, 48
	v_readlane_b32 s58, v25, 48
	v_readlane_b32 s50, v21, 48
	v_readlane_b32 s60, v26, 48
	v_readlane_b32 s52, v22, 48
	v_readlane_b32 s62, v27, 48
	v_readlane_b32 s54, v23, 48
	v_readlane_b32 s64, v28, 48
	v_readlane_b32 s56, v24, 48
	v_readlane_b32 s66, v29, 48
	v_pk_fma_f32 v[52:53], v[168:169], s[48:49], v[52:53] op_sel_hi:[1,0,1]
	v_pk_fma_f32 v[54:55], v[170:171], s[48:49], v[54:55] op_sel_hi:[1,0,1]
	v_pk_fma_f32 v[56:57], v[172:173], s[58:59], v[56:57] op_sel_hi:[1,0,1]
	v_pk_fma_f32 v[58:59], v[174:175], s[58:59], v[58:59] op_sel_hi:[1,0,1]
	v_pk_fma_f32 v[60:61], v[168:169], s[50:51], v[60:61] op_sel_hi:[1,0,1]
	v_pk_fma_f32 v[62:63], v[170:171], s[50:51], v[62:63] op_sel_hi:[1,0,1]
	v_pk_fma_f32 v[64:65], v[172:173], s[60:61], v[64:65] op_sel_hi:[1,0,1]
	v_pk_fma_f32 v[66:67], v[174:175], s[60:61], v[66:67] op_sel_hi:[1,0,1]
	v_pk_fma_f32 v[68:69], v[168:169], s[52:53], v[68:69] op_sel_hi:[1,0,1]
	v_pk_fma_f32 v[70:71], v[170:171], s[52:53], v[70:71] op_sel_hi:[1,0,1]
	v_pk_fma_f32 v[72:73], v[172:173], s[62:63], v[72:73] op_sel_hi:[1,0,1]
	v_pk_fma_f32 v[74:75], v[174:175], s[62:63], v[74:75] op_sel_hi:[1,0,1]
	v_pk_fma_f32 v[76:77], v[168:169], s[54:55], v[76:77] op_sel_hi:[1,0,1]
	v_pk_fma_f32 v[78:79], v[170:171], s[54:55], v[78:79] op_sel_hi:[1,0,1]
	v_pk_fma_f32 v[80:81], v[172:173], s[64:65], v[80:81] op_sel_hi:[1,0,1]
	v_pk_fma_f32 v[82:83], v[174:175], s[64:65], v[82:83] op_sel_hi:[1,0,1]
	v_pk_fma_f32 v[84:85], v[168:169], s[56:57], v[84:85] op_sel_hi:[1,0,1]
	v_pk_fma_f32 v[86:87], v[170:171], s[56:57], v[86:87] op_sel_hi:[1,0,1]
	v_pk_fma_f32 v[88:89], v[172:173], s[66:67], v[88:89] op_sel_hi:[1,0,1]
	v_pk_fma_f32 v[90:91], v[174:175], s[66:67], v[90:91] op_sel_hi:[1,0,1]
	global_load_dwordx4 v[224:227], v232, s[2:3] offset:3072
	global_load_dwordx4 v[228:231], v232, s[40:41] offset:3072
	s_add_u32 s2, s2, 0x1000
	s_addc_u32 s3, s3, 0
	s_add_u32 s40, s40, 0x1000
	s_addc_u32 s41, s41, 0
	s_waitcnt vmcnt(12)
	v_readlane_b32 s48, v20, 49
	v_readlane_b32 s58, v25, 49
	v_readlane_b32 s50, v21, 49
	v_readlane_b32 s60, v26, 49
	v_readlane_b32 s52, v22, 49
	v_readlane_b32 s62, v27, 49
	v_readlane_b32 s54, v23, 49
	v_readlane_b32 s64, v28, 49
	v_readlane_b32 s56, v24, 49
	v_readlane_b32 s66, v29, 49
	v_pk_fma_f32 v[52:53], v[176:177], s[48:49], v[52:53] op_sel_hi:[1,0,1]
	v_pk_fma_f32 v[54:55], v[178:179], s[48:49], v[54:55] op_sel_hi:[1,0,1]
	v_pk_fma_f32 v[56:57], v[180:181], s[58:59], v[56:57] op_sel_hi:[1,0,1]
	v_pk_fma_f32 v[58:59], v[182:183], s[58:59], v[58:59] op_sel_hi:[1,0,1]
	v_pk_fma_f32 v[60:61], v[176:177], s[50:51], v[60:61] op_sel_hi:[1,0,1]
	v_pk_fma_f32 v[62:63], v[178:179], s[50:51], v[62:63] op_sel_hi:[1,0,1]
	v_pk_fma_f32 v[64:65], v[180:181], s[60:61], v[64:65] op_sel_hi:[1,0,1]
	v_pk_fma_f32 v[66:67], v[182:183], s[60:61], v[66:67] op_sel_hi:[1,0,1]
	v_pk_fma_f32 v[68:69], v[176:177], s[52:53], v[68:69] op_sel_hi:[1,0,1]
	v_pk_fma_f32 v[70:71], v[178:179], s[52:53], v[70:71] op_sel_hi:[1,0,1]
	v_pk_fma_f32 v[72:73], v[180:181], s[62:63], v[72:73] op_sel_hi:[1,0,1]
	v_pk_fma_f32 v[74:75], v[182:183], s[62:63], v[74:75] op_sel_hi:[1,0,1]
	v_pk_fma_f32 v[76:77], v[176:177], s[54:55], v[76:77] op_sel_hi:[1,0,1]
	v_pk_fma_f32 v[78:79], v[178:179], s[54:55], v[78:79] op_sel_hi:[1,0,1]
	v_pk_fma_f32 v[80:81], v[180:181], s[64:65], v[80:81] op_sel_hi:[1,0,1]
	v_pk_fma_f32 v[82:83], v[182:183], s[64:65], v[82:83] op_sel_hi:[1,0,1]
	v_pk_fma_f32 v[84:85], v[176:177], s[56:57], v[84:85] op_sel_hi:[1,0,1]
	v_pk_fma_f32 v[86:87], v[178:179], s[56:57], v[86:87] op_sel_hi:[1,0,1]
	v_pk_fma_f32 v[88:89], v[180:181], s[66:67], v[88:89] op_sel_hi:[1,0,1]
	v_pk_fma_f32 v[90:91], v[182:183], s[66:67], v[90:91] op_sel_hi:[1,0,1]
	global_load_dwordx4 v[168:171], v232, s[2:3]
	global_load_dwordx4 v[172:175], v232, s[40:41]
	s_waitcnt vmcnt(12)
	v_readlane_b32 s48, v20, 50
	v_readlane_b32 s58, v25, 50
	v_readlane_b32 s50, v21, 50
	v_readlane_b32 s60, v26, 50
	v_readlane_b32 s52, v22, 50
	v_readlane_b32 s62, v27, 50
	v_readlane_b32 s54, v23, 50
	v_readlane_b32 s64, v28, 50
	v_readlane_b32 s56, v24, 50
	v_readlane_b32 s66, v29, 50
	v_pk_fma_f32 v[52:53], v[184:185], s[48:49], v[52:53] op_sel_hi:[1,0,1]
	v_pk_fma_f32 v[54:55], v[186:187], s[48:49], v[54:55] op_sel_hi:[1,0,1]
	v_pk_fma_f32 v[56:57], v[188:189], s[58:59], v[56:57] op_sel_hi:[1,0,1]
	v_pk_fma_f32 v[58:59], v[190:191], s[58:59], v[58:59] op_sel_hi:[1,0,1]
	v_pk_fma_f32 v[60:61], v[184:185], s[50:51], v[60:61] op_sel_hi:[1,0,1]
	v_pk_fma_f32 v[62:63], v[186:187], s[50:51], v[62:63] op_sel_hi:[1,0,1]
	v_pk_fma_f32 v[64:65], v[188:189], s[60:61], v[64:65] op_sel_hi:[1,0,1]
	v_pk_fma_f32 v[66:67], v[190:191], s[60:61], v[66:67] op_sel_hi:[1,0,1]
	v_pk_fma_f32 v[68:69], v[184:185], s[52:53], v[68:69] op_sel_hi:[1,0,1]
	v_pk_fma_f32 v[70:71], v[186:187], s[52:53], v[70:71] op_sel_hi:[1,0,1]
	v_pk_fma_f32 v[72:73], v[188:189], s[62:63], v[72:73] op_sel_hi:[1,0,1]
	v_pk_fma_f32 v[74:75], v[190:191], s[62:63], v[74:75] op_sel_hi:[1,0,1]
	v_pk_fma_f32 v[76:77], v[184:185], s[54:55], v[76:77] op_sel_hi:[1,0,1]
	v_pk_fma_f32 v[78:79], v[186:187], s[54:55], v[78:79] op_sel_hi:[1,0,1]
	v_pk_fma_f32 v[80:81], v[188:189], s[64:65], v[80:81] op_sel_hi:[1,0,1]
	v_pk_fma_f32 v[82:83], v[190:191], s[64:65], v[82:83] op_sel_hi:[1,0,1]
	v_pk_fma_f32 v[84:85], v[184:185], s[56:57], v[84:85] op_sel_hi:[1,0,1]
	v_pk_fma_f32 v[86:87], v[186:187], s[56:57], v[86:87] op_sel_hi:[1,0,1]
	v_pk_fma_f32 v[88:89], v[188:189], s[66:67], v[88:89] op_sel_hi:[1,0,1]
	v_pk_fma_f32 v[90:91], v[190:191], s[66:67], v[90:91] op_sel_hi:[1,0,1]
	global_load_dwordx4 v[176:179], v232, s[2:3] offset:1024
	global_load_dwordx4 v[180:183], v232, s[40:41] offset:1024
	s_waitcnt vmcnt(12)
	v_readlane_b32 s48, v20, 51
	v_readlane_b32 s58, v25, 51
	v_readlane_b32 s50, v21, 51
	v_readlane_b32 s60, v26, 51
	v_readlane_b32 s52, v22, 51
	v_readlane_b32 s62, v27, 51
	v_readlane_b32 s54, v23, 51
	v_readlane_b32 s64, v28, 51
	v_readlane_b32 s56, v24, 51
	v_readlane_b32 s66, v29, 51
	v_pk_fma_f32 v[52:53], v[192:193], s[48:49], v[52:53] op_sel_hi:[1,0,1]
	v_pk_fma_f32 v[54:55], v[194:195], s[48:49], v[54:55] op_sel_hi:[1,0,1]
	v_pk_fma_f32 v[56:57], v[196:197], s[58:59], v[56:57] op_sel_hi:[1,0,1]
	v_pk_fma_f32 v[58:59], v[198:199], s[58:59], v[58:59] op_sel_hi:[1,0,1]
	v_pk_fma_f32 v[60:61], v[192:193], s[50:51], v[60:61] op_sel_hi:[1,0,1]
	v_pk_fma_f32 v[62:63], v[194:195], s[50:51], v[62:63] op_sel_hi:[1,0,1]
	v_pk_fma_f32 v[64:65], v[196:197], s[60:61], v[64:65] op_sel_hi:[1,0,1]
	v_pk_fma_f32 v[66:67], v[198:199], s[60:61], v[66:67] op_sel_hi:[1,0,1]
	v_pk_fma_f32 v[68:69], v[192:193], s[52:53], v[68:69] op_sel_hi:[1,0,1]
	v_pk_fma_f32 v[70:71], v[194:195], s[52:53], v[70:71] op_sel_hi:[1,0,1]
	v_pk_fma_f32 v[72:73], v[196:197], s[62:63], v[72:73] op_sel_hi:[1,0,1]
	v_pk_fma_f32 v[74:75], v[198:199], s[62:63], v[74:75] op_sel_hi:[1,0,1]
	v_pk_fma_f32 v[76:77], v[192:193], s[54:55], v[76:77] op_sel_hi:[1,0,1]
	v_pk_fma_f32 v[78:79], v[194:195], s[54:55], v[78:79] op_sel_hi:[1,0,1]
	v_pk_fma_f32 v[80:81], v[196:197], s[64:65], v[80:81] op_sel_hi:[1,0,1]
	v_pk_fma_f32 v[82:83], v[198:199], s[64:65], v[82:83] op_sel_hi:[1,0,1]
	v_pk_fma_f32 v[84:85], v[192:193], s[56:57], v[84:85] op_sel_hi:[1,0,1]
	v_pk_fma_f32 v[86:87], v[194:195], s[56:57], v[86:87] op_sel_hi:[1,0,1]
	v_pk_fma_f32 v[88:89], v[196:197], s[66:67], v[88:89] op_sel_hi:[1,0,1]
	v_pk_fma_f32 v[90:91], v[198:199], s[66:67], v[90:91] op_sel_hi:[1,0,1]
	global_load_dwordx4 v[184:187], v232, s[2:3] offset:2048
	global_load_dwordx4 v[188:191], v232, s[40:41] offset:2048
	s_waitcnt vmcnt(12)
	v_readlane_b32 s48, v20, 52
	v_readlane_b32 s58, v25, 52
	v_readlane_b32 s50, v21, 52
	v_readlane_b32 s60, v26, 52
	v_readlane_b32 s52, v22, 52
	v_readlane_b32 s62, v27, 52
	v_readlane_b32 s54, v23, 52
	v_readlane_b32 s64, v28, 52
	v_readlane_b32 s56, v24, 52
	v_readlane_b32 s66, v29, 52
	v_pk_fma_f32 v[52:53], v[200:201], s[48:49], v[52:53] op_sel_hi:[1,0,1]
	v_pk_fma_f32 v[54:55], v[202:203], s[48:49], v[54:55] op_sel_hi:[1,0,1]
	v_pk_fma_f32 v[56:57], v[204:205], s[58:59], v[56:57] op_sel_hi:[1,0,1]
	v_pk_fma_f32 v[58:59], v[206:207], s[58:59], v[58:59] op_sel_hi:[1,0,1]
	v_pk_fma_f32 v[60:61], v[200:201], s[50:51], v[60:61] op_sel_hi:[1,0,1]
	v_pk_fma_f32 v[62:63], v[202:203], s[50:51], v[62:63] op_sel_hi:[1,0,1]
	v_pk_fma_f32 v[64:65], v[204:205], s[60:61], v[64:65] op_sel_hi:[1,0,1]
	v_pk_fma_f32 v[66:67], v[206:207], s[60:61], v[66:67] op_sel_hi:[1,0,1]
	v_pk_fma_f32 v[68:69], v[200:201], s[52:53], v[68:69] op_sel_hi:[1,0,1]
	v_pk_fma_f32 v[70:71], v[202:203], s[52:53], v[70:71] op_sel_hi:[1,0,1]
	v_pk_fma_f32 v[72:73], v[204:205], s[62:63], v[72:73] op_sel_hi:[1,0,1]
	v_pk_fma_f32 v[74:75], v[206:207], s[62:63], v[74:75] op_sel_hi:[1,0,1]
	v_pk_fma_f32 v[76:77], v[200:201], s[54:55], v[76:77] op_sel_hi:[1,0,1]
	v_pk_fma_f32 v[78:79], v[202:203], s[54:55], v[78:79] op_sel_hi:[1,0,1]
	v_pk_fma_f32 v[80:81], v[204:205], s[64:65], v[80:81] op_sel_hi:[1,0,1]
	v_pk_fma_f32 v[82:83], v[206:207], s[64:65], v[82:83] op_sel_hi:[1,0,1]
	v_pk_fma_f32 v[84:85], v[200:201], s[56:57], v[84:85] op_sel_hi:[1,0,1]
	v_pk_fma_f32 v[86:87], v[202:203], s[56:57], v[86:87] op_sel_hi:[1,0,1]
	v_pk_fma_f32 v[88:89], v[204:205], s[66:67], v[88:89] op_sel_hi:[1,0,1]
	v_pk_fma_f32 v[90:91], v[206:207], s[66:67], v[90:91] op_sel_hi:[1,0,1]
	global_load_dwordx4 v[192:195], v232, s[2:3] offset:3072
	global_load_dwordx4 v[196:199], v232, s[40:41] offset:3072
	s_add_u32 s2, s2, 0x1000
	s_addc_u32 s3, s3, 0
	s_add_u32 s40, s40, 0x1000
	s_addc_u32 s41, s41, 0
	s_waitcnt vmcnt(12)
	v_readlane_b32 s48, v20, 53
	v_readlane_b32 s58, v25, 53
	v_readlane_b32 s50, v21, 53
	v_readlane_b32 s60, v26, 53
	v_readlane_b32 s52, v22, 53
	v_readlane_b32 s62, v27, 53
	v_readlane_b32 s54, v23, 53
	v_readlane_b32 s64, v28, 53
	v_readlane_b32 s56, v24, 53
	v_readlane_b32 s66, v29, 53
	v_pk_fma_f32 v[52:53], v[208:209], s[48:49], v[52:53] op_sel_hi:[1,0,1]
	v_pk_fma_f32 v[54:55], v[210:211], s[48:49], v[54:55] op_sel_hi:[1,0,1]
	v_pk_fma_f32 v[56:57], v[212:213], s[58:59], v[56:57] op_sel_hi:[1,0,1]
	v_pk_fma_f32 v[58:59], v[214:215], s[58:59], v[58:59] op_sel_hi:[1,0,1]
	v_pk_fma_f32 v[60:61], v[208:209], s[50:51], v[60:61] op_sel_hi:[1,0,1]
	v_pk_fma_f32 v[62:63], v[210:211], s[50:51], v[62:63] op_sel_hi:[1,0,1]
	v_pk_fma_f32 v[64:65], v[212:213], s[60:61], v[64:65] op_sel_hi:[1,0,1]
	v_pk_fma_f32 v[66:67], v[214:215], s[60:61], v[66:67] op_sel_hi:[1,0,1]
	v_pk_fma_f32 v[68:69], v[208:209], s[52:53], v[68:69] op_sel_hi:[1,0,1]
	v_pk_fma_f32 v[70:71], v[210:211], s[52:53], v[70:71] op_sel_hi:[1,0,1]
	v_pk_fma_f32 v[72:73], v[212:213], s[62:63], v[72:73] op_sel_hi:[1,0,1]
	v_pk_fma_f32 v[74:75], v[214:215], s[62:63], v[74:75] op_sel_hi:[1,0,1]
	v_pk_fma_f32 v[76:77], v[208:209], s[54:55], v[76:77] op_sel_hi:[1,0,1]
	v_pk_fma_f32 v[78:79], v[210:211], s[54:55], v[78:79] op_sel_hi:[1,0,1]
	v_pk_fma_f32 v[80:81], v[212:213], s[64:65], v[80:81] op_sel_hi:[1,0,1]
	v_pk_fma_f32 v[82:83], v[214:215], s[64:65], v[82:83] op_sel_hi:[1,0,1]
	v_pk_fma_f32 v[84:85], v[208:209], s[56:57], v[84:85] op_sel_hi:[1,0,1]
	v_pk_fma_f32 v[86:87], v[210:211], s[56:57], v[86:87] op_sel_hi:[1,0,1]
	v_pk_fma_f32 v[88:89], v[212:213], s[66:67], v[88:89] op_sel_hi:[1,0,1]
	v_pk_fma_f32 v[90:91], v[214:215], s[66:67], v[90:91] op_sel_hi:[1,0,1]
	global_load_dwordx4 v[200:203], v232, s[2:3]
	global_load_dwordx4 v[204:207], v232, s[40:41]
	s_waitcnt vmcnt(12)
	v_readlane_b32 s48, v20, 54
	v_readlane_b32 s58, v25, 54
	v_readlane_b32 s50, v21, 54
	v_readlane_b32 s60, v26, 54
	v_readlane_b32 s52, v22, 54
	v_readlane_b32 s62, v27, 54
	v_readlane_b32 s54, v23, 54
	v_readlane_b32 s64, v28, 54
	v_readlane_b32 s56, v24, 54
	v_readlane_b32 s66, v29, 54
	v_pk_fma_f32 v[52:53], v[216:217], s[48:49], v[52:53] op_sel_hi:[1,0,1]
	v_pk_fma_f32 v[54:55], v[218:219], s[48:49], v[54:55] op_sel_hi:[1,0,1]
	v_pk_fma_f32 v[56:57], v[220:221], s[58:59], v[56:57] op_sel_hi:[1,0,1]
	v_pk_fma_f32 v[58:59], v[222:223], s[58:59], v[58:59] op_sel_hi:[1,0,1]
	v_pk_fma_f32 v[60:61], v[216:217], s[50:51], v[60:61] op_sel_hi:[1,0,1]
	v_pk_fma_f32 v[62:63], v[218:219], s[50:51], v[62:63] op_sel_hi:[1,0,1]
	v_pk_fma_f32 v[64:65], v[220:221], s[60:61], v[64:65] op_sel_hi:[1,0,1]
	v_pk_fma_f32 v[66:67], v[222:223], s[60:61], v[66:67] op_sel_hi:[1,0,1]
	v_pk_fma_f32 v[68:69], v[216:217], s[52:53], v[68:69] op_sel_hi:[1,0,1]
	v_pk_fma_f32 v[70:71], v[218:219], s[52:53], v[70:71] op_sel_hi:[1,0,1]
	v_pk_fma_f32 v[72:73], v[220:221], s[62:63], v[72:73] op_sel_hi:[1,0,1]
	v_pk_fma_f32 v[74:75], v[222:223], s[62:63], v[74:75] op_sel_hi:[1,0,1]
	v_pk_fma_f32 v[76:77], v[216:217], s[54:55], v[76:77] op_sel_hi:[1,0,1]
	v_pk_fma_f32 v[78:79], v[218:219], s[54:55], v[78:79] op_sel_hi:[1,0,1]
	v_pk_fma_f32 v[80:81], v[220:221], s[64:65], v[80:81] op_sel_hi:[1,0,1]
	v_pk_fma_f32 v[82:83], v[222:223], s[64:65], v[82:83] op_sel_hi:[1,0,1]
	v_pk_fma_f32 v[84:85], v[216:217], s[56:57], v[84:85] op_sel_hi:[1,0,1]
	v_pk_fma_f32 v[86:87], v[218:219], s[56:57], v[86:87] op_sel_hi:[1,0,1]
	v_pk_fma_f32 v[88:89], v[220:221], s[66:67], v[88:89] op_sel_hi:[1,0,1]
	v_pk_fma_f32 v[90:91], v[222:223], s[66:67], v[90:91] op_sel_hi:[1,0,1]
	global_load_dwordx4 v[208:211], v232, s[2:3] offset:1024
	global_load_dwordx4 v[212:215], v232, s[40:41] offset:1024
	s_waitcnt vmcnt(12)
	v_readlane_b32 s48, v20, 55
	v_readlane_b32 s58, v25, 55
	v_readlane_b32 s50, v21, 55
	v_readlane_b32 s60, v26, 55
	v_readlane_b32 s52, v22, 55
	v_readlane_b32 s62, v27, 55
	v_readlane_b32 s54, v23, 55
	v_readlane_b32 s64, v28, 55
	v_readlane_b32 s56, v24, 55
	v_readlane_b32 s66, v29, 55
	v_pk_fma_f32 v[52:53], v[224:225], s[48:49], v[52:53] op_sel_hi:[1,0,1]
	v_pk_fma_f32 v[54:55], v[226:227], s[48:49], v[54:55] op_sel_hi:[1,0,1]
	v_pk_fma_f32 v[56:57], v[228:229], s[58:59], v[56:57] op_sel_hi:[1,0,1]
	v_pk_fma_f32 v[58:59], v[230:231], s[58:59], v[58:59] op_sel_hi:[1,0,1]
	v_pk_fma_f32 v[60:61], v[224:225], s[50:51], v[60:61] op_sel_hi:[1,0,1]
	v_pk_fma_f32 v[62:63], v[226:227], s[50:51], v[62:63] op_sel_hi:[1,0,1]
	v_pk_fma_f32 v[64:65], v[228:229], s[60:61], v[64:65] op_sel_hi:[1,0,1]
	v_pk_fma_f32 v[66:67], v[230:231], s[60:61], v[66:67] op_sel_hi:[1,0,1]
	v_pk_fma_f32 v[68:69], v[224:225], s[52:53], v[68:69] op_sel_hi:[1,0,1]
	v_pk_fma_f32 v[70:71], v[226:227], s[52:53], v[70:71] op_sel_hi:[1,0,1]
	v_pk_fma_f32 v[72:73], v[228:229], s[62:63], v[72:73] op_sel_hi:[1,0,1]
	v_pk_fma_f32 v[74:75], v[230:231], s[62:63], v[74:75] op_sel_hi:[1,0,1]
	v_pk_fma_f32 v[76:77], v[224:225], s[54:55], v[76:77] op_sel_hi:[1,0,1]
	v_pk_fma_f32 v[78:79], v[226:227], s[54:55], v[78:79] op_sel_hi:[1,0,1]
	v_pk_fma_f32 v[80:81], v[228:229], s[64:65], v[80:81] op_sel_hi:[1,0,1]
	v_pk_fma_f32 v[82:83], v[230:231], s[64:65], v[82:83] op_sel_hi:[1,0,1]
	v_pk_fma_f32 v[84:85], v[224:225], s[56:57], v[84:85] op_sel_hi:[1,0,1]
	v_pk_fma_f32 v[86:87], v[226:227], s[56:57], v[86:87] op_sel_hi:[1,0,1]
	v_pk_fma_f32 v[88:89], v[228:229], s[66:67], v[88:89] op_sel_hi:[1,0,1]
	v_pk_fma_f32 v[90:91], v[230:231], s[66:67], v[90:91] op_sel_hi:[1,0,1]
	global_load_dwordx4 v[216:219], v232, s[2:3] offset:2048
	global_load_dwordx4 v[220:223], v232, s[40:41] offset:2048
	s_waitcnt vmcnt(12)
	v_readlane_b32 s48, v20, 56
	v_readlane_b32 s58, v25, 56
	v_readlane_b32 s50, v21, 56
	v_readlane_b32 s60, v26, 56
	v_readlane_b32 s52, v22, 56
	v_readlane_b32 s62, v27, 56
	v_readlane_b32 s54, v23, 56
	v_readlane_b32 s64, v28, 56
	v_readlane_b32 s56, v24, 56
	v_readlane_b32 s66, v29, 56
	v_pk_fma_f32 v[52:53], v[168:169], s[48:49], v[52:53] op_sel_hi:[1,0,1]
	v_pk_fma_f32 v[54:55], v[170:171], s[48:49], v[54:55] op_sel_hi:[1,0,1]
	v_pk_fma_f32 v[56:57], v[172:173], s[58:59], v[56:57] op_sel_hi:[1,0,1]
	v_pk_fma_f32 v[58:59], v[174:175], s[58:59], v[58:59] op_sel_hi:[1,0,1]
	v_pk_fma_f32 v[60:61], v[168:169], s[50:51], v[60:61] op_sel_hi:[1,0,1]
	v_pk_fma_f32 v[62:63], v[170:171], s[50:51], v[62:63] op_sel_hi:[1,0,1]
	v_pk_fma_f32 v[64:65], v[172:173], s[60:61], v[64:65] op_sel_hi:[1,0,1]
	v_pk_fma_f32 v[66:67], v[174:175], s[60:61], v[66:67] op_sel_hi:[1,0,1]
	v_pk_fma_f32 v[68:69], v[168:169], s[52:53], v[68:69] op_sel_hi:[1,0,1]
	v_pk_fma_f32 v[70:71], v[170:171], s[52:53], v[70:71] op_sel_hi:[1,0,1]
	v_pk_fma_f32 v[72:73], v[172:173], s[62:63], v[72:73] op_sel_hi:[1,0,1]
	v_pk_fma_f32 v[74:75], v[174:175], s[62:63], v[74:75] op_sel_hi:[1,0,1]
	v_pk_fma_f32 v[76:77], v[168:169], s[54:55], v[76:77] op_sel_hi:[1,0,1]
	v_pk_fma_f32 v[78:79], v[170:171], s[54:55], v[78:79] op_sel_hi:[1,0,1]
	v_pk_fma_f32 v[80:81], v[172:173], s[64:65], v[80:81] op_sel_hi:[1,0,1]
	v_pk_fma_f32 v[82:83], v[174:175], s[64:65], v[82:83] op_sel_hi:[1,0,1]
	v_pk_fma_f32 v[84:85], v[168:169], s[56:57], v[84:85] op_sel_hi:[1,0,1]
	v_pk_fma_f32 v[86:87], v[170:171], s[56:57], v[86:87] op_sel_hi:[1,0,1]
	v_pk_fma_f32 v[88:89], v[172:173], s[66:67], v[88:89] op_sel_hi:[1,0,1]
	v_pk_fma_f32 v[90:91], v[174:175], s[66:67], v[90:91] op_sel_hi:[1,0,1]
	global_load_dwordx4 v[224:227], v232, s[2:3] offset:3072
	global_load_dwordx4 v[228:231], v232, s[40:41] offset:3072
	s_add_u32 s2, s2, 0x1000
	s_addc_u32 s3, s3, 0
	s_add_u32 s40, s40, 0x1000
	s_addc_u32 s41, s41, 0
	s_waitcnt vmcnt(12)
	v_readlane_b32 s48, v20, 57
	v_readlane_b32 s58, v25, 57
	v_readlane_b32 s50, v21, 57
	v_readlane_b32 s60, v26, 57
	v_readlane_b32 s52, v22, 57
	v_readlane_b32 s62, v27, 57
	v_readlane_b32 s54, v23, 57
	v_readlane_b32 s64, v28, 57
	v_readlane_b32 s56, v24, 57
	v_readlane_b32 s66, v29, 57
	v_pk_fma_f32 v[52:53], v[176:177], s[48:49], v[52:53] op_sel_hi:[1,0,1]
	v_pk_fma_f32 v[54:55], v[178:179], s[48:49], v[54:55] op_sel_hi:[1,0,1]
	v_pk_fma_f32 v[56:57], v[180:181], s[58:59], v[56:57] op_sel_hi:[1,0,1]
	v_pk_fma_f32 v[58:59], v[182:183], s[58:59], v[58:59] op_sel_hi:[1,0,1]
	v_pk_fma_f32 v[60:61], v[176:177], s[50:51], v[60:61] op_sel_hi:[1,0,1]
	v_pk_fma_f32 v[62:63], v[178:179], s[50:51], v[62:63] op_sel_hi:[1,0,1]
	v_pk_fma_f32 v[64:65], v[180:181], s[60:61], v[64:65] op_sel_hi:[1,0,1]
	v_pk_fma_f32 v[66:67], v[182:183], s[60:61], v[66:67] op_sel_hi:[1,0,1]
	v_pk_fma_f32 v[68:69], v[176:177], s[52:53], v[68:69] op_sel_hi:[1,0,1]
	v_pk_fma_f32 v[70:71], v[178:179], s[52:53], v[70:71] op_sel_hi:[1,0,1]
	v_pk_fma_f32 v[72:73], v[180:181], s[62:63], v[72:73] op_sel_hi:[1,0,1]
	v_pk_fma_f32 v[74:75], v[182:183], s[62:63], v[74:75] op_sel_hi:[1,0,1]
	v_pk_fma_f32 v[76:77], v[176:177], s[54:55], v[76:77] op_sel_hi:[1,0,1]
	v_pk_fma_f32 v[78:79], v[178:179], s[54:55], v[78:79] op_sel_hi:[1,0,1]
	v_pk_fma_f32 v[80:81], v[180:181], s[64:65], v[80:81] op_sel_hi:[1,0,1]
	v_pk_fma_f32 v[82:83], v[182:183], s[64:65], v[82:83] op_sel_hi:[1,0,1]
	v_pk_fma_f32 v[84:85], v[176:177], s[56:57], v[84:85] op_sel_hi:[1,0,1]
	v_pk_fma_f32 v[86:87], v[178:179], s[56:57], v[86:87] op_sel_hi:[1,0,1]
	v_pk_fma_f32 v[88:89], v[180:181], s[66:67], v[88:89] op_sel_hi:[1,0,1]
	v_pk_fma_f32 v[90:91], v[182:183], s[66:67], v[90:91] op_sel_hi:[1,0,1]
	s_waitcnt vmcnt(10)
	v_readlane_b32 s48, v20, 58
	v_readlane_b32 s58, v25, 58
	v_readlane_b32 s50, v21, 58
	v_readlane_b32 s60, v26, 58
	v_readlane_b32 s52, v22, 58
	v_readlane_b32 s62, v27, 58
	v_readlane_b32 s54, v23, 58
	v_readlane_b32 s64, v28, 58
	v_readlane_b32 s56, v24, 58
	v_readlane_b32 s66, v29, 58
	v_pk_fma_f32 v[52:53], v[184:185], s[48:49], v[52:53] op_sel_hi:[1,0,1]
	v_pk_fma_f32 v[54:55], v[186:187], s[48:49], v[54:55] op_sel_hi:[1,0,1]
	v_pk_fma_f32 v[56:57], v[188:189], s[58:59], v[56:57] op_sel_hi:[1,0,1]
	v_pk_fma_f32 v[58:59], v[190:191], s[58:59], v[58:59] op_sel_hi:[1,0,1]
	v_pk_fma_f32 v[60:61], v[184:185], s[50:51], v[60:61] op_sel_hi:[1,0,1]
	v_pk_fma_f32 v[62:63], v[186:187], s[50:51], v[62:63] op_sel_hi:[1,0,1]
	v_pk_fma_f32 v[64:65], v[188:189], s[60:61], v[64:65] op_sel_hi:[1,0,1]
	v_pk_fma_f32 v[66:67], v[190:191], s[60:61], v[66:67] op_sel_hi:[1,0,1]
	v_pk_fma_f32 v[68:69], v[184:185], s[52:53], v[68:69] op_sel_hi:[1,0,1]
	v_pk_fma_f32 v[70:71], v[186:187], s[52:53], v[70:71] op_sel_hi:[1,0,1]
	v_pk_fma_f32 v[72:73], v[188:189], s[62:63], v[72:73] op_sel_hi:[1,0,1]
	v_pk_fma_f32 v[74:75], v[190:191], s[62:63], v[74:75] op_sel_hi:[1,0,1]
	v_pk_fma_f32 v[76:77], v[184:185], s[54:55], v[76:77] op_sel_hi:[1,0,1]
	v_pk_fma_f32 v[78:79], v[186:187], s[54:55], v[78:79] op_sel_hi:[1,0,1]
	v_pk_fma_f32 v[80:81], v[188:189], s[64:65], v[80:81] op_sel_hi:[1,0,1]
	v_pk_fma_f32 v[82:83], v[190:191], s[64:65], v[82:83] op_sel_hi:[1,0,1]
	v_pk_fma_f32 v[84:85], v[184:185], s[56:57], v[84:85] op_sel_hi:[1,0,1]
	v_pk_fma_f32 v[86:87], v[186:187], s[56:57], v[86:87] op_sel_hi:[1,0,1]
	v_pk_fma_f32 v[88:89], v[188:189], s[66:67], v[88:89] op_sel_hi:[1,0,1]
	v_pk_fma_f32 v[90:91], v[190:191], s[66:67], v[90:91] op_sel_hi:[1,0,1]
	s_waitcnt vmcnt(8)
	v_readlane_b32 s48, v20, 59
	v_readlane_b32 s58, v25, 59
	v_readlane_b32 s50, v21, 59
	v_readlane_b32 s60, v26, 59
	v_readlane_b32 s52, v22, 59
	v_readlane_b32 s62, v27, 59
	v_readlane_b32 s54, v23, 59
	v_readlane_b32 s64, v28, 59
	v_readlane_b32 s56, v24, 59
	v_readlane_b32 s66, v29, 59
	v_pk_fma_f32 v[52:53], v[192:193], s[48:49], v[52:53] op_sel_hi:[1,0,1]
	v_pk_fma_f32 v[54:55], v[194:195], s[48:49], v[54:55] op_sel_hi:[1,0,1]
	v_pk_fma_f32 v[56:57], v[196:197], s[58:59], v[56:57] op_sel_hi:[1,0,1]
	v_pk_fma_f32 v[58:59], v[198:199], s[58:59], v[58:59] op_sel_hi:[1,0,1]
	v_pk_fma_f32 v[60:61], v[192:193], s[50:51], v[60:61] op_sel_hi:[1,0,1]
	v_pk_fma_f32 v[62:63], v[194:195], s[50:51], v[62:63] op_sel_hi:[1,0,1]
	v_pk_fma_f32 v[64:65], v[196:197], s[60:61], v[64:65] op_sel_hi:[1,0,1]
	v_pk_fma_f32 v[66:67], v[198:199], s[60:61], v[66:67] op_sel_hi:[1,0,1]
	v_pk_fma_f32 v[68:69], v[192:193], s[52:53], v[68:69] op_sel_hi:[1,0,1]
	v_pk_fma_f32 v[70:71], v[194:195], s[52:53], v[70:71] op_sel_hi:[1,0,1]
	v_pk_fma_f32 v[72:73], v[196:197], s[62:63], v[72:73] op_sel_hi:[1,0,1]
	v_pk_fma_f32 v[74:75], v[198:199], s[62:63], v[74:75] op_sel_hi:[1,0,1]
	v_pk_fma_f32 v[76:77], v[192:193], s[54:55], v[76:77] op_sel_hi:[1,0,1]
	v_pk_fma_f32 v[78:79], v[194:195], s[54:55], v[78:79] op_sel_hi:[1,0,1]
	v_pk_fma_f32 v[80:81], v[196:197], s[64:65], v[80:81] op_sel_hi:[1,0,1]
	v_pk_fma_f32 v[82:83], v[198:199], s[64:65], v[82:83] op_sel_hi:[1,0,1]
	v_pk_fma_f32 v[84:85], v[192:193], s[56:57], v[84:85] op_sel_hi:[1,0,1]
	v_pk_fma_f32 v[86:87], v[194:195], s[56:57], v[86:87] op_sel_hi:[1,0,1]
	v_pk_fma_f32 v[88:89], v[196:197], s[66:67], v[88:89] op_sel_hi:[1,0,1]
	v_pk_fma_f32 v[90:91], v[198:199], s[66:67], v[90:91] op_sel_hi:[1,0,1]
	s_waitcnt vmcnt(6)
	v_readlane_b32 s48, v20, 60
	v_readlane_b32 s58, v25, 60
	v_readlane_b32 s50, v21, 60
	v_readlane_b32 s60, v26, 60
	v_readlane_b32 s52, v22, 60
	v_readlane_b32 s62, v27, 60
	v_readlane_b32 s54, v23, 60
	v_readlane_b32 s64, v28, 60
	v_readlane_b32 s56, v24, 60
	v_readlane_b32 s66, v29, 60
	v_pk_fma_f32 v[52:53], v[200:201], s[48:49], v[52:53] op_sel_hi:[1,0,1]
	v_pk_fma_f32 v[54:55], v[202:203], s[48:49], v[54:55] op_sel_hi:[1,0,1]
	v_pk_fma_f32 v[56:57], v[204:205], s[58:59], v[56:57] op_sel_hi:[1,0,1]
	v_pk_fma_f32 v[58:59], v[206:207], s[58:59], v[58:59] op_sel_hi:[1,0,1]
	v_pk_fma_f32 v[60:61], v[200:201], s[50:51], v[60:61] op_sel_hi:[1,0,1]
	v_pk_fma_f32 v[62:63], v[202:203], s[50:51], v[62:63] op_sel_hi:[1,0,1]
	v_pk_fma_f32 v[64:65], v[204:205], s[60:61], v[64:65] op_sel_hi:[1,0,1]
	v_pk_fma_f32 v[66:67], v[206:207], s[60:61], v[66:67] op_sel_hi:[1,0,1]
	v_pk_fma_f32 v[68:69], v[200:201], s[52:53], v[68:69] op_sel_hi:[1,0,1]
	v_pk_fma_f32 v[70:71], v[202:203], s[52:53], v[70:71] op_sel_hi:[1,0,1]
	v_pk_fma_f32 v[72:73], v[204:205], s[62:63], v[72:73] op_sel_hi:[1,0,1]
	v_pk_fma_f32 v[74:75], v[206:207], s[62:63], v[74:75] op_sel_hi:[1,0,1]
	v_pk_fma_f32 v[76:77], v[200:201], s[54:55], v[76:77] op_sel_hi:[1,0,1]
	v_pk_fma_f32 v[78:79], v[202:203], s[54:55], v[78:79] op_sel_hi:[1,0,1]
	v_pk_fma_f32 v[80:81], v[204:205], s[64:65], v[80:81] op_sel_hi:[1,0,1]
	v_pk_fma_f32 v[82:83], v[206:207], s[64:65], v[82:83] op_sel_hi:[1,0,1]
	v_pk_fma_f32 v[84:85], v[200:201], s[56:57], v[84:85] op_sel_hi:[1,0,1]
	v_pk_fma_f32 v[86:87], v[202:203], s[56:57], v[86:87] op_sel_hi:[1,0,1]
	v_pk_fma_f32 v[88:89], v[204:205], s[66:67], v[88:89] op_sel_hi:[1,0,1]
	v_pk_fma_f32 v[90:91], v[206:207], s[66:67], v[90:91] op_sel_hi:[1,0,1]
	s_waitcnt vmcnt(4)
	v_readlane_b32 s48, v20, 61
	v_readlane_b32 s58, v25, 61
	v_readlane_b32 s50, v21, 61
	v_readlane_b32 s60, v26, 61
	v_readlane_b32 s52, v22, 61
	v_readlane_b32 s62, v27, 61
	v_readlane_b32 s54, v23, 61
	v_readlane_b32 s64, v28, 61
	v_readlane_b32 s56, v24, 61
	v_readlane_b32 s66, v29, 61
	v_pk_fma_f32 v[52:53], v[208:209], s[48:49], v[52:53] op_sel_hi:[1,0,1]
	v_pk_fma_f32 v[54:55], v[210:211], s[48:49], v[54:55] op_sel_hi:[1,0,1]
	v_pk_fma_f32 v[56:57], v[212:213], s[58:59], v[56:57] op_sel_hi:[1,0,1]
	v_pk_fma_f32 v[58:59], v[214:215], s[58:59], v[58:59] op_sel_hi:[1,0,1]
	v_pk_fma_f32 v[60:61], v[208:209], s[50:51], v[60:61] op_sel_hi:[1,0,1]
	v_pk_fma_f32 v[62:63], v[210:211], s[50:51], v[62:63] op_sel_hi:[1,0,1]
	v_pk_fma_f32 v[64:65], v[212:213], s[60:61], v[64:65] op_sel_hi:[1,0,1]
	v_pk_fma_f32 v[66:67], v[214:215], s[60:61], v[66:67] op_sel_hi:[1,0,1]
	v_pk_fma_f32 v[68:69], v[208:209], s[52:53], v[68:69] op_sel_hi:[1,0,1]
	v_pk_fma_f32 v[70:71], v[210:211], s[52:53], v[70:71] op_sel_hi:[1,0,1]
	v_pk_fma_f32 v[72:73], v[212:213], s[62:63], v[72:73] op_sel_hi:[1,0,1]
	v_pk_fma_f32 v[74:75], v[214:215], s[62:63], v[74:75] op_sel_hi:[1,0,1]
	v_pk_fma_f32 v[76:77], v[208:209], s[54:55], v[76:77] op_sel_hi:[1,0,1]
	v_pk_fma_f32 v[78:79], v[210:211], s[54:55], v[78:79] op_sel_hi:[1,0,1]
	v_pk_fma_f32 v[80:81], v[212:213], s[64:65], v[80:81] op_sel_hi:[1,0,1]
	v_pk_fma_f32 v[82:83], v[214:215], s[64:65], v[82:83] op_sel_hi:[1,0,1]
	v_pk_fma_f32 v[84:85], v[208:209], s[56:57], v[84:85] op_sel_hi:[1,0,1]
	v_pk_fma_f32 v[86:87], v[210:211], s[56:57], v[86:87] op_sel_hi:[1,0,1]
	v_pk_fma_f32 v[88:89], v[212:213], s[66:67], v[88:89] op_sel_hi:[1,0,1]
	v_pk_fma_f32 v[90:91], v[214:215], s[66:67], v[90:91] op_sel_hi:[1,0,1]
	s_waitcnt vmcnt(2)
	v_readlane_b32 s48, v20, 62
	v_readlane_b32 s58, v25, 62
	v_readlane_b32 s50, v21, 62
	v_readlane_b32 s60, v26, 62
	v_readlane_b32 s52, v22, 62
	v_readlane_b32 s62, v27, 62
	v_readlane_b32 s54, v23, 62
	v_readlane_b32 s64, v28, 62
	v_readlane_b32 s56, v24, 62
	v_readlane_b32 s66, v29, 62
	v_pk_fma_f32 v[52:53], v[216:217], s[48:49], v[52:53] op_sel_hi:[1,0,1]
	v_pk_fma_f32 v[54:55], v[218:219], s[48:49], v[54:55] op_sel_hi:[1,0,1]
	v_pk_fma_f32 v[56:57], v[220:221], s[58:59], v[56:57] op_sel_hi:[1,0,1]
	v_pk_fma_f32 v[58:59], v[222:223], s[58:59], v[58:59] op_sel_hi:[1,0,1]
	v_pk_fma_f32 v[60:61], v[216:217], s[50:51], v[60:61] op_sel_hi:[1,0,1]
	v_pk_fma_f32 v[62:63], v[218:219], s[50:51], v[62:63] op_sel_hi:[1,0,1]
	v_pk_fma_f32 v[64:65], v[220:221], s[60:61], v[64:65] op_sel_hi:[1,0,1]
	v_pk_fma_f32 v[66:67], v[222:223], s[60:61], v[66:67] op_sel_hi:[1,0,1]
	v_pk_fma_f32 v[68:69], v[216:217], s[52:53], v[68:69] op_sel_hi:[1,0,1]
	v_pk_fma_f32 v[70:71], v[218:219], s[52:53], v[70:71] op_sel_hi:[1,0,1]
	v_pk_fma_f32 v[72:73], v[220:221], s[62:63], v[72:73] op_sel_hi:[1,0,1]
	v_pk_fma_f32 v[74:75], v[222:223], s[62:63], v[74:75] op_sel_hi:[1,0,1]
	v_pk_fma_f32 v[76:77], v[216:217], s[54:55], v[76:77] op_sel_hi:[1,0,1]
	v_pk_fma_f32 v[78:79], v[218:219], s[54:55], v[78:79] op_sel_hi:[1,0,1]
	v_pk_fma_f32 v[80:81], v[220:221], s[64:65], v[80:81] op_sel_hi:[1,0,1]
	v_pk_fma_f32 v[82:83], v[222:223], s[64:65], v[82:83] op_sel_hi:[1,0,1]
	v_pk_fma_f32 v[84:85], v[216:217], s[56:57], v[84:85] op_sel_hi:[1,0,1]
	v_pk_fma_f32 v[86:87], v[218:219], s[56:57], v[86:87] op_sel_hi:[1,0,1]
	v_pk_fma_f32 v[88:89], v[220:221], s[66:67], v[88:89] op_sel_hi:[1,0,1]
	v_pk_fma_f32 v[90:91], v[222:223], s[66:67], v[90:91] op_sel_hi:[1,0,1]
	s_waitcnt vmcnt(0)
	v_readlane_b32 s48, v20, 63
	v_readlane_b32 s58, v25, 63
	v_readlane_b32 s50, v21, 63
	v_readlane_b32 s60, v26, 63
	v_readlane_b32 s52, v22, 63
	v_readlane_b32 s62, v27, 63
	v_readlane_b32 s54, v23, 63
	v_readlane_b32 s64, v28, 63
	v_readlane_b32 s56, v24, 63
	v_readlane_b32 s66, v29, 63
	v_pk_fma_f32 v[52:53], v[224:225], s[48:49], v[52:53] op_sel_hi:[1,0,1]
	v_pk_fma_f32 v[54:55], v[226:227], s[48:49], v[54:55] op_sel_hi:[1,0,1]
	v_pk_fma_f32 v[56:57], v[228:229], s[58:59], v[56:57] op_sel_hi:[1,0,1]
	v_pk_fma_f32 v[58:59], v[230:231], s[58:59], v[58:59] op_sel_hi:[1,0,1]
	v_pk_fma_f32 v[60:61], v[224:225], s[50:51], v[60:61] op_sel_hi:[1,0,1]
	v_pk_fma_f32 v[62:63], v[226:227], s[50:51], v[62:63] op_sel_hi:[1,0,1]
	v_pk_fma_f32 v[64:65], v[228:229], s[60:61], v[64:65] op_sel_hi:[1,0,1]
	v_pk_fma_f32 v[66:67], v[230:231], s[60:61], v[66:67] op_sel_hi:[1,0,1]
	v_pk_fma_f32 v[68:69], v[224:225], s[52:53], v[68:69] op_sel_hi:[1,0,1]
	v_pk_fma_f32 v[70:71], v[226:227], s[52:53], v[70:71] op_sel_hi:[1,0,1]
	v_pk_fma_f32 v[72:73], v[228:229], s[62:63], v[72:73] op_sel_hi:[1,0,1]
	v_pk_fma_f32 v[74:75], v[230:231], s[62:63], v[74:75] op_sel_hi:[1,0,1]
	v_pk_fma_f32 v[76:77], v[224:225], s[54:55], v[76:77] op_sel_hi:[1,0,1]
	v_pk_fma_f32 v[78:79], v[226:227], s[54:55], v[78:79] op_sel_hi:[1,0,1]
	v_pk_fma_f32 v[80:81], v[228:229], s[64:65], v[80:81] op_sel_hi:[1,0,1]
	v_pk_fma_f32 v[82:83], v[230:231], s[64:65], v[82:83] op_sel_hi:[1,0,1]
	v_pk_fma_f32 v[84:85], v[224:225], s[56:57], v[84:85] op_sel_hi:[1,0,1]
	v_pk_fma_f32 v[86:87], v[226:227], s[56:57], v[86:87] op_sel_hi:[1,0,1]
	v_pk_fma_f32 v[88:89], v[228:229], s[66:67], v[88:89] op_sel_hi:[1,0,1]
	v_pk_fma_f32 v[90:91], v[230:231], s[66:67], v[90:91] op_sel_hi:[1,0,1]
	s_mov_b32 s6, s13
	s_cmp_ge_u32 s6, 0x2800
	s_cbranch_scc1 .Lgprep_sk1
	v_mul_f32_e32 v92, 0xbfb8aa3b, v52
	v_exp_f32_e32 v92, v92
	s_nop 0
	v_add_f32_e32 v92, 1.0, v92
	v_div_scale_f32 v93, s[24:25], v92, v92, 1.0
	v_rcp_f32_e32 v94, v93
	s_nop 0
	v_fma_f32 v95, -v93, v94, 1.0
	v_fmac_f32_e32 v94, v95, v94
	v_div_scale_f32 v95, vcc, 1.0, v92, 1.0
	v_mul_f32_e32 v96, v95, v94
	v_fma_f32 v97, -v93, v96, v95
	v_fmac_f32_e32 v96, v97, v94
	v_fma_f32 v93, -v93, v96, v95
	v_div_fmas_f32 v93, v93, v94, v96
	v_div_fixup_f32 v52, v93, v92, 1.0
	v_mul_f32_e32 v52, 0xbf1b4598, v52
	v_mul_f32_e32 v52, 0x3fb8aa3b, v52
	v_exp_f32_e32 v52, v52
	v_mul_f32_e32 v92, 0xbfb8aa3b, v56
	v_exp_f32_e32 v92, v92
	s_nop 0
	v_add_f32_e32 v92, 1.0, v92
	v_div_scale_f32 v93, s[24:25], v92, v92, 1.0
	v_rcp_f32_e32 v94, v93
	s_nop 0
	v_fma_f32 v95, -v93, v94, 1.0
	v_fmac_f32_e32 v94, v95, v94
	v_div_scale_f32 v95, vcc, 1.0, v92, 1.0
	v_mul_f32_e32 v96, v95, v94
	v_fma_f32 v97, -v93, v96, v95
	v_fmac_f32_e32 v96, v97, v94
	v_fma_f32 v93, -v93, v96, v95
	v_div_fmas_f32 v93, v93, v94, v96
	v_div_fixup_f32 v56, v93, v92, 1.0
	v_mul_f32_e32 v92, 0xbfb8aa3b, v53
	v_exp_f32_e32 v92, v92
	s_nop 0
	v_add_f32_e32 v92, 1.0, v92
	v_div_scale_f32 v93, s[24:25], v92, v92, 1.0
	v_rcp_f32_e32 v94, v93
	s_nop 0
	v_fma_f32 v95, -v93, v94, 1.0
	v_fmac_f32_e32 v94, v95, v94
	v_div_scale_f32 v95, vcc, 1.0, v92, 1.0
	v_mul_f32_e32 v96, v95, v94
	v_fma_f32 v97, -v93, v96, v95
	v_fmac_f32_e32 v96, v97, v94
	v_fma_f32 v93, -v93, v96, v95
	v_div_fmas_f32 v93, v93, v94, v96
	v_div_fixup_f32 v53, v93, v92, 1.0
	v_mul_f32_e32 v53, 0xbf1b4598, v53
	v_mul_f32_e32 v53, 0x3fb8aa3b, v53
	v_exp_f32_e32 v53, v53
	v_mul_f32_e32 v92, 0xbfb8aa3b, v57
	v_exp_f32_e32 v92, v92
	s_nop 0
	v_add_f32_e32 v92, 1.0, v92
	v_div_scale_f32 v93, s[24:25], v92, v92, 1.0
	v_rcp_f32_e32 v94, v93
	s_nop 0
	v_fma_f32 v95, -v93, v94, 1.0
	v_fmac_f32_e32 v94, v95, v94
	v_div_scale_f32 v95, vcc, 1.0, v92, 1.0
	v_mul_f32_e32 v96, v95, v94
	v_fma_f32 v97, -v93, v96, v95
	v_fmac_f32_e32 v96, v97, v94
	v_fma_f32 v93, -v93, v96, v95
	v_div_fmas_f32 v93, v93, v94, v96
	v_div_fixup_f32 v57, v93, v92, 1.0
	v_mul_f32_e32 v92, 0xbfb8aa3b, v54
	v_exp_f32_e32 v92, v92
	s_nop 0
	v_add_f32_e32 v92, 1.0, v92
	v_div_scale_f32 v93, s[24:25], v92, v92, 1.0
	v_rcp_f32_e32 v94, v93
	s_nop 0
	v_fma_f32 v95, -v93, v94, 1.0
	v_fmac_f32_e32 v94, v95, v94
	v_div_scale_f32 v95, vcc, 1.0, v92, 1.0
	v_mul_f32_e32 v96, v95, v94
	v_fma_f32 v97, -v93, v96, v95
	v_fmac_f32_e32 v96, v97, v94
	v_fma_f32 v93, -v93, v96, v95
	v_div_fmas_f32 v93, v93, v94, v96
	v_div_fixup_f32 v54, v93, v92, 1.0
	v_mul_f32_e32 v54, 0xbf1b4598, v54
	v_mul_f32_e32 v54, 0x3fb8aa3b, v54
	v_exp_f32_e32 v54, v54
	v_mul_f32_e32 v92, 0xbfb8aa3b, v58
	v_exp_f32_e32 v92, v92
	s_nop 0
	v_add_f32_e32 v92, 1.0, v92
	v_div_scale_f32 v93, s[24:25], v92, v92, 1.0
	v_rcp_f32_e32 v94, v93
	s_nop 0
	v_fma_f32 v95, -v93, v94, 1.0
	v_fmac_f32_e32 v94, v95, v94
	v_div_scale_f32 v95, vcc, 1.0, v92, 1.0
	v_mul_f32_e32 v96, v95, v94
	v_fma_f32 v97, -v93, v96, v95
	v_fmac_f32_e32 v96, v97, v94
	v_fma_f32 v93, -v93, v96, v95
	v_div_fmas_f32 v93, v93, v94, v96
	v_div_fixup_f32 v58, v93, v92, 1.0
	v_mul_f32_e32 v92, 0xbfb8aa3b, v55
	v_exp_f32_e32 v92, v92
	s_nop 0
	v_add_f32_e32 v92, 1.0, v92
	v_div_scale_f32 v93, s[24:25], v92, v92, 1.0
	v_rcp_f32_e32 v94, v93
	s_nop 0
	v_fma_f32 v95, -v93, v94, 1.0
	v_fmac_f32_e32 v94, v95, v94
	v_div_scale_f32 v95, vcc, 1.0, v92, 1.0
	v_mul_f32_e32 v96, v95, v94
	v_fma_f32 v97, -v93, v96, v95
	v_fmac_f32_e32 v96, v97, v94
	v_fma_f32 v93, -v93, v96, v95
	v_div_fmas_f32 v93, v93, v94, v96
	v_div_fixup_f32 v55, v93, v92, 1.0
	v_mul_f32_e32 v55, 0xbf1b4598, v55
	v_mul_f32_e32 v55, 0x3fb8aa3b, v55
	v_exp_f32_e32 v55, v55
	v_mul_f32_e32 v92, 0xbfb8aa3b, v59
	v_exp_f32_e32 v92, v92
	s_nop 0
	v_add_f32_e32 v92, 1.0, v92
	v_div_scale_f32 v93, s[24:25], v92, v92, 1.0
	v_rcp_f32_e32 v94, v93
	s_nop 0
	v_fma_f32 v95, -v93, v94, 1.0
	v_fmac_f32_e32 v94, v95, v94
	v_div_scale_f32 v95, vcc, 1.0, v92, 1.0
	v_mul_f32_e32 v96, v95, v94
	v_fma_f32 v97, -v93, v96, v95
	v_fmac_f32_e32 v96, v97, v94
	v_fma_f32 v93, -v93, v96, v95
	v_div_fmas_f32 v93, v93, v94, v96
	v_div_fixup_f32 v59, v93, v92, 1.0
	s_mul_i32 s7, s6, 0x1400
	s_add_u32 s7, s7, 0x800
	s_add_u32 s8, s82, s7
	s_addc_u32 s9, s83, 0
	global_store_dwordx4 v232, v[52:55], s[8:9] offset:1024
	global_store_dwordx4 v232, v[56:59], s[8:9] offset:2048
	s_add_u32 s6, s13, 1
	s_cmp_ge_u32 s6, 0x2800
	s_cbranch_scc1 .Lgprep_sk1
	v_mul_f32_e32 v92, 0xbfb8aa3b, v60
	v_exp_f32_e32 v92, v92
	s_nop 0
	v_add_f32_e32 v92, 1.0, v92
	v_div_scale_f32 v93, s[24:25], v92, v92, 1.0
	v_rcp_f32_e32 v94, v93
	s_nop 0
	v_fma_f32 v95, -v93, v94, 1.0
	v_fmac_f32_e32 v94, v95, v94
	v_div_scale_f32 v95, vcc, 1.0, v92, 1.0
	v_mul_f32_e32 v96, v95, v94
	v_fma_f32 v97, -v93, v96, v95
	v_fmac_f32_e32 v96, v97, v94
	v_fma_f32 v93, -v93, v96, v95
	v_div_fmas_f32 v93, v93, v94, v96
	v_div_fixup_f32 v60, v93, v92, 1.0
	v_mul_f32_e32 v60, 0xbf1b4598, v60
	v_mul_f32_e32 v60, 0x3fb8aa3b, v60
	v_exp_f32_e32 v60, v60
	v_mul_f32_e32 v92, 0xbfb8aa3b, v64
	v_exp_f32_e32 v92, v92
	s_nop 0
	v_add_f32_e32 v92, 1.0, v92
	v_div_scale_f32 v93, s[24:25], v92, v92, 1.0
	v_rcp_f32_e32 v94, v93
	s_nop 0
	v_fma_f32 v95, -v93, v94, 1.0
	v_fmac_f32_e32 v94, v95, v94
	v_div_scale_f32 v95, vcc, 1.0, v92, 1.0
	v_mul_f32_e32 v96, v95, v94
	v_fma_f32 v97, -v93, v96, v95
	v_fmac_f32_e32 v96, v97, v94
	v_fma_f32 v93, -v93, v96, v95
	v_div_fmas_f32 v93, v93, v94, v96
	v_div_fixup_f32 v64, v93, v92, 1.0
	v_mul_f32_e32 v92, 0xbfb8aa3b, v61
	v_exp_f32_e32 v92, v92
	s_nop 0
	v_add_f32_e32 v92, 1.0, v92
	v_div_scale_f32 v93, s[24:25], v92, v92, 1.0
	v_rcp_f32_e32 v94, v93
	s_nop 0
	v_fma_f32 v95, -v93, v94, 1.0
	v_fmac_f32_e32 v94, v95, v94
	v_div_scale_f32 v95, vcc, 1.0, v92, 1.0
	v_mul_f32_e32 v96, v95, v94
	v_fma_f32 v97, -v93, v96, v95
	v_fmac_f32_e32 v96, v97, v94
	v_fma_f32 v93, -v93, v96, v95
	v_div_fmas_f32 v93, v93, v94, v96
	v_div_fixup_f32 v61, v93, v92, 1.0
	v_mul_f32_e32 v61, 0xbf1b4598, v61
	v_mul_f32_e32 v61, 0x3fb8aa3b, v61
	v_exp_f32_e32 v61, v61
	v_mul_f32_e32 v92, 0xbfb8aa3b, v65
	v_exp_f32_e32 v92, v92
	s_nop 0
	v_add_f32_e32 v92, 1.0, v92
	v_div_scale_f32 v93, s[24:25], v92, v92, 1.0
	v_rcp_f32_e32 v94, v93
	s_nop 0
	v_fma_f32 v95, -v93, v94, 1.0
	v_fmac_f32_e32 v94, v95, v94
	v_div_scale_f32 v95, vcc, 1.0, v92, 1.0
	v_mul_f32_e32 v96, v95, v94
	v_fma_f32 v97, -v93, v96, v95
	v_fmac_f32_e32 v96, v97, v94
	v_fma_f32 v93, -v93, v96, v95
	v_div_fmas_f32 v93, v93, v94, v96
	v_div_fixup_f32 v65, v93, v92, 1.0
	v_mul_f32_e32 v92, 0xbfb8aa3b, v62
	v_exp_f32_e32 v92, v92
	s_nop 0
	v_add_f32_e32 v92, 1.0, v92
	v_div_scale_f32 v93, s[24:25], v92, v92, 1.0
	v_rcp_f32_e32 v94, v93
	s_nop 0
	v_fma_f32 v95, -v93, v94, 1.0
	v_fmac_f32_e32 v94, v95, v94
	v_div_scale_f32 v95, vcc, 1.0, v92, 1.0
	v_mul_f32_e32 v96, v95, v94
	v_fma_f32 v97, -v93, v96, v95
	v_fmac_f32_e32 v96, v97, v94
	v_fma_f32 v93, -v93, v96, v95
	v_div_fmas_f32 v93, v93, v94, v96
	v_div_fixup_f32 v62, v93, v92, 1.0
	v_mul_f32_e32 v62, 0xbf1b4598, v62
	v_mul_f32_e32 v62, 0x3fb8aa3b, v62
	v_exp_f32_e32 v62, v62
	v_mul_f32_e32 v92, 0xbfb8aa3b, v66
	v_exp_f32_e32 v92, v92
	s_nop 0
	v_add_f32_e32 v92, 1.0, v92
	v_div_scale_f32 v93, s[24:25], v92, v92, 1.0
	v_rcp_f32_e32 v94, v93
	s_nop 0
	v_fma_f32 v95, -v93, v94, 1.0
	v_fmac_f32_e32 v94, v95, v94
	v_div_scale_f32 v95, vcc, 1.0, v92, 1.0
	v_mul_f32_e32 v96, v95, v94
	v_fma_f32 v97, -v93, v96, v95
	v_fmac_f32_e32 v96, v97, v94
	v_fma_f32 v93, -v93, v96, v95
	v_div_fmas_f32 v93, v93, v94, v96
	v_div_fixup_f32 v66, v93, v92, 1.0
	v_mul_f32_e32 v92, 0xbfb8aa3b, v63
	v_exp_f32_e32 v92, v92
	s_nop 0
	v_add_f32_e32 v92, 1.0, v92
	v_div_scale_f32 v93, s[24:25], v92, v92, 1.0
	v_rcp_f32_e32 v94, v93
	s_nop 0
	v_fma_f32 v95, -v93, v94, 1.0
	v_fmac_f32_e32 v94, v95, v94
	v_div_scale_f32 v95, vcc, 1.0, v92, 1.0
	v_mul_f32_e32 v96, v95, v94
	v_fma_f32 v97, -v93, v96, v95
	v_fmac_f32_e32 v96, v97, v94
	v_fma_f32 v93, -v93, v96, v95
	v_div_fmas_f32 v93, v93, v94, v96
	v_div_fixup_f32 v63, v93, v92, 1.0
	v_mul_f32_e32 v63, 0xbf1b4598, v63
	v_mul_f32_e32 v63, 0x3fb8aa3b, v63
	v_exp_f32_e32 v63, v63
	v_mul_f32_e32 v92, 0xbfb8aa3b, v67
	v_exp_f32_e32 v92, v92
	s_nop 0
	v_add_f32_e32 v92, 1.0, v92
	v_div_scale_f32 v93, s[24:25], v92, v92, 1.0
	v_rcp_f32_e32 v94, v93
	s_nop 0
	v_fma_f32 v95, -v93, v94, 1.0
	v_fmac_f32_e32 v94, v95, v94
	v_div_scale_f32 v95, vcc, 1.0, v92, 1.0
	v_mul_f32_e32 v96, v95, v94
	v_fma_f32 v97, -v93, v96, v95
	v_fmac_f32_e32 v96, v97, v94
	v_fma_f32 v93, -v93, v96, v95
	v_div_fmas_f32 v93, v93, v94, v96
	v_div_fixup_f32 v67, v93, v92, 1.0
	s_mul_i32 s7, s6, 0x1400
	s_add_u32 s7, s7, 0x800
	s_add_u32 s8, s82, s7
	s_addc_u32 s9, s83, 0
	global_store_dwordx4 v232, v[60:63], s[8:9] offset:1024
	global_store_dwordx4 v232, v[64:67], s[8:9] offset:2048
	s_add_u32 s6, s13, 2
	s_cmp_ge_u32 s6, 0x2800
	s_cbranch_scc1 .Lgprep_sk1
	v_mul_f32_e32 v92, 0xbfb8aa3b, v68
	v_exp_f32_e32 v92, v92
	s_nop 0
	v_add_f32_e32 v92, 1.0, v92
	v_div_scale_f32 v93, s[24:25], v92, v92, 1.0
	v_rcp_f32_e32 v94, v93
	s_nop 0
	v_fma_f32 v95, -v93, v94, 1.0
	v_fmac_f32_e32 v94, v95, v94
	v_div_scale_f32 v95, vcc, 1.0, v92, 1.0
	v_mul_f32_e32 v96, v95, v94
	v_fma_f32 v97, -v93, v96, v95
	v_fmac_f32_e32 v96, v97, v94
	v_fma_f32 v93, -v93, v96, v95
	v_div_fmas_f32 v93, v93, v94, v96
	v_div_fixup_f32 v68, v93, v92, 1.0
	v_mul_f32_e32 v68, 0xbf1b4598, v68
	v_mul_f32_e32 v68, 0x3fb8aa3b, v68
	v_exp_f32_e32 v68, v68
	v_mul_f32_e32 v92, 0xbfb8aa3b, v72
	v_exp_f32_e32 v92, v92
	s_nop 0
	v_add_f32_e32 v92, 1.0, v92
	v_div_scale_f32 v93, s[24:25], v92, v92, 1.0
	v_rcp_f32_e32 v94, v93
	s_nop 0
	v_fma_f32 v95, -v93, v94, 1.0
	v_fmac_f32_e32 v94, v95, v94
	v_div_scale_f32 v95, vcc, 1.0, v92, 1.0
	v_mul_f32_e32 v96, v95, v94
	v_fma_f32 v97, -v93, v96, v95
	v_fmac_f32_e32 v96, v97, v94
	v_fma_f32 v93, -v93, v96, v95
	v_div_fmas_f32 v93, v93, v94, v96
	v_div_fixup_f32 v72, v93, v92, 1.0
	v_mul_f32_e32 v92, 0xbfb8aa3b, v69
	v_exp_f32_e32 v92, v92
	s_nop 0
	v_add_f32_e32 v92, 1.0, v92
	v_div_scale_f32 v93, s[24:25], v92, v92, 1.0
	v_rcp_f32_e32 v94, v93
	s_nop 0
	v_fma_f32 v95, -v93, v94, 1.0
	v_fmac_f32_e32 v94, v95, v94
	v_div_scale_f32 v95, vcc, 1.0, v92, 1.0
	v_mul_f32_e32 v96, v95, v94
	v_fma_f32 v97, -v93, v96, v95
	v_fmac_f32_e32 v96, v97, v94
	v_fma_f32 v93, -v93, v96, v95
	v_div_fmas_f32 v93, v93, v94, v96
	v_div_fixup_f32 v69, v93, v92, 1.0
	v_mul_f32_e32 v69, 0xbf1b4598, v69
	v_mul_f32_e32 v69, 0x3fb8aa3b, v69
	v_exp_f32_e32 v69, v69
	v_mul_f32_e32 v92, 0xbfb8aa3b, v73
	v_exp_f32_e32 v92, v92
	s_nop 0
	v_add_f32_e32 v92, 1.0, v92
	v_div_scale_f32 v93, s[24:25], v92, v92, 1.0
	v_rcp_f32_e32 v94, v93
	s_nop 0
	v_fma_f32 v95, -v93, v94, 1.0
	v_fmac_f32_e32 v94, v95, v94
	v_div_scale_f32 v95, vcc, 1.0, v92, 1.0
	v_mul_f32_e32 v96, v95, v94
	v_fma_f32 v97, -v93, v96, v95
	v_fmac_f32_e32 v96, v97, v94
	v_fma_f32 v93, -v93, v96, v95
	v_div_fmas_f32 v93, v93, v94, v96
	v_div_fixup_f32 v73, v93, v92, 1.0
	v_mul_f32_e32 v92, 0xbfb8aa3b, v70
	v_exp_f32_e32 v92, v92
	s_nop 0
	v_add_f32_e32 v92, 1.0, v92
	v_div_scale_f32 v93, s[24:25], v92, v92, 1.0
	v_rcp_f32_e32 v94, v93
	s_nop 0
	v_fma_f32 v95, -v93, v94, 1.0
	v_fmac_f32_e32 v94, v95, v94
	v_div_scale_f32 v95, vcc, 1.0, v92, 1.0
	v_mul_f32_e32 v96, v95, v94
	v_fma_f32 v97, -v93, v96, v95
	v_fmac_f32_e32 v96, v97, v94
	v_fma_f32 v93, -v93, v96, v95
	v_div_fmas_f32 v93, v93, v94, v96
	v_div_fixup_f32 v70, v93, v92, 1.0
	v_mul_f32_e32 v70, 0xbf1b4598, v70
	v_mul_f32_e32 v70, 0x3fb8aa3b, v70
	v_exp_f32_e32 v70, v70
	v_mul_f32_e32 v92, 0xbfb8aa3b, v74
	v_exp_f32_e32 v92, v92
	s_nop 0
	v_add_f32_e32 v92, 1.0, v92
	v_div_scale_f32 v93, s[24:25], v92, v92, 1.0
	v_rcp_f32_e32 v94, v93
	s_nop 0
	v_fma_f32 v95, -v93, v94, 1.0
	v_fmac_f32_e32 v94, v95, v94
	v_div_scale_f32 v95, vcc, 1.0, v92, 1.0
	v_mul_f32_e32 v96, v95, v94
	v_fma_f32 v97, -v93, v96, v95
	v_fmac_f32_e32 v96, v97, v94
	v_fma_f32 v93, -v93, v96, v95
	v_div_fmas_f32 v93, v93, v94, v96
	v_div_fixup_f32 v74, v93, v92, 1.0
	v_mul_f32_e32 v92, 0xbfb8aa3b, v71
	v_exp_f32_e32 v92, v92
	s_nop 0
	v_add_f32_e32 v92, 1.0, v92
	v_div_scale_f32 v93, s[24:25], v92, v92, 1.0
	v_rcp_f32_e32 v94, v93
	s_nop 0
	v_fma_f32 v95, -v93, v94, 1.0
	v_fmac_f32_e32 v94, v95, v94
	v_div_scale_f32 v95, vcc, 1.0, v92, 1.0
	v_mul_f32_e32 v96, v95, v94
	v_fma_f32 v97, -v93, v96, v95
	v_fmac_f32_e32 v96, v97, v94
	v_fma_f32 v93, -v93, v96, v95
	v_div_fmas_f32 v93, v93, v94, v96
	v_div_fixup_f32 v71, v93, v92, 1.0
	v_mul_f32_e32 v71, 0xbf1b4598, v71
	v_mul_f32_e32 v71, 0x3fb8aa3b, v71
	v_exp_f32_e32 v71, v71
	v_mul_f32_e32 v92, 0xbfb8aa3b, v75
	v_exp_f32_e32 v92, v92
	s_nop 0
	v_add_f32_e32 v92, 1.0, v92
	v_div_scale_f32 v93, s[24:25], v92, v92, 1.0
	v_rcp_f32_e32 v94, v93
	s_nop 0
	v_fma_f32 v95, -v93, v94, 1.0
	v_fmac_f32_e32 v94, v95, v94
	v_div_scale_f32 v95, vcc, 1.0, v92, 1.0
	v_mul_f32_e32 v96, v95, v94
	v_fma_f32 v97, -v93, v96, v95
	v_fmac_f32_e32 v96, v97, v94
	v_fma_f32 v93, -v93, v96, v95
	v_div_fmas_f32 v93, v93, v94, v96
	v_div_fixup_f32 v75, v93, v92, 1.0
	s_mul_i32 s7, s6, 0x1400
	s_add_u32 s7, s7, 0x800
	s_add_u32 s8, s82, s7
	s_addc_u32 s9, s83, 0
	global_store_dwordx4 v232, v[68:71], s[8:9] offset:1024
	global_store_dwordx4 v232, v[72:75], s[8:9] offset:2048
	s_add_u32 s6, s13, 3
	s_cmp_ge_u32 s6, 0x2800
	s_cbranch_scc1 .Lgprep_sk1
	v_mul_f32_e32 v92, 0xbfb8aa3b, v76
	v_exp_f32_e32 v92, v92
	s_nop 0
	v_add_f32_e32 v92, 1.0, v92
	v_div_scale_f32 v93, s[24:25], v92, v92, 1.0
	v_rcp_f32_e32 v94, v93
	s_nop 0
	v_fma_f32 v95, -v93, v94, 1.0
	v_fmac_f32_e32 v94, v95, v94
	v_div_scale_f32 v95, vcc, 1.0, v92, 1.0
	v_mul_f32_e32 v96, v95, v94
	v_fma_f32 v97, -v93, v96, v95
	v_fmac_f32_e32 v96, v97, v94
	v_fma_f32 v93, -v93, v96, v95
	v_div_fmas_f32 v93, v93, v94, v96
	v_div_fixup_f32 v76, v93, v92, 1.0
	v_mul_f32_e32 v76, 0xbf1b4598, v76
	v_mul_f32_e32 v76, 0x3fb8aa3b, v76
	v_exp_f32_e32 v76, v76
	v_mul_f32_e32 v92, 0xbfb8aa3b, v80
	v_exp_f32_e32 v92, v92
	s_nop 0
	v_add_f32_e32 v92, 1.0, v92
	v_div_scale_f32 v93, s[24:25], v92, v92, 1.0
	v_rcp_f32_e32 v94, v93
	s_nop 0
	v_fma_f32 v95, -v93, v94, 1.0
	v_fmac_f32_e32 v94, v95, v94
	v_div_scale_f32 v95, vcc, 1.0, v92, 1.0
	v_mul_f32_e32 v96, v95, v94
	v_fma_f32 v97, -v93, v96, v95
	v_fmac_f32_e32 v96, v97, v94
	v_fma_f32 v93, -v93, v96, v95
	v_div_fmas_f32 v93, v93, v94, v96
	v_div_fixup_f32 v80, v93, v92, 1.0
	v_mul_f32_e32 v92, 0xbfb8aa3b, v77
	v_exp_f32_e32 v92, v92
	s_nop 0
	v_add_f32_e32 v92, 1.0, v92
	v_div_scale_f32 v93, s[24:25], v92, v92, 1.0
	v_rcp_f32_e32 v94, v93
	s_nop 0
	v_fma_f32 v95, -v93, v94, 1.0
	v_fmac_f32_e32 v94, v95, v94
	v_div_scale_f32 v95, vcc, 1.0, v92, 1.0
	v_mul_f32_e32 v96, v95, v94
	v_fma_f32 v97, -v93, v96, v95
	v_fmac_f32_e32 v96, v97, v94
	v_fma_f32 v93, -v93, v96, v95
	v_div_fmas_f32 v93, v93, v94, v96
	v_div_fixup_f32 v77, v93, v92, 1.0
	v_mul_f32_e32 v77, 0xbf1b4598, v77
	v_mul_f32_e32 v77, 0x3fb8aa3b, v77
	v_exp_f32_e32 v77, v77
	v_mul_f32_e32 v92, 0xbfb8aa3b, v81
	v_exp_f32_e32 v92, v92
	s_nop 0
	v_add_f32_e32 v92, 1.0, v92
	v_div_scale_f32 v93, s[24:25], v92, v92, 1.0
	v_rcp_f32_e32 v94, v93
	s_nop 0
	v_fma_f32 v95, -v93, v94, 1.0
	v_fmac_f32_e32 v94, v95, v94
	v_div_scale_f32 v95, vcc, 1.0, v92, 1.0
	v_mul_f32_e32 v96, v95, v94
	v_fma_f32 v97, -v93, v96, v95
	v_fmac_f32_e32 v96, v97, v94
	v_fma_f32 v93, -v93, v96, v95
	v_div_fmas_f32 v93, v93, v94, v96
	v_div_fixup_f32 v81, v93, v92, 1.0
	v_mul_f32_e32 v92, 0xbfb8aa3b, v78
	v_exp_f32_e32 v92, v92
	s_nop 0
	v_add_f32_e32 v92, 1.0, v92
	v_div_scale_f32 v93, s[24:25], v92, v92, 1.0
	v_rcp_f32_e32 v94, v93
	s_nop 0
	v_fma_f32 v95, -v93, v94, 1.0
	v_fmac_f32_e32 v94, v95, v94
	v_div_scale_f32 v95, vcc, 1.0, v92, 1.0
	v_mul_f32_e32 v96, v95, v94
	v_fma_f32 v97, -v93, v96, v95
	v_fmac_f32_e32 v96, v97, v94
	v_fma_f32 v93, -v93, v96, v95
	v_div_fmas_f32 v93, v93, v94, v96
	v_div_fixup_f32 v78, v93, v92, 1.0
	v_mul_f32_e32 v78, 0xbf1b4598, v78
	v_mul_f32_e32 v78, 0x3fb8aa3b, v78
	v_exp_f32_e32 v78, v78
	v_mul_f32_e32 v92, 0xbfb8aa3b, v82
	v_exp_f32_e32 v92, v92
	s_nop 0
	v_add_f32_e32 v92, 1.0, v92
	v_div_scale_f32 v93, s[24:25], v92, v92, 1.0
	v_rcp_f32_e32 v94, v93
	s_nop 0
	v_fma_f32 v95, -v93, v94, 1.0
	v_fmac_f32_e32 v94, v95, v94
	v_div_scale_f32 v95, vcc, 1.0, v92, 1.0
	v_mul_f32_e32 v96, v95, v94
	v_fma_f32 v97, -v93, v96, v95
	v_fmac_f32_e32 v96, v97, v94
	v_fma_f32 v93, -v93, v96, v95
	v_div_fmas_f32 v93, v93, v94, v96
	v_div_fixup_f32 v82, v93, v92, 1.0
	v_mul_f32_e32 v92, 0xbfb8aa3b, v79
	v_exp_f32_e32 v92, v92
	s_nop 0
	v_add_f32_e32 v92, 1.0, v92
	v_div_scale_f32 v93, s[24:25], v92, v92, 1.0
	v_rcp_f32_e32 v94, v93
	s_nop 0
	v_fma_f32 v95, -v93, v94, 1.0
	v_fmac_f32_e32 v94, v95, v94
	v_div_scale_f32 v95, vcc, 1.0, v92, 1.0
	v_mul_f32_e32 v96, v95, v94
	v_fma_f32 v97, -v93, v96, v95
	v_fmac_f32_e32 v96, v97, v94
	v_fma_f32 v93, -v93, v96, v95
	v_div_fmas_f32 v93, v93, v94, v96
	v_div_fixup_f32 v79, v93, v92, 1.0
	v_mul_f32_e32 v79, 0xbf1b4598, v79
	v_mul_f32_e32 v79, 0x3fb8aa3b, v79
	v_exp_f32_e32 v79, v79
	v_mul_f32_e32 v92, 0xbfb8aa3b, v83
	v_exp_f32_e32 v92, v92
	s_nop 0
	v_add_f32_e32 v92, 1.0, v92
	v_div_scale_f32 v93, s[24:25], v92, v92, 1.0
	v_rcp_f32_e32 v94, v93
	s_nop 0
	v_fma_f32 v95, -v93, v94, 1.0
	v_fmac_f32_e32 v94, v95, v94
	v_div_scale_f32 v95, vcc, 1.0, v92, 1.0
	v_mul_f32_e32 v96, v95, v94
	v_fma_f32 v97, -v93, v96, v95
	v_fmac_f32_e32 v96, v97, v94
	v_fma_f32 v93, -v93, v96, v95
	v_div_fmas_f32 v93, v93, v94, v96
	v_div_fixup_f32 v83, v93, v92, 1.0
	s_mul_i32 s7, s6, 0x1400
	s_add_u32 s7, s7, 0x800
	s_add_u32 s8, s82, s7
	s_addc_u32 s9, s83, 0
	global_store_dwordx4 v232, v[76:79], s[8:9] offset:1024
	global_store_dwordx4 v232, v[80:83], s[8:9] offset:2048
	s_add_u32 s6, s13, 4
	s_cmp_ge_u32 s6, 0x2800
	s_cbranch_scc1 .Lgprep_sk1
	v_mul_f32_e32 v92, 0xbfb8aa3b, v84
	v_exp_f32_e32 v92, v92
	s_nop 0
	v_add_f32_e32 v92, 1.0, v92
	v_div_scale_f32 v93, s[24:25], v92, v92, 1.0
	v_rcp_f32_e32 v94, v93
	s_nop 0
	v_fma_f32 v95, -v93, v94, 1.0
	v_fmac_f32_e32 v94, v95, v94
	v_div_scale_f32 v95, vcc, 1.0, v92, 1.0
	v_mul_f32_e32 v96, v95, v94
	v_fma_f32 v97, -v93, v96, v95
	v_fmac_f32_e32 v96, v97, v94
	v_fma_f32 v93, -v93, v96, v95
	v_div_fmas_f32 v93, v93, v94, v96
	v_div_fixup_f32 v84, v93, v92, 1.0
	v_mul_f32_e32 v84, 0xbf1b4598, v84
	v_mul_f32_e32 v84, 0x3fb8aa3b, v84
	v_exp_f32_e32 v84, v84
	v_mul_f32_e32 v92, 0xbfb8aa3b, v88
	v_exp_f32_e32 v92, v92
	s_nop 0
	v_add_f32_e32 v92, 1.0, v92
	v_div_scale_f32 v93, s[24:25], v92, v92, 1.0
	v_rcp_f32_e32 v94, v93
	s_nop 0
	v_fma_f32 v95, -v93, v94, 1.0
	v_fmac_f32_e32 v94, v95, v94
	v_div_scale_f32 v95, vcc, 1.0, v92, 1.0
	v_mul_f32_e32 v96, v95, v94
	v_fma_f32 v97, -v93, v96, v95
	v_fmac_f32_e32 v96, v97, v94
	v_fma_f32 v93, -v93, v96, v95
	v_div_fmas_f32 v93, v93, v94, v96
	v_div_fixup_f32 v88, v93, v92, 1.0
	v_mul_f32_e32 v92, 0xbfb8aa3b, v85
	v_exp_f32_e32 v92, v92
	s_nop 0
	v_add_f32_e32 v92, 1.0, v92
	v_div_scale_f32 v93, s[24:25], v92, v92, 1.0
	v_rcp_f32_e32 v94, v93
	s_nop 0
	v_fma_f32 v95, -v93, v94, 1.0
	v_fmac_f32_e32 v94, v95, v94
	v_div_scale_f32 v95, vcc, 1.0, v92, 1.0
	v_mul_f32_e32 v96, v95, v94
	v_fma_f32 v97, -v93, v96, v95
	v_fmac_f32_e32 v96, v97, v94
	v_fma_f32 v93, -v93, v96, v95
	v_div_fmas_f32 v93, v93, v94, v96
	v_div_fixup_f32 v85, v93, v92, 1.0
	v_mul_f32_e32 v85, 0xbf1b4598, v85
	v_mul_f32_e32 v85, 0x3fb8aa3b, v85
	v_exp_f32_e32 v85, v85
	v_mul_f32_e32 v92, 0xbfb8aa3b, v89
	v_exp_f32_e32 v92, v92
	s_nop 0
	v_add_f32_e32 v92, 1.0, v92
	v_div_scale_f32 v93, s[24:25], v92, v92, 1.0
	v_rcp_f32_e32 v94, v93
	s_nop 0
	v_fma_f32 v95, -v93, v94, 1.0
	v_fmac_f32_e32 v94, v95, v94
	v_div_scale_f32 v95, vcc, 1.0, v92, 1.0
	v_mul_f32_e32 v96, v95, v94
	v_fma_f32 v97, -v93, v96, v95
	v_fmac_f32_e32 v96, v97, v94
	v_fma_f32 v93, -v93, v96, v95
	v_div_fmas_f32 v93, v93, v94, v96
	v_div_fixup_f32 v89, v93, v92, 1.0
	v_mul_f32_e32 v92, 0xbfb8aa3b, v86
	v_exp_f32_e32 v92, v92
	s_nop 0
	v_add_f32_e32 v92, 1.0, v92
	v_div_scale_f32 v93, s[24:25], v92, v92, 1.0
	v_rcp_f32_e32 v94, v93
	s_nop 0
	v_fma_f32 v95, -v93, v94, 1.0
	v_fmac_f32_e32 v94, v95, v94
	v_div_scale_f32 v95, vcc, 1.0, v92, 1.0
	v_mul_f32_e32 v96, v95, v94
	v_fma_f32 v97, -v93, v96, v95
	v_fmac_f32_e32 v96, v97, v94
	v_fma_f32 v93, -v93, v96, v95
	v_div_fmas_f32 v93, v93, v94, v96
	v_div_fixup_f32 v86, v93, v92, 1.0
	v_mul_f32_e32 v86, 0xbf1b4598, v86
	v_mul_f32_e32 v86, 0x3fb8aa3b, v86
	v_exp_f32_e32 v86, v86
	v_mul_f32_e32 v92, 0xbfb8aa3b, v90
	v_exp_f32_e32 v92, v92
	s_nop 0
	v_add_f32_e32 v92, 1.0, v92
	v_div_scale_f32 v93, s[24:25], v92, v92, 1.0
	v_rcp_f32_e32 v94, v93
	s_nop 0
	v_fma_f32 v95, -v93, v94, 1.0
	v_fmac_f32_e32 v94, v95, v94
	v_div_scale_f32 v95, vcc, 1.0, v92, 1.0
	v_mul_f32_e32 v96, v95, v94
	v_fma_f32 v97, -v93, v96, v95
	v_fmac_f32_e32 v96, v97, v94
	v_fma_f32 v93, -v93, v96, v95
	v_div_fmas_f32 v93, v93, v94, v96
	v_div_fixup_f32 v90, v93, v92, 1.0
	v_mul_f32_e32 v92, 0xbfb8aa3b, v87
	v_exp_f32_e32 v92, v92
	s_nop 0
	v_add_f32_e32 v92, 1.0, v92
	v_div_scale_f32 v93, s[24:25], v92, v92, 1.0
	v_rcp_f32_e32 v94, v93
	s_nop 0
	v_fma_f32 v95, -v93, v94, 1.0
	v_fmac_f32_e32 v94, v95, v94
	v_div_scale_f32 v95, vcc, 1.0, v92, 1.0
	v_mul_f32_e32 v96, v95, v94
	v_fma_f32 v97, -v93, v96, v95
	v_fmac_f32_e32 v96, v97, v94
	v_fma_f32 v93, -v93, v96, v95
	v_div_fmas_f32 v93, v93, v94, v96
	v_div_fixup_f32 v87, v93, v92, 1.0
	v_mul_f32_e32 v87, 0xbf1b4598, v87
	v_mul_f32_e32 v87, 0x3fb8aa3b, v87
	v_exp_f32_e32 v87, v87
	v_mul_f32_e32 v92, 0xbfb8aa3b, v91
	v_exp_f32_e32 v92, v92
	s_nop 0
	v_add_f32_e32 v92, 1.0, v92
	v_div_scale_f32 v93, s[24:25], v92, v92, 1.0
	v_rcp_f32_e32 v94, v93
	s_nop 0
	v_fma_f32 v95, -v93, v94, 1.0
	v_fmac_f32_e32 v94, v95, v94
	v_div_scale_f32 v95, vcc, 1.0, v92, 1.0
	v_mul_f32_e32 v96, v95, v94
	v_fma_f32 v97, -v93, v96, v95
	v_fmac_f32_e32 v96, v97, v94
	v_fma_f32 v93, -v93, v96, v95
	v_div_fmas_f32 v93, v93, v94, v96
	v_div_fixup_f32 v91, v93, v92, 1.0
	s_mul_i32 s7, s6, 0x1400
	s_add_u32 s7, s7, 0x800
	s_add_u32 s8, s82, s7
	s_addc_u32 s9, s83, 0
	global_store_dwordx4 v232, v[84:87], s[8:9] offset:1024
	global_store_dwordx4 v232, v[88:91], s[8:9] offset:2048
	s_branch .Lgprep_e1

.Lgprep_e1:
	s_add_u32 s13, s13, s14
	s_cmp_lt_u32 s13, 0x2800
	s_cbranch_scc1 .Lgprep_batch

.LBB0_801:
	s_andn2_b64 vcc, exec, s[2:3]
	s_cbranch_vccnz .LBB0_857
	v_readlane_b32 s10, v164, 0
	v_readlane_b32 s11, v162, 14
	v_lshrrev_b32_e32 v241, 6, v128
	v_and_b32_e32 v242, 63, v128
	v_readlane_b32 s16, v164, 49
	v_readlane_b32 s17, v164, 50
	v_readlane_b32 s18, v164, 57
	v_readlane_b32 s19, v164, 58
	v_readfirstlane_b32 s12, v241
	v_lshlrev_b32_e32 v248, 4, v242
	v_lshlrev_b32_e32 v249, 2, v242
	v_lshlrev_b32_e32 v250, 3, v242
	v_readlane_b32 s20, v164, 59
	v_readlane_b32 s21, v164, 60
	v_readlane_b32 s22, v164, 55
	v_readlane_b32 s23, v164, 56
	s_lshl_b32 s13, s10, 2
	s_add_u32 s13, s13, s12
	s_mul_i32 s13, s13, 5
	s_mul_i32 s14, s11, 20
	s_lshl_b32 s4, s34, 10
	s_add_u32 s18, s18, s4
	s_addc_u32 s19, s19, 0
	s_add_u32 s20, s20, s4
	s_addc_u32 s21, s21, 0
	s_add_u32 s22, s22, s4
	s_addc_u32 s23, s23, 0
	s_lshl_b32 s4, s34, 16
	s_add_u32 s16, s16, s4
	s_addc_u32 s17, s17, 0
	global_load_dwordx4 v[110:113], v248, s[18:19]
	global_load_dwordx4 v[118:121], v248, s[20:21]
	global_load_dwordx4 v[122:125], v248, s[22:23]
.Lgpost_batch:
	s_mov_b32 s6, s13
	s_min_u32 s6, s6, 0x27ff
	s_mul_i32 s7, s6, 0x2f00
	s_add_u32 s7, s7, 0x2000
	s_add_u32 s8, s74, s7
	s_addc_u32 s9, s75, 0
	global_load_dword v0, v249, s[8:9] offset:3584
	s_add_u32 s6, s13, 1
	s_min_u32 s6, s6, 0x27ff
	s_mul_i32 s7, s6, 0x2f00
	s_add_u32 s7, s7, 0x2000
	s_add_u32 s8, s74, s7
	s_addc_u32 s9, s75, 0
	global_load_dword v22, v249, s[8:9] offset:3584
	s_add_u32 s6, s13, 2
	s_min_u32 s6, s6, 0x27ff
	s_mul_i32 s7, s6, 0x2f00
	s_add_u32 s7, s7, 0x2000
	s_add_u32 s8, s74, s7
	s_addc_u32 s9, s75, 0
	global_load_dword v44, v249, s[8:9] offset:3584
	s_add_u32 s6, s13, 3
	s_min_u32 s6, s6, 0x27ff
	s_mul_i32 s7, s6, 0x2f00
	s_add_u32 s7, s7, 0x2000
	s_add_u32 s8, s74, s7
	s_addc_u32 s9, s75, 0
	global_load_dword v66, v249, s[8:9] offset:3584
	s_add_u32 s6, s13, 4
	s_min_u32 s6, s6, 0x27ff
	s_mul_i32 s7, s6, 0x2f00
	s_add_u32 s7, s7, 0x2000
	s_add_u32 s8, s74, s7
	s_addc_u32 s9, s75, 0
	global_load_dword v88, v249, s[8:9] offset:3584
	s_mov_b32 s6, s13
	s_min_u32 s6, s6, 0x27ff
	s_mul_i32 s7, s6, 0x2f00
	s_add_u32 s7, s7, 0x2000
	s_add_u32 s8, s74, s7
	s_addc_u32 s9, s75, 0
	global_load_dwordx4 v[10:13], v248, s[8:9]
	global_load_dwordx4 v[14:17], v248, s[8:9] offset:1024
	global_load_dwordx4 v[18:21], v248, s[8:9] offset:2048
	s_lshl_b32 s7, s6, 10
	s_add_u32 s8, s72, s7
	s_addc_u32 s9, s73, 0
	global_load_dwordx4 v[2:5], v248, s[8:9]
	s_add_u32 s8, s8, 0xa00000
	s_addc_u32 s9, s9, 0
	global_load_dwordx4 v[6:9], v248, s[8:9]
	s_add_u32 s6, s13, 1
	s_min_u32 s6, s6, 0x27ff
	s_mul_i32 s7, s6, 0x2f00
	s_add_u32 s7, s7, 0x2000
	s_add_u32 s8, s74, s7
	s_addc_u32 s9, s75, 0
	global_load_dwordx4 v[32:35], v248, s[8:9]
	global_load_dwordx4 v[36:39], v248, s[8:9] offset:1024
	global_load_dwordx4 v[40:43], v248, s[8:9] offset:2048
	s_lshl_b32 s7, s6, 10
	s_add_u32 s8, s72, s7
	s_addc_u32 s9, s73, 0
	global_load_dwordx4 v[24:27], v248, s[8:9]
	s_add_u32 s8, s8, 0xa00000
	s_addc_u32 s9, s9, 0
	global_load_dwordx4 v[28:31], v248, s[8:9]
	s_add_u32 s6, s13, 2
	s_min_u32 s6, s6, 0x27ff
	s_mul_i32 s7, s6, 0x2f00
	s_add_u32 s7, s7, 0x2000
	s_add_u32 s8, s74, s7
	s_addc_u32 s9, s75, 0
	global_load_dwordx4 v[54:57], v248, s[8:9]
	global_load_dwordx4 v[58:61], v248, s[8:9] offset:1024
	global_load_dwordx4 v[62:65], v248, s[8:9] offset:2048
	s_lshl_b32 s7, s6, 10
	s_add_u32 s8, s72, s7
	s_addc_u32 s9, s73, 0
	global_load_dwordx4 v[46:49], v248, s[8:9]
	s_add_u32 s8, s8, 0xa00000
	s_addc_u32 s9, s9, 0
	global_load_dwordx4 v[50:53], v248, s[8:9]
	s_add_u32 s6, s13, 3
	s_min_u32 s6, s6, 0x27ff
	s_mul_i32 s7, s6, 0x2f00
	s_add_u32 s7, s7, 0x2000
	s_add_u32 s8, s74, s7
	s_addc_u32 s9, s75, 0
	global_load_dwordx4 v[76:79], v248, s[8:9]
	global_load_dwordx4 v[80:83], v248, s[8:9] offset:1024
	global_load_dwordx4 v[84:87], v248, s[8:9] offset:2048
	s_lshl_b32 s7, s6, 10
	s_add_u32 s8, s72, s7
	s_addc_u32 s9, s73, 0
	global_load_dwordx4 v[68:71], v248, s[8:9]
	s_add_u32 s8, s8, 0xa00000
	s_addc_u32 s9, s9, 0
	global_load_dwordx4 v[72:75], v248, s[8:9]
	s_add_u32 s6, s13, 4
	s_min_u32 s6, s6, 0x27ff
	s_mul_i32 s7, s6, 0x2f00
	s_add_u32 s7, s7, 0x2000
	s_add_u32 s8, s74, s7
	s_addc_u32 s9, s75, 0
	global_load_dwordx4 v[98:101], v248, s[8:9]
	global_load_dwordx4 v[102:105], v248, s[8:9] offset:1024
	global_load_dwordx4 v[106:109], v248, s[8:9] offset:2048
	s_lshl_b32 s7, s6, 10
	s_add_u32 s8, s72, s7
	s_addc_u32 s9, s73, 0
	global_load_dwordx4 v[90:93], v248, s[8:9]
	s_add_u32 s8, s8, 0xa00000
	s_addc_u32 s9, s9, 0
	global_load_dwordx4 v[94:97], v248, s[8:9]
	s_mov_b32 s8, s16
	s_mov_b32 s9, s17
	global_load_dwordx4 v[188:191], v248, s[8:9]
	global_load_dwordx4 v[192:195], v248, s[8:9] offset:1024
	global_load_dwordx4 v[196:199], v248, s[8:9] offset:2048
	global_load_dwordx4 v[200:203], v248, s[8:9] offset:3072
	s_add_u32 s8, s8, 0x1000
	s_addc_u32 s9, s9, 0
	global_load_dwordx4 v[204:207], v248, s[8:9]
	global_load_dwordx4 v[208:211], v248, s[8:9] offset:1024
	global_load_dwordx4 v[212:215], v248, s[8:9] offset:2048
	global_load_dwordx4 v[216:219], v248, s[8:9] offset:3072
	s_add_u32 s8, s8, 0x1000
	s_addc_u32 s9, s9, 0
	global_load_dwordx4 v[220:223], v248, s[8:9]
	global_load_dwordx4 v[224:227], v248, s[8:9] offset:1024
	s_waitcnt vmcnt(35)
	v_mul_f32_e32 v241, 0xbfb8aa3b, v0
	v_exp_f32_e32 v241, v241
	s_nop 0
	v_add_f32_e32 v241, 1.0, v241
	v_div_scale_f32 v242, s[24:25], v241, v241, 1.0
	v_rcp_f32_e32 v243, v242
	s_nop 0
	v_fma_f32 v244, -v242, v243, 1.0
	v_fmac_f32_e32 v243, v244, v243
	v_div_scale_f32 v244, vcc, 1.0, v241, 1.0
	v_mul_f32_e32 v245, v244, v243
	v_fma_f32 v246, -v242, v245, v244
	v_fmac_f32_e32 v245, v246, v243
	v_fma_f32 v242, -v242, v245, v244
	v_div_fmas_f32 v242, v242, v243, v245
	v_div_fixup_f32 v236, v242, v241, 1.0
	v_mul_f32_e32 v241, 0xbfb8aa3b, v22
	v_exp_f32_e32 v241, v241
	s_nop 0
	v_add_f32_e32 v241, 1.0, v241
	v_div_scale_f32 v242, s[24:25], v241, v241, 1.0
	v_rcp_f32_e32 v243, v242
	s_nop 0
	v_fma_f32 v244, -v242, v243, 1.0
	v_fmac_f32_e32 v243, v244, v243
	v_div_scale_f32 v244, vcc, 1.0, v241, 1.0
	v_mul_f32_e32 v245, v244, v243
	v_fma_f32 v246, -v242, v245, v244
	v_fmac_f32_e32 v245, v246, v243
	v_fma_f32 v242, -v242, v245, v244
	v_div_fmas_f32 v242, v242, v243, v245
	v_div_fixup_f32 v237, v242, v241, 1.0
	v_mul_f32_e32 v241, 0xbfb8aa3b, v44
	v_exp_f32_e32 v241, v241
	s_nop 0
	v_add_f32_e32 v241, 1.0, v241
	v_div_scale_f32 v242, s[24:25], v241, v241, 1.0
	v_rcp_f32_e32 v243, v242
	s_nop 0
	v_fma_f32 v244, -v242, v243, 1.0
	v_fmac_f32_e32 v243, v244, v243
	v_div_scale_f32 v244, vcc, 1.0, v241, 1.0
	v_mul_f32_e32 v245, v244, v243
	v_fma_f32 v246, -v242, v245, v244
	v_fmac_f32_e32 v245, v246, v243
	v_fma_f32 v242, -v242, v245, v244
	v_div_fmas_f32 v242, v242, v243, v245
	v_div_fixup_f32 v238, v242, v241, 1.0
	v_mul_f32_e32 v241, 0xbfb8aa3b, v66
	v_exp_f32_e32 v241, v241
	s_nop 0
	v_add_f32_e32 v241, 1.0, v241
	v_div_scale_f32 v242, s[24:25], v241, v241, 1.0
	v_rcp_f32_e32 v243, v242
	s_nop 0
	v_fma_f32 v244, -v242, v243, 1.0
	v_fmac_f32_e32 v243, v244, v243
	v_div_scale_f32 v244, vcc, 1.0, v241, 1.0
	v_mul_f32_e32 v245, v244, v243
	v_fma_f32 v246, -v242, v245, v244
	v_fmac_f32_e32 v245, v246, v243
	v_fma_f32 v242, -v242, v245, v244
	v_div_fmas_f32 v242, v242, v243, v245
	v_div_fixup_f32 v239, v242, v241, 1.0
	v_mul_f32_e32 v241, 0xbfb8aa3b, v88
	v_exp_f32_e32 v241, v241
	s_nop 0
	v_add_f32_e32 v241, 1.0, v241
	v_div_scale_f32 v242, s[24:25], v241, v241, 1.0
	v_rcp_f32_e32 v243, v242
	s_nop 0
	v_fma_f32 v244, -v242, v243, 1.0
	v_fmac_f32_e32 v243, v244, v243
	v_div_scale_f32 v244, vcc, 1.0, v241, 1.0
	v_mul_f32_e32 v245, v244, v243
	v_fma_f32 v246, -v242, v245, v244
	v_fmac_f32_e32 v245, v246, v243
	v_fma_f32 v242, -v242, v245, v244
	v_div_fmas_f32 v242, v242, v243, v245
	v_div_fixup_f32 v240, v242, v241, 1.0
	v_mov_b32_e32 v168, 0
	v_mov_b32_e32 v169, 0
	v_mov_b32_e32 v170, 0
	v_mov_b32_e32 v171, 0
	v_mov_b32_e32 v172, 0
	v_mov_b32_e32 v173, 0
	v_mov_b32_e32 v174, 0
	v_mov_b32_e32 v175, 0
	v_mov_b32_e32 v176, 0
	v_mov_b32_e32 v177, 0
	v_mov_b32_e32 v178, 0
	v_mov_b32_e32 v179, 0
	v_mov_b32_e32 v180, 0
	v_mov_b32_e32 v181, 0
	v_mov_b32_e32 v182, 0
	v_mov_b32_e32 v183, 0
	v_mov_b32_e32 v184, 0
	v_mov_b32_e32 v185, 0
	v_mov_b32_e32 v186, 0
	v_mov_b32_e32 v187, 0
	global_load_dwordx4 v[228:231], v248, s[8:9] offset:2048
	s_waitcnt vmcnt(10)
	v_readlane_b32 s50, v236, 0
	v_readlane_b32 s52, v237, 0
	v_readlane_b32 s54, v238, 0
	v_readlane_b32 s56, v239, 0
	v_readlane_b32 s58, v240, 0
	v_pk_fma_f32 v[168:169], v[188:189], s[50:51], v[168:169] op_sel_hi:[1,0,1]
	v_pk_fma_f32 v[170:171], v[190:191], s[50:51], v[170:171] op_sel_hi:[1,0,1]
	v_pk_fma_f32 v[172:173], v[188:189], s[52:53], v[172:173] op_sel_hi:[1,0,1]
	v_pk_fma_f32 v[174:175], v[190:191], s[52:53], v[174:175] op_sel_hi:[1,0,1]
	v_pk_fma_f32 v[176:177], v[188:189], s[54:55], v[176:177] op_sel_hi:[1,0,1]
	v_pk_fma_f32 v[178:179], v[190:191], s[54:55], v[178:179] op_sel_hi:[1,0,1]
	v_pk_fma_f32 v[180:181], v[188:189], s[56:57], v[180:181] op_sel_hi:[1,0,1]
	v_pk_fma_f32 v[182:183], v[190:191], s[56:57], v[182:183] op_sel_hi:[1,0,1]
	v_pk_fma_f32 v[184:185], v[188:189], s[58:59], v[184:185] op_sel_hi:[1,0,1]
	v_pk_fma_f32 v[186:187], v[190:191], s[58:59], v[186:187] op_sel_hi:[1,0,1]
	global_load_dwordx4 v[232:235], v248, s[8:9] offset:3072
	s_add_u32 s8, s8, 0x1000
	s_addc_u32 s9, s9, 0
	s_waitcnt vmcnt(10)
	v_readlane_b32 s50, v236, 1
	v_readlane_b32 s52, v237, 1
	v_readlane_b32 s54, v238, 1
	v_readlane_b32 s56, v239, 1
	v_readlane_b32 s58, v240, 1
	v_pk_fma_f32 v[168:169], v[192:193], s[50:51], v[168:169] op_sel_hi:[1,0,1]
	v_pk_fma_f32 v[170:171], v[194:195], s[50:51], v[170:171] op_sel_hi:[1,0,1]
	v_pk_fma_f32 v[172:173], v[192:193], s[52:53], v[172:173] op_sel_hi:[1,0,1]
	v_pk_fma_f32 v[174:175], v[194:195], s[52:53], v[174:175] op_sel_hi:[1,0,1]
	v_pk_fma_f32 v[176:177], v[192:193], s[54:55], v[176:177] op_sel_hi:[1,0,1]
	v_pk_fma_f32 v[178:179], v[194:195], s[54:55], v[178:179] op_sel_hi:[1,0,1]
	v_pk_fma_f32 v[180:181], v[192:193], s[56:57], v[180:181] op_sel_hi:[1,0,1]
	v_pk_fma_f32 v[182:183], v[194:195], s[56:57], v[182:183] op_sel_hi:[1,0,1]
	v_pk_fma_f32 v[184:185], v[192:193], s[58:59], v[184:185] op_sel_hi:[1,0,1]
	v_pk_fma_f32 v[186:187], v[194:195], s[58:59], v[186:187] op_sel_hi:[1,0,1]
	global_load_dwordx4 v[188:191], v248, s[8:9]
	s_waitcnt vmcnt(10)
	v_readlane_b32 s50, v236, 2
	v_readlane_b32 s52, v237, 2
	v_readlane_b32 s54, v238, 2
	v_readlane_b32 s56, v239, 2
	v_readlane_b32 s58, v240, 2
	v_pk_fma_f32 v[168:169], v[196:197], s[50:51], v[168:169] op_sel_hi:[1,0,1]
	v_pk_fma_f32 v[170:171], v[198:199], s[50:51], v[170:171] op_sel_hi:[1,0,1]
	v_pk_fma_f32 v[172:173], v[196:197], s[52:53], v[172:173] op_sel_hi:[1,0,1]
	v_pk_fma_f32 v[174:175], v[198:199], s[52:53], v[174:175] op_sel_hi:[1,0,1]
	v_pk_fma_f32 v[176:177], v[196:197], s[54:55], v[176:177] op_sel_hi:[1,0,1]
	v_pk_fma_f32 v[178:179], v[198:199], s[54:55], v[178:179] op_sel_hi:[1,0,1]
	v_pk_fma_f32 v[180:181], v[196:197], s[56:57], v[180:181] op_sel_hi:[1,0,1]
	v_pk_fma_f32 v[182:183], v[198:199], s[56:57], v[182:183] op_sel_hi:[1,0,1]
	v_pk_fma_f32 v[184:185], v[196:197], s[58:59], v[184:185] op_sel_hi:[1,0,1]
	v_pk_fma_f32 v[186:187], v[198:199], s[58:59], v[186:187] op_sel_hi:[1,0,1]
	global_load_dwordx4 v[192:195], v248, s[8:9] offset:1024
	s_waitcnt vmcnt(10)
	v_readlane_b32 s50, v236, 3
	v_readlane_b32 s52, v237, 3
	v_readlane_b32 s54, v238, 3
	v_readlane_b32 s56, v239, 3
	v_readlane_b32 s58, v240, 3
	v_pk_fma_f32 v[168:169], v[200:201], s[50:51], v[168:169] op_sel_hi:[1,0,1]
	v_pk_fma_f32 v[170:171], v[202:203], s[50:51], v[170:171] op_sel_hi:[1,0,1]
	v_pk_fma_f32 v[172:173], v[200:201], s[52:53], v[172:173] op_sel_hi:[1,0,1]
	v_pk_fma_f32 v[174:175], v[202:203], s[52:53], v[174:175] op_sel_hi:[1,0,1]
	v_pk_fma_f32 v[176:177], v[200:201], s[54:55], v[176:177] op_sel_hi:[1,0,1]
	v_pk_fma_f32 v[178:179], v[202:203], s[54:55], v[178:179] op_sel_hi:[1,0,1]
	v_pk_fma_f32 v[180:181], v[200:201], s[56:57], v[180:181] op_sel_hi:[1,0,1]
	v_pk_fma_f32 v[182:183], v[202:203], s[56:57], v[182:183] op_sel_hi:[1,0,1]
	v_pk_fma_f32 v[184:185], v[200:201], s[58:59], v[184:185] op_sel_hi:[1,0,1]
	v_pk_fma_f32 v[186:187], v[202:203], s[58:59], v[186:187] op_sel_hi:[1,0,1]
	global_load_dwordx4 v[196:199], v248, s[8:9] offset:2048
	s_waitcnt vmcnt(10)
	v_readlane_b32 s50, v236, 4
	v_readlane_b32 s52, v237, 4
	v_readlane_b32 s54, v238, 4
	v_readlane_b32 s56, v239, 4
	v_readlane_b32 s58, v240, 4
	v_pk_fma_f32 v[168:169], v[204:205], s[50:51], v[168:169] op_sel_hi:[1,0,1]
	v_pk_fma_f32 v[170:171], v[206:207], s[50:51], v[170:171] op_sel_hi:[1,0,1]
	v_pk_fma_f32 v[172:173], v[204:205], s[52:53], v[172:173] op_sel_hi:[1,0,1]
	v_pk_fma_f32 v[174:175], v[206:207], s[52:53], v[174:175] op_sel_hi:[1,0,1]
	v_pk_fma_f32 v[176:177], v[204:205], s[54:55], v[176:177] op_sel_hi:[1,0,1]
	v_pk_fma_f32 v[178:179], v[206:207], s[54:55], v[178:179] op_sel_hi:[1,0,1]
	v_pk_fma_f32 v[180:181], v[204:205], s[56:57], v[180:181] op_sel_hi:[1,0,1]
	v_pk_fma_f32 v[182:183], v[206:207], s[56:57], v[182:183] op_sel_hi:[1,0,1]
	v_pk_fma_f32 v[184:185], v[204:205], s[58:59], v[184:185] op_sel_hi:[1,0,1]
	v_pk_fma_f32 v[186:187], v[206:207], s[58:59], v[186:187] op_sel_hi:[1,0,1]
	global_load_dwordx4 v[200:203], v248, s[8:9] offset:3072
	s_add_u32 s8, s8, 0x1000
	s_addc_u32 s9, s9, 0
	s_waitcnt vmcnt(10)
	v_readlane_b32 s50, v236, 5
	v_readlane_b32 s52, v237, 5
	v_readlane_b32 s54, v238, 5
	v_readlane_b32 s56, v239, 5
	v_readlane_b32 s58, v240, 5
	v_pk_fma_f32 v[168:169], v[208:209], s[50:51], v[168:169] op_sel_hi:[1,0,1]
	v_pk_fma_f32 v[170:171], v[210:211], s[50:51], v[170:171] op_sel_hi:[1,0,1]
	v_pk_fma_f32 v[172:173], v[208:209], s[52:53], v[172:173] op_sel_hi:[1,0,1]
	v_pk_fma_f32 v[174:175], v[210:211], s[52:53], v[174:175] op_sel_hi:[1,0,1]
	v_pk_fma_f32 v[176:177], v[208:209], s[54:55], v[176:177] op_sel_hi:[1,0,1]
	v_pk_fma_f32 v[178:179], v[210:211], s[54:55], v[178:179] op_sel_hi:[1,0,1]
	v_pk_fma_f32 v[180:181], v[208:209], s[56:57], v[180:181] op_sel_hi:[1,0,1]
	v_pk_fma_f32 v[182:183], v[210:211], s[56:57], v[182:183] op_sel_hi:[1,0,1]
	v_pk_fma_f32 v[184:185], v[208:209], s[58:59], v[184:185] op_sel_hi:[1,0,1]
	v_pk_fma_f32 v[186:187], v[210:211], s[58:59], v[186:187] op_sel_hi:[1,0,1]
	global_load_dwordx4 v[204:207], v248, s[8:9]
	s_waitcnt vmcnt(10)
	v_readlane_b32 s50, v236, 6
	v_readlane_b32 s52, v237, 6
	v_readlane_b32 s54, v238, 6
	v_readlane_b32 s56, v239, 6
	v_readlane_b32 s58, v240, 6
	v_pk_fma_f32 v[168:169], v[212:213], s[50:51], v[168:169] op_sel_hi:[1,0,1]
	v_pk_fma_f32 v[170:171], v[214:215], s[50:51], v[170:171] op_sel_hi:[1,0,1]
	v_pk_fma_f32 v[172:173], v[212:213], s[52:53], v[172:173] op_sel_hi:[1,0,1]
	v_pk_fma_f32 v[174:175], v[214:215], s[52:53], v[174:175] op_sel_hi:[1,0,1]
	v_pk_fma_f32 v[176:177], v[212:213], s[54:55], v[176:177] op_sel_hi:[1,0,1]
	v_pk_fma_f32 v[178:179], v[214:215], s[54:55], v[178:179] op_sel_hi:[1,0,1]
	v_pk_fma_f32 v[180:181], v[212:213], s[56:57], v[180:181] op_sel_hi:[1,0,1]
	v_pk_fma_f32 v[182:183], v[214:215], s[56:57], v[182:183] op_sel_hi:[1,0,1]
	v_pk_fma_f32 v[184:185], v[212:213], s[58:59], v[184:185] op_sel_hi:[1,0,1]
	v_pk_fma_f32 v[186:187], v[214:215], s[58:59], v[186:187] op_sel_hi:[1,0,1]
	global_load_dwordx4 v[208:211], v248, s[8:9] offset:1024
	s_waitcnt vmcnt(10)
	v_readlane_b32 s50, v236, 7
	v_readlane_b32 s52, v237, 7
	v_readlane_b32 s54, v238, 7
	v_readlane_b32 s56, v239, 7
	v_readlane_b32 s58, v240, 7
	v_pk_fma_f32 v[168:169], v[216:217], s[50:51], v[168:169] op_sel_hi:[1,0,1]
	v_pk_fma_f32 v[170:171], v[218:219], s[50:51], v[170:171] op_sel_hi:[1,0,1]
	v_pk_fma_f32 v[172:173], v[216:217], s[52:53], v[172:173] op_sel_hi:[1,0,1]
	v_pk_fma_f32 v[174:175], v[218:219], s[52:53], v[174:175] op_sel_hi:[1,0,1]
	v_pk_fma_f32 v[176:177], v[216:217], s[54:55], v[176:177] op_sel_hi:[1,0,1]
	v_pk_fma_f32 v[178:179], v[218:219], s[54:55], v[178:179] op_sel_hi:[1,0,1]
	v_pk_fma_f32 v[180:181], v[216:217], s[56:57], v[180:181] op_sel_hi:[1,0,1]
	v_pk_fma_f32 v[182:183], v[218:219], s[56:57], v[182:183] op_sel_hi:[1,0,1]
	v_pk_fma_f32 v[184:185], v[216:217], s[58:59], v[184:185] op_sel_hi:[1,0,1]
	v_pk_fma_f32 v[186:187], v[218:219], s[58:59], v[186:187] op_sel_hi:[1,0,1]
	global_load_dwordx4 v[212:215], v248, s[8:9] offset:2048
	s_waitcnt vmcnt(10)
	v_readlane_b32 s50, v236, 8
	v_readlane_b32 s52, v237, 8
	v_readlane_b32 s54, v238, 8
	v_readlane_b32 s56, v239, 8
	v_readlane_b32 s58, v240, 8
	v_pk_fma_f32 v[168:169], v[220:221], s[50:51], v[168:169] op_sel_hi:[1,0,1]
	v_pk_fma_f32 v[170:171], v[222:223], s[50:51], v[170:171] op_sel_hi:[1,0,1]
	v_pk_fma_f32 v[172:173], v[220:221], s[52:53], v[172:173] op_sel_hi:[1,0,1]
	v_pk_fma_f32 v[174:175], v[222:223], s[52:53], v[174:175] op_sel_hi:[1,0,1]
	v_pk_fma_f32 v[176:177], v[220:221], s[54:55], v[176:177] op_sel_hi:[1,0,1]
	v_pk_fma_f32 v[178:179], v[222:223], s[54:55], v[178:179] op_sel_hi:[1,0,1]
	v_pk_fma_f32 v[180:181], v[220:221], s[56:57], v[180:181] op_sel_hi:[1,0,1]
	v_pk_fma_f32 v[182:183], v[222:223], s[56:57], v[182:183] op_sel_hi:[1,0,1]
	v_pk_fma_f32 v[184:185], v[220:221], s[58:59], v[184:185] op_sel_hi:[1,0,1]
	v_pk_fma_f32 v[186:187], v[222:223], s[58:59], v[186:187] op_sel_hi:[1,0,1]
	global_load_dwordx4 v[216:219], v248, s[8:9] offset:3072
	s_add_u32 s8, s8, 0x1000
	s_addc_u32 s9, s9, 0
	s_waitcnt vmcnt(10)
	v_readlane_b32 s50, v236, 9
	v_readlane_b32 s52, v237, 9
	v_readlane_b32 s54, v238, 9
	v_readlane_b32 s56, v239, 9
	v_readlane_b32 s58, v240, 9
	v_pk_fma_f32 v[168:169], v[224:225], s[50:51], v[168:169] op_sel_hi:[1,0,1]
	v_pk_fma_f32 v[170:171], v[226:227], s[50:51], v[170:171] op_sel_hi:[1,0,1]
	v_pk_fma_f32 v[172:173], v[224:225], s[52:53], v[172:173] op_sel_hi:[1,0,1]
	v_pk_fma_f32 v[174:175], v[226:227], s[52:53], v[174:175] op_sel_hi:[1,0,1]
	v_pk_fma_f32 v[176:177], v[224:225], s[54:55], v[176:177] op_sel_hi:[1,0,1]
	v_pk_fma_f32 v[178:179], v[226:227], s[54:55], v[178:179] op_sel_hi:[1,0,1]
	v_pk_fma_f32 v[180:181], v[224:225], s[56:57], v[180:181] op_sel_hi:[1,0,1]
	v_pk_fma_f32 v[182:183], v[226:227], s[56:57], v[182:183] op_sel_hi:[1,0,1]
	v_pk_fma_f32 v[184:185], v[224:225], s[58:59], v[184:185] op_sel_hi:[1,0,1]
	v_pk_fma_f32 v[186:187], v[226:227], s[58:59], v[186:187] op_sel_hi:[1,0,1]
	global_load_dwordx4 v[220:223], v248, s[8:9]
	s_waitcnt vmcnt(10)
	v_readlane_b32 s50, v236, 10
	v_readlane_b32 s52, v237, 10
	v_readlane_b32 s54, v238, 10
	v_readlane_b32 s56, v239, 10
	v_readlane_b32 s58, v240, 10
	v_pk_fma_f32 v[168:169], v[228:229], s[50:51], v[168:169] op_sel_hi:[1,0,1]
	v_pk_fma_f32 v[170:171], v[230:231], s[50:51], v[170:171] op_sel_hi:[1,0,1]
	v_pk_fma_f32 v[172:173], v[228:229], s[52:53], v[172:173] op_sel_hi:[1,0,1]
	v_pk_fma_f32 v[174:175], v[230:231], s[52:53], v[174:175] op_sel_hi:[1,0,1]
	v_pk_fma_f32 v[176:177], v[228:229], s[54:55], v[176:177] op_sel_hi:[1,0,1]
	v_pk_fma_f32 v[178:179], v[230:231], s[54:55], v[178:179] op_sel_hi:[1,0,1]
	v_pk_fma_f32 v[180:181], v[228:229], s[56:57], v[180:181] op_sel_hi:[1,0,1]
	v_pk_fma_f32 v[182:183], v[230:231], s[56:57], v[182:183] op_sel_hi:[1,0,1]
	v_pk_fma_f32 v[184:185], v[228:229], s[58:59], v[184:185] op_sel_hi:[1,0,1]
	v_pk_fma_f32 v[186:187], v[230:231], s[58:59], v[186:187] op_sel_hi:[1,0,1]
	global_load_dwordx4 v[224:227], v248, s[8:9] offset:1024
	s_waitcnt vmcnt(10)
	v_readlane_b32 s50, v236, 11
	v_readlane_b32 s52, v237, 11
	v_readlane_b32 s54, v238, 11
	v_readlane_b32 s56, v239, 11
	v_readlane_b32 s58, v240, 11
	v_pk_fma_f32 v[168:169], v[232:233], s[50:51], v[168:169] op_sel_hi:[1,0,1]
	v_pk_fma_f32 v[170:171], v[234:235], s[50:51], v[170:171] op_sel_hi:[1,0,1]
	v_pk_fma_f32 v[172:173], v[232:233], s[52:53], v[172:173] op_sel_hi:[1,0,1]
	v_pk_fma_f32 v[174:175], v[234:235], s[52:53], v[174:175] op_sel_hi:[1,0,1]
	v_pk_fma_f32 v[176:177], v[232:233], s[54:55], v[176:177] op_sel_hi:[1,0,1]
	v_pk_fma_f32 v[178:179], v[234:235], s[54:55], v[178:179] op_sel_hi:[1,0,1]
	v_pk_fma_f32 v[180:181], v[232:233], s[56:57], v[180:181] op_sel_hi:[1,0,1]
	v_pk_fma_f32 v[182:183], v[234:235], s[56:57], v[182:183] op_sel_hi:[1,0,1]
	v_pk_fma_f32 v[184:185], v[232:233], s[58:59], v[184:185] op_sel_hi:[1,0,1]
	v_pk_fma_f32 v[186:187], v[234:235], s[58:59], v[186:187] op_sel_hi:[1,0,1]
	global_load_dwordx4 v[228:231], v248, s[8:9] offset:2048
	s_waitcnt vmcnt(10)
	v_readlane_b32 s50, v236, 12
	v_readlane_b32 s52, v237, 12
	v_readlane_b32 s54, v238, 12
	v_readlane_b32 s56, v239, 12
	v_readlane_b32 s58, v240, 12
	v_pk_fma_f32 v[168:169], v[188:189], s[50:51], v[168:169] op_sel_hi:[1,0,1]
	v_pk_fma_f32 v[170:171], v[190:191], s[50:51], v[170:171] op_sel_hi:[1,0,1]
	v_pk_fma_f32 v[172:173], v[188:189], s[52:53], v[172:173] op_sel_hi:[1,0,1]
	v_pk_fma_f32 v[174:175], v[190:191], s[52:53], v[174:175] op_sel_hi:[1,0,1]
	v_pk_fma_f32 v[176:177], v[188:189], s[54:55], v[176:177] op_sel_hi:[1,0,1]
	v_pk_fma_f32 v[178:179], v[190:191], s[54:55], v[178:179] op_sel_hi:[1,0,1]
	v_pk_fma_f32 v[180:181], v[188:189], s[56:57], v[180:181] op_sel_hi:[1,0,1]
	v_pk_fma_f32 v[182:183], v[190:191], s[56:57], v[182:183] op_sel_hi:[1,0,1]
	v_pk_fma_f32 v[184:185], v[188:189], s[58:59], v[184:185] op_sel_hi:[1,0,1]
	v_pk_fma_f32 v[186:187], v[190:191], s[58:59], v[186:187] op_sel_hi:[1,0,1]
	global_load_dwordx4 v[232:235], v248, s[8:9] offset:3072
	s_add_u32 s8, s8, 0x1000
	s_addc_u32 s9, s9, 0
	s_waitcnt vmcnt(10)
	v_readlane_b32 s50, v236, 13
	v_readlane_b32 s52, v237, 13
	v_readlane_b32 s54, v238, 13
	v_readlane_b32 s56, v239, 13
	v_readlane_b32 s58, v240, 13
	v_pk_fma_f32 v[168:169], v[192:193], s[50:51], v[168:169] op_sel_hi:[1,0,1]
	v_pk_fma_f32 v[170:171], v[194:195], s[50:51], v[170:171] op_sel_hi:[1,0,1]
	v_pk_fma_f32 v[172:173], v[192:193], s[52:53], v[172:173] op_sel_hi:[1,0,1]
	v_pk_fma_f32 v[174:175], v[194:195], s[52:53], v[174:175] op_sel_hi:[1,0,1]
	v_pk_fma_f32 v[176:177], v[192:193], s[54:55], v[176:177] op_sel_hi:[1,0,1]
	v_pk_fma_f32 v[178:179], v[194:195], s[54:55], v[178:179] op_sel_hi:[1,0,1]
	v_pk_fma_f32 v[180:181], v[192:193], s[56:57], v[180:181] op_sel_hi:[1,0,1]
	v_pk_fma_f32 v[182:183], v[194:195], s[56:57], v[182:183] op_sel_hi:[1,0,1]
	v_pk_fma_f32 v[184:185], v[192:193], s[58:59], v[184:185] op_sel_hi:[1,0,1]
	v_pk_fma_f32 v[186:187], v[194:195], s[58:59], v[186:187] op_sel_hi:[1,0,1]
	global_load_dwordx4 v[188:191], v248, s[8:9]
	s_waitcnt vmcnt(10)
	v_readlane_b32 s50, v236, 14
	v_readlane_b32 s52, v237, 14
	v_readlane_b32 s54, v238, 14
	v_readlane_b32 s56, v239, 14
	v_readlane_b32 s58, v240, 14
	v_pk_fma_f32 v[168:169], v[196:197], s[50:51], v[168:169] op_sel_hi:[1,0,1]
	v_pk_fma_f32 v[170:171], v[198:199], s[50:51], v[170:171] op_sel_hi:[1,0,1]
	v_pk_fma_f32 v[172:173], v[196:197], s[52:53], v[172:173] op_sel_hi:[1,0,1]
	v_pk_fma_f32 v[174:175], v[198:199], s[52:53], v[174:175] op_sel_hi:[1,0,1]
	v_pk_fma_f32 v[176:177], v[196:197], s[54:55], v[176:177] op_sel_hi:[1,0,1]
	v_pk_fma_f32 v[178:179], v[198:199], s[54:55], v[178:179] op_sel_hi:[1,0,1]
	v_pk_fma_f32 v[180:181], v[196:197], s[56:57], v[180:181] op_sel_hi:[1,0,1]
	v_pk_fma_f32 v[182:183], v[198:199], s[56:57], v[182:183] op_sel_hi:[1,0,1]
	v_pk_fma_f32 v[184:185], v[196:197], s[58:59], v[184:185] op_sel_hi:[1,0,1]
	v_pk_fma_f32 v[186:187], v[198:199], s[58:59], v[186:187] op_sel_hi:[1,0,1]
	global_load_dwordx4 v[192:195], v248, s[8:9] offset:1024
	s_waitcnt vmcnt(10)
	v_readlane_b32 s50, v236, 15
	v_readlane_b32 s52, v237, 15
	v_readlane_b32 s54, v238, 15
	v_readlane_b32 s56, v239, 15
	v_readlane_b32 s58, v240, 15
	v_pk_fma_f32 v[168:169], v[200:201], s[50:51], v[168:169] op_sel_hi:[1,0,1]
	v_pk_fma_f32 v[170:171], v[202:203], s[50:51], v[170:171] op_sel_hi:[1,0,1]
	v_pk_fma_f32 v[172:173], v[200:201], s[52:53], v[172:173] op_sel_hi:[1,0,1]
	v_pk_fma_f32 v[174:175], v[202:203], s[52:53], v[174:175] op_sel_hi:[1,0,1]
	v_pk_fma_f32 v[176:177], v[200:201], s[54:55], v[176:177] op_sel_hi:[1,0,1]
	v_pk_fma_f32 v[178:179], v[202:203], s[54:55], v[178:179] op_sel_hi:[1,0,1]
	v_pk_fma_f32 v[180:181], v[200:201], s[56:57], v[180:181] op_sel_hi:[1,0,1]
	v_pk_fma_f32 v[182:183], v[202:203], s[56:57], v[182:183] op_sel_hi:[1,0,1]
	v_pk_fma_f32 v[184:185], v[200:201], s[58:59], v[184:185] op_sel_hi:[1,0,1]
	v_pk_fma_f32 v[186:187], v[202:203], s[58:59], v[186:187] op_sel_hi:[1,0,1]
	global_load_dwordx4 v[196:199], v248, s[8:9] offset:2048
	s_waitcnt vmcnt(10)
	v_readlane_b32 s50, v236, 16
	v_readlane_b32 s52, v237, 16
	v_readlane_b32 s54, v238, 16
	v_readlane_b32 s56, v239, 16
	v_readlane_b32 s58, v240, 16
	v_pk_fma_f32 v[168:169], v[204:205], s[50:51], v[168:169] op_sel_hi:[1,0,1]
	v_pk_fma_f32 v[170:171], v[206:207], s[50:51], v[170:171] op_sel_hi:[1,0,1]
	v_pk_fma_f32 v[172:173], v[204:205], s[52:53], v[172:173] op_sel_hi:[1,0,1]
	v_pk_fma_f32 v[174:175], v[206:207], s[52:53], v[174:175] op_sel_hi:[1,0,1]
	v_pk_fma_f32 v[176:177], v[204:205], s[54:55], v[176:177] op_sel_hi:[1,0,1]
	v_pk_fma_f32 v[178:179], v[206:207], s[54:55], v[178:179] op_sel_hi:[1,0,1]
	v_pk_fma_f32 v[180:181], v[204:205], s[56:57], v[180:181] op_sel_hi:[1,0,1]
	v_pk_fma_f32 v[182:183], v[206:207], s[56:57], v[182:183] op_sel_hi:[1,0,1]
	v_pk_fma_f32 v[184:185], v[204:205], s[58:59], v[184:185] op_sel_hi:[1,0,1]
	v_pk_fma_f32 v[186:187], v[206:207], s[58:59], v[186:187] op_sel_hi:[1,0,1]
	global_load_dwordx4 v[200:203], v248, s[8:9] offset:3072
	s_add_u32 s8, s8, 0x1000
	s_addc_u32 s9, s9, 0
	s_waitcnt vmcnt(10)
	v_readlane_b32 s50, v236, 17
	v_readlane_b32 s52, v237, 17
	v_readlane_b32 s54, v238, 17
	v_readlane_b32 s56, v239, 17
	v_readlane_b32 s58, v240, 17
	v_pk_fma_f32 v[168:169], v[208:209], s[50:51], v[168:169] op_sel_hi:[1,0,1]
	v_pk_fma_f32 v[170:171], v[210:211], s[50:51], v[170:171] op_sel_hi:[1,0,1]
	v_pk_fma_f32 v[172:173], v[208:209], s[52:53], v[172:173] op_sel_hi:[1,0,1]
	v_pk_fma_f32 v[174:175], v[210:211], s[52:53], v[174:175] op_sel_hi:[1,0,1]
	v_pk_fma_f32 v[176:177], v[208:209], s[54:55], v[176:177] op_sel_hi:[1,0,1]
	v_pk_fma_f32 v[178:179], v[210:211], s[54:55], v[178:179] op_sel_hi:[1,0,1]
	v_pk_fma_f32 v[180:181], v[208:209], s[56:57], v[180:181] op_sel_hi:[1,0,1]
	v_pk_fma_f32 v[182:183], v[210:211], s[56:57], v[182:183] op_sel_hi:[1,0,1]
	v_pk_fma_f32 v[184:185], v[208:209], s[58:59], v[184:185] op_sel_hi:[1,0,1]
	v_pk_fma_f32 v[186:187], v[210:211], s[58:59], v[186:187] op_sel_hi:[1,0,1]
	global_load_dwordx4 v[204:207], v248, s[8:9]
	s_waitcnt vmcnt(10)
	v_readlane_b32 s50, v236, 18
	v_readlane_b32 s52, v237, 18
	v_readlane_b32 s54, v238, 18
	v_readlane_b32 s56, v239, 18
	v_readlane_b32 s58, v240, 18
	v_pk_fma_f32 v[168:169], v[212:213], s[50:51], v[168:169] op_sel_hi:[1,0,1]
	v_pk_fma_f32 v[170:171], v[214:215], s[50:51], v[170:171] op_sel_hi:[1,0,1]
	v_pk_fma_f32 v[172:173], v[212:213], s[52:53], v[172:173] op_sel_hi:[1,0,1]
	v_pk_fma_f32 v[174:175], v[214:215], s[52:53], v[174:175] op_sel_hi:[1,0,1]
	v_pk_fma_f32 v[176:177], v[212:213], s[54:55], v[176:177] op_sel_hi:[1,0,1]
	v_pk_fma_f32 v[178:179], v[214:215], s[54:55], v[178:179] op_sel_hi:[1,0,1]
	v_pk_fma_f32 v[180:181], v[212:213], s[56:57], v[180:181] op_sel_hi:[1,0,1]
	v_pk_fma_f32 v[182:183], v[214:215], s[56:57], v[182:183] op_sel_hi:[1,0,1]
	v_pk_fma_f32 v[184:185], v[212:213], s[58:59], v[184:185] op_sel_hi:[1,0,1]
	v_pk_fma_f32 v[186:187], v[214:215], s[58:59], v[186:187] op_sel_hi:[1,0,1]
	global_load_dwordx4 v[208:211], v248, s[8:9] offset:1024
	s_waitcnt vmcnt(10)
	v_readlane_b32 s50, v236, 19
	v_readlane_b32 s52, v237, 19
	v_readlane_b32 s54, v238, 19
	v_readlane_b32 s56, v239, 19
	v_readlane_b32 s58, v240, 19
	v_pk_fma_f32 v[168:169], v[216:217], s[50:51], v[168:169] op_sel_hi:[1,0,1]
	v_pk_fma_f32 v[170:171], v[218:219], s[50:51], v[170:171] op_sel_hi:[1,0,1]
	v_pk_fma_f32 v[172:173], v[216:217], s[52:53], v[172:173] op_sel_hi:[1,0,1]
	v_pk_fma_f32 v[174:175], v[218:219], s[52:53], v[174:175] op_sel_hi:[1,0,1]
	v_pk_fma_f32 v[176:177], v[216:217], s[54:55], v[176:177] op_sel_hi:[1,0,1]
	v_pk_fma_f32 v[178:179], v[218:219], s[54:55], v[178:179] op_sel_hi:[1,0,1]
	v_pk_fma_f32 v[180:181], v[216:217], s[56:57], v[180:181] op_sel_hi:[1,0,1]
	v_pk_fma_f32 v[182:183], v[218:219], s[56:57], v[182:183] op_sel_hi:[1,0,1]
	v_pk_fma_f32 v[184:185], v[216:217], s[58:59], v[184:185] op_sel_hi:[1,0,1]
	v_pk_fma_f32 v[186:187], v[218:219], s[58:59], v[186:187] op_sel_hi:[1,0,1]
	global_load_dwordx4 v[212:215], v248, s[8:9] offset:2048
	s_waitcnt vmcnt(10)
	v_readlane_b32 s50, v236, 20
	v_readlane_b32 s52, v237, 20
	v_readlane_b32 s54, v238, 20
	v_readlane_b32 s56, v239, 20
	v_readlane_b32 s58, v240, 20
	v_pk_fma_f32 v[168:169], v[220:221], s[50:51], v[168:169] op_sel_hi:[1,0,1]
	v_pk_fma_f32 v[170:171], v[222:223], s[50:51], v[170:171] op_sel_hi:[1,0,1]
	v_pk_fma_f32 v[172:173], v[220:221], s[52:53], v[172:173] op_sel_hi:[1,0,1]
	v_pk_fma_f32 v[174:175], v[222:223], s[52:53], v[174:175] op_sel_hi:[1,0,1]
	v_pk_fma_f32 v[176:177], v[220:221], s[54:55], v[176:177] op_sel_hi:[1,0,1]
	v_pk_fma_f32 v[178:179], v[222:223], s[54:55], v[178:179] op_sel_hi:[1,0,1]
	v_pk_fma_f32 v[180:181], v[220:221], s[56:57], v[180:181] op_sel_hi:[1,0,1]
	v_pk_fma_f32 v[182:183], v[222:223], s[56:57], v[182:183] op_sel_hi:[1,0,1]
	v_pk_fma_f32 v[184:185], v[220:221], s[58:59], v[184:185] op_sel_hi:[1,0,1]
	v_pk_fma_f32 v[186:187], v[222:223], s[58:59], v[186:187] op_sel_hi:[1,0,1]
	global_load_dwordx4 v[216:219], v248, s[8:9] offset:3072
	s_add_u32 s8, s8, 0x1000
	s_addc_u32 s9, s9, 0
	s_waitcnt vmcnt(10)
	v_readlane_b32 s50, v236, 21
	v_readlane_b32 s52, v237, 21
	v_readlane_b32 s54, v238, 21
	v_readlane_b32 s56, v239, 21
	v_readlane_b32 s58, v240, 21
	v_pk_fma_f32 v[168:169], v[224:225], s[50:51], v[168:169] op_sel_hi:[1,0,1]
	v_pk_fma_f32 v[170:171], v[226:227], s[50:51], v[170:171] op_sel_hi:[1,0,1]
	v_pk_fma_f32 v[172:173], v[224:225], s[52:53], v[172:173] op_sel_hi:[1,0,1]
	v_pk_fma_f32 v[174:175], v[226:227], s[52:53], v[174:175] op_sel_hi:[1,0,1]
	v_pk_fma_f32 v[176:177], v[224:225], s[54:55], v[176:177] op_sel_hi:[1,0,1]
	v_pk_fma_f32 v[178:179], v[226:227], s[54:55], v[178:179] op_sel_hi:[1,0,1]
	v_pk_fma_f32 v[180:181], v[224:225], s[56:57], v[180:181] op_sel_hi:[1,0,1]
	v_pk_fma_f32 v[182:183], v[226:227], s[56:57], v[182:183] op_sel_hi:[1,0,1]
	v_pk_fma_f32 v[184:185], v[224:225], s[58:59], v[184:185] op_sel_hi:[1,0,1]
	v_pk_fma_f32 v[186:187], v[226:227], s[58:59], v[186:187] op_sel_hi:[1,0,1]
	global_load_dwordx4 v[220:223], v248, s[8:9]
	s_waitcnt vmcnt(10)
	v_readlane_b32 s50, v236, 22
	v_readlane_b32 s52, v237, 22
	v_readlane_b32 s54, v238, 22
	v_readlane_b32 s56, v239, 22
	v_readlane_b32 s58, v240, 22
	v_pk_fma_f32 v[168:169], v[228:229], s[50:51], v[168:169] op_sel_hi:[1,0,1]
	v_pk_fma_f32 v[170:171], v[230:231], s[50:51], v[170:171] op_sel_hi:[1,0,1]
	v_pk_fma_f32 v[172:173], v[228:229], s[52:53], v[172:173] op_sel_hi:[1,0,1]
	v_pk_fma_f32 v[174:175], v[230:231], s[52:53], v[174:175] op_sel_hi:[1,0,1]
	v_pk_fma_f32 v[176:177], v[228:229], s[54:55], v[176:177] op_sel_hi:[1,0,1]
	v_pk_fma_f32 v[178:179], v[230:231], s[54:55], v[178:179] op_sel_hi:[1,0,1]
	v_pk_fma_f32 v[180:181], v[228:229], s[56:57], v[180:181] op_sel_hi:[1,0,1]
	v_pk_fma_f32 v[182:183], v[230:231], s[56:57], v[182:183] op_sel_hi:[1,0,1]
	v_pk_fma_f32 v[184:185], v[228:229], s[58:59], v[184:185] op_sel_hi:[1,0,1]
	v_pk_fma_f32 v[186:187], v[230:231], s[58:59], v[186:187] op_sel_hi:[1,0,1]
	global_load_dwordx4 v[224:227], v248, s[8:9] offset:1024
	s_waitcnt vmcnt(10)
	v_readlane_b32 s50, v236, 23
	v_readlane_b32 s52, v237, 23
	v_readlane_b32 s54, v238, 23
	v_readlane_b32 s56, v239, 23
	v_readlane_b32 s58, v240, 23
	v_pk_fma_f32 v[168:169], v[232:233], s[50:51], v[168:169] op_sel_hi:[1,0,1]
	v_pk_fma_f32 v[170:171], v[234:235], s[50:51], v[170:171] op_sel_hi:[1,0,1]
	v_pk_fma_f32 v[172:173], v[232:233], s[52:53], v[172:173] op_sel_hi:[1,0,1]
	v_pk_fma_f32 v[174:175], v[234:235], s[52:53], v[174:175] op_sel_hi:[1,0,1]
	v_pk_fma_f32 v[176:177], v[232:233], s[54:55], v[176:177] op_sel_hi:[1,0,1]
	v_pk_fma_f32 v[178:179], v[234:235], s[54:55], v[178:179] op_sel_hi:[1,0,1]
	v_pk_fma_f32 v[180:181], v[232:233], s[56:57], v[180:181] op_sel_hi:[1,0,1]
	v_pk_fma_f32 v[182:183], v[234:235], s[56:57], v[182:183] op_sel_hi:[1,0,1]
	v_pk_fma_f32 v[184:185], v[232:233], s[58:59], v[184:185] op_sel_hi:[1,0,1]
	v_pk_fma_f32 v[186:187], v[234:235], s[58:59], v[186:187] op_sel_hi:[1,0,1]
	global_load_dwordx4 v[228:231], v248, s[8:9] offset:2048
	s_waitcnt vmcnt(10)
	v_readlane_b32 s50, v236, 24
	v_readlane_b32 s52, v237, 24
	v_readlane_b32 s54, v238, 24
	v_readlane_b32 s56, v239, 24
	v_readlane_b32 s58, v240, 24
	v_pk_fma_f32 v[168:169], v[188:189], s[50:51], v[168:169] op_sel_hi:[1,0,1]
	v_pk_fma_f32 v[170:171], v[190:191], s[50:51], v[170:171] op_sel_hi:[1,0,1]
	v_pk_fma_f32 v[172:173], v[188:189], s[52:53], v[172:173] op_sel_hi:[1,0,1]
	v_pk_fma_f32 v[174:175], v[190:191], s[52:53], v[174:175] op_sel_hi:[1,0,1]
	v_pk_fma_f32 v[176:177], v[188:189], s[54:55], v[176:177] op_sel_hi:[1,0,1]
	v_pk_fma_f32 v[178:179], v[190:191], s[54:55], v[178:179] op_sel_hi:[1,0,1]
	v_pk_fma_f32 v[180:181], v[188:189], s[56:57], v[180:181] op_sel_hi:[1,0,1]
	v_pk_fma_f32 v[182:183], v[190:191], s[56:57], v[182:183] op_sel_hi:[1,0,1]
	v_pk_fma_f32 v[184:185], v[188:189], s[58:59], v[184:185] op_sel_hi:[1,0,1]
	v_pk_fma_f32 v[186:187], v[190:191], s[58:59], v[186:187] op_sel_hi:[1,0,1]
	global_load_dwordx4 v[232:235], v248, s[8:9] offset:3072
	s_add_u32 s8, s8, 0x1000
	s_addc_u32 s9, s9, 0
	s_waitcnt vmcnt(10)
	v_readlane_b32 s50, v236, 25
	v_readlane_b32 s52, v237, 25
	v_readlane_b32 s54, v238, 25
	v_readlane_b32 s56, v239, 25
	v_readlane_b32 s58, v240, 25
	v_pk_fma_f32 v[168:169], v[192:193], s[50:51], v[168:169] op_sel_hi:[1,0,1]
	v_pk_fma_f32 v[170:171], v[194:195], s[50:51], v[170:171] op_sel_hi:[1,0,1]
	v_pk_fma_f32 v[172:173], v[192:193], s[52:53], v[172:173] op_sel_hi:[1,0,1]
	v_pk_fma_f32 v[174:175], v[194:195], s[52:53], v[174:175] op_sel_hi:[1,0,1]
	v_pk_fma_f32 v[176:177], v[192:193], s[54:55], v[176:177] op_sel_hi:[1,0,1]
	v_pk_fma_f32 v[178:179], v[194:195], s[54:55], v[178:179] op_sel_hi:[1,0,1]
	v_pk_fma_f32 v[180:181], v[192:193], s[56:57], v[180:181] op_sel_hi:[1,0,1]
	v_pk_fma_f32 v[182:183], v[194:195], s[56:57], v[182:183] op_sel_hi:[1,0,1]
	v_pk_fma_f32 v[184:185], v[192:193], s[58:59], v[184:185] op_sel_hi:[1,0,1]
	v_pk_fma_f32 v[186:187], v[194:195], s[58:59], v[186:187] op_sel_hi:[1,0,1]
	global_load_dwordx4 v[188:191], v248, s[8:9]
	s_waitcnt vmcnt(10)
	v_readlane_b32 s50, v236, 26
	v_readlane_b32 s52, v237, 26
	v_readlane_b32 s54, v238, 26
	v_readlane_b32 s56, v239, 26
	v_readlane_b32 s58, v240, 26
	v_pk_fma_f32 v[168:169], v[196:197], s[50:51], v[168:169] op_sel_hi:[1,0,1]
	v_pk_fma_f32 v[170:171], v[198:199], s[50:51], v[170:171] op_sel_hi:[1,0,1]
	v_pk_fma_f32 v[172:173], v[196:197], s[52:53], v[172:173] op_sel_hi:[1,0,1]
	v_pk_fma_f32 v[174:175], v[198:199], s[52:53], v[174:175] op_sel_hi:[1,0,1]
	v_pk_fma_f32 v[176:177], v[196:197], s[54:55], v[176:177] op_sel_hi:[1,0,1]
	v_pk_fma_f32 v[178:179], v[198:199], s[54:55], v[178:179] op_sel_hi:[1,0,1]
	v_pk_fma_f32 v[180:181], v[196:197], s[56:57], v[180:181] op_sel_hi:[1,0,1]
	v_pk_fma_f32 v[182:183], v[198:199], s[56:57], v[182:183] op_sel_hi:[1,0,1]
	v_pk_fma_f32 v[184:185], v[196:197], s[58:59], v[184:185] op_sel_hi:[1,0,1]
	v_pk_fma_f32 v[186:187], v[198:199], s[58:59], v[186:187] op_sel_hi:[1,0,1]
	global_load_dwordx4 v[192:195], v248, s[8:9] offset:1024
	s_waitcnt vmcnt(10)
	v_readlane_b32 s50, v236, 27
	v_readlane_b32 s52, v237, 27
	v_readlane_b32 s54, v238, 27
	v_readlane_b32 s56, v239, 27
	v_readlane_b32 s58, v240, 27
	v_pk_fma_f32 v[168:169], v[200:201], s[50:51], v[168:169] op_sel_hi:[1,0,1]
	v_pk_fma_f32 v[170:171], v[202:203], s[50:51], v[170:171] op_sel_hi:[1,0,1]
	v_pk_fma_f32 v[172:173], v[200:201], s[52:53], v[172:173] op_sel_hi:[1,0,1]
	v_pk_fma_f32 v[174:175], v[202:203], s[52:53], v[174:175] op_sel_hi:[1,0,1]
	v_pk_fma_f32 v[176:177], v[200:201], s[54:55], v[176:177] op_sel_hi:[1,0,1]
	v_pk_fma_f32 v[178:179], v[202:203], s[54:55], v[178:179] op_sel_hi:[1,0,1]
	v_pk_fma_f32 v[180:181], v[200:201], s[56:57], v[180:181] op_sel_hi:[1,0,1]
	v_pk_fma_f32 v[182:183], v[202:203], s[56:57], v[182:183] op_sel_hi:[1,0,1]
	v_pk_fma_f32 v[184:185], v[200:201], s[58:59], v[184:185] op_sel_hi:[1,0,1]
	v_pk_fma_f32 v[186:187], v[202:203], s[58:59], v[186:187] op_sel_hi:[1,0,1]
	global_load_dwordx4 v[196:199], v248, s[8:9] offset:2048
	s_waitcnt vmcnt(10)
	v_readlane_b32 s50, v236, 28
	v_readlane_b32 s52, v237, 28
	v_readlane_b32 s54, v238, 28
	v_readlane_b32 s56, v239, 28
	v_readlane_b32 s58, v240, 28
	v_pk_fma_f32 v[168:169], v[204:205], s[50:51], v[168:169] op_sel_hi:[1,0,1]
	v_pk_fma_f32 v[170:171], v[206:207], s[50:51], v[170:171] op_sel_hi:[1,0,1]
	v_pk_fma_f32 v[172:173], v[204:205], s[52:53], v[172:173] op_sel_hi:[1,0,1]
	v_pk_fma_f32 v[174:175], v[206:207], s[52:53], v[174:175] op_sel_hi:[1,0,1]
	v_pk_fma_f32 v[176:177], v[204:205], s[54:55], v[176:177] op_sel_hi:[1,0,1]
	v_pk_fma_f32 v[178:179], v[206:207], s[54:55], v[178:179] op_sel_hi:[1,0,1]
	v_pk_fma_f32 v[180:181], v[204:205], s[56:57], v[180:181] op_sel_hi:[1,0,1]
	v_pk_fma_f32 v[182:183], v[206:207], s[56:57], v[182:183] op_sel_hi:[1,0,1]
	v_pk_fma_f32 v[184:185], v[204:205], s[58:59], v[184:185] op_sel_hi:[1,0,1]
	v_pk_fma_f32 v[186:187], v[206:207], s[58:59], v[186:187] op_sel_hi:[1,0,1]
	global_load_dwordx4 v[200:203], v248, s[8:9] offset:3072
	s_add_u32 s8, s8, 0x1000
	s_addc_u32 s9, s9, 0
	s_waitcnt vmcnt(10)
	v_readlane_b32 s50, v236, 29
	v_readlane_b32 s52, v237, 29
	v_readlane_b32 s54, v238, 29
	v_readlane_b32 s56, v239, 29
	v_readlane_b32 s58, v240, 29
	v_pk_fma_f32 v[168:169], v[208:209], s[50:51], v[168:169] op_sel_hi:[1,0,1]
	v_pk_fma_f32 v[170:171], v[210:211], s[50:51], v[170:171] op_sel_hi:[1,0,1]
	v_pk_fma_f32 v[172:173], v[208:209], s[52:53], v[172:173] op_sel_hi:[1,0,1]
	v_pk_fma_f32 v[174:175], v[210:211], s[52:53], v[174:175] op_sel_hi:[1,0,1]
	v_pk_fma_f32 v[176:177], v[208:209], s[54:55], v[176:177] op_sel_hi:[1,0,1]
	v_pk_fma_f32 v[178:179], v[210:211], s[54:55], v[178:179] op_sel_hi:[1,0,1]
	v_pk_fma_f32 v[180:181], v[208:209], s[56:57], v[180:181] op_sel_hi:[1,0,1]
	v_pk_fma_f32 v[182:183], v[210:211], s[56:57], v[182:183] op_sel_hi:[1,0,1]
	v_pk_fma_f32 v[184:185], v[208:209], s[58:59], v[184:185] op_sel_hi:[1,0,1]
	v_pk_fma_f32 v[186:187], v[210:211], s[58:59], v[186:187] op_sel_hi:[1,0,1]
	global_load_dwordx4 v[204:207], v248, s[8:9]
	s_waitcnt vmcnt(10)
	v_readlane_b32 s50, v236, 30
	v_readlane_b32 s52, v237, 30
	v_readlane_b32 s54, v238, 30
	v_readlane_b32 s56, v239, 30
	v_readlane_b32 s58, v240, 30
	v_pk_fma_f32 v[168:169], v[212:213], s[50:51], v[168:169] op_sel_hi:[1,0,1]
	v_pk_fma_f32 v[170:171], v[214:215], s[50:51], v[170:171] op_sel_hi:[1,0,1]
	v_pk_fma_f32 v[172:173], v[212:213], s[52:53], v[172:173] op_sel_hi:[1,0,1]
	v_pk_fma_f32 v[174:175], v[214:215], s[52:53], v[174:175] op_sel_hi:[1,0,1]
	v_pk_fma_f32 v[176:177], v[212:213], s[54:55], v[176:177] op_sel_hi:[1,0,1]
	v_pk_fma_f32 v[178:179], v[214:215], s[54:55], v[178:179] op_sel_hi:[1,0,1]
	v_pk_fma_f32 v[180:181], v[212:213], s[56:57], v[180:181] op_sel_hi:[1,0,1]
	v_pk_fma_f32 v[182:183], v[214:215], s[56:57], v[182:183] op_sel_hi:[1,0,1]
	v_pk_fma_f32 v[184:185], v[212:213], s[58:59], v[184:185] op_sel_hi:[1,0,1]
	v_pk_fma_f32 v[186:187], v[214:215], s[58:59], v[186:187] op_sel_hi:[1,0,1]
	global_load_dwordx4 v[208:211], v248, s[8:9] offset:1024
	s_waitcnt vmcnt(10)
	v_readlane_b32 s50, v236, 31
	v_readlane_b32 s52, v237, 31
	v_readlane_b32 s54, v238, 31
	v_readlane_b32 s56, v239, 31
	v_readlane_b32 s58, v240, 31
	v_pk_fma_f32 v[168:169], v[216:217], s[50:51], v[168:169] op_sel_hi:[1,0,1]
	v_pk_fma_f32 v[170:171], v[218:219], s[50:51], v[170:171] op_sel_hi:[1,0,1]
	v_pk_fma_f32 v[172:173], v[216:217], s[52:53], v[172:173] op_sel_hi:[1,0,1]
	v_pk_fma_f32 v[174:175], v[218:219], s[52:53], v[174:175] op_sel_hi:[1,0,1]
	v_pk_fma_f32 v[176:177], v[216:217], s[54:55], v[176:177] op_sel_hi:[1,0,1]
	v_pk_fma_f32 v[178:179], v[218:219], s[54:55], v[178:179] op_sel_hi:[1,0,1]
	v_pk_fma_f32 v[180:181], v[216:217], s[56:57], v[180:181] op_sel_hi:[1,0,1]
	v_pk_fma_f32 v[182:183], v[218:219], s[56:57], v[182:183] op_sel_hi:[1,0,1]
	v_pk_fma_f32 v[184:185], v[216:217], s[58:59], v[184:185] op_sel_hi:[1,0,1]
	v_pk_fma_f32 v[186:187], v[218:219], s[58:59], v[186:187] op_sel_hi:[1,0,1]
	global_load_dwordx4 v[212:215], v248, s[8:9] offset:2048
	s_waitcnt vmcnt(10)
	v_readlane_b32 s50, v236, 32
	v_readlane_b32 s52, v237, 32
	v_readlane_b32 s54, v238, 32
	v_readlane_b32 s56, v239, 32
	v_readlane_b32 s58, v240, 32
	v_pk_fma_f32 v[168:169], v[220:221], s[50:51], v[168:169] op_sel_hi:[1,0,1]
	v_pk_fma_f32 v[170:171], v[222:223], s[50:51], v[170:171] op_sel_hi:[1,0,1]
	v_pk_fma_f32 v[172:173], v[220:221], s[52:53], v[172:173] op_sel_hi:[1,0,1]
	v_pk_fma_f32 v[174:175], v[222:223], s[52:53], v[174:175] op_sel_hi:[1,0,1]
	v_pk_fma_f32 v[176:177], v[220:221], s[54:55], v[176:177] op_sel_hi:[1,0,1]
	v_pk_fma_f32 v[178:179], v[222:223], s[54:55], v[178:179] op_sel_hi:[1,0,1]
	v_pk_fma_f32 v[180:181], v[220:221], s[56:57], v[180:181] op_sel_hi:[1,0,1]
	v_pk_fma_f32 v[182:183], v[222:223], s[56:57], v[182:183] op_sel_hi:[1,0,1]
	v_pk_fma_f32 v[184:185], v[220:221], s[58:59], v[184:185] op_sel_hi:[1,0,1]
	v_pk_fma_f32 v[186:187], v[222:223], s[58:59], v[186:187] op_sel_hi:[1,0,1]
	global_load_dwordx4 v[216:219], v248, s[8:9] offset:3072
	s_add_u32 s8, s8, 0x1000
	s_addc_u32 s9, s9, 0
	s_waitcnt vmcnt(10)
	v_readlane_b32 s50, v236, 33
	v_readlane_b32 s52, v237, 33
	v_readlane_b32 s54, v238, 33
	v_readlane_b32 s56, v239, 33
	v_readlane_b32 s58, v240, 33
	v_pk_fma_f32 v[168:169], v[224:225], s[50:51], v[168:169] op_sel_hi:[1,0,1]
	v_pk_fma_f32 v[170:171], v[226:227], s[50:51], v[170:171] op_sel_hi:[1,0,1]
	v_pk_fma_f32 v[172:173], v[224:225], s[52:53], v[172:173] op_sel_hi:[1,0,1]
	v_pk_fma_f32 v[174:175], v[226:227], s[52:53], v[174:175] op_sel_hi:[1,0,1]
	v_pk_fma_f32 v[176:177], v[224:225], s[54:55], v[176:177] op_sel_hi:[1,0,1]
	v_pk_fma_f32 v[178:179], v[226:227], s[54:55], v[178:179] op_sel_hi:[1,0,1]
	v_pk_fma_f32 v[180:181], v[224:225], s[56:57], v[180:181] op_sel_hi:[1,0,1]
	v_pk_fma_f32 v[182:183], v[226:227], s[56:57], v[182:183] op_sel_hi:[1,0,1]
	v_pk_fma_f32 v[184:185], v[224:225], s[58:59], v[184:185] op_sel_hi:[1,0,1]
	v_pk_fma_f32 v[186:187], v[226:227], s[58:59], v[186:187] op_sel_hi:[1,0,1]
	global_load_dwordx4 v[220:223], v248, s[8:9]
	s_waitcnt vmcnt(10)
	v_readlane_b32 s50, v236, 34
	v_readlane_b32 s52, v237, 34
	v_readlane_b32 s54, v238, 34
	v_readlane_b32 s56, v239, 34
	v_readlane_b32 s58, v240, 34
	v_pk_fma_f32 v[168:169], v[228:229], s[50:51], v[168:169] op_sel_hi:[1,0,1]
	v_pk_fma_f32 v[170:171], v[230:231], s[50:51], v[170:171] op_sel_hi:[1,0,1]
	v_pk_fma_f32 v[172:173], v[228:229], s[52:53], v[172:173] op_sel_hi:[1,0,1]
	v_pk_fma_f32 v[174:175], v[230:231], s[52:53], v[174:175] op_sel_hi:[1,0,1]
	v_pk_fma_f32 v[176:177], v[228:229], s[54:55], v[176:177] op_sel_hi:[1,0,1]
	v_pk_fma_f32 v[178:179], v[230:231], s[54:55], v[178:179] op_sel_hi:[1,0,1]
	v_pk_fma_f32 v[180:181], v[228:229], s[56:57], v[180:181] op_sel_hi:[1,0,1]
	v_pk_fma_f32 v[182:183], v[230:231], s[56:57], v[182:183] op_sel_hi:[1,0,1]
	v_pk_fma_f32 v[184:185], v[228:229], s[58:59], v[184:185] op_sel_hi:[1,0,1]
	v_pk_fma_f32 v[186:187], v[230:231], s[58:59], v[186:187] op_sel_hi:[1,0,1]
	global_load_dwordx4 v[224:227], v248, s[8:9] offset:1024
	s_waitcnt vmcnt(10)
	v_readlane_b32 s50, v236, 35
	v_readlane_b32 s52, v237, 35
	v_readlane_b32 s54, v238, 35
	v_readlane_b32 s56, v239, 35
	v_readlane_b32 s58, v240, 35
	v_pk_fma_f32 v[168:169], v[232:233], s[50:51], v[168:169] op_sel_hi:[1,0,1]
	v_pk_fma_f32 v[170:171], v[234:235], s[50:51], v[170:171] op_sel_hi:[1,0,1]
	v_pk_fma_f32 v[172:173], v[232:233], s[52:53], v[172:173] op_sel_hi:[1,0,1]
	v_pk_fma_f32 v[174:175], v[234:235], s[52:53], v[174:175] op_sel_hi:[1,0,1]
	v_pk_fma_f32 v[176:177], v[232:233], s[54:55], v[176:177] op_sel_hi:[1,0,1]
	v_pk_fma_f32 v[178:179], v[234:235], s[54:55], v[178:179] op_sel_hi:[1,0,1]
	v_pk_fma_f32 v[180:181], v[232:233], s[56:57], v[180:181] op_sel_hi:[1,0,1]
	v_pk_fma_f32 v[182:183], v[234:235], s[56:57], v[182:183] op_sel_hi:[1,0,1]
	v_pk_fma_f32 v[184:185], v[232:233], s[58:59], v[184:185] op_sel_hi:[1,0,1]
	v_pk_fma_f32 v[186:187], v[234:235], s[58:59], v[186:187] op_sel_hi:[1,0,1]
	global_load_dwordx4 v[228:231], v248, s[8:9] offset:2048
	s_waitcnt vmcnt(10)
	v_readlane_b32 s50, v236, 36
	v_readlane_b32 s52, v237, 36
	v_readlane_b32 s54, v238, 36
	v_readlane_b32 s56, v239, 36
	v_readlane_b32 s58, v240, 36
	v_pk_fma_f32 v[168:169], v[188:189], s[50:51], v[168:169] op_sel_hi:[1,0,1]
	v_pk_fma_f32 v[170:171], v[190:191], s[50:51], v[170:171] op_sel_hi:[1,0,1]
	v_pk_fma_f32 v[172:173], v[188:189], s[52:53], v[172:173] op_sel_hi:[1,0,1]
	v_pk_fma_f32 v[174:175], v[190:191], s[52:53], v[174:175] op_sel_hi:[1,0,1]
	v_pk_fma_f32 v[176:177], v[188:189], s[54:55], v[176:177] op_sel_hi:[1,0,1]
	v_pk_fma_f32 v[178:179], v[190:191], s[54:55], v[178:179] op_sel_hi:[1,0,1]
	v_pk_fma_f32 v[180:181], v[188:189], s[56:57], v[180:181] op_sel_hi:[1,0,1]
	v_pk_fma_f32 v[182:183], v[190:191], s[56:57], v[182:183] op_sel_hi:[1,0,1]
	v_pk_fma_f32 v[184:185], v[188:189], s[58:59], v[184:185] op_sel_hi:[1,0,1]
	v_pk_fma_f32 v[186:187], v[190:191], s[58:59], v[186:187] op_sel_hi:[1,0,1]
	global_load_dwordx4 v[232:235], v248, s[8:9] offset:3072
	s_add_u32 s8, s8, 0x1000
	s_addc_u32 s9, s9, 0
	s_waitcnt vmcnt(10)
	v_readlane_b32 s50, v236, 37
	v_readlane_b32 s52, v237, 37
	v_readlane_b32 s54, v238, 37
	v_readlane_b32 s56, v239, 37
	v_readlane_b32 s58, v240, 37
	v_pk_fma_f32 v[168:169], v[192:193], s[50:51], v[168:169] op_sel_hi:[1,0,1]
	v_pk_fma_f32 v[170:171], v[194:195], s[50:51], v[170:171] op_sel_hi:[1,0,1]
	v_pk_fma_f32 v[172:173], v[192:193], s[52:53], v[172:173] op_sel_hi:[1,0,1]
	v_pk_fma_f32 v[174:175], v[194:195], s[52:53], v[174:175] op_sel_hi:[1,0,1]
	v_pk_fma_f32 v[176:177], v[192:193], s[54:55], v[176:177] op_sel_hi:[1,0,1]
	v_pk_fma_f32 v[178:179], v[194:195], s[54:55], v[178:179] op_sel_hi:[1,0,1]
	v_pk_fma_f32 v[180:181], v[192:193], s[56:57], v[180:181] op_sel_hi:[1,0,1]
	v_pk_fma_f32 v[182:183], v[194:195], s[56:57], v[182:183] op_sel_hi:[1,0,1]
	v_pk_fma_f32 v[184:185], v[192:193], s[58:59], v[184:185] op_sel_hi:[1,0,1]
	v_pk_fma_f32 v[186:187], v[194:195], s[58:59], v[186:187] op_sel_hi:[1,0,1]
	global_load_dwordx4 v[188:191], v248, s[8:9]
	s_waitcnt vmcnt(10)
	v_readlane_b32 s50, v236, 38
	v_readlane_b32 s52, v237, 38
	v_readlane_b32 s54, v238, 38
	v_readlane_b32 s56, v239, 38
	v_readlane_b32 s58, v240, 38
	v_pk_fma_f32 v[168:169], v[196:197], s[50:51], v[168:169] op_sel_hi:[1,0,1]
	v_pk_fma_f32 v[170:171], v[198:199], s[50:51], v[170:171] op_sel_hi:[1,0,1]
	v_pk_fma_f32 v[172:173], v[196:197], s[52:53], v[172:173] op_sel_hi:[1,0,1]
	v_pk_fma_f32 v[174:175], v[198:199], s[52:53], v[174:175] op_sel_hi:[1,0,1]
	v_pk_fma_f32 v[176:177], v[196:197], s[54:55], v[176:177] op_sel_hi:[1,0,1]
	v_pk_fma_f32 v[178:179], v[198:199], s[54:55], v[178:179] op_sel_hi:[1,0,1]
	v_pk_fma_f32 v[180:181], v[196:197], s[56:57], v[180:181] op_sel_hi:[1,0,1]
	v_pk_fma_f32 v[182:183], v[198:199], s[56:57], v[182:183] op_sel_hi:[1,0,1]
	v_pk_fma_f32 v[184:185], v[196:197], s[58:59], v[184:185] op_sel_hi:[1,0,1]
	v_pk_fma_f32 v[186:187], v[198:199], s[58:59], v[186:187] op_sel_hi:[1,0,1]
	global_load_dwordx4 v[192:195], v248, s[8:9] offset:1024
	s_waitcnt vmcnt(10)
	v_readlane_b32 s50, v236, 39
	v_readlane_b32 s52, v237, 39
	v_readlane_b32 s54, v238, 39
	v_readlane_b32 s56, v239, 39
	v_readlane_b32 s58, v240, 39
	v_pk_fma_f32 v[168:169], v[200:201], s[50:51], v[168:169] op_sel_hi:[1,0,1]
	v_pk_fma_f32 v[170:171], v[202:203], s[50:51], v[170:171] op_sel_hi:[1,0,1]
	v_pk_fma_f32 v[172:173], v[200:201], s[52:53], v[172:173] op_sel_hi:[1,0,1]
	v_pk_fma_f32 v[174:175], v[202:203], s[52:53], v[174:175] op_sel_hi:[1,0,1]
	v_pk_fma_f32 v[176:177], v[200:201], s[54:55], v[176:177] op_sel_hi:[1,0,1]
	v_pk_fma_f32 v[178:179], v[202:203], s[54:55], v[178:179] op_sel_hi:[1,0,1]
	v_pk_fma_f32 v[180:181], v[200:201], s[56:57], v[180:181] op_sel_hi:[1,0,1]
	v_pk_fma_f32 v[182:183], v[202:203], s[56:57], v[182:183] op_sel_hi:[1,0,1]
	v_pk_fma_f32 v[184:185], v[200:201], s[58:59], v[184:185] op_sel_hi:[1,0,1]
	v_pk_fma_f32 v[186:187], v[202:203], s[58:59], v[186:187] op_sel_hi:[1,0,1]
	global_load_dwordx4 v[196:199], v248, s[8:9] offset:2048
	s_waitcnt vmcnt(10)
	v_readlane_b32 s50, v236, 40
	v_readlane_b32 s52, v237, 40
	v_readlane_b32 s54, v238, 40
	v_readlane_b32 s56, v239, 40
	v_readlane_b32 s58, v240, 40
	v_pk_fma_f32 v[168:169], v[204:205], s[50:51], v[168:169] op_sel_hi:[1,0,1]
	v_pk_fma_f32 v[170:171], v[206:207], s[50:51], v[170:171] op_sel_hi:[1,0,1]
	v_pk_fma_f32 v[172:173], v[204:205], s[52:53], v[172:173] op_sel_hi:[1,0,1]
	v_pk_fma_f32 v[174:175], v[206:207], s[52:53], v[174:175] op_sel_hi:[1,0,1]
	v_pk_fma_f32 v[176:177], v[204:205], s[54:55], v[176:177] op_sel_hi:[1,0,1]
	v_pk_fma_f32 v[178:179], v[206:207], s[54:55], v[178:179] op_sel_hi:[1,0,1]
	v_pk_fma_f32 v[180:181], v[204:205], s[56:57], v[180:181] op_sel_hi:[1,0,1]
	v_pk_fma_f32 v[182:183], v[206:207], s[56:57], v[182:183] op_sel_hi:[1,0,1]
	v_pk_fma_f32 v[184:185], v[204:205], s[58:59], v[184:185] op_sel_hi:[1,0,1]
	v_pk_fma_f32 v[186:187], v[206:207], s[58:59], v[186:187] op_sel_hi:[1,0,1]
	global_load_dwordx4 v[200:203], v248, s[8:9] offset:3072
	s_add_u32 s8, s8, 0x1000
	s_addc_u32 s9, s9, 0
	s_waitcnt vmcnt(10)
	v_readlane_b32 s50, v236, 41
	v_readlane_b32 s52, v237, 41
	v_readlane_b32 s54, v238, 41
	v_readlane_b32 s56, v239, 41
	v_readlane_b32 s58, v240, 41
	v_pk_fma_f32 v[168:169], v[208:209], s[50:51], v[168:169] op_sel_hi:[1,0,1]
	v_pk_fma_f32 v[170:171], v[210:211], s[50:51], v[170:171] op_sel_hi:[1,0,1]
	v_pk_fma_f32 v[172:173], v[208:209], s[52:53], v[172:173] op_sel_hi:[1,0,1]
	v_pk_fma_f32 v[174:175], v[210:211], s[52:53], v[174:175] op_sel_hi:[1,0,1]
	v_pk_fma_f32 v[176:177], v[208:209], s[54:55], v[176:177] op_sel_hi:[1,0,1]
	v_pk_fma_f32 v[178:179], v[210:211], s[54:55], v[178:179] op_sel_hi:[1,0,1]
	v_pk_fma_f32 v[180:181], v[208:209], s[56:57], v[180:181] op_sel_hi:[1,0,1]
	v_pk_fma_f32 v[182:183], v[210:211], s[56:57], v[182:183] op_sel_hi:[1,0,1]
	v_pk_fma_f32 v[184:185], v[208:209], s[58:59], v[184:185] op_sel_hi:[1,0,1]
	v_pk_fma_f32 v[186:187], v[210:211], s[58:59], v[186:187] op_sel_hi:[1,0,1]
	global_load_dwordx4 v[204:207], v248, s[8:9]
	s_waitcnt vmcnt(10)
	v_readlane_b32 s50, v236, 42
	v_readlane_b32 s52, v237, 42
	v_readlane_b32 s54, v238, 42
	v_readlane_b32 s56, v239, 42
	v_readlane_b32 s58, v240, 42
	v_pk_fma_f32 v[168:169], v[212:213], s[50:51], v[168:169] op_sel_hi:[1,0,1]
	v_pk_fma_f32 v[170:171], v[214:215], s[50:51], v[170:171] op_sel_hi:[1,0,1]
	v_pk_fma_f32 v[172:173], v[212:213], s[52:53], v[172:173] op_sel_hi:[1,0,1]
	v_pk_fma_f32 v[174:175], v[214:215], s[52:53], v[174:175] op_sel_hi:[1,0,1]
	v_pk_fma_f32 v[176:177], v[212:213], s[54:55], v[176:177] op_sel_hi:[1,0,1]
	v_pk_fma_f32 v[178:179], v[214:215], s[54:55], v[178:179] op_sel_hi:[1,0,1]
	v_pk_fma_f32 v[180:181], v[212:213], s[56:57], v[180:181] op_sel_hi:[1,0,1]
	v_pk_fma_f32 v[182:183], v[214:215], s[56:57], v[182:183] op_sel_hi:[1,0,1]
	v_pk_fma_f32 v[184:185], v[212:213], s[58:59], v[184:185] op_sel_hi:[1,0,1]
	v_pk_fma_f32 v[186:187], v[214:215], s[58:59], v[186:187] op_sel_hi:[1,0,1]
	global_load_dwordx4 v[208:211], v248, s[8:9] offset:1024
	s_waitcnt vmcnt(10)
	v_readlane_b32 s50, v236, 43
	v_readlane_b32 s52, v237, 43
	v_readlane_b32 s54, v238, 43
	v_readlane_b32 s56, v239, 43
	v_readlane_b32 s58, v240, 43
	v_pk_fma_f32 v[168:169], v[216:217], s[50:51], v[168:169] op_sel_hi:[1,0,1]
	v_pk_fma_f32 v[170:171], v[218:219], s[50:51], v[170:171] op_sel_hi:[1,0,1]
	v_pk_fma_f32 v[172:173], v[216:217], s[52:53], v[172:173] op_sel_hi:[1,0,1]
	v_pk_fma_f32 v[174:175], v[218:219], s[52:53], v[174:175] op_sel_hi:[1,0,1]
	v_pk_fma_f32 v[176:177], v[216:217], s[54:55], v[176:177] op_sel_hi:[1,0,1]
	v_pk_fma_f32 v[178:179], v[218:219], s[54:55], v[178:179] op_sel_hi:[1,0,1]
	v_pk_fma_f32 v[180:181], v[216:217], s[56:57], v[180:181] op_sel_hi:[1,0,1]
	v_pk_fma_f32 v[182:183], v[218:219], s[56:57], v[182:183] op_sel_hi:[1,0,1]
	v_pk_fma_f32 v[184:185], v[216:217], s[58:59], v[184:185] op_sel_hi:[1,0,1]
	v_pk_fma_f32 v[186:187], v[218:219], s[58:59], v[186:187] op_sel_hi:[1,0,1]
	global_load_dwordx4 v[212:215], v248, s[8:9] offset:2048
	s_waitcnt vmcnt(10)
	v_readlane_b32 s50, v236, 44
	v_readlane_b32 s52, v237, 44
	v_readlane_b32 s54, v238, 44
	v_readlane_b32 s56, v239, 44
	v_readlane_b32 s58, v240, 44
	v_pk_fma_f32 v[168:169], v[220:221], s[50:51], v[168:169] op_sel_hi:[1,0,1]
	v_pk_fma_f32 v[170:171], v[222:223], s[50:51], v[170:171] op_sel_hi:[1,0,1]
	v_pk_fma_f32 v[172:173], v[220:221], s[52:53], v[172:173] op_sel_hi:[1,0,1]
	v_pk_fma_f32 v[174:175], v[222:223], s[52:53], v[174:175] op_sel_hi:[1,0,1]
	v_pk_fma_f32 v[176:177], v[220:221], s[54:55], v[176:177] op_sel_hi:[1,0,1]
	v_pk_fma_f32 v[178:179], v[222:223], s[54:55], v[178:179] op_sel_hi:[1,0,1]
	v_pk_fma_f32 v[180:181], v[220:221], s[56:57], v[180:181] op_sel_hi:[1,0,1]
	v_pk_fma_f32 v[182:183], v[222:223], s[56:57], v[182:183] op_sel_hi:[1,0,1]
	v_pk_fma_f32 v[184:185], v[220:221], s[58:59], v[184:185] op_sel_hi:[1,0,1]
	v_pk_fma_f32 v[186:187], v[222:223], s[58:59], v[186:187] op_sel_hi:[1,0,1]
	global_load_dwordx4 v[216:219], v248, s[8:9] offset:3072
	s_add_u32 s8, s8, 0x1000
	s_addc_u32 s9, s9, 0
	s_waitcnt vmcnt(10)
	v_readlane_b32 s50, v236, 45
	v_readlane_b32 s52, v237, 45
	v_readlane_b32 s54, v238, 45
	v_readlane_b32 s56, v239, 45
	v_readlane_b32 s58, v240, 45
	v_pk_fma_f32 v[168:169], v[224:225], s[50:51], v[168:169] op_sel_hi:[1,0,1]
	v_pk_fma_f32 v[170:171], v[226:227], s[50:51], v[170:171] op_sel_hi:[1,0,1]
	v_pk_fma_f32 v[172:173], v[224:225], s[52:53], v[172:173] op_sel_hi:[1,0,1]
	v_pk_fma_f32 v[174:175], v[226:227], s[52:53], v[174:175] op_sel_hi:[1,0,1]
	v_pk_fma_f32 v[176:177], v[224:225], s[54:55], v[176:177] op_sel_hi:[1,0,1]
	v_pk_fma_f32 v[178:179], v[226:227], s[54:55], v[178:179] op_sel_hi:[1,0,1]
	v_pk_fma_f32 v[180:181], v[224:225], s[56:57], v[180:181] op_sel_hi:[1,0,1]
	v_pk_fma_f32 v[182:183], v[226:227], s[56:57], v[182:183] op_sel_hi:[1,0,1]
	v_pk_fma_f32 v[184:185], v[224:225], s[58:59], v[184:185] op_sel_hi:[1,0,1]
	v_pk_fma_f32 v[186:187], v[226:227], s[58:59], v[186:187] op_sel_hi:[1,0,1]
	global_load_dwordx4 v[220:223], v248, s[8:9]
	s_waitcnt vmcnt(10)
	v_readlane_b32 s50, v236, 46
	v_readlane_b32 s52, v237, 46
	v_readlane_b32 s54, v238, 46
	v_readlane_b32 s56, v239, 46
	v_readlane_b32 s58, v240, 46
	v_pk_fma_f32 v[168:169], v[228:229], s[50:51], v[168:169] op_sel_hi:[1,0,1]
	v_pk_fma_f32 v[170:171], v[230:231], s[50:51], v[170:171] op_sel_hi:[1,0,1]
	v_pk_fma_f32 v[172:173], v[228:229], s[52:53], v[172:173] op_sel_hi:[1,0,1]
	v_pk_fma_f32 v[174:175], v[230:231], s[52:53], v[174:175] op_sel_hi:[1,0,1]
	v_pk_fma_f32 v[176:177], v[228:229], s[54:55], v[176:177] op_sel_hi:[1,0,1]
	v_pk_fma_f32 v[178:179], v[230:231], s[54:55], v[178:179] op_sel_hi:[1,0,1]
	v_pk_fma_f32 v[180:181], v[228:229], s[56:57], v[180:181] op_sel_hi:[1,0,1]
	v_pk_fma_f32 v[182:183], v[230:231], s[56:57], v[182:183] op_sel_hi:[1,0,1]
	v_pk_fma_f32 v[184:185], v[228:229], s[58:59], v[184:185] op_sel_hi:[1,0,1]
	v_pk_fma_f32 v[186:187], v[230:231], s[58:59], v[186:187] op_sel_hi:[1,0,1]
	global_load_dwordx4 v[224:227], v248, s[8:9] offset:1024
	s_waitcnt vmcnt(10)
	v_readlane_b32 s50, v236, 47
	v_readlane_b32 s52, v237, 47
	v_readlane_b32 s54, v238, 47
	v_readlane_b32 s56, v239, 47
	v_readlane_b32 s58, v240, 47
	v_pk_fma_f32 v[168:169], v[232:233], s[50:51], v[168:169] op_sel_hi:[1,0,1]
	v_pk_fma_f32 v[170:171], v[234:235], s[50:51], v[170:171] op_sel_hi:[1,0,1]
	v_pk_fma_f32 v[172:173], v[232:233], s[52:53], v[172:173] op_sel_hi:[1,0,1]
	v_pk_fma_f32 v[174:175], v[234:235], s[52:53], v[174:175] op_sel_hi:[1,0,1]
	v_pk_fma_f32 v[176:177], v[232:233], s[54:55], v[176:177] op_sel_hi:[1,0,1]
	v_pk_fma_f32 v[178:179], v[234:235], s[54:55], v[178:179] op_sel_hi:[1,0,1]
	v_pk_fma_f32 v[180:181], v[232:233], s[56:57], v[180:181] op_sel_hi:[1,0,1]
	v_pk_fma_f32 v[182:183], v[234:235], s[56:57], v[182:183] op_sel_hi:[1,0,1]
	v_pk_fma_f32 v[184:185], v[232:233], s[58:59], v[184:185] op_sel_hi:[1,0,1]
	v_pk_fma_f32 v[186:187], v[234:235], s[58:59], v[186:187] op_sel_hi:[1,0,1]
	global_load_dwordx4 v[228:231], v248, s[8:9] offset:2048
	s_waitcnt vmcnt(10)
	v_readlane_b32 s50, v236, 48
	v_readlane_b32 s52, v237, 48
	v_readlane_b32 s54, v238, 48
	v_readlane_b32 s56, v239, 48
	v_readlane_b32 s58, v240, 48
	v_pk_fma_f32 v[168:169], v[188:189], s[50:51], v[168:169] op_sel_hi:[1,0,1]
	v_pk_fma_f32 v[170:171], v[190:191], s[50:51], v[170:171] op_sel_hi:[1,0,1]
	v_pk_fma_f32 v[172:173], v[188:189], s[52:53], v[172:173] op_sel_hi:[1,0,1]
	v_pk_fma_f32 v[174:175], v[190:191], s[52:53], v[174:175] op_sel_hi:[1,0,1]
	v_pk_fma_f32 v[176:177], v[188:189], s[54:55], v[176:177] op_sel_hi:[1,0,1]
	v_pk_fma_f32 v[178:179], v[190:191], s[54:55], v[178:179] op_sel_hi:[1,0,1]
	v_pk_fma_f32 v[180:181], v[188:189], s[56:57], v[180:181] op_sel_hi:[1,0,1]
	v_pk_fma_f32 v[182:183], v[190:191], s[56:57], v[182:183] op_sel_hi:[1,0,1]
	v_pk_fma_f32 v[184:185], v[188:189], s[58:59], v[184:185] op_sel_hi:[1,0,1]
	v_pk_fma_f32 v[186:187], v[190:191], s[58:59], v[186:187] op_sel_hi:[1,0,1]
	global_load_dwordx4 v[232:235], v248, s[8:9] offset:3072
	s_add_u32 s8, s8, 0x1000
	s_addc_u32 s9, s9, 0
	s_waitcnt vmcnt(10)
	v_readlane_b32 s50, v236, 49
	v_readlane_b32 s52, v237, 49
	v_readlane_b32 s54, v238, 49
	v_readlane_b32 s56, v239, 49
	v_readlane_b32 s58, v240, 49
	v_pk_fma_f32 v[168:169], v[192:193], s[50:51], v[168:169] op_sel_hi:[1,0,1]
	v_pk_fma_f32 v[170:171], v[194:195], s[50:51], v[170:171] op_sel_hi:[1,0,1]
	v_pk_fma_f32 v[172:173], v[192:193], s[52:53], v[172:173] op_sel_hi:[1,0,1]
	v_pk_fma_f32 v[174:175], v[194:195], s[52:53], v[174:175] op_sel_hi:[1,0,1]
	v_pk_fma_f32 v[176:177], v[192:193], s[54:55], v[176:177] op_sel_hi:[1,0,1]
	v_pk_fma_f32 v[178:179], v[194:195], s[54:55], v[178:179] op_sel_hi:[1,0,1]
	v_pk_fma_f32 v[180:181], v[192:193], s[56:57], v[180:181] op_sel_hi:[1,0,1]
	v_pk_fma_f32 v[182:183], v[194:195], s[56:57], v[182:183] op_sel_hi:[1,0,1]
	v_pk_fma_f32 v[184:185], v[192:193], s[58:59], v[184:185] op_sel_hi:[1,0,1]
	v_pk_fma_f32 v[186:187], v[194:195], s[58:59], v[186:187] op_sel_hi:[1,0,1]
	global_load_dwordx4 v[188:191], v248, s[8:9]
	s_waitcnt vmcnt(10)
	v_readlane_b32 s50, v236, 50
	v_readlane_b32 s52, v237, 50
	v_readlane_b32 s54, v238, 50
	v_readlane_b32 s56, v239, 50
	v_readlane_b32 s58, v240, 50
	v_pk_fma_f32 v[168:169], v[196:197], s[50:51], v[168:169] op_sel_hi:[1,0,1]
	v_pk_fma_f32 v[170:171], v[198:199], s[50:51], v[170:171] op_sel_hi:[1,0,1]
	v_pk_fma_f32 v[172:173], v[196:197], s[52:53], v[172:173] op_sel_hi:[1,0,1]
	v_pk_fma_f32 v[174:175], v[198:199], s[52:53], v[174:175] op_sel_hi:[1,0,1]
	v_pk_fma_f32 v[176:177], v[196:197], s[54:55], v[176:177] op_sel_hi:[1,0,1]
	v_pk_fma_f32 v[178:179], v[198:199], s[54:55], v[178:179] op_sel_hi:[1,0,1]
	v_pk_fma_f32 v[180:181], v[196:197], s[56:57], v[180:181] op_sel_hi:[1,0,1]
	v_pk_fma_f32 v[182:183], v[198:199], s[56:57], v[182:183] op_sel_hi:[1,0,1]
	v_pk_fma_f32 v[184:185], v[196:197], s[58:59], v[184:185] op_sel_hi:[1,0,1]
	v_pk_fma_f32 v[186:187], v[198:199], s[58:59], v[186:187] op_sel_hi:[1,0,1]
	global_load_dwordx4 v[192:195], v248, s[8:9] offset:1024
	s_waitcnt vmcnt(10)
	v_readlane_b32 s50, v236, 51
	v_readlane_b32 s52, v237, 51
	v_readlane_b32 s54, v238, 51
	v_readlane_b32 s56, v239, 51
	v_readlane_b32 s58, v240, 51
	v_pk_fma_f32 v[168:169], v[200:201], s[50:51], v[168:169] op_sel_hi:[1,0,1]
	v_pk_fma_f32 v[170:171], v[202:203], s[50:51], v[170:171] op_sel_hi:[1,0,1]
	v_pk_fma_f32 v[172:173], v[200:201], s[52:53], v[172:173] op_sel_hi:[1,0,1]
	v_pk_fma_f32 v[174:175], v[202:203], s[52:53], v[174:175] op_sel_hi:[1,0,1]
	v_pk_fma_f32 v[176:177], v[200:201], s[54:55], v[176:177] op_sel_hi:[1,0,1]
	v_pk_fma_f32 v[178:179], v[202:203], s[54:55], v[178:179] op_sel_hi:[1,0,1]
	v_pk_fma_f32 v[180:181], v[200:201], s[56:57], v[180:181] op_sel_hi:[1,0,1]
	v_pk_fma_f32 v[182:183], v[202:203], s[56:57], v[182:183] op_sel_hi:[1,0,1]
	v_pk_fma_f32 v[184:185], v[200:201], s[58:59], v[184:185] op_sel_hi:[1,0,1]
	v_pk_fma_f32 v[186:187], v[202:203], s[58:59], v[186:187] op_sel_hi:[1,0,1]
	global_load_dwordx4 v[196:199], v248, s[8:9] offset:2048
	s_waitcnt vmcnt(10)
	v_readlane_b32 s50, v236, 52
	v_readlane_b32 s52, v237, 52
	v_readlane_b32 s54, v238, 52
	v_readlane_b32 s56, v239, 52
	v_readlane_b32 s58, v240, 52
	v_pk_fma_f32 v[168:169], v[204:205], s[50:51], v[168:169] op_sel_hi:[1,0,1]
	v_pk_fma_f32 v[170:171], v[206:207], s[50:51], v[170:171] op_sel_hi:[1,0,1]
	v_pk_fma_f32 v[172:173], v[204:205], s[52:53], v[172:173] op_sel_hi:[1,0,1]
	v_pk_fma_f32 v[174:175], v[206:207], s[52:53], v[174:175] op_sel_hi:[1,0,1]
	v_pk_fma_f32 v[176:177], v[204:205], s[54:55], v[176:177] op_sel_hi:[1,0,1]
	v_pk_fma_f32 v[178:179], v[206:207], s[54:55], v[178:179] op_sel_hi:[1,0,1]
	v_pk_fma_f32 v[180:181], v[204:205], s[56:57], v[180:181] op_sel_hi:[1,0,1]
	v_pk_fma_f32 v[182:183], v[206:207], s[56:57], v[182:183] op_sel_hi:[1,0,1]
	v_pk_fma_f32 v[184:185], v[204:205], s[58:59], v[184:185] op_sel_hi:[1,0,1]
	v_pk_fma_f32 v[186:187], v[206:207], s[58:59], v[186:187] op_sel_hi:[1,0,1]
	global_load_dwordx4 v[200:203], v248, s[8:9] offset:3072
	s_add_u32 s8, s8, 0x1000
	s_addc_u32 s9, s9, 0
	s_waitcnt vmcnt(10)
	v_readlane_b32 s50, v236, 53
	v_readlane_b32 s52, v237, 53
	v_readlane_b32 s54, v238, 53
	v_readlane_b32 s56, v239, 53
	v_readlane_b32 s58, v240, 53
	v_pk_fma_f32 v[168:169], v[208:209], s[50:51], v[168:169] op_sel_hi:[1,0,1]
	v_pk_fma_f32 v[170:171], v[210:211], s[50:51], v[170:171] op_sel_hi:[1,0,1]
	v_pk_fma_f32 v[172:173], v[208:209], s[52:53], v[172:173] op_sel_hi:[1,0,1]
	v_pk_fma_f32 v[174:175], v[210:211], s[52:53], v[174:175] op_sel_hi:[1,0,1]
	v_pk_fma_f32 v[176:177], v[208:209], s[54:55], v[176:177] op_sel_hi:[1,0,1]
	v_pk_fma_f32 v[178:179], v[210:211], s[54:55], v[178:179] op_sel_hi:[1,0,1]
	v_pk_fma_f32 v[180:181], v[208:209], s[56:57], v[180:181] op_sel_hi:[1,0,1]
	v_pk_fma_f32 v[182:183], v[210:211], s[56:57], v[182:183] op_sel_hi:[1,0,1]
	v_pk_fma_f32 v[184:185], v[208:209], s[58:59], v[184:185] op_sel_hi:[1,0,1]
	v_pk_fma_f32 v[186:187], v[210:211], s[58:59], v[186:187] op_sel_hi:[1,0,1]
	s_waitcnt vmcnt(9)
	v_readlane_b32 s50, v236, 54
	v_readlane_b32 s52, v237, 54
	v_readlane_b32 s54, v238, 54
	v_readlane_b32 s56, v239, 54
	v_readlane_b32 s58, v240, 54
	v_pk_fma_f32 v[168:169], v[212:213], s[50:51], v[168:169] op_sel_hi:[1,0,1]
	v_pk_fma_f32 v[170:171], v[214:215], s[50:51], v[170:171] op_sel_hi:[1,0,1]
	v_pk_fma_f32 v[172:173], v[212:213], s[52:53], v[172:173] op_sel_hi:[1,0,1]
	v_pk_fma_f32 v[174:175], v[214:215], s[52:53], v[174:175] op_sel_hi:[1,0,1]
	v_pk_fma_f32 v[176:177], v[212:213], s[54:55], v[176:177] op_sel_hi:[1,0,1]
	v_pk_fma_f32 v[178:179], v[214:215], s[54:55], v[178:179] op_sel_hi:[1,0,1]
	v_pk_fma_f32 v[180:181], v[212:213], s[56:57], v[180:181] op_sel_hi:[1,0,1]
	v_pk_fma_f32 v[182:183], v[214:215], s[56:57], v[182:183] op_sel_hi:[1,0,1]
	v_pk_fma_f32 v[184:185], v[212:213], s[58:59], v[184:185] op_sel_hi:[1,0,1]
	v_pk_fma_f32 v[186:187], v[214:215], s[58:59], v[186:187] op_sel_hi:[1,0,1]
	s_waitcnt vmcnt(8)
	v_readlane_b32 s50, v236, 55
	v_readlane_b32 s52, v237, 55
	v_readlane_b32 s54, v238, 55
	v_readlane_b32 s56, v239, 55
	v_readlane_b32 s58, v240, 55
	v_pk_fma_f32 v[168:169], v[216:217], s[50:51], v[168:169] op_sel_hi:[1,0,1]
	v_pk_fma_f32 v[170:171], v[218:219], s[50:51], v[170:171] op_sel_hi:[1,0,1]
	v_pk_fma_f32 v[172:173], v[216:217], s[52:53], v[172:173] op_sel_hi:[1,0,1]
	v_pk_fma_f32 v[174:175], v[218:219], s[52:53], v[174:175] op_sel_hi:[1,0,1]
	v_pk_fma_f32 v[176:177], v[216:217], s[54:55], v[176:177] op_sel_hi:[1,0,1]
	v_pk_fma_f32 v[178:179], v[218:219], s[54:55], v[178:179] op_sel_hi:[1,0,1]
	v_pk_fma_f32 v[180:181], v[216:217], s[56:57], v[180:181] op_sel_hi:[1,0,1]
	v_pk_fma_f32 v[182:183], v[218:219], s[56:57], v[182:183] op_sel_hi:[1,0,1]
	v_pk_fma_f32 v[184:185], v[216:217], s[58:59], v[184:185] op_sel_hi:[1,0,1]
	v_pk_fma_f32 v[186:187], v[218:219], s[58:59], v[186:187] op_sel_hi:[1,0,1]
	s_waitcnt vmcnt(7)
	v_readlane_b32 s50, v236, 56
	v_readlane_b32 s52, v237, 56
	v_readlane_b32 s54, v238, 56
	v_readlane_b32 s56, v239, 56
	v_readlane_b32 s58, v240, 56
	v_pk_fma_f32 v[168:169], v[220:221], s[50:51], v[168:169] op_sel_hi:[1,0,1]
	v_pk_fma_f32 v[170:171], v[222:223], s[50:51], v[170:171] op_sel_hi:[1,0,1]
	v_pk_fma_f32 v[172:173], v[220:221], s[52:53], v[172:173] op_sel_hi:[1,0,1]
	v_pk_fma_f32 v[174:175], v[222:223], s[52:53], v[174:175] op_sel_hi:[1,0,1]
	v_pk_fma_f32 v[176:177], v[220:221], s[54:55], v[176:177] op_sel_hi:[1,0,1]
	v_pk_fma_f32 v[178:179], v[222:223], s[54:55], v[178:179] op_sel_hi:[1,0,1]
	v_pk_fma_f32 v[180:181], v[220:221], s[56:57], v[180:181] op_sel_hi:[1,0,1]
	v_pk_fma_f32 v[182:183], v[222:223], s[56:57], v[182:183] op_sel_hi:[1,0,1]
	v_pk_fma_f32 v[184:185], v[220:221], s[58:59], v[184:185] op_sel_hi:[1,0,1]
	v_pk_fma_f32 v[186:187], v[222:223], s[58:59], v[186:187] op_sel_hi:[1,0,1]
	s_waitcnt vmcnt(6)
	v_readlane_b32 s50, v236, 57
	v_readlane_b32 s52, v237, 57
	v_readlane_b32 s54, v238, 57
	v_readlane_b32 s56, v239, 57
	v_readlane_b32 s58, v240, 57
	v_pk_fma_f32 v[168:169], v[224:225], s[50:51], v[168:169] op_sel_hi:[1,0,1]
	v_pk_fma_f32 v[170:171], v[226:227], s[50:51], v[170:171] op_sel_hi:[1,0,1]
	v_pk_fma_f32 v[172:173], v[224:225], s[52:53], v[172:173] op_sel_hi:[1,0,1]
	v_pk_fma_f32 v[174:175], v[226:227], s[52:53], v[174:175] op_sel_hi:[1,0,1]
	v_pk_fma_f32 v[176:177], v[224:225], s[54:55], v[176:177] op_sel_hi:[1,0,1]
	v_pk_fma_f32 v[178:179], v[226:227], s[54:55], v[178:179] op_sel_hi:[1,0,1]
	v_pk_fma_f32 v[180:181], v[224:225], s[56:57], v[180:181] op_sel_hi:[1,0,1]
	v_pk_fma_f32 v[182:183], v[226:227], s[56:57], v[182:183] op_sel_hi:[1,0,1]
	v_pk_fma_f32 v[184:185], v[224:225], s[58:59], v[184:185] op_sel_hi:[1,0,1]
	v_pk_fma_f32 v[186:187], v[226:227], s[58:59], v[186:187] op_sel_hi:[1,0,1]
	s_waitcnt vmcnt(5)
	v_readlane_b32 s50, v236, 58
	v_readlane_b32 s52, v237, 58
	v_readlane_b32 s54, v238, 58
	v_readlane_b32 s56, v239, 58
	v_readlane_b32 s58, v240, 58
	v_pk_fma_f32 v[168:169], v[228:229], s[50:51], v[168:169] op_sel_hi:[1,0,1]
	v_pk_fma_f32 v[170:171], v[230:231], s[50:51], v[170:171] op_sel_hi:[1,0,1]
	v_pk_fma_f32 v[172:173], v[228:229], s[52:53], v[172:173] op_sel_hi:[1,0,1]
	v_pk_fma_f32 v[174:175], v[230:231], s[52:53], v[174:175] op_sel_hi:[1,0,1]
	v_pk_fma_f32 v[176:177], v[228:229], s[54:55], v[176:177] op_sel_hi:[1,0,1]
	v_pk_fma_f32 v[178:179], v[230:231], s[54:55], v[178:179] op_sel_hi:[1,0,1]
	v_pk_fma_f32 v[180:181], v[228:229], s[56:57], v[180:181] op_sel_hi:[1,0,1]
	v_pk_fma_f32 v[182:183], v[230:231], s[56:57], v[182:183] op_sel_hi:[1,0,1]
	v_pk_fma_f32 v[184:185], v[228:229], s[58:59], v[184:185] op_sel_hi:[1,0,1]
	v_pk_fma_f32 v[186:187], v[230:231], s[58:59], v[186:187] op_sel_hi:[1,0,1]
	s_waitcnt vmcnt(4)
	v_readlane_b32 s50, v236, 59
	v_readlane_b32 s52, v237, 59
	v_readlane_b32 s54, v238, 59
	v_readlane_b32 s56, v239, 59
	v_readlane_b32 s58, v240, 59
	v_pk_fma_f32 v[168:169], v[232:233], s[50:51], v[168:169] op_sel_hi:[1,0,1]
	v_pk_fma_f32 v[170:171], v[234:235], s[50:51], v[170:171] op_sel_hi:[1,0,1]
	v_pk_fma_f32 v[172:173], v[232:233], s[52:53], v[172:173] op_sel_hi:[1,0,1]
	v_pk_fma_f32 v[174:175], v[234:235], s[52:53], v[174:175] op_sel_hi:[1,0,1]
	v_pk_fma_f32 v[176:177], v[232:233], s[54:55], v[176:177] op_sel_hi:[1,0,1]
	v_pk_fma_f32 v[178:179], v[234:235], s[54:55], v[178:179] op_sel_hi:[1,0,1]
	v_pk_fma_f32 v[180:181], v[232:233], s[56:57], v[180:181] op_sel_hi:[1,0,1]
	v_pk_fma_f32 v[182:183], v[234:235], s[56:57], v[182:183] op_sel_hi:[1,0,1]
	v_pk_fma_f32 v[184:185], v[232:233], s[58:59], v[184:185] op_sel_hi:[1,0,1]
	v_pk_fma_f32 v[186:187], v[234:235], s[58:59], v[186:187] op_sel_hi:[1,0,1]
	s_waitcnt vmcnt(3)
	v_readlane_b32 s50, v236, 60
	v_readlane_b32 s52, v237, 60
	v_readlane_b32 s54, v238, 60
	v_readlane_b32 s56, v239, 60
	v_readlane_b32 s58, v240, 60
	v_pk_fma_f32 v[168:169], v[188:189], s[50:51], v[168:169] op_sel_hi:[1,0,1]
	v_pk_fma_f32 v[170:171], v[190:191], s[50:51], v[170:171] op_sel_hi:[1,0,1]
	v_pk_fma_f32 v[172:173], v[188:189], s[52:53], v[172:173] op_sel_hi:[1,0,1]
	v_pk_fma_f32 v[174:175], v[190:191], s[52:53], v[174:175] op_sel_hi:[1,0,1]
	v_pk_fma_f32 v[176:177], v[188:189], s[54:55], v[176:177] op_sel_hi:[1,0,1]
	v_pk_fma_f32 v[178:179], v[190:191], s[54:55], v[178:179] op_sel_hi:[1,0,1]
	v_pk_fma_f32 v[180:181], v[188:189], s[56:57], v[180:181] op_sel_hi:[1,0,1]
	v_pk_fma_f32 v[182:183], v[190:191], s[56:57], v[182:183] op_sel_hi:[1,0,1]
	v_pk_fma_f32 v[184:185], v[188:189], s[58:59], v[184:185] op_sel_hi:[1,0,1]
	v_pk_fma_f32 v[186:187], v[190:191], s[58:59], v[186:187] op_sel_hi:[1,0,1]
	s_waitcnt vmcnt(2)
	v_readlane_b32 s50, v236, 61
	v_readlane_b32 s52, v237, 61
	v_readlane_b32 s54, v238, 61
	v_readlane_b32 s56, v239, 61
	v_readlane_b32 s58, v240, 61
	v_pk_fma_f32 v[168:169], v[192:193], s[50:51], v[168:169] op_sel_hi:[1,0,1]
	v_pk_fma_f32 v[170:171], v[194:195], s[50:51], v[170:171] op_sel_hi:[1,0,1]
	v_pk_fma_f32 v[172:173], v[192:193], s[52:53], v[172:173] op_sel_hi:[1,0,1]
	v_pk_fma_f32 v[174:175], v[194:195], s[52:53], v[174:175] op_sel_hi:[1,0,1]
	v_pk_fma_f32 v[176:177], v[192:193], s[54:55], v[176:177] op_sel_hi:[1,0,1]
	v_pk_fma_f32 v[178:179], v[194:195], s[54:55], v[178:179] op_sel_hi:[1,0,1]
	v_pk_fma_f32 v[180:181], v[192:193], s[56:57], v[180:181] op_sel_hi:[1,0,1]
	v_pk_fma_f32 v[182:183], v[194:195], s[56:57], v[182:183] op_sel_hi:[1,0,1]
	v_pk_fma_f32 v[184:185], v[192:193], s[58:59], v[184:185] op_sel_hi:[1,0,1]
	v_pk_fma_f32 v[186:187], v[194:195], s[58:59], v[186:187] op_sel_hi:[1,0,1]
	s_waitcnt vmcnt(1)
	v_readlane_b32 s50, v236, 62
	v_readlane_b32 s52, v237, 62
	v_readlane_b32 s54, v238, 62
	v_readlane_b32 s56, v239, 62
	v_readlane_b32 s58, v240, 62
	v_pk_fma_f32 v[168:169], v[196:197], s[50:51], v[168:169] op_sel_hi:[1,0,1]
	v_pk_fma_f32 v[170:171], v[198:199], s[50:51], v[170:171] op_sel_hi:[1,0,1]
	v_pk_fma_f32 v[172:173], v[196:197], s[52:53], v[172:173] op_sel_hi:[1,0,1]
	v_pk_fma_f32 v[174:175], v[198:199], s[52:53], v[174:175] op_sel_hi:[1,0,1]
	v_pk_fma_f32 v[176:177], v[196:197], s[54:55], v[176:177] op_sel_hi:[1,0,1]
	v_pk_fma_f32 v[178:179], v[198:199], s[54:55], v[178:179] op_sel_hi:[1,0,1]
	v_pk_fma_f32 v[180:181], v[196:197], s[56:57], v[180:181] op_sel_hi:[1,0,1]
	v_pk_fma_f32 v[182:183], v[198:199], s[56:57], v[182:183] op_sel_hi:[1,0,1]
	v_pk_fma_f32 v[184:185], v[196:197], s[58:59], v[184:185] op_sel_hi:[1,0,1]
	v_pk_fma_f32 v[186:187], v[198:199], s[58:59], v[186:187] op_sel_hi:[1,0,1]
	s_waitcnt vmcnt(0)
	v_readlane_b32 s50, v236, 63
	v_readlane_b32 s52, v237, 63
	v_readlane_b32 s54, v238, 63
	v_readlane_b32 s56, v239, 63
	v_readlane_b32 s58, v240, 63
	v_pk_fma_f32 v[168:169], v[200:201], s[50:51], v[168:169] op_sel_hi:[1,0,1]
	v_pk_fma_f32 v[170:171], v[202:203], s[50:51], v[170:171] op_sel_hi:[1,0,1]
	v_pk_fma_f32 v[172:173], v[200:201], s[52:53], v[172:173] op_sel_hi:[1,0,1]
	v_pk_fma_f32 v[174:175], v[202:203], s[52:53], v[174:175] op_sel_hi:[1,0,1]
	v_pk_fma_f32 v[176:177], v[200:201], s[54:55], v[176:177] op_sel_hi:[1,0,1]
	v_pk_fma_f32 v[178:179], v[202:203], s[54:55], v[178:179] op_sel_hi:[1,0,1]
	v_pk_fma_f32 v[180:181], v[200:201], s[56:57], v[180:181] op_sel_hi:[1,0,1]
	v_pk_fma_f32 v[182:183], v[202:203], s[56:57], v[182:183] op_sel_hi:[1,0,1]
	v_pk_fma_f32 v[184:185], v[200:201], s[58:59], v[184:185] op_sel_hi:[1,0,1]
	v_pk_fma_f32 v[186:187], v[202:203], s[58:59], v[186:187] op_sel_hi:[1,0,1]
	s_mov_b32 s6, s13
	s_cmp_ge_u32 s6, 0x2800
	s_cbranch_scc1 .Lgpost_bend
	v_add_f32_e32 v2, v2, v6
	v_add_f32_e32 v3, v3, v7
	v_add_f32_e32 v4, v4, v8
	v_add_f32_e32 v5, v5, v9
	v_add_f32_e32 v241, v2, v3
	v_add_f32_e32 v242, v4, v5
	v_add_f32_e32 v241, v241, v242
	s_nop 1
	v_add_f32_dpp v241, v241, v241 quad_perm:[1,0,3,2] row_mask:0xf bank_mask:0xf bound_ctrl:1
	s_nop 1
	v_add_f32_dpp v241, v241, v241 quad_perm:[2,3,0,1] row_mask:0xf bank_mask:0xf bound_ctrl:1
	s_nop 1
	v_add_f32_dpp v241, v241, v241 row_half_mirror row_mask:0xf bank_mask:0xf bound_ctrl:1
	s_nop 1
	v_add_f32_dpp v241, v241, v241 row_mirror row_mask:0xf bank_mask:0xf bound_ctrl:1
	v_mul_f32_e32 v241, 0x3c800000, v241
	v_sub_f32_e32 v2, v2, v241
	v_sub_f32_e32 v3, v3, v241
	v_sub_f32_e32 v4, v4, v241
	v_sub_f32_e32 v5, v5, v241
	v_mul_f32_e32 v243, v10, v14
	v_mul_f32_e32 v244, v11, v15
	v_mul_f32_e32 v245, v12, v16
	v_mul_f32_e32 v246, v13, v17
	v_mul_f32_e32 v243, v122, v243
	v_mul_f32_e32 v245, v124, v245
	v_fmac_f32_e32 v243, v123, v244
	v_fmac_f32_e32 v245, v125, v246
	v_add_f32_e32 v243, v243, v245
	s_nop 1
	v_add_f32_dpp v243, v243, v243 quad_perm:[1,0,3,2] row_mask:0xf bank_mask:0xf bound_ctrl:1
	s_nop 1
	v_add_f32_dpp v243, v243, v243 quad_perm:[2,3,0,1] row_mask:0xf bank_mask:0xf bound_ctrl:1
	s_nop 1
	v_add_f32_dpp v243, v243, v243 row_half_mirror row_mask:0xf bank_mask:0xf bound_ctrl:1
	s_nop 1
	v_add_f32_dpp v243, v243, v243 row_mirror row_mask:0xf bank_mask:0xf bound_ctrl:1
	v_mul_f32_e32 v244, v3, v3
	v_mul_f32_e32 v245, v5, v5
	v_fmac_f32_e32 v244, v2, v2
	v_fmac_f32_e32 v245, v4, v4
	v_add_f32_e32 v244, v244, v245
	s_nop 1
	v_add_f32_dpp v244, v244, v244 quad_perm:[1,0,3,2] row_mask:0xf bank_mask:0xf bound_ctrl:1
	s_nop 1
	v_add_f32_dpp v244, v244, v244 quad_perm:[2,3,0,1] row_mask:0xf bank_mask:0xf bound_ctrl:1
	s_nop 1
	v_add_f32_dpp v244, v244, v244 row_half_mirror row_mask:0xf bank_mask:0xf bound_ctrl:1
	s_nop 1
	v_add_f32_dpp v244, v244, v244 row_mirror row_mask:0xf bank_mask:0xf bound_ctrl:1
	v_fmamk_f32 v244, v244, 0x3c800000, v132
	v_rsq_f32_e32 v244, v244
	s_nop 0
	v_mul_f32_e32 v245, v2, v244
	v_fma_f32 v245, v110, v245, v118
	v_fmac_f32_e32 v245, v18, v243
	v_mul_f32_e32 v6, v168, v245
	v_mul_f32_e32 v245, v3, v244
	v_fma_f32 v245, v111, v245, v119
	v_fmac_f32_e32 v245, v19, v243
	v_mul_f32_e32 v7, v169, v245
	v_mul_f32_e32 v245, v4, v244
	v_fma_f32 v245, v112, v245, v120
	v_fmac_f32_e32 v245, v20, v243
	v_mul_f32_e32 v8, v170, v245
	v_mul_f32_e32 v245, v5, v244
	v_fma_f32 v245, v113, v245, v121
	v_fmac_f32_e32 v245, v21, v243
	v_mul_f32_e32 v9, v171, v245
	v_cvt_pk_bf16_f32 v10, v6, v7
	v_cvt_pk_bf16_f32 v11, v8, v9
	s_lshl_b32 s7, s6, 11
	s_add_u32 s7, s7, 0x600
	s_add_u32 s8, s80, s7
	s_addc_u32 s9, s81, 0
	global_store_dwordx2 v250, v[10:11], s[8:9]
	s_add_u32 s6, s13, 1
	s_cmp_ge_u32 s6, 0x2800
	s_cbranch_scc1 .Lgpost_bend
	v_add_f32_e32 v24, v24, v28
	v_add_f32_e32 v25, v25, v29
	v_add_f32_e32 v26, v26, v30
	v_add_f32_e32 v27, v27, v31
	v_add_f32_e32 v241, v24, v25
	v_add_f32_e32 v242, v26, v27
	v_add_f32_e32 v241, v241, v242
	s_nop 1
	v_add_f32_dpp v241, v241, v241 quad_perm:[1,0,3,2] row_mask:0xf bank_mask:0xf bound_ctrl:1
	s_nop 1
	v_add_f32_dpp v241, v241, v241 quad_perm:[2,3,0,1] row_mask:0xf bank_mask:0xf bound_ctrl:1
	s_nop 1
	v_add_f32_dpp v241, v241, v241 row_half_mirror row_mask:0xf bank_mask:0xf bound_ctrl:1
	s_nop 1
	v_add_f32_dpp v241, v241, v241 row_mirror row_mask:0xf bank_mask:0xf bound_ctrl:1
	v_mul_f32_e32 v241, 0x3c800000, v241
	v_sub_f32_e32 v24, v24, v241
	v_sub_f32_e32 v25, v25, v241
	v_sub_f32_e32 v26, v26, v241
	v_sub_f32_e32 v27, v27, v241
	v_mul_f32_e32 v243, v32, v36
	v_mul_f32_e32 v244, v33, v37
	v_mul_f32_e32 v245, v34, v38
	v_mul_f32_e32 v246, v35, v39
	v_mul_f32_e32 v243, v122, v243
	v_mul_f32_e32 v245, v124, v245
	v_fmac_f32_e32 v243, v123, v244
	v_fmac_f32_e32 v245, v125, v246
	v_add_f32_e32 v243, v243, v245
	s_nop 1
	v_add_f32_dpp v243, v243, v243 quad_perm:[1,0,3,2] row_mask:0xf bank_mask:0xf bound_ctrl:1
	s_nop 1
	v_add_f32_dpp v243, v243, v243 quad_perm:[2,3,0,1] row_mask:0xf bank_mask:0xf bound_ctrl:1
	s_nop 1
	v_add_f32_dpp v243, v243, v243 row_half_mirror row_mask:0xf bank_mask:0xf bound_ctrl:1
	s_nop 1
	v_add_f32_dpp v243, v243, v243 row_mirror row_mask:0xf bank_mask:0xf bound_ctrl:1
	v_mul_f32_e32 v244, v25, v25
	v_mul_f32_e32 v245, v27, v27
	v_fmac_f32_e32 v244, v24, v24
	v_fmac_f32_e32 v245, v26, v26
	v_add_f32_e32 v244, v244, v245
	s_nop 1
	v_add_f32_dpp v244, v244, v244 quad_perm:[1,0,3,2] row_mask:0xf bank_mask:0xf bound_ctrl:1
	s_nop 1
	v_add_f32_dpp v244, v244, v244 quad_perm:[2,3,0,1] row_mask:0xf bank_mask:0xf bound_ctrl:1
	s_nop 1
	v_add_f32_dpp v244, v244, v244 row_half_mirror row_mask:0xf bank_mask:0xf bound_ctrl:1
	s_nop 1
	v_add_f32_dpp v244, v244, v244 row_mirror row_mask:0xf bank_mask:0xf bound_ctrl:1
	v_fmamk_f32 v244, v244, 0x3c800000, v132
	v_rsq_f32_e32 v244, v244
	s_nop 0
	v_mul_f32_e32 v245, v24, v244
	v_fma_f32 v245, v110, v245, v118
	v_fmac_f32_e32 v245, v40, v243
	v_mul_f32_e32 v28, v172, v245
	v_mul_f32_e32 v245, v25, v244
	v_fma_f32 v245, v111, v245, v119
	v_fmac_f32_e32 v245, v41, v243
	v_mul_f32_e32 v29, v173, v245
	v_mul_f32_e32 v245, v26, v244
	v_fma_f32 v245, v112, v245, v120
	v_fmac_f32_e32 v245, v42, v243
	v_mul_f32_e32 v30, v174, v245
	v_mul_f32_e32 v245, v27, v244
	v_fma_f32 v245, v113, v245, v121
	v_fmac_f32_e32 v245, v43, v243
	v_mul_f32_e32 v31, v175, v245
	v_cvt_pk_bf16_f32 v32, v28, v29
	v_cvt_pk_bf16_f32 v33, v30, v31
	s_lshl_b32 s7, s6, 11
	s_add_u32 s7, s7, 0x600
	s_add_u32 s8, s80, s7
	s_addc_u32 s9, s81, 0
	global_store_dwordx2 v250, v[32:33], s[8:9]
	s_add_u32 s6, s13, 2
	s_cmp_ge_u32 s6, 0x2800
	s_cbranch_scc1 .Lgpost_bend
	v_add_f32_e32 v46, v46, v50
	v_add_f32_e32 v47, v47, v51
	v_add_f32_e32 v48, v48, v52
	v_add_f32_e32 v49, v49, v53
	v_add_f32_e32 v241, v46, v47
	v_add_f32_e32 v242, v48, v49
	v_add_f32_e32 v241, v241, v242
	s_nop 1
	v_add_f32_dpp v241, v241, v241 quad_perm:[1,0,3,2] row_mask:0xf bank_mask:0xf bound_ctrl:1
	s_nop 1
	v_add_f32_dpp v241, v241, v241 quad_perm:[2,3,0,1] row_mask:0xf bank_mask:0xf bound_ctrl:1
	s_nop 1
	v_add_f32_dpp v241, v241, v241 row_half_mirror row_mask:0xf bank_mask:0xf bound_ctrl:1
	s_nop 1
	v_add_f32_dpp v241, v241, v241 row_mirror row_mask:0xf bank_mask:0xf bound_ctrl:1
	v_mul_f32_e32 v241, 0x3c800000, v241
	v_sub_f32_e32 v46, v46, v241
	v_sub_f32_e32 v47, v47, v241
	v_sub_f32_e32 v48, v48, v241
	v_sub_f32_e32 v49, v49, v241
	v_mul_f32_e32 v243, v54, v58
	v_mul_f32_e32 v244, v55, v59
	v_mul_f32_e32 v245, v56, v60
	v_mul_f32_e32 v246, v57, v61
	v_mul_f32_e32 v243, v122, v243
	v_mul_f32_e32 v245, v124, v245
	v_fmac_f32_e32 v243, v123, v244
	v_fmac_f32_e32 v245, v125, v246
	v_add_f32_e32 v243, v243, v245
	s_nop 1
	v_add_f32_dpp v243, v243, v243 quad_perm:[1,0,3,2] row_mask:0xf bank_mask:0xf bound_ctrl:1
	s_nop 1
	v_add_f32_dpp v243, v243, v243 quad_perm:[2,3,0,1] row_mask:0xf bank_mask:0xf bound_ctrl:1
	s_nop 1
	v_add_f32_dpp v243, v243, v243 row_half_mirror row_mask:0xf bank_mask:0xf bound_ctrl:1
	s_nop 1
	v_add_f32_dpp v243, v243, v243 row_mirror row_mask:0xf bank_mask:0xf bound_ctrl:1
	v_mul_f32_e32 v244, v47, v47
	v_mul_f32_e32 v245, v49, v49
	v_fmac_f32_e32 v244, v46, v46
	v_fmac_f32_e32 v245, v48, v48
	v_add_f32_e32 v244, v244, v245
	s_nop 1
	v_add_f32_dpp v244, v244, v244 quad_perm:[1,0,3,2] row_mask:0xf bank_mask:0xf bound_ctrl:1
	s_nop 1
	v_add_f32_dpp v244, v244, v244 quad_perm:[2,3,0,1] row_mask:0xf bank_mask:0xf bound_ctrl:1
	s_nop 1
	v_add_f32_dpp v244, v244, v244 row_half_mirror row_mask:0xf bank_mask:0xf bound_ctrl:1
	s_nop 1
	v_add_f32_dpp v244, v244, v244 row_mirror row_mask:0xf bank_mask:0xf bound_ctrl:1
	v_fmamk_f32 v244, v244, 0x3c800000, v132
	v_rsq_f32_e32 v244, v244
	s_nop 0
	v_mul_f32_e32 v245, v46, v244
	v_fma_f32 v245, v110, v245, v118
	v_fmac_f32_e32 v245, v62, v243
	v_mul_f32_e32 v50, v176, v245
	v_mul_f32_e32 v245, v47, v244
	v_fma_f32 v245, v111, v245, v119
	v_fmac_f32_e32 v245, v63, v243
	v_mul_f32_e32 v51, v177, v245
	v_mul_f32_e32 v245, v48, v244
	v_fma_f32 v245, v112, v245, v120
	v_fmac_f32_e32 v245, v64, v243
	v_mul_f32_e32 v52, v178, v245
	v_mul_f32_e32 v245, v49, v244
	v_fma_f32 v245, v113, v245, v121
	v_fmac_f32_e32 v245, v65, v243
	v_mul_f32_e32 v53, v179, v245
	v_cvt_pk_bf16_f32 v54, v50, v51
	v_cvt_pk_bf16_f32 v55, v52, v53
	s_lshl_b32 s7, s6, 11
	s_add_u32 s7, s7, 0x600
	s_add_u32 s8, s80, s7
	s_addc_u32 s9, s81, 0
	global_store_dwordx2 v250, v[54:55], s[8:9]
	s_add_u32 s6, s13, 3
	s_cmp_ge_u32 s6, 0x2800
	s_cbranch_scc1 .Lgpost_bend
	v_add_f32_e32 v68, v68, v72
	v_add_f32_e32 v69, v69, v73
	v_add_f32_e32 v70, v70, v74
	v_add_f32_e32 v71, v71, v75
	v_add_f32_e32 v241, v68, v69
	v_add_f32_e32 v242, v70, v71
	v_add_f32_e32 v241, v241, v242
	s_nop 1
	v_add_f32_dpp v241, v241, v241 quad_perm:[1,0,3,2] row_mask:0xf bank_mask:0xf bound_ctrl:1
	s_nop 1
	v_add_f32_dpp v241, v241, v241 quad_perm:[2,3,0,1] row_mask:0xf bank_mask:0xf bound_ctrl:1
	s_nop 1
	v_add_f32_dpp v241, v241, v241 row_half_mirror row_mask:0xf bank_mask:0xf bound_ctrl:1
	s_nop 1
	v_add_f32_dpp v241, v241, v241 row_mirror row_mask:0xf bank_mask:0xf bound_ctrl:1
	v_mul_f32_e32 v241, 0x3c800000, v241
	v_sub_f32_e32 v68, v68, v241
	v_sub_f32_e32 v69, v69, v241
	v_sub_f32_e32 v70, v70, v241
	v_sub_f32_e32 v71, v71, v241
	v_mul_f32_e32 v243, v76, v80
	v_mul_f32_e32 v244, v77, v81
	v_mul_f32_e32 v245, v78, v82
	v_mul_f32_e32 v246, v79, v83
	v_mul_f32_e32 v243, v122, v243
	v_mul_f32_e32 v245, v124, v245
	v_fmac_f32_e32 v243, v123, v244
	v_fmac_f32_e32 v245, v125, v246
	v_add_f32_e32 v243, v243, v245
	s_nop 1
	v_add_f32_dpp v243, v243, v243 quad_perm:[1,0,3,2] row_mask:0xf bank_mask:0xf bound_ctrl:1
	s_nop 1
	v_add_f32_dpp v243, v243, v243 quad_perm:[2,3,0,1] row_mask:0xf bank_mask:0xf bound_ctrl:1
	s_nop 1
	v_add_f32_dpp v243, v243, v243 row_half_mirror row_mask:0xf bank_mask:0xf bound_ctrl:1
	s_nop 1
	v_add_f32_dpp v243, v243, v243 row_mirror row_mask:0xf bank_mask:0xf bound_ctrl:1
	v_mul_f32_e32 v244, v69, v69
	v_mul_f32_e32 v245, v71, v71
	v_fmac_f32_e32 v244, v68, v68
	v_fmac_f32_e32 v245, v70, v70
	v_add_f32_e32 v244, v244, v245
	s_nop 1
	v_add_f32_dpp v244, v244, v244 quad_perm:[1,0,3,2] row_mask:0xf bank_mask:0xf bound_ctrl:1
	s_nop 1
	v_add_f32_dpp v244, v244, v244 quad_perm:[2,3,0,1] row_mask:0xf bank_mask:0xf bound_ctrl:1
	s_nop 1
	v_add_f32_dpp v244, v244, v244 row_half_mirror row_mask:0xf bank_mask:0xf bound_ctrl:1
	s_nop 1
	v_add_f32_dpp v244, v244, v244 row_mirror row_mask:0xf bank_mask:0xf bound_ctrl:1
	v_fmamk_f32 v244, v244, 0x3c800000, v132
	v_rsq_f32_e32 v244, v244
	s_nop 0
	v_mul_f32_e32 v245, v68, v244
	v_fma_f32 v245, v110, v245, v118
	v_fmac_f32_e32 v245, v84, v243
	v_mul_f32_e32 v72, v180, v245
	v_mul_f32_e32 v245, v69, v244
	v_fma_f32 v245, v111, v245, v119
	v_fmac_f32_e32 v245, v85, v243
	v_mul_f32_e32 v73, v181, v245
	v_mul_f32_e32 v245, v70, v244
	v_fma_f32 v245, v112, v245, v120
	v_fmac_f32_e32 v245, v86, v243
	v_mul_f32_e32 v74, v182, v245
	v_mul_f32_e32 v245, v71, v244
	v_fma_f32 v245, v113, v245, v121
	v_fmac_f32_e32 v245, v87, v243
	v_mul_f32_e32 v75, v183, v245
	v_cvt_pk_bf16_f32 v76, v72, v73
	v_cvt_pk_bf16_f32 v77, v74, v75
	s_lshl_b32 s7, s6, 11
	s_add_u32 s7, s7, 0x600
	s_add_u32 s8, s80, s7
	s_addc_u32 s9, s81, 0
	global_store_dwordx2 v250, v[76:77], s[8:9]
	s_add_u32 s6, s13, 4
	s_cmp_ge_u32 s6, 0x2800
	s_cbranch_scc1 .Lgpost_bend
	v_add_f32_e32 v90, v90, v94
	v_add_f32_e32 v91, v91, v95
	v_add_f32_e32 v92, v92, v96
	v_add_f32_e32 v93, v93, v97
	v_add_f32_e32 v241, v90, v91
	v_add_f32_e32 v242, v92, v93
	v_add_f32_e32 v241, v241, v242
	s_nop 1
	v_add_f32_dpp v241, v241, v241 quad_perm:[1,0,3,2] row_mask:0xf bank_mask:0xf bound_ctrl:1
	s_nop 1
	v_add_f32_dpp v241, v241, v241 quad_perm:[2,3,0,1] row_mask:0xf bank_mask:0xf bound_ctrl:1
	s_nop 1
	v_add_f32_dpp v241, v241, v241 row_half_mirror row_mask:0xf bank_mask:0xf bound_ctrl:1
	s_nop 1
	v_add_f32_dpp v241, v241, v241 row_mirror row_mask:0xf bank_mask:0xf bound_ctrl:1
	v_mul_f32_e32 v241, 0x3c800000, v241
	v_sub_f32_e32 v90, v90, v241
	v_sub_f32_e32 v91, v91, v241
	v_sub_f32_e32 v92, v92, v241
	v_sub_f32_e32 v93, v93, v241
	v_mul_f32_e32 v243, v98, v102
	v_mul_f32_e32 v244, v99, v103
	v_mul_f32_e32 v245, v100, v104
	v_mul_f32_e32 v246, v101, v105
	v_mul_f32_e32 v243, v122, v243
	v_mul_f32_e32 v245, v124, v245
	v_fmac_f32_e32 v243, v123, v244
	v_fmac_f32_e32 v245, v125, v246
	v_add_f32_e32 v243, v243, v245
	s_nop 1
	v_add_f32_dpp v243, v243, v243 quad_perm:[1,0,3,2] row_mask:0xf bank_mask:0xf bound_ctrl:1
	s_nop 1
	v_add_f32_dpp v243, v243, v243 quad_perm:[2,3,0,1] row_mask:0xf bank_mask:0xf bound_ctrl:1
	s_nop 1
	v_add_f32_dpp v243, v243, v243 row_half_mirror row_mask:0xf bank_mask:0xf bound_ctrl:1
	s_nop 1
	v_add_f32_dpp v243, v243, v243 row_mirror row_mask:0xf bank_mask:0xf bound_ctrl:1
	v_mul_f32_e32 v244, v91, v91
	v_mul_f32_e32 v245, v93, v93
	v_fmac_f32_e32 v244, v90, v90
	v_fmac_f32_e32 v245, v92, v92
	v_add_f32_e32 v244, v244, v245
	s_nop 1
	v_add_f32_dpp v244, v244, v244 quad_perm:[1,0,3,2] row_mask:0xf bank_mask:0xf bound_ctrl:1
	s_nop 1
	v_add_f32_dpp v244, v244, v244 quad_perm:[2,3,0,1] row_mask:0xf bank_mask:0xf bound_ctrl:1
	s_nop 1
	v_add_f32_dpp v244, v244, v244 row_half_mirror row_mask:0xf bank_mask:0xf bound_ctrl:1
	s_nop 1
	v_add_f32_dpp v244, v244, v244 row_mirror row_mask:0xf bank_mask:0xf bound_ctrl:1
	v_fmamk_f32 v244, v244, 0x3c800000, v132
	v_rsq_f32_e32 v244, v244
	s_nop 0
	v_mul_f32_e32 v245, v90, v244
	v_fma_f32 v245, v110, v245, v118
	v_fmac_f32_e32 v245, v106, v243
	v_mul_f32_e32 v94, v184, v245
	v_mul_f32_e32 v245, v91, v244
	v_fma_f32 v245, v111, v245, v119
	v_fmac_f32_e32 v245, v107, v243
	v_mul_f32_e32 v95, v185, v245
	v_mul_f32_e32 v245, v92, v244
	v_fma_f32 v245, v112, v245, v120
	v_fmac_f32_e32 v245, v108, v243
	v_mul_f32_e32 v96, v186, v245
	v_mul_f32_e32 v245, v93, v244
	v_fma_f32 v245, v113, v245, v121
	v_fmac_f32_e32 v245, v109, v243
	v_mul_f32_e32 v97, v187, v245
	v_cvt_pk_bf16_f32 v98, v94, v95
	v_cvt_pk_bf16_f32 v99, v96, v97
	s_lshl_b32 s7, s6, 11
	s_add_u32 s7, s7, 0x600
	s_add_u32 s8, s80, s7
	s_addc_u32 s9, s81, 0
	global_store_dwordx2 v250, v[98:99], s[8:9]
